# in-proj softplus(dt) epilogue: the 8 dt_bias values are loaded once into registers, per-element load+wait chain removed
# baseline (speedup 1.0000x reference)
;     __device__ __forceinline__ void operator()(const f32x4 (&acc)[2][2][4][2], const Unit& u, int wr, int wc, int fr, int fq) const {
;     ...
;                     for (int m = 0; m < 4; ++m) { const int r = row0 + ai * HALF + m * 16;
;                         const f32x4 v0 = acc[ai][0][m][0], v1 = acc[ai][0][m][1]; float* dp = DT + (size_t)r * 32 + c0;
; #pragma unroll
;                         for (int i = 0; i < 4; ++i) { float x0 = v0[i] + dt_bias[c0 + i], x1 = v1[i] + dt_bias[c0 + 4 + i];
;                             dp[i] = x0 > 20.f ? x0 : log1pf(__expf(x0)); dp[4 + i] = x1 > 20.f ? x1 : log1pf(__expf(x1)); }
.LBB0_783:
	global_load_dword v200, v[140:141], off
	global_load_dword v201, v[140:141], off offset:4
	global_load_dword v202, v[140:141], off offset:8
	global_load_dword v203, v[140:141], off offset:12
	global_load_dword v204, v[140:141], off offset:16
	global_load_dword v205, v[140:141], off offset:20
	global_load_dword v206, v[140:141], off offset:24
	global_load_dword v207, v[140:141], off offset:28
	s_waitcnt vmcnt(0)
	v_mov_b32_e32 v136, v200
	v_add_f32_e32 v151, v124, v136
	v_mov_b32_e32 v136, v204
	v_cmp_nlt_f32_e32 vcc, s67, v151
	s_and_saveexec_b64 s[24:25], vcc
	s_cbranch_execz .LBB0_785
	v_mul_f32_e32 v151, 0x3fb8aa3b, v151
	v_exp_f32_e32 v153, v151
	s_nop 0
	v_add_f32_e32 v151, 1.0, v153
	v_frexp_mant_f32_e32 v172, v151
	v_cvt_f64_f32_e32 v[154:155], v151
	v_add_f32_e32 v156, -1.0, v151
	v_frexp_exp_i32_f64_e32 v154, v[154:155]
	v_cmp_gt_f32_e32 vcc, s68, v172
	v_sub_f32_e32 v173, v156, v151
	v_sub_f32_e32 v156, v153, v156
	v_subbrev_co_u32_e32 v178, vcc, 0, v154, vcc
	v_add_f32_e32 v173, 1.0, v173
	v_sub_u32_e32 v154, 0, v178
	v_add_f32_e32 v156, v156, v173
	v_ldexp_f32 v151, v151, v154
	v_ldexp_f32 v154, v156, v154
	v_add_f32_e32 v156, -1.0, v151
	v_add_f32_e32 v155, 1.0, v156
	v_sub_f32_e32 v155, v151, v155
	v_add_f32_e32 v172, v154, v155
	v_add_f32_e32 v155, 1.0, v151
	v_add_f32_e32 v173, -1.0, v155
	v_sub_f32_e32 v151, v151, v173
	v_add_f32_e32 v151, v154, v151
	v_add_f32_e32 v179, v155, v151
	v_rcp_f32_e32 v180, v179
	v_sub_f32_e32 v154, v179, v155
	v_add_f32_e32 v155, v156, v172
	v_sub_f32_e32 v151, v151, v154
	v_sub_f32_e32 v154, v155, v156
	v_mul_f32_e32 v181, v155, v180
	v_sub_f32_e32 v156, v172, v154
	v_mul_f32_e32 v172, v179, v181
	v_fma_f32 v174, v181, v179, -v172
	v_fmac_f32_e32 v174, v181, v151
	v_add_f32_e32 v154, v172, v174
	v_sub_f32_e32 v173, v155, v154
	v_pk_add_f32 v[176:177], v[154:155], v[172:173] neg_lo:[0,1] neg_hi:[0,1]
	v_mov_b32_e32 v175, v154
	v_pk_add_f32 v[154:155], v[176:177], v[174:175] neg_lo:[0,1] neg_hi:[0,1]
	v_cmp_neq_f32_e32 vcc, s70, v153
	v_add_f32_e32 v155, v156, v155
	v_add_f32_e32 v154, v154, v155
	v_add_f32_e32 v155, v173, v154
	v_mul_f32_e32 v156, v180, v155
	v_mul_f32_e32 v172, v179, v156
	v_fma_f32 v174, v156, v179, -v172
	v_fmac_f32_e32 v174, v156, v151
	v_sub_f32_e32 v151, v173, v155
	v_add_f32_e32 v151, v154, v151
	v_add_f32_e32 v154, v172, v174
	v_sub_f32_e32 v173, v155, v154
	v_pk_add_f32 v[176:177], v[154:155], v[172:173] neg_lo:[0,1] neg_hi:[0,1]
	v_mov_b32_e32 v175, v154
	v_pk_add_f32 v[154:155], v[176:177], v[174:175] neg_lo:[0,1] neg_hi:[0,1]
	s_nop 0
	v_add_f32_e32 v151, v151, v155
	v_add_f32_e32 v151, v154, v151
	v_add_f32_e32 v155, v181, v156
	v_add_f32_e32 v151, v173, v151
	v_sub_f32_e32 v154, v155, v181
	v_mul_f32_e32 v151, v180, v151
	v_sub_f32_e32 v154, v156, v154
	v_add_f32_e32 v156, v154, v151
	v_add_f32_e32 v172, v155, v156
	v_cvt_f32_i32_e32 v154, v178
	v_mul_f32_e32 v174, v172, v172
	v_sub_f32_e32 v155, v172, v155
	v_fmamk_f32 v151, v174, 0x3e9b6dac, v166
	v_sub_f32_e32 v155, v156, v155
	v_fmaak_f32 v151, v174, v151, 0x3f2aaada
	v_ldexp_f32 v156, v155, 1
	v_mul_f32_e32 v155, v172, v174
	v_pk_mul_f32 v[174:175], v[154:155], v[150:151]
	v_ldexp_f32 v173, v172, 1
	v_fma_f32 v172, v154, s69, -v174
	v_fmac_f32_e32 v172, 0xb102e308, v154
	v_pk_add_f32 v[154:155], v[174:175], v[172:173]
	v_mov_b32_e32 v176, v174
	v_sub_f32_e32 v151, v155, v173
	v_sub_f32_e32 v151, v175, v151
	v_add_f32_e32 v177, v156, v151
	v_pk_add_f32 v[174:175], v[154:155], v[174:175] neg_lo:[0,1] neg_hi:[0,1]
	v_pk_add_f32 v[178:179], v[154:155], v[176:177]
	v_mov_b32_e32 v173, v154
	v_mov_b32_e32 v175, v179
	v_pk_add_f32 v[180:181], v[172:173], v[174:175] neg_lo:[0,1] neg_hi:[0,1]
	v_pk_add_f32 v[172:173], v[172:173], v[174:175]
	v_mov_b32_e32 v176, v177
	v_pk_add_f32 v[174:175], v[172:173], v[154:155] op_sel:[1,0] op_sel_hi:[0,1] neg_lo:[0,1] neg_hi:[0,1]
	v_pk_add_f32 v[182:183], v[178:179], v[174:175] op_sel_hi:[1,0] neg_lo:[0,1] neg_hi:[0,1]
	v_mov_b32_e32 v178, v179
	v_mov_b32_e32 v179, v173
	v_pk_mov_b32 v[174:175], v[154:155], v[174:175] op_sel:[1,0]
	v_mov_b32_e32 v177, v154
	v_pk_add_f32 v[174:175], v[178:179], v[174:175] neg_lo:[0,1] neg_hi:[0,1]
	v_mov_b32_e32 v182, v180
	v_pk_add_f32 v[154:155], v[176:177], v[174:175] neg_lo:[0,1] neg_hi:[0,1]
	v_mov_b32_e32 v181, v173
	v_pk_add_f32 v[174:175], v[182:183], v[154:155]
	s_nop 0
	v_pk_add_f32 v[176:177], v[174:175], v[174:175] op_sel:[0,1] op_sel_hi:[1,0]
	s_nop 0
	v_pk_add_f32 v[172:173], v[172:173], v[176:177] op_sel:[1,0] op_sel_hi:[0,1]
	v_mov_b32_e32 v175, v172
	v_pk_add_f32 v[178:179], v[174:175], v[180:181] neg_lo:[0,1] neg_hi:[0,1]
	v_mov_b32_e32 v155, v176
	v_sub_f32_e32 v151, v174, v178
	v_pk_add_f32 v[154:155], v[154:155], v[178:179] neg_lo:[0,1] neg_hi:[0,1]
	v_sub_f32_e32 v151, v180, v151
	v_add_f32_e32 v151, v154, v151
	v_add_f32_e32 v151, v151, v155
	v_add_f32_e32 v151, v172, v151
	v_cndmask_b32_e32 v151, v167, v151, vcc
	v_cmp_ngt_f32_e32 vcc, -1.0, v153
	s_nop 1
	v_cndmask_b32_e32 v151, v168, v151, vcc
	v_cmp_neq_f32_e32 vcc, -1.0, v153
	s_nop 1
	v_cndmask_b32_e32 v151, v169, v151, vcc
	v_cmp_lt_f32_e64 vcc, |v153|, s71
	s_nop 1
	v_cndmask_b32_e32 v151, v151, v153, vcc
;     __device__ __forceinline__ void operator()(const f32x4 (&acc)[2][2][4][2], const Unit& u, int wr, int wc, int fr, int fq) const {
;     ...
;                     for (int m = 0; m < 4; ++m) { const int r = row0 + ai * HALF + m * 16;
;                         const f32x4 v0 = acc[ai][0][m][0], v1 = acc[ai][0][m][1]; float* dp = DT + (size_t)r * 32 + c0;
; #pragma unroll
;                         for (int i = 0; i < 4; ++i) { float x0 = v0[i] + dt_bias[c0 + i], x1 = v1[i] + dt_bias[c0 + 4 + i];
;                             dp[i] = x0 > 20.f ? x0 : log1pf(__expf(x0)); dp[4 + i] = x1 > 20.f ? x1 : log1pf(__expf(x1)); }
.LBB0_785:
	s_or_b64 exec, exec, s[24:25]
	v_ashrrev_i32_e32 v153, 31, v152
	v_lshlrev_b64 v[154:155], 7, v[152:153]
	v_add_f32_e32 v136, v120, v136
	v_lshl_add_u64 v[154:155], v[138:139], 0, v[154:155]
	v_cmp_nlt_f32_e32 vcc, s67, v136
	flat_store_dword v[154:155], v151
	s_and_saveexec_b64 s[24:25], vcc
	s_cbranch_execz .LBB0_787
	v_mul_f32_e32 v136, 0x3fb8aa3b, v136
	v_exp_f32_e32 v136, v136
	s_nop 0
	v_add_f32_e32 v151, 1.0, v136
	v_frexp_mant_f32_e32 v174, v151
	v_cvt_f64_f32_e32 v[172:173], v151
	v_add_f32_e32 v156, -1.0, v151
	v_frexp_exp_i32_f64_e32 v172, v[172:173]
	v_cmp_gt_f32_e32 vcc, s68, v174
	v_sub_f32_e32 v175, v156, v151
	v_sub_f32_e32 v156, v136, v156
	v_subbrev_co_u32_e32 v180, vcc, 0, v172, vcc
	v_add_f32_e32 v175, 1.0, v175
	v_sub_u32_e32 v172, 0, v180
	v_add_f32_e32 v156, v156, v175
	v_ldexp_f32 v151, v151, v172
	v_ldexp_f32 v156, v156, v172
	v_add_f32_e32 v172, -1.0, v151
	v_add_f32_e32 v173, 1.0, v172
	v_sub_f32_e32 v173, v151, v173
	v_add_f32_e32 v174, v156, v173
	v_add_f32_e32 v173, 1.0, v151
	v_add_f32_e32 v175, -1.0, v173
	v_sub_f32_e32 v151, v151, v175
	v_add_f32_e32 v151, v156, v151
	v_add_f32_e32 v156, v173, v151
	v_rcp_f32_e32 v181, v156
	v_sub_f32_e32 v173, v156, v173
	v_sub_f32_e32 v151, v151, v173
	v_add_f32_e32 v173, v172, v174
	v_sub_f32_e32 v172, v173, v172
	v_mul_f32_e32 v183, v173, v181
	v_sub_f32_e32 v182, v174, v172
	v_mul_f32_e32 v174, v156, v183
	v_fma_f32 v176, v183, v156, -v174
	v_fmac_f32_e32 v176, v183, v151
	v_add_f32_e32 v172, v174, v176
	v_sub_f32_e32 v175, v173, v172
	v_pk_add_f32 v[178:179], v[172:173], v[174:175] neg_lo:[0,1] neg_hi:[0,1]
	v_mov_b32_e32 v177, v172
	v_pk_add_f32 v[172:173], v[178:179], v[176:177] neg_lo:[0,1] neg_hi:[0,1]
	v_cmp_neq_f32_e32 vcc, s70, v136
	v_add_f32_e32 v173, v182, v173
	v_add_f32_e32 v172, v172, v173
	v_add_f32_e32 v173, v175, v172
	v_mul_f32_e32 v182, v181, v173
	v_mul_f32_e32 v174, v156, v182
	v_fma_f32 v176, v182, v156, -v174
	v_fmac_f32_e32 v176, v182, v151
	v_sub_f32_e32 v151, v175, v173
	v_add_f32_e32 v151, v172, v151
	v_add_f32_e32 v172, v174, v176
	v_sub_f32_e32 v175, v173, v172
	v_pk_add_f32 v[178:179], v[172:173], v[174:175] neg_lo:[0,1] neg_hi:[0,1]
	v_mov_b32_e32 v177, v172
	v_pk_add_f32 v[172:173], v[178:179], v[176:177] neg_lo:[0,1] neg_hi:[0,1]
	v_add_f32_e32 v156, v183, v182
	v_add_f32_e32 v151, v151, v173
	v_add_f32_e32 v151, v172, v151
	v_add_f32_e32 v151, v175, v151
	v_sub_f32_e32 v172, v156, v183
	v_mul_f32_e32 v151, v181, v151
	v_sub_f32_e32 v172, v182, v172
	v_add_f32_e32 v173, v172, v151
	v_add_f32_e32 v174, v156, v173
	v_cvt_f32_i32_e32 v172, v180
	v_mul_f32_e32 v176, v174, v174
	v_fmamk_f32 v151, v176, 0x3e9b6dac, v166
	v_sub_f32_e32 v156, v174, v156
	v_fmaak_f32 v151, v176, v151, 0x3f2aaada
	v_sub_f32_e32 v156, v173, v156
	v_mul_f32_e32 v173, v174, v176
	v_pk_mul_f32 v[176:177], v[172:173], v[150:151]
	v_ldexp_f32 v175, v174, 1
	v_fma_f32 v174, v172, s69, -v176
	v_fmac_f32_e32 v174, 0xb102e308, v172
	v_pk_add_f32 v[172:173], v[176:177], v[174:175]
	v_ldexp_f32 v156, v156, 1
	v_sub_f32_e32 v151, v173, v175
	v_sub_f32_e32 v151, v177, v151
	v_add_f32_e32 v179, v156, v151
	v_mov_b32_e32 v178, v176
	v_pk_add_f32 v[176:177], v[172:173], v[176:177] neg_lo:[0,1] neg_hi:[0,1]
	v_pk_add_f32 v[180:181], v[172:173], v[178:179]
	v_mov_b32_e32 v175, v172
	v_mov_b32_e32 v177, v181
	v_pk_add_f32 v[182:183], v[174:175], v[176:177] neg_lo:[0,1] neg_hi:[0,1]
	v_pk_add_f32 v[174:175], v[174:175], v[176:177]
	v_mov_b32_e32 v178, v179
	v_pk_add_f32 v[176:177], v[174:175], v[172:173] op_sel:[1,0] op_sel_hi:[0,1] neg_lo:[0,1] neg_hi:[0,1]
	v_pk_add_f32 v[184:185], v[180:181], v[176:177] op_sel_hi:[1,0] neg_lo:[0,1] neg_hi:[0,1]
	v_mov_b32_e32 v180, v181
	v_mov_b32_e32 v181, v175
	v_pk_mov_b32 v[176:177], v[172:173], v[176:177] op_sel:[1,0]
	v_mov_b32_e32 v179, v172
	v_pk_add_f32 v[176:177], v[180:181], v[176:177] neg_lo:[0,1] neg_hi:[0,1]
	v_mov_b32_e32 v184, v182
	v_pk_add_f32 v[172:173], v[178:179], v[176:177] neg_lo:[0,1] neg_hi:[0,1]
	v_mov_b32_e32 v183, v175
	v_pk_add_f32 v[176:177], v[184:185], v[172:173]
	s_nop 0
	v_pk_add_f32 v[178:179], v[176:177], v[176:177] op_sel:[0,1] op_sel_hi:[1,0]
	s_nop 0
	v_pk_add_f32 v[174:175], v[174:175], v[178:179] op_sel:[1,0] op_sel_hi:[0,1]
	v_mov_b32_e32 v177, v174
	v_pk_add_f32 v[180:181], v[176:177], v[182:183] neg_lo:[0,1] neg_hi:[0,1]
	v_mov_b32_e32 v173, v178
	v_sub_f32_e32 v151, v176, v180
	v_pk_add_f32 v[172:173], v[172:173], v[180:181] neg_lo:[0,1] neg_hi:[0,1]
	v_sub_f32_e32 v151, v182, v151
	v_add_f32_e32 v151, v172, v151
	v_add_f32_e32 v151, v151, v173
	v_add_f32_e32 v151, v174, v151
	v_cndmask_b32_e32 v151, v167, v151, vcc
	v_cmp_ngt_f32_e32 vcc, -1.0, v136
	s_nop 1
	v_cndmask_b32_e32 v151, v168, v151, vcc
	v_cmp_neq_f32_e32 vcc, -1.0, v136
	s_nop 1
	v_cndmask_b32_e32 v151, v169, v151, vcc
	v_cmp_lt_f32_e64 vcc, |v136|, s71
	s_nop 1
	v_cndmask_b32_e32 v136, v151, v136, vcc
;     __device__ __forceinline__ void operator()(const f32x4 (&acc)[2][2][4][2], const Unit& u, int wr, int wc, int fr, int fq) const {
;     ...
;                     for (int m = 0; m < 4; ++m) { const int r = row0 + ai * HALF + m * 16;
;                         const f32x4 v0 = acc[ai][0][m][0], v1 = acc[ai][0][m][1]; float* dp = DT + (size_t)r * 32 + c0;
; #pragma unroll
;                         for (int i = 0; i < 4; ++i) { float x0 = v0[i] + dt_bias[c0 + i], x1 = v1[i] + dt_bias[c0 + 4 + i];
;                             dp[i] = x0 > 20.f ? x0 : log1pf(__expf(x0)); dp[4 + i] = x1 > 20.f ? x1 : log1pf(__expf(x1)); }
.LBB0_787:
	s_or_b64 exec, exec, s[24:25]
	flat_store_dword v[154:155], v136 offset:16
	v_mov_b32_e32 v136, v201
	v_add_f32_e32 v151, v125, v136
	v_mov_b32_e32 v136, v205
	v_cmp_nlt_f32_e32 vcc, s67, v151
	s_and_saveexec_b64 s[24:25], vcc
	s_cbranch_execz .LBB0_789
	v_mul_f32_e32 v151, 0x3fb8aa3b, v151
	v_exp_f32_e32 v156, v151
	s_nop 0
	v_add_f32_e32 v151, 1.0, v156
	v_frexp_mant_f32_e32 v175, v151
	v_cvt_f64_f32_e32 v[172:173], v151
	v_add_f32_e32 v174, -1.0, v151
	v_frexp_exp_i32_f64_e32 v172, v[172:173]
	v_cmp_gt_f32_e32 vcc, s68, v175
	v_sub_f32_e32 v176, v174, v151
	v_sub_f32_e32 v174, v156, v174
	v_subbrev_co_u32_e32 v180, vcc, 0, v172, vcc
	v_add_f32_e32 v176, 1.0, v176
	v_sub_u32_e32 v172, 0, v180
	v_add_f32_e32 v174, v174, v176
	v_ldexp_f32 v151, v151, v172
	v_ldexp_f32 v172, v174, v172
	v_add_f32_e32 v174, -1.0, v151
	v_add_f32_e32 v173, 1.0, v174
	v_sub_f32_e32 v173, v151, v173
	v_add_f32_e32 v175, v172, v173
	v_add_f32_e32 v173, 1.0, v151
	v_add_f32_e32 v176, -1.0, v173
	v_sub_f32_e32 v151, v151, v176
	v_add_f32_e32 v151, v172, v151
	v_add_f32_e32 v181, v173, v151
	v_rcp_f32_e32 v182, v181
	v_sub_f32_e32 v172, v181, v173
	v_add_f32_e32 v173, v174, v175
	v_sub_f32_e32 v151, v151, v172
	v_mul_f32_e32 v184, v173, v182
	v_sub_f32_e32 v172, v173, v174
	v_mul_f32_e32 v174, v181, v184
	v_fma_f32 v176, v184, v181, -v174
	v_fmac_f32_e32 v176, v184, v151
	v_sub_f32_e32 v183, v175, v172
	v_add_f32_e32 v172, v174, v176
	v_sub_f32_e32 v175, v173, v172
	v_pk_add_f32 v[178:179], v[172:173], v[174:175] neg_lo:[0,1] neg_hi:[0,1]
	v_mov_b32_e32 v177, v172
	v_pk_add_f32 v[172:173], v[178:179], v[176:177] neg_lo:[0,1] neg_hi:[0,1]
	v_cmp_neq_f32_e32 vcc, s70, v156
	v_add_f32_e32 v173, v183, v173
	v_add_f32_e32 v172, v172, v173
	v_add_f32_e32 v173, v175, v172
	v_mul_f32_e32 v183, v182, v173
	v_mul_f32_e32 v174, v181, v183
	v_fma_f32 v176, v183, v181, -v174
	v_fmac_f32_e32 v176, v183, v151
	v_sub_f32_e32 v151, v175, v173
	v_add_f32_e32 v151, v172, v151
	v_add_f32_e32 v172, v174, v176
	v_sub_f32_e32 v175, v173, v172
	v_pk_add_f32 v[178:179], v[172:173], v[174:175] neg_lo:[0,1] neg_hi:[0,1]
	v_mov_b32_e32 v177, v172
	v_pk_add_f32 v[172:173], v[178:179], v[176:177] neg_lo:[0,1] neg_hi:[0,1]
	s_nop 0
	v_add_f32_e32 v151, v151, v173
	v_add_f32_e32 v151, v172, v151
	v_add_f32_e32 v173, v184, v183
	v_add_f32_e32 v151, v175, v151
	v_sub_f32_e32 v172, v173, v184
	v_mul_f32_e32 v151, v182, v151
	v_sub_f32_e32 v172, v183, v172
	v_add_f32_e32 v174, v172, v151
	v_add_f32_e32 v176, v173, v174
	v_cvt_f32_i32_e32 v172, v180
	v_mul_f32_e32 v177, v176, v176
	v_sub_f32_e32 v173, v176, v173
	v_fmamk_f32 v151, v177, 0x3e9b6dac, v166
	v_sub_f32_e32 v173, v174, v173
	v_fmaak_f32 v151, v177, v151, 0x3f2aaada
	v_ldexp_f32 v178, v173, 1
	v_mul_f32_e32 v173, v176, v177
	v_ldexp_f32 v175, v176, 1
	v_pk_mul_f32 v[176:177], v[172:173], v[150:151]
	s_nop 0
	v_fma_f32 v174, v172, s69, -v176
	v_fmac_f32_e32 v174, 0xb102e308, v172
	v_pk_add_f32 v[172:173], v[176:177], v[174:175]
	s_nop 0
	v_sub_f32_e32 v151, v173, v175
	v_sub_f32_e32 v151, v177, v151
	v_add_f32_e32 v179, v178, v151
	v_mov_b32_e32 v178, v176
	v_pk_add_f32 v[176:177], v[172:173], v[176:177] neg_lo:[0,1] neg_hi:[0,1]
	v_pk_add_f32 v[180:181], v[172:173], v[178:179]
	v_mov_b32_e32 v175, v172
	v_mov_b32_e32 v177, v181
	v_pk_add_f32 v[182:183], v[174:175], v[176:177] neg_lo:[0,1] neg_hi:[0,1]
	v_pk_add_f32 v[174:175], v[174:175], v[176:177]
	v_mov_b32_e32 v178, v179
	v_pk_add_f32 v[176:177], v[174:175], v[172:173] op_sel:[1,0] op_sel_hi:[0,1] neg_lo:[0,1] neg_hi:[0,1]
	v_pk_add_f32 v[184:185], v[180:181], v[176:177] op_sel_hi:[1,0] neg_lo:[0,1] neg_hi:[0,1]
	v_mov_b32_e32 v180, v181
	v_mov_b32_e32 v181, v175
	v_pk_mov_b32 v[176:177], v[172:173], v[176:177] op_sel:[1,0]
	v_mov_b32_e32 v179, v172
	v_pk_add_f32 v[176:177], v[180:181], v[176:177] neg_lo:[0,1] neg_hi:[0,1]
	v_mov_b32_e32 v184, v182
	v_pk_add_f32 v[172:173], v[178:179], v[176:177] neg_lo:[0,1] neg_hi:[0,1]
	v_mov_b32_e32 v183, v175
	v_pk_add_f32 v[176:177], v[184:185], v[172:173]
	s_nop 0
	v_pk_add_f32 v[178:179], v[176:177], v[176:177] op_sel:[0,1] op_sel_hi:[1,0]
	s_nop 0
	v_pk_add_f32 v[174:175], v[174:175], v[178:179] op_sel:[1,0] op_sel_hi:[0,1]
	v_mov_b32_e32 v177, v174
	v_pk_add_f32 v[180:181], v[176:177], v[182:183] neg_lo:[0,1] neg_hi:[0,1]
	v_mov_b32_e32 v173, v178
	v_sub_f32_e32 v151, v176, v180
	v_pk_add_f32 v[172:173], v[172:173], v[180:181] neg_lo:[0,1] neg_hi:[0,1]
	v_sub_f32_e32 v151, v182, v151
	v_add_f32_e32 v151, v172, v151
	v_add_f32_e32 v151, v151, v173
	v_add_f32_e32 v151, v174, v151
	v_cndmask_b32_e32 v151, v167, v151, vcc
	v_cmp_ngt_f32_e32 vcc, -1.0, v156
	s_nop 1
	v_cndmask_b32_e32 v151, v168, v151, vcc
	v_cmp_neq_f32_e32 vcc, -1.0, v156
	s_nop 1
	v_cndmask_b32_e32 v151, v169, v151, vcc
	v_cmp_lt_f32_e64 vcc, |v156|, s71
	s_nop 1
	v_cndmask_b32_e32 v151, v151, v156, vcc
;     __device__ __forceinline__ void operator()(const f32x4 (&acc)[2][2][4][2], const Unit& u, int wr, int wc, int fr, int fq) const {
;     ...
;                     for (int m = 0; m < 4; ++m) { const int r = row0 + ai * HALF + m * 16;
;                         const f32x4 v0 = acc[ai][0][m][0], v1 = acc[ai][0][m][1]; float* dp = DT + (size_t)r * 32 + c0;
; #pragma unroll
;                         for (int i = 0; i < 4; ++i) { float x0 = v0[i] + dt_bias[c0 + i], x1 = v1[i] + dt_bias[c0 + 4 + i];
;                             dp[i] = x0 > 20.f ? x0 : log1pf(__expf(x0)); dp[4 + i] = x1 > 20.f ? x1 : log1pf(__expf(x1)); }
.LBB0_789:
	s_or_b64 exec, exec, s[24:25]
	v_add_f32_e32 v136, v121, v136
	v_cmp_nlt_f32_e32 vcc, s67, v136
	flat_store_dword v[154:155], v151 offset:4
	s_and_saveexec_b64 s[24:25], vcc
	s_cbranch_execz .LBB0_791
	v_mul_f32_e32 v136, 0x3fb8aa3b, v136
	v_exp_f32_e32 v136, v136
	s_nop 0
	v_add_f32_e32 v151, 1.0, v136
	v_frexp_mant_f32_e32 v174, v151
	v_cvt_f64_f32_e32 v[172:173], v151
	v_add_f32_e32 v156, -1.0, v151
	v_frexp_exp_i32_f64_e32 v172, v[172:173]
	v_cmp_gt_f32_e32 vcc, s68, v174
	v_sub_f32_e32 v175, v156, v151
	v_sub_f32_e32 v156, v136, v156
	v_subbrev_co_u32_e32 v180, vcc, 0, v172, vcc
	v_add_f32_e32 v175, 1.0, v175
	v_sub_u32_e32 v172, 0, v180
	v_add_f32_e32 v156, v156, v175
	v_ldexp_f32 v151, v151, v172
	v_ldexp_f32 v156, v156, v172
	v_add_f32_e32 v172, -1.0, v151
	v_add_f32_e32 v173, 1.0, v172
	v_sub_f32_e32 v173, v151, v173
	v_add_f32_e32 v174, v156, v173
	v_add_f32_e32 v173, 1.0, v151
	v_add_f32_e32 v175, -1.0, v173
	v_sub_f32_e32 v151, v151, v175
	v_add_f32_e32 v151, v156, v151
	v_add_f32_e32 v156, v173, v151
	v_rcp_f32_e32 v181, v156
	v_sub_f32_e32 v173, v156, v173
	v_sub_f32_e32 v151, v151, v173
	v_add_f32_e32 v173, v172, v174
	v_sub_f32_e32 v172, v173, v172
	v_mul_f32_e32 v183, v173, v181
	v_sub_f32_e32 v182, v174, v172
	v_mul_f32_e32 v174, v156, v183
	v_fma_f32 v176, v183, v156, -v174
	v_fmac_f32_e32 v176, v183, v151
	v_add_f32_e32 v172, v174, v176
	v_sub_f32_e32 v175, v173, v172
	v_pk_add_f32 v[178:179], v[172:173], v[174:175] neg_lo:[0,1] neg_hi:[0,1]
	v_mov_b32_e32 v177, v172
	v_pk_add_f32 v[172:173], v[178:179], v[176:177] neg_lo:[0,1] neg_hi:[0,1]
	v_cmp_neq_f32_e32 vcc, s70, v136
	v_add_f32_e32 v173, v182, v173
	v_add_f32_e32 v172, v172, v173
	v_add_f32_e32 v173, v175, v172
	v_mul_f32_e32 v182, v181, v173
	v_mul_f32_e32 v174, v156, v182
	v_fma_f32 v176, v182, v156, -v174
	v_fmac_f32_e32 v176, v182, v151
	v_sub_f32_e32 v151, v175, v173
	v_add_f32_e32 v151, v172, v151
	v_add_f32_e32 v172, v174, v176
	v_sub_f32_e32 v175, v173, v172
	v_pk_add_f32 v[178:179], v[172:173], v[174:175] neg_lo:[0,1] neg_hi:[0,1]
	v_mov_b32_e32 v177, v172
	v_pk_add_f32 v[172:173], v[178:179], v[176:177] neg_lo:[0,1] neg_hi:[0,1]
	v_add_f32_e32 v156, v183, v182
	v_add_f32_e32 v151, v151, v173
	v_add_f32_e32 v151, v172, v151
	v_add_f32_e32 v151, v175, v151
	v_sub_f32_e32 v172, v156, v183
	v_mul_f32_e32 v151, v181, v151
	v_sub_f32_e32 v172, v182, v172
	v_add_f32_e32 v173, v172, v151
	v_add_f32_e32 v174, v156, v173
	v_cvt_f32_i32_e32 v172, v180
	v_mul_f32_e32 v176, v174, v174
	v_fmamk_f32 v151, v176, 0x3e9b6dac, v166
	v_sub_f32_e32 v156, v174, v156
	v_fmaak_f32 v151, v176, v151, 0x3f2aaada
	v_sub_f32_e32 v156, v173, v156
	v_mul_f32_e32 v173, v174, v176
	v_pk_mul_f32 v[176:177], v[172:173], v[150:151]
	v_ldexp_f32 v175, v174, 1
	v_fma_f32 v174, v172, s69, -v176
	v_fmac_f32_e32 v174, 0xb102e308, v172
	v_pk_add_f32 v[172:173], v[176:177], v[174:175]
	v_ldexp_f32 v156, v156, 1
	v_sub_f32_e32 v151, v173, v175
	v_sub_f32_e32 v151, v177, v151
	v_add_f32_e32 v179, v156, v151
	v_mov_b32_e32 v178, v176
	v_pk_add_f32 v[176:177], v[172:173], v[176:177] neg_lo:[0,1] neg_hi:[0,1]
	v_pk_add_f32 v[180:181], v[172:173], v[178:179]
	v_mov_b32_e32 v175, v172
	v_mov_b32_e32 v177, v181
	v_pk_add_f32 v[182:183], v[174:175], v[176:177] neg_lo:[0,1] neg_hi:[0,1]
	v_pk_add_f32 v[174:175], v[174:175], v[176:177]
	v_mov_b32_e32 v178, v179
	v_pk_add_f32 v[176:177], v[174:175], v[172:173] op_sel:[1,0] op_sel_hi:[0,1] neg_lo:[0,1] neg_hi:[0,1]
	v_pk_add_f32 v[184:185], v[180:181], v[176:177] op_sel_hi:[1,0] neg_lo:[0,1] neg_hi:[0,1]
	v_mov_b32_e32 v180, v181
	v_mov_b32_e32 v181, v175
	v_pk_mov_b32 v[176:177], v[172:173], v[176:177] op_sel:[1,0]
	v_mov_b32_e32 v179, v172
	v_pk_add_f32 v[176:177], v[180:181], v[176:177] neg_lo:[0,1] neg_hi:[0,1]
	v_mov_b32_e32 v184, v182
	v_pk_add_f32 v[172:173], v[178:179], v[176:177] neg_lo:[0,1] neg_hi:[0,1]
	v_mov_b32_e32 v183, v175
	v_pk_add_f32 v[176:177], v[184:185], v[172:173]
	s_nop 0
	v_pk_add_f32 v[178:179], v[176:177], v[176:177] op_sel:[0,1] op_sel_hi:[1,0]
	s_nop 0
	v_pk_add_f32 v[174:175], v[174:175], v[178:179] op_sel:[1,0] op_sel_hi:[0,1]
	v_mov_b32_e32 v177, v174
	v_pk_add_f32 v[180:181], v[176:177], v[182:183] neg_lo:[0,1] neg_hi:[0,1]
	v_mov_b32_e32 v173, v178
	v_sub_f32_e32 v151, v176, v180
	v_pk_add_f32 v[172:173], v[172:173], v[180:181] neg_lo:[0,1] neg_hi:[0,1]
	v_sub_f32_e32 v151, v182, v151
	v_add_f32_e32 v151, v172, v151
	v_add_f32_e32 v151, v151, v173
	v_add_f32_e32 v151, v174, v151
	v_cndmask_b32_e32 v151, v167, v151, vcc
	v_cmp_ngt_f32_e32 vcc, -1.0, v136
	s_nop 1
	v_cndmask_b32_e32 v151, v168, v151, vcc
	v_cmp_neq_f32_e32 vcc, -1.0, v136
	s_nop 1
	v_cndmask_b32_e32 v151, v169, v151, vcc
	v_cmp_lt_f32_e64 vcc, |v136|, s71
	s_nop 1
	v_cndmask_b32_e32 v136, v151, v136, vcc
;     __device__ __forceinline__ void operator()(const f32x4 (&acc)[2][2][4][2], const Unit& u, int wr, int wc, int fr, int fq) const {
;     ...
;                     for (int m = 0; m < 4; ++m) { const int r = row0 + ai * HALF + m * 16;
;                         const f32x4 v0 = acc[ai][0][m][0], v1 = acc[ai][0][m][1]; float* dp = DT + (size_t)r * 32 + c0;
; #pragma unroll
;                         for (int i = 0; i < 4; ++i) { float x0 = v0[i] + dt_bias[c0 + i], x1 = v1[i] + dt_bias[c0 + 4 + i];
;                             dp[i] = x0 > 20.f ? x0 : log1pf(__expf(x0)); dp[4 + i] = x1 > 20.f ? x1 : log1pf(__expf(x1)); }
.LBB0_791:
	s_or_b64 exec, exec, s[24:25]
	flat_store_dword v[154:155], v136 offset:20
	v_mov_b32_e32 v136, v202
	v_add_f32_e32 v151, v126, v136
	v_mov_b32_e32 v136, v206
	v_cmp_nlt_f32_e32 vcc, s67, v151
	s_and_saveexec_b64 s[24:25], vcc
	s_cbranch_execz .LBB0_793
	v_mul_f32_e32 v151, 0x3fb8aa3b, v151
	v_exp_f32_e32 v156, v151
	s_nop 0
	v_add_f32_e32 v151, 1.0, v156
	v_frexp_mant_f32_e32 v175, v151
	v_cvt_f64_f32_e32 v[172:173], v151
	v_add_f32_e32 v174, -1.0, v151
	v_frexp_exp_i32_f64_e32 v172, v[172:173]
	v_cmp_gt_f32_e32 vcc, s68, v175
	v_sub_f32_e32 v176, v174, v151
	v_sub_f32_e32 v174, v156, v174
	v_subbrev_co_u32_e32 v180, vcc, 0, v172, vcc
	v_add_f32_e32 v176, 1.0, v176
	v_sub_u32_e32 v172, 0, v180
	v_add_f32_e32 v174, v174, v176
	v_ldexp_f32 v151, v151, v172
	v_ldexp_f32 v172, v174, v172
	v_add_f32_e32 v174, -1.0, v151
	v_add_f32_e32 v173, 1.0, v174
	v_sub_f32_e32 v173, v151, v173
	v_add_f32_e32 v175, v172, v173
	v_add_f32_e32 v173, 1.0, v151
	v_add_f32_e32 v176, -1.0, v173
	v_sub_f32_e32 v151, v151, v176
	v_add_f32_e32 v151, v172, v151
	v_add_f32_e32 v181, v173, v151
	v_rcp_f32_e32 v182, v181
	v_sub_f32_e32 v172, v181, v173
	v_add_f32_e32 v173, v174, v175
	v_sub_f32_e32 v151, v151, v172
	v_mul_f32_e32 v184, v173, v182
	v_sub_f32_e32 v172, v173, v174
	v_mul_f32_e32 v174, v181, v184
	v_fma_f32 v176, v184, v181, -v174
	v_fmac_f32_e32 v176, v184, v151
	v_sub_f32_e32 v183, v175, v172
	v_add_f32_e32 v172, v174, v176
	v_sub_f32_e32 v175, v173, v172
	v_pk_add_f32 v[178:179], v[172:173], v[174:175] neg_lo:[0,1] neg_hi:[0,1]
	v_mov_b32_e32 v177, v172
	v_pk_add_f32 v[172:173], v[178:179], v[176:177] neg_lo:[0,1] neg_hi:[0,1]
	v_cmp_neq_f32_e32 vcc, s70, v156
	v_add_f32_e32 v173, v183, v173
	v_add_f32_e32 v172, v172, v173
	v_add_f32_e32 v173, v175, v172
	v_mul_f32_e32 v183, v182, v173
	v_mul_f32_e32 v174, v181, v183
	v_fma_f32 v176, v183, v181, -v174
	v_fmac_f32_e32 v176, v183, v151
	v_sub_f32_e32 v151, v175, v173
	v_add_f32_e32 v151, v172, v151
	v_add_f32_e32 v172, v174, v176
	v_sub_f32_e32 v175, v173, v172
	v_pk_add_f32 v[178:179], v[172:173], v[174:175] neg_lo:[0,1] neg_hi:[0,1]
	v_mov_b32_e32 v177, v172
	v_pk_add_f32 v[172:173], v[178:179], v[176:177] neg_lo:[0,1] neg_hi:[0,1]
	s_nop 0
	v_add_f32_e32 v151, v151, v173
	v_add_f32_e32 v151, v172, v151
	v_add_f32_e32 v173, v184, v183
	v_add_f32_e32 v151, v175, v151
	v_sub_f32_e32 v172, v173, v184
	v_mul_f32_e32 v151, v182, v151
	v_sub_f32_e32 v172, v183, v172
	v_add_f32_e32 v174, v172, v151
	v_add_f32_e32 v176, v173, v174
	v_cvt_f32_i32_e32 v172, v180
	v_mul_f32_e32 v177, v176, v176
	v_sub_f32_e32 v173, v176, v173
	v_fmamk_f32 v151, v177, 0x3e9b6dac, v166
	v_sub_f32_e32 v173, v174, v173
	v_fmaak_f32 v151, v177, v151, 0x3f2aaada
	v_ldexp_f32 v178, v173, 1
	v_mul_f32_e32 v173, v176, v177
	v_ldexp_f32 v175, v176, 1
	v_pk_mul_f32 v[176:177], v[172:173], v[150:151]
	s_nop 0
	v_fma_f32 v174, v172, s69, -v176
	v_fmac_f32_e32 v174, 0xb102e308, v172
	v_pk_add_f32 v[172:173], v[176:177], v[174:175]
	s_nop 0
	v_sub_f32_e32 v151, v173, v175
	v_sub_f32_e32 v151, v177, v151
	v_add_f32_e32 v179, v178, v151
	v_mov_b32_e32 v178, v176
	v_pk_add_f32 v[176:177], v[172:173], v[176:177] neg_lo:[0,1] neg_hi:[0,1]
	v_pk_add_f32 v[180:181], v[172:173], v[178:179]
	v_mov_b32_e32 v175, v172
	v_mov_b32_e32 v177, v181
	v_pk_add_f32 v[182:183], v[174:175], v[176:177] neg_lo:[0,1] neg_hi:[0,1]
	v_pk_add_f32 v[174:175], v[174:175], v[176:177]
	v_mov_b32_e32 v178, v179
	v_pk_add_f32 v[176:177], v[174:175], v[172:173] op_sel:[1,0] op_sel_hi:[0,1] neg_lo:[0,1] neg_hi:[0,1]
	v_pk_add_f32 v[184:185], v[180:181], v[176:177] op_sel_hi:[1,0] neg_lo:[0,1] neg_hi:[0,1]
	v_mov_b32_e32 v180, v181
	v_mov_b32_e32 v181, v175
	v_pk_mov_b32 v[176:177], v[172:173], v[176:177] op_sel:[1,0]
	v_mov_b32_e32 v179, v172
	v_pk_add_f32 v[176:177], v[180:181], v[176:177] neg_lo:[0,1] neg_hi:[0,1]
	v_mov_b32_e32 v184, v182
	v_pk_add_f32 v[172:173], v[178:179], v[176:177] neg_lo:[0,1] neg_hi:[0,1]
	v_mov_b32_e32 v183, v175
	v_pk_add_f32 v[176:177], v[184:185], v[172:173]
	s_nop 0
	v_pk_add_f32 v[178:179], v[176:177], v[176:177] op_sel:[0,1] op_sel_hi:[1,0]
	s_nop 0
	v_pk_add_f32 v[174:175], v[174:175], v[178:179] op_sel:[1,0] op_sel_hi:[0,1]
	v_mov_b32_e32 v177, v174
	v_pk_add_f32 v[180:181], v[176:177], v[182:183] neg_lo:[0,1] neg_hi:[0,1]
	v_mov_b32_e32 v173, v178
	v_sub_f32_e32 v151, v176, v180
	v_pk_add_f32 v[172:173], v[172:173], v[180:181] neg_lo:[0,1] neg_hi:[0,1]
	v_sub_f32_e32 v151, v182, v151
	v_add_f32_e32 v151, v172, v151
	v_add_f32_e32 v151, v151, v173
	v_add_f32_e32 v151, v174, v151
	v_cndmask_b32_e32 v151, v167, v151, vcc
	v_cmp_ngt_f32_e32 vcc, -1.0, v156
	s_nop 1
	v_cndmask_b32_e32 v151, v168, v151, vcc
	v_cmp_neq_f32_e32 vcc, -1.0, v156
	s_nop 1
	v_cndmask_b32_e32 v151, v169, v151, vcc
	v_cmp_lt_f32_e64 vcc, |v156|, s71
	s_nop 1
	v_cndmask_b32_e32 v151, v151, v156, vcc
;     __device__ __forceinline__ void operator()(const f32x4 (&acc)[2][2][4][2], const Unit& u, int wr, int wc, int fr, int fq) const {
;     ...
;                     for (int m = 0; m < 4; ++m) { const int r = row0 + ai * HALF + m * 16;
;                         const f32x4 v0 = acc[ai][0][m][0], v1 = acc[ai][0][m][1]; float* dp = DT + (size_t)r * 32 + c0;
; #pragma unroll
;                         for (int i = 0; i < 4; ++i) { float x0 = v0[i] + dt_bias[c0 + i], x1 = v1[i] + dt_bias[c0 + 4 + i];
;                             dp[i] = x0 > 20.f ? x0 : log1pf(__expf(x0)); dp[4 + i] = x1 > 20.f ? x1 : log1pf(__expf(x1)); }
.LBB0_793:
	s_or_b64 exec, exec, s[24:25]
	v_add_f32_e32 v136, v122, v136
	v_cmp_nlt_f32_e32 vcc, s67, v136
	flat_store_dword v[154:155], v151 offset:8
	s_and_saveexec_b64 s[24:25], vcc
	s_cbranch_execz .LBB0_795
	v_mul_f32_e32 v136, 0x3fb8aa3b, v136
	v_exp_f32_e32 v136, v136
	s_nop 0
	v_add_f32_e32 v151, 1.0, v136
	v_frexp_mant_f32_e32 v174, v151
	v_cvt_f64_f32_e32 v[172:173], v151
	v_add_f32_e32 v156, -1.0, v151
	v_frexp_exp_i32_f64_e32 v172, v[172:173]
	v_cmp_gt_f32_e32 vcc, s68, v174
	v_sub_f32_e32 v175, v156, v151
	v_sub_f32_e32 v156, v136, v156
	v_subbrev_co_u32_e32 v180, vcc, 0, v172, vcc
	v_add_f32_e32 v175, 1.0, v175
	v_sub_u32_e32 v172, 0, v180
	v_add_f32_e32 v156, v156, v175
	v_ldexp_f32 v151, v151, v172
	v_ldexp_f32 v156, v156, v172
	v_add_f32_e32 v172, -1.0, v151
	v_add_f32_e32 v173, 1.0, v172
	v_sub_f32_e32 v173, v151, v173
	v_add_f32_e32 v174, v156, v173
	v_add_f32_e32 v173, 1.0, v151
	v_add_f32_e32 v175, -1.0, v173
	v_sub_f32_e32 v151, v151, v175
	v_add_f32_e32 v151, v156, v151
	v_add_f32_e32 v156, v173, v151
	v_rcp_f32_e32 v181, v156
	v_sub_f32_e32 v173, v156, v173
	v_sub_f32_e32 v151, v151, v173
	v_add_f32_e32 v173, v172, v174
	v_sub_f32_e32 v172, v173, v172
	v_mul_f32_e32 v183, v173, v181
	v_sub_f32_e32 v182, v174, v172
	v_mul_f32_e32 v174, v156, v183
	v_fma_f32 v176, v183, v156, -v174
	v_fmac_f32_e32 v176, v183, v151
	v_add_f32_e32 v172, v174, v176
	v_sub_f32_e32 v175, v173, v172
	v_pk_add_f32 v[178:179], v[172:173], v[174:175] neg_lo:[0,1] neg_hi:[0,1]
	v_mov_b32_e32 v177, v172
	v_pk_add_f32 v[172:173], v[178:179], v[176:177] neg_lo:[0,1] neg_hi:[0,1]
	v_cmp_neq_f32_e32 vcc, s70, v136
	v_add_f32_e32 v173, v182, v173
	v_add_f32_e32 v172, v172, v173
	v_add_f32_e32 v173, v175, v172
	v_mul_f32_e32 v182, v181, v173
	v_mul_f32_e32 v174, v156, v182
	v_fma_f32 v176, v182, v156, -v174
	v_fmac_f32_e32 v176, v182, v151
	v_sub_f32_e32 v151, v175, v173
	v_add_f32_e32 v151, v172, v151
	v_add_f32_e32 v172, v174, v176
	v_sub_f32_e32 v175, v173, v172
	v_pk_add_f32 v[178:179], v[172:173], v[174:175] neg_lo:[0,1] neg_hi:[0,1]
	v_mov_b32_e32 v177, v172
	v_pk_add_f32 v[172:173], v[178:179], v[176:177] neg_lo:[0,1] neg_hi:[0,1]
	v_add_f32_e32 v156, v183, v182
	v_add_f32_e32 v151, v151, v173
	v_add_f32_e32 v151, v172, v151
	v_add_f32_e32 v151, v175, v151
	v_sub_f32_e32 v172, v156, v183
	v_mul_f32_e32 v151, v181, v151
	v_sub_f32_e32 v172, v182, v172
	v_add_f32_e32 v173, v172, v151
	v_add_f32_e32 v174, v156, v173
	v_cvt_f32_i32_e32 v172, v180
	v_mul_f32_e32 v176, v174, v174
	v_fmamk_f32 v151, v176, 0x3e9b6dac, v166
	v_sub_f32_e32 v156, v174, v156
	v_fmaak_f32 v151, v176, v151, 0x3f2aaada
	v_sub_f32_e32 v156, v173, v156
	v_mul_f32_e32 v173, v174, v176
	v_pk_mul_f32 v[176:177], v[172:173], v[150:151]
	v_ldexp_f32 v175, v174, 1
	v_fma_f32 v174, v172, s69, -v176
	v_fmac_f32_e32 v174, 0xb102e308, v172
	v_pk_add_f32 v[172:173], v[176:177], v[174:175]
	v_ldexp_f32 v156, v156, 1
	v_sub_f32_e32 v151, v173, v175
	v_sub_f32_e32 v151, v177, v151
	v_add_f32_e32 v179, v156, v151
	v_mov_b32_e32 v178, v176
	v_pk_add_f32 v[176:177], v[172:173], v[176:177] neg_lo:[0,1] neg_hi:[0,1]
	v_pk_add_f32 v[180:181], v[172:173], v[178:179]
	v_mov_b32_e32 v175, v172
	v_mov_b32_e32 v177, v181
	v_pk_add_f32 v[182:183], v[174:175], v[176:177] neg_lo:[0,1] neg_hi:[0,1]
	v_pk_add_f32 v[174:175], v[174:175], v[176:177]
	v_mov_b32_e32 v178, v179
	v_pk_add_f32 v[176:177], v[174:175], v[172:173] op_sel:[1,0] op_sel_hi:[0,1] neg_lo:[0,1] neg_hi:[0,1]
	v_pk_add_f32 v[184:185], v[180:181], v[176:177] op_sel_hi:[1,0] neg_lo:[0,1] neg_hi:[0,1]
	v_mov_b32_e32 v180, v181
	v_mov_b32_e32 v181, v175
	v_pk_mov_b32 v[176:177], v[172:173], v[176:177] op_sel:[1,0]
	v_mov_b32_e32 v179, v172
	v_pk_add_f32 v[176:177], v[180:181], v[176:177] neg_lo:[0,1] neg_hi:[0,1]
	v_mov_b32_e32 v184, v182
	v_pk_add_f32 v[172:173], v[178:179], v[176:177] neg_lo:[0,1] neg_hi:[0,1]
	v_mov_b32_e32 v183, v175
	v_pk_add_f32 v[176:177], v[184:185], v[172:173]
	s_nop 0
	v_pk_add_f32 v[178:179], v[176:177], v[176:177] op_sel:[0,1] op_sel_hi:[1,0]
	s_nop 0
	v_pk_add_f32 v[174:175], v[174:175], v[178:179] op_sel:[1,0] op_sel_hi:[0,1]
	v_mov_b32_e32 v177, v174
	v_pk_add_f32 v[180:181], v[176:177], v[182:183] neg_lo:[0,1] neg_hi:[0,1]
	v_mov_b32_e32 v173, v178
	v_sub_f32_e32 v151, v176, v180
	v_pk_add_f32 v[172:173], v[172:173], v[180:181] neg_lo:[0,1] neg_hi:[0,1]
	v_sub_f32_e32 v151, v182, v151
	v_add_f32_e32 v151, v172, v151
	v_add_f32_e32 v151, v151, v173
	v_add_f32_e32 v151, v174, v151
	v_cndmask_b32_e32 v151, v167, v151, vcc
	v_cmp_ngt_f32_e32 vcc, -1.0, v136
	s_nop 1
	v_cndmask_b32_e32 v151, v168, v151, vcc
	v_cmp_neq_f32_e32 vcc, -1.0, v136
	s_nop 1
	v_cndmask_b32_e32 v151, v169, v151, vcc
	v_cmp_lt_f32_e64 vcc, |v136|, s71
	s_nop 1
	v_cndmask_b32_e32 v136, v151, v136, vcc
;     __device__ __forceinline__ void operator()(const f32x4 (&acc)[2][2][4][2], const Unit& u, int wr, int wc, int fr, int fq) const {
;     ...
;                     for (int m = 0; m < 4; ++m) { const int r = row0 + ai * HALF + m * 16;
;                         const f32x4 v0 = acc[ai][0][m][0], v1 = acc[ai][0][m][1]; float* dp = DT + (size_t)r * 32 + c0;
; #pragma unroll
;                         for (int i = 0; i < 4; ++i) { float x0 = v0[i] + dt_bias[c0 + i], x1 = v1[i] + dt_bias[c0 + 4 + i];
;                             dp[i] = x0 > 20.f ? x0 : log1pf(__expf(x0)); dp[4 + i] = x1 > 20.f ? x1 : log1pf(__expf(x1)); }
.LBB0_795:
	s_or_b64 exec, exec, s[24:25]
	flat_store_dword v[154:155], v136 offset:24
	v_mov_b32_e32 v136, v203
	v_add_f32_e32 v151, v127, v136
	v_mov_b32_e32 v136, v207
	v_cmp_nlt_f32_e32 vcc, s67, v151
	s_and_saveexec_b64 s[24:25], vcc
	s_cbranch_execz .LBB0_797
	v_mul_f32_e32 v151, 0x3fb8aa3b, v151
	v_exp_f32_e32 v156, v151
	s_nop 0
	v_add_f32_e32 v151, 1.0, v156
	v_frexp_mant_f32_e32 v175, v151
	v_cvt_f64_f32_e32 v[172:173], v151
	v_add_f32_e32 v174, -1.0, v151
	v_frexp_exp_i32_f64_e32 v172, v[172:173]
	v_cmp_gt_f32_e32 vcc, s68, v175
	v_sub_f32_e32 v176, v174, v151
	v_sub_f32_e32 v174, v156, v174
	v_subbrev_co_u32_e32 v180, vcc, 0, v172, vcc
	v_add_f32_e32 v176, 1.0, v176
	v_sub_u32_e32 v172, 0, v180
	v_add_f32_e32 v174, v174, v176
	v_ldexp_f32 v151, v151, v172
	v_ldexp_f32 v172, v174, v172
	v_add_f32_e32 v174, -1.0, v151
	v_add_f32_e32 v173, 1.0, v174
	v_sub_f32_e32 v173, v151, v173
	v_add_f32_e32 v175, v172, v173
	v_add_f32_e32 v173, 1.0, v151
	v_add_f32_e32 v176, -1.0, v173
	v_sub_f32_e32 v151, v151, v176
	v_add_f32_e32 v151, v172, v151
	v_add_f32_e32 v181, v173, v151
	v_rcp_f32_e32 v182, v181
	v_sub_f32_e32 v172, v181, v173
	v_add_f32_e32 v173, v174, v175
	v_sub_f32_e32 v151, v151, v172
	v_mul_f32_e32 v184, v173, v182
	v_sub_f32_e32 v172, v173, v174
	v_mul_f32_e32 v174, v181, v184
	v_fma_f32 v176, v184, v181, -v174
	v_fmac_f32_e32 v176, v184, v151
	v_sub_f32_e32 v183, v175, v172
	v_add_f32_e32 v172, v174, v176
	v_sub_f32_e32 v175, v173, v172
	v_pk_add_f32 v[178:179], v[172:173], v[174:175] neg_lo:[0,1] neg_hi:[0,1]
	v_mov_b32_e32 v177, v172
	v_pk_add_f32 v[172:173], v[178:179], v[176:177] neg_lo:[0,1] neg_hi:[0,1]
	v_cmp_neq_f32_e32 vcc, s70, v156
	v_add_f32_e32 v173, v183, v173
	v_add_f32_e32 v172, v172, v173
	v_add_f32_e32 v173, v175, v172
	v_mul_f32_e32 v183, v182, v173
	v_mul_f32_e32 v174, v181, v183
	v_fma_f32 v176, v183, v181, -v174
	v_fmac_f32_e32 v176, v183, v151
	v_sub_f32_e32 v151, v175, v173
	v_add_f32_e32 v151, v172, v151
	v_add_f32_e32 v172, v174, v176
	v_sub_f32_e32 v175, v173, v172
	v_pk_add_f32 v[178:179], v[172:173], v[174:175] neg_lo:[0,1] neg_hi:[0,1]
	v_mov_b32_e32 v177, v172
	v_pk_add_f32 v[172:173], v[178:179], v[176:177] neg_lo:[0,1] neg_hi:[0,1]
	s_nop 0
	v_add_f32_e32 v151, v151, v173
	v_add_f32_e32 v151, v172, v151
	v_add_f32_e32 v173, v184, v183
	v_add_f32_e32 v151, v175, v151
	v_sub_f32_e32 v172, v173, v184
	v_mul_f32_e32 v151, v182, v151
	v_sub_f32_e32 v172, v183, v172
	v_add_f32_e32 v174, v172, v151
	v_add_f32_e32 v176, v173, v174
	v_cvt_f32_i32_e32 v172, v180
	v_mul_f32_e32 v177, v176, v176
	v_sub_f32_e32 v173, v176, v173
	v_fmamk_f32 v151, v177, 0x3e9b6dac, v166
	v_sub_f32_e32 v173, v174, v173
	v_fmaak_f32 v151, v177, v151, 0x3f2aaada
	v_ldexp_f32 v178, v173, 1
	v_mul_f32_e32 v173, v176, v177
	v_ldexp_f32 v175, v176, 1
	v_pk_mul_f32 v[176:177], v[172:173], v[150:151]
	s_nop 0
	v_fma_f32 v174, v172, s69, -v176
	v_fmac_f32_e32 v174, 0xb102e308, v172
	v_pk_add_f32 v[172:173], v[176:177], v[174:175]
	s_nop 0
	v_sub_f32_e32 v151, v173, v175
	v_sub_f32_e32 v151, v177, v151
	v_add_f32_e32 v179, v178, v151
	v_mov_b32_e32 v178, v176
	v_pk_add_f32 v[176:177], v[172:173], v[176:177] neg_lo:[0,1] neg_hi:[0,1]
	v_pk_add_f32 v[180:181], v[172:173], v[178:179]
	v_mov_b32_e32 v175, v172
	v_mov_b32_e32 v177, v181
	v_pk_add_f32 v[182:183], v[174:175], v[176:177] neg_lo:[0,1] neg_hi:[0,1]
	v_pk_add_f32 v[174:175], v[174:175], v[176:177]
	v_mov_b32_e32 v178, v179
	v_pk_add_f32 v[176:177], v[174:175], v[172:173] op_sel:[1,0] op_sel_hi:[0,1] neg_lo:[0,1] neg_hi:[0,1]
	v_pk_add_f32 v[184:185], v[180:181], v[176:177] op_sel_hi:[1,0] neg_lo:[0,1] neg_hi:[0,1]
	v_mov_b32_e32 v180, v181
	v_mov_b32_e32 v181, v175
	v_pk_mov_b32 v[176:177], v[172:173], v[176:177] op_sel:[1,0]
	v_mov_b32_e32 v179, v172
	v_pk_add_f32 v[176:177], v[180:181], v[176:177] neg_lo:[0,1] neg_hi:[0,1]
	v_mov_b32_e32 v184, v182
	v_pk_add_f32 v[172:173], v[178:179], v[176:177] neg_lo:[0,1] neg_hi:[0,1]
	v_mov_b32_e32 v183, v175
	v_pk_add_f32 v[176:177], v[184:185], v[172:173]
	s_nop 0
	v_pk_add_f32 v[178:179], v[176:177], v[176:177] op_sel:[0,1] op_sel_hi:[1,0]
	s_nop 0
	v_pk_add_f32 v[174:175], v[174:175], v[178:179] op_sel:[1,0] op_sel_hi:[0,1]
	v_mov_b32_e32 v177, v174
	v_pk_add_f32 v[180:181], v[176:177], v[182:183] neg_lo:[0,1] neg_hi:[0,1]
	v_mov_b32_e32 v173, v178
	v_sub_f32_e32 v151, v176, v180
	v_pk_add_f32 v[172:173], v[172:173], v[180:181] neg_lo:[0,1] neg_hi:[0,1]
	v_sub_f32_e32 v151, v182, v151
	v_add_f32_e32 v151, v172, v151
	v_add_f32_e32 v151, v151, v173
	v_add_f32_e32 v151, v174, v151
	v_cndmask_b32_e32 v151, v167, v151, vcc
	v_cmp_ngt_f32_e32 vcc, -1.0, v156
	s_nop 1
	v_cndmask_b32_e32 v151, v168, v151, vcc
	v_cmp_neq_f32_e32 vcc, -1.0, v156
	s_nop 1
	v_cndmask_b32_e32 v151, v169, v151, vcc
	v_cmp_lt_f32_e64 vcc, |v156|, s71
	s_nop 1
	v_cndmask_b32_e32 v151, v151, v156, vcc
;     __device__ __forceinline__ void operator()(const f32x4 (&acc)[2][2][4][2], const Unit& u, int wr, int wc, int fr, int fq) const {
;     ...
;                     for (int m = 0; m < 4; ++m) { const int r = row0 + ai * HALF + m * 16;
;                         const f32x4 v0 = acc[ai][0][m][0], v1 = acc[ai][0][m][1]; float* dp = DT + (size_t)r * 32 + c0;
; #pragma unroll
;                         for (int i = 0; i < 4; ++i) { float x0 = v0[i] + dt_bias[c0 + i], x1 = v1[i] + dt_bias[c0 + 4 + i];
;                             dp[i] = x0 > 20.f ? x0 : log1pf(__expf(x0)); dp[4 + i] = x1 > 20.f ? x1 : log1pf(__expf(x1)); }
.LBB0_797:
	s_or_b64 exec, exec, s[24:25]
	v_add_f32_e32 v136, v123, v136
	v_cmp_nlt_f32_e32 vcc, s67, v136
	flat_store_dword v[154:155], v151 offset:12
	s_and_saveexec_b64 s[24:25], vcc
	s_cbranch_execz .LBB0_799
	v_mul_f32_e32 v136, 0x3fb8aa3b, v136
	v_exp_f32_e32 v136, v136
	s_nop 0
	v_add_f32_e32 v151, 1.0, v136
	v_frexp_mant_f32_e32 v174, v151
	v_cvt_f64_f32_e32 v[172:173], v151
	v_add_f32_e32 v156, -1.0, v151
	v_frexp_exp_i32_f64_e32 v172, v[172:173]
	v_cmp_gt_f32_e32 vcc, s68, v174
	v_sub_f32_e32 v175, v156, v151
	v_sub_f32_e32 v156, v136, v156
	v_subbrev_co_u32_e32 v180, vcc, 0, v172, vcc
	v_add_f32_e32 v175, 1.0, v175
	v_sub_u32_e32 v172, 0, v180
	v_add_f32_e32 v156, v156, v175
	v_ldexp_f32 v151, v151, v172
	v_ldexp_f32 v156, v156, v172
	v_add_f32_e32 v172, -1.0, v151
	v_add_f32_e32 v173, 1.0, v172
	v_sub_f32_e32 v173, v151, v173
	v_add_f32_e32 v174, v156, v173
	v_add_f32_e32 v173, 1.0, v151
	v_add_f32_e32 v175, -1.0, v173
	v_sub_f32_e32 v151, v151, v175
	v_add_f32_e32 v151, v156, v151
	v_add_f32_e32 v156, v173, v151
	v_rcp_f32_e32 v181, v156
	v_sub_f32_e32 v173, v156, v173
	v_sub_f32_e32 v151, v151, v173
	v_add_f32_e32 v173, v172, v174
	v_sub_f32_e32 v172, v173, v172
	v_mul_f32_e32 v183, v173, v181
	v_sub_f32_e32 v182, v174, v172
	v_mul_f32_e32 v174, v156, v183
	v_fma_f32 v176, v183, v156, -v174
	v_fmac_f32_e32 v176, v183, v151
	v_add_f32_e32 v172, v174, v176
	v_sub_f32_e32 v175, v173, v172
	v_pk_add_f32 v[178:179], v[172:173], v[174:175] neg_lo:[0,1] neg_hi:[0,1]
	v_mov_b32_e32 v177, v172
	v_pk_add_f32 v[172:173], v[178:179], v[176:177] neg_lo:[0,1] neg_hi:[0,1]
	v_cmp_neq_f32_e32 vcc, s70, v136
	v_add_f32_e32 v173, v182, v173
	v_add_f32_e32 v172, v172, v173
	v_add_f32_e32 v173, v175, v172
	v_mul_f32_e32 v182, v181, v173
	v_mul_f32_e32 v174, v156, v182
	v_fma_f32 v176, v182, v156, -v174
	v_fmac_f32_e32 v176, v182, v151
	v_sub_f32_e32 v151, v175, v173
	v_add_f32_e32 v151, v172, v151
	v_add_f32_e32 v172, v174, v176
	v_sub_f32_e32 v175, v173, v172
	v_pk_add_f32 v[178:179], v[172:173], v[174:175] neg_lo:[0,1] neg_hi:[0,1]
	v_mov_b32_e32 v177, v172
	v_pk_add_f32 v[172:173], v[178:179], v[176:177] neg_lo:[0,1] neg_hi:[0,1]
	v_add_f32_e32 v156, v183, v182
	v_add_f32_e32 v151, v151, v173
	v_add_f32_e32 v151, v172, v151
	v_add_f32_e32 v151, v175, v151
	v_sub_f32_e32 v172, v156, v183
	v_mul_f32_e32 v151, v181, v151
	v_sub_f32_e32 v172, v182, v172
	v_add_f32_e32 v173, v172, v151
	v_add_f32_e32 v174, v156, v173
	v_cvt_f32_i32_e32 v172, v180
	v_mul_f32_e32 v176, v174, v174
	v_fmamk_f32 v151, v176, 0x3e9b6dac, v166
	v_sub_f32_e32 v156, v174, v156
	v_fmaak_f32 v151, v176, v151, 0x3f2aaada
	v_sub_f32_e32 v156, v173, v156
	v_mul_f32_e32 v173, v174, v176
	v_pk_mul_f32 v[176:177], v[172:173], v[150:151]
	v_ldexp_f32 v175, v174, 1
	v_fma_f32 v174, v172, s69, -v176
	v_fmac_f32_e32 v174, 0xb102e308, v172
	v_pk_add_f32 v[172:173], v[176:177], v[174:175]
	v_ldexp_f32 v156, v156, 1
	v_sub_f32_e32 v151, v173, v175
	v_sub_f32_e32 v151, v177, v151
	v_add_f32_e32 v179, v156, v151
	v_mov_b32_e32 v178, v176
	v_pk_add_f32 v[176:177], v[172:173], v[176:177] neg_lo:[0,1] neg_hi:[0,1]
	v_pk_add_f32 v[180:181], v[172:173], v[178:179]
	v_mov_b32_e32 v175, v172
	v_mov_b32_e32 v177, v181
	v_pk_add_f32 v[182:183], v[174:175], v[176:177] neg_lo:[0,1] neg_hi:[0,1]
	v_pk_add_f32 v[174:175], v[174:175], v[176:177]
	v_mov_b32_e32 v178, v179
	v_pk_add_f32 v[176:177], v[174:175], v[172:173] op_sel:[1,0] op_sel_hi:[0,1] neg_lo:[0,1] neg_hi:[0,1]
	v_pk_add_f32 v[184:185], v[180:181], v[176:177] op_sel_hi:[1,0] neg_lo:[0,1] neg_hi:[0,1]
	v_mov_b32_e32 v180, v181
	v_mov_b32_e32 v181, v175
	v_pk_mov_b32 v[176:177], v[172:173], v[176:177] op_sel:[1,0]
	v_mov_b32_e32 v179, v172
	v_pk_add_f32 v[176:177], v[180:181], v[176:177] neg_lo:[0,1] neg_hi:[0,1]
	v_mov_b32_e32 v184, v182
	v_pk_add_f32 v[172:173], v[178:179], v[176:177] neg_lo:[0,1] neg_hi:[0,1]
	v_mov_b32_e32 v183, v175
	v_pk_add_f32 v[176:177], v[184:185], v[172:173]
	s_nop 0
	v_pk_add_f32 v[178:179], v[176:177], v[176:177] op_sel:[0,1] op_sel_hi:[1,0]
	s_nop 0
	v_pk_add_f32 v[174:175], v[174:175], v[178:179] op_sel:[1,0] op_sel_hi:[0,1]
	v_mov_b32_e32 v177, v174
	v_pk_add_f32 v[180:181], v[176:177], v[182:183] neg_lo:[0,1] neg_hi:[0,1]
	v_mov_b32_e32 v173, v178
	v_sub_f32_e32 v151, v176, v180
	v_pk_add_f32 v[172:173], v[172:173], v[180:181] neg_lo:[0,1] neg_hi:[0,1]
	v_sub_f32_e32 v151, v182, v151
	v_add_f32_e32 v151, v172, v151
	v_add_f32_e32 v151, v151, v173
	v_add_f32_e32 v151, v174, v151
	v_cndmask_b32_e32 v151, v167, v151, vcc
	v_cmp_ngt_f32_e32 vcc, -1.0, v136
	s_nop 1
	v_cndmask_b32_e32 v151, v168, v151, vcc
	v_cmp_neq_f32_e32 vcc, -1.0, v136
	s_nop 1
	v_cndmask_b32_e32 v151, v169, v151, vcc
	v_cmp_lt_f32_e64 vcc, |v136|, s71
	s_nop 1
	v_cndmask_b32_e32 v136, v151, v136, vcc
;     __device__ __forceinline__ void operator()(const f32x4 (&acc)[2][2][4][2], const Unit& u, int wr, int wc, int fr, int fq) const {
;     ...
;                     for (int m = 0; m < 4; ++m) { const int r = row0 + ai * HALF + m * 16;
;                         const f32x4 v0 = acc[ai][0][m][0], v1 = acc[ai][0][m][1]; float* dp = DT + (size_t)r * 32 + c0;
; #pragma unroll
;                         for (int i = 0; i < 4; ++i) { float x0 = v0[i] + dt_bias[c0 + i], x1 = v1[i] + dt_bias[c0 + 4 + i];
;                             dp[i] = x0 > 20.f ? x0 : log1pf(__expf(x0)); dp[4 + i] = x1 > 20.f ? x1 : log1pf(__expf(x1)); }
;                         __builtin_amdgcn_sched_barrier(0); }
.LBB0_799:
	s_or_b64 exec, exec, s[24:25]
	flat_store_dword v[154:155], v136 offset:28
	v_mov_b32_e32 v136, v200
	v_add_f32_e32 v151, v108, v136
	v_mov_b32_e32 v136, v204
	v_cmp_nlt_f32_e32 vcc, s67, v151
	s_and_saveexec_b64 s[24:25], vcc
	s_cbranch_execz .LBB0_801
	v_mul_f32_e32 v151, 0x3fb8aa3b, v151
	v_exp_f32_e32 v156, v151
	s_nop 0
	v_add_f32_e32 v151, 1.0, v156
	v_frexp_mant_f32_e32 v173, v151
	v_cvt_f64_f32_e32 v[154:155], v151
	v_add_f32_e32 v172, -1.0, v151
	v_frexp_exp_i32_f64_e32 v154, v[154:155]
	v_cmp_gt_f32_e32 vcc, s68, v173
	v_sub_f32_e32 v174, v172, v151
	v_sub_f32_e32 v172, v156, v172
	v_subbrev_co_u32_e32 v178, vcc, 0, v154, vcc
	v_add_f32_e32 v174, 1.0, v174
	v_sub_u32_e32 v154, 0, v178
	v_add_f32_e32 v172, v172, v174
	v_ldexp_f32 v151, v151, v154
	v_ldexp_f32 v154, v172, v154
	v_add_f32_e32 v172, -1.0, v151
	v_add_f32_e32 v155, 1.0, v172
	v_sub_f32_e32 v155, v151, v155
	v_add_f32_e32 v173, v154, v155
	v_add_f32_e32 v155, 1.0, v151
	v_add_f32_e32 v174, -1.0, v155
	v_sub_f32_e32 v151, v151, v174
	v_add_f32_e32 v151, v154, v151
	v_add_f32_e32 v179, v155, v151
	v_rcp_f32_e32 v180, v179
	v_sub_f32_e32 v154, v179, v155
	v_add_f32_e32 v155, v172, v173
	v_sub_f32_e32 v151, v151, v154
	v_mul_f32_e32 v182, v155, v180
	v_sub_f32_e32 v154, v155, v172
	v_mul_f32_e32 v172, v179, v182
	v_fma_f32 v174, v182, v179, -v172
	v_fmac_f32_e32 v174, v182, v151
	v_sub_f32_e32 v181, v173, v154
	v_add_f32_e32 v154, v172, v174
	v_sub_f32_e32 v173, v155, v154
	v_pk_add_f32 v[176:177], v[154:155], v[172:173] neg_lo:[0,1] neg_hi:[0,1]
	v_mov_b32_e32 v175, v154
	v_pk_add_f32 v[154:155], v[176:177], v[174:175] neg_lo:[0,1] neg_hi:[0,1]
	v_cmp_neq_f32_e32 vcc, s70, v156
	v_add_f32_e32 v155, v181, v155
	v_add_f32_e32 v154, v154, v155
	v_add_f32_e32 v155, v173, v154
	v_mul_f32_e32 v181, v180, v155
	v_mul_f32_e32 v172, v179, v181
	v_fma_f32 v174, v181, v179, -v172
	v_fmac_f32_e32 v174, v181, v151
	v_sub_f32_e32 v151, v173, v155
	v_add_f32_e32 v151, v154, v151
	v_add_f32_e32 v154, v172, v174
	v_sub_f32_e32 v173, v155, v154
	v_pk_add_f32 v[176:177], v[154:155], v[172:173] neg_lo:[0,1] neg_hi:[0,1]
	v_mov_b32_e32 v175, v154
	v_pk_add_f32 v[154:155], v[176:177], v[174:175] neg_lo:[0,1] neg_hi:[0,1]
	s_nop 0
	v_add_f32_e32 v151, v151, v155
	v_add_f32_e32 v151, v154, v151
	v_add_f32_e32 v155, v182, v181
	v_add_f32_e32 v151, v173, v151
	v_sub_f32_e32 v154, v155, v182
	v_mul_f32_e32 v151, v180, v151
	v_sub_f32_e32 v154, v181, v154
	v_add_f32_e32 v172, v154, v151
	v_add_f32_e32 v174, v155, v172
	v_cvt_f32_i32_e32 v154, v178
	v_mul_f32_e32 v175, v174, v174
	v_sub_f32_e32 v155, v174, v155
	v_fmamk_f32 v151, v175, 0x3e9b6dac, v166
	v_sub_f32_e32 v155, v172, v155
	v_fmaak_f32 v151, v175, v151, 0x3f2aaada
	v_ldexp_f32 v176, v155, 1
	v_mul_f32_e32 v155, v174, v175
	v_ldexp_f32 v173, v174, 1
	v_pk_mul_f32 v[174:175], v[154:155], v[150:151]
	s_nop 0
	v_fma_f32 v172, v154, s69, -v174
	v_fmac_f32_e32 v172, 0xb102e308, v154
	v_pk_add_f32 v[154:155], v[174:175], v[172:173]
	s_nop 0
	v_sub_f32_e32 v151, v155, v173
	v_sub_f32_e32 v151, v175, v151
	v_add_f32_e32 v177, v176, v151
	v_mov_b32_e32 v176, v174
	v_pk_add_f32 v[174:175], v[154:155], v[174:175] neg_lo:[0,1] neg_hi:[0,1]
	v_pk_add_f32 v[178:179], v[154:155], v[176:177]
	v_mov_b32_e32 v173, v154
	v_mov_b32_e32 v175, v179
	v_pk_add_f32 v[180:181], v[172:173], v[174:175] neg_lo:[0,1] neg_hi:[0,1]
	v_pk_add_f32 v[172:173], v[172:173], v[174:175]
	v_mov_b32_e32 v176, v177
	v_pk_add_f32 v[174:175], v[172:173], v[154:155] op_sel:[1,0] op_sel_hi:[0,1] neg_lo:[0,1] neg_hi:[0,1]
	v_pk_add_f32 v[182:183], v[178:179], v[174:175] op_sel_hi:[1,0] neg_lo:[0,1] neg_hi:[0,1]
	v_mov_b32_e32 v178, v179
	v_mov_b32_e32 v179, v173
	v_pk_mov_b32 v[174:175], v[154:155], v[174:175] op_sel:[1,0]
	v_mov_b32_e32 v177, v154
	v_pk_add_f32 v[174:175], v[178:179], v[174:175] neg_lo:[0,1] neg_hi:[0,1]
	v_mov_b32_e32 v182, v180
	v_pk_add_f32 v[154:155], v[176:177], v[174:175] neg_lo:[0,1] neg_hi:[0,1]
	v_mov_b32_e32 v181, v173
	v_pk_add_f32 v[174:175], v[182:183], v[154:155]
	s_nop 0
	v_pk_add_f32 v[176:177], v[174:175], v[174:175] op_sel:[0,1] op_sel_hi:[1,0]
	s_nop 0
	v_pk_add_f32 v[172:173], v[172:173], v[176:177] op_sel:[1,0] op_sel_hi:[0,1]
	v_mov_b32_e32 v175, v172
	v_pk_add_f32 v[178:179], v[174:175], v[180:181] neg_lo:[0,1] neg_hi:[0,1]
	v_mov_b32_e32 v155, v176
	v_sub_f32_e32 v151, v174, v178
	v_pk_add_f32 v[154:155], v[154:155], v[178:179] neg_lo:[0,1] neg_hi:[0,1]
	v_sub_f32_e32 v151, v180, v151
	v_add_f32_e32 v151, v154, v151
	v_add_f32_e32 v151, v151, v155
	v_add_f32_e32 v151, v172, v151
	v_cndmask_b32_e32 v151, v167, v151, vcc
	v_cmp_ngt_f32_e32 vcc, -1.0, v156
	s_nop 1
	v_cndmask_b32_e32 v151, v168, v151, vcc
	v_cmp_neq_f32_e32 vcc, -1.0, v156
	s_nop 1
	v_cndmask_b32_e32 v151, v169, v151, vcc
	v_cmp_lt_f32_e64 vcc, |v156|, s71
	s_nop 1
	v_cndmask_b32_e32 v151, v151, v156, vcc
;     __device__ __forceinline__ void operator()(const f32x4 (&acc)[2][2][4][2], const Unit& u, int wr, int wc, int fr, int fq) const {
;     ...
;                     for (int m = 0; m < 4; ++m) { const int r = row0 + ai * HALF + m * 16;
;                         const f32x4 v0 = acc[ai][0][m][0], v1 = acc[ai][0][m][1]; float* dp = DT + (size_t)r * 32 + c0;
; #pragma unroll
;                         for (int i = 0; i < 4; ++i) { float x0 = v0[i] + dt_bias[c0 + i], x1 = v1[i] + dt_bias[c0 + 4 + i];
;                             dp[i] = x0 > 20.f ? x0 : log1pf(__expf(x0)); dp[4 + i] = x1 > 20.f ? x1 : log1pf(__expf(x1)); }
.LBB0_801:
	s_or_b64 exec, exec, s[24:25]
	v_or_b32_e32 v154, 16, v152
	v_ashrrev_i32_e32 v155, 31, v154
	v_lshlrev_b64 v[154:155], 7, v[154:155]
	v_add_f32_e32 v136, v104, v136
	v_lshl_add_u64 v[154:155], v[138:139], 0, v[154:155]
	v_cmp_nlt_f32_e32 vcc, s67, v136
	flat_store_dword v[154:155], v151
	s_and_saveexec_b64 s[24:25], vcc
	s_cbranch_execz .LBB0_803
	v_mul_f32_e32 v136, 0x3fb8aa3b, v136
	v_exp_f32_e32 v136, v136
	s_nop 0
	v_add_f32_e32 v151, 1.0, v136
	v_frexp_mant_f32_e32 v174, v151
	v_cvt_f64_f32_e32 v[172:173], v151
	v_add_f32_e32 v156, -1.0, v151
	v_frexp_exp_i32_f64_e32 v172, v[172:173]
	v_cmp_gt_f32_e32 vcc, s68, v174
	v_sub_f32_e32 v175, v156, v151
	v_sub_f32_e32 v156, v136, v156
	v_subbrev_co_u32_e32 v180, vcc, 0, v172, vcc
	v_add_f32_e32 v175, 1.0, v175
	v_sub_u32_e32 v172, 0, v180
	v_add_f32_e32 v156, v156, v175
	v_ldexp_f32 v151, v151, v172
	v_ldexp_f32 v156, v156, v172
	v_add_f32_e32 v172, -1.0, v151
	v_add_f32_e32 v173, 1.0, v172
	v_sub_f32_e32 v173, v151, v173
	v_add_f32_e32 v174, v156, v173
	v_add_f32_e32 v173, 1.0, v151
	v_add_f32_e32 v175, -1.0, v173
	v_sub_f32_e32 v151, v151, v175
	v_add_f32_e32 v151, v156, v151
	v_add_f32_e32 v156, v173, v151
	v_rcp_f32_e32 v181, v156
	v_sub_f32_e32 v173, v156, v173
	v_sub_f32_e32 v151, v151, v173
	v_add_f32_e32 v173, v172, v174
	v_sub_f32_e32 v172, v173, v172
	v_mul_f32_e32 v183, v173, v181
	v_sub_f32_e32 v182, v174, v172
	v_mul_f32_e32 v174, v156, v183
	v_fma_f32 v176, v183, v156, -v174
	v_fmac_f32_e32 v176, v183, v151
	v_add_f32_e32 v172, v174, v176
	v_sub_f32_e32 v175, v173, v172
	v_pk_add_f32 v[178:179], v[172:173], v[174:175] neg_lo:[0,1] neg_hi:[0,1]
	v_mov_b32_e32 v177, v172
	v_pk_add_f32 v[172:173], v[178:179], v[176:177] neg_lo:[0,1] neg_hi:[0,1]
	v_cmp_neq_f32_e32 vcc, s70, v136
	v_add_f32_e32 v173, v182, v173
	v_add_f32_e32 v172, v172, v173
	v_add_f32_e32 v173, v175, v172
	v_mul_f32_e32 v182, v181, v173
	v_mul_f32_e32 v174, v156, v182
	v_fma_f32 v176, v182, v156, -v174
	v_fmac_f32_e32 v176, v182, v151
	v_sub_f32_e32 v151, v175, v173
	v_add_f32_e32 v151, v172, v151
	v_add_f32_e32 v172, v174, v176
	v_sub_f32_e32 v175, v173, v172
	v_pk_add_f32 v[178:179], v[172:173], v[174:175] neg_lo:[0,1] neg_hi:[0,1]
	v_mov_b32_e32 v177, v172
	v_pk_add_f32 v[172:173], v[178:179], v[176:177] neg_lo:[0,1] neg_hi:[0,1]
	v_add_f32_e32 v156, v183, v182
	v_add_f32_e32 v151, v151, v173
	v_add_f32_e32 v151, v172, v151
	v_add_f32_e32 v151, v175, v151
	v_sub_f32_e32 v172, v156, v183
	v_mul_f32_e32 v151, v181, v151
	v_sub_f32_e32 v172, v182, v172
	v_add_f32_e32 v173, v172, v151
	v_add_f32_e32 v174, v156, v173
	v_cvt_f32_i32_e32 v172, v180
	v_mul_f32_e32 v176, v174, v174
	v_fmamk_f32 v151, v176, 0x3e9b6dac, v166
	v_sub_f32_e32 v156, v174, v156
	v_fmaak_f32 v151, v176, v151, 0x3f2aaada
	v_sub_f32_e32 v156, v173, v156
	v_mul_f32_e32 v173, v174, v176
	v_pk_mul_f32 v[176:177], v[172:173], v[150:151]
	v_ldexp_f32 v175, v174, 1
	v_fma_f32 v174, v172, s69, -v176
	v_fmac_f32_e32 v174, 0xb102e308, v172
	v_pk_add_f32 v[172:173], v[176:177], v[174:175]
	v_ldexp_f32 v156, v156, 1
	v_sub_f32_e32 v151, v173, v175
	v_sub_f32_e32 v151, v177, v151
	v_add_f32_e32 v179, v156, v151
	v_mov_b32_e32 v178, v176
	v_pk_add_f32 v[176:177], v[172:173], v[176:177] neg_lo:[0,1] neg_hi:[0,1]
	v_pk_add_f32 v[180:181], v[172:173], v[178:179]
	v_mov_b32_e32 v175, v172
	v_mov_b32_e32 v177, v181
	v_pk_add_f32 v[182:183], v[174:175], v[176:177] neg_lo:[0,1] neg_hi:[0,1]
	v_pk_add_f32 v[174:175], v[174:175], v[176:177]
	v_mov_b32_e32 v178, v179
	v_pk_add_f32 v[176:177], v[174:175], v[172:173] op_sel:[1,0] op_sel_hi:[0,1] neg_lo:[0,1] neg_hi:[0,1]
	v_pk_add_f32 v[184:185], v[180:181], v[176:177] op_sel_hi:[1,0] neg_lo:[0,1] neg_hi:[0,1]
	v_mov_b32_e32 v180, v181
	v_mov_b32_e32 v181, v175
	v_pk_mov_b32 v[176:177], v[172:173], v[176:177] op_sel:[1,0]
	v_mov_b32_e32 v179, v172
	v_pk_add_f32 v[176:177], v[180:181], v[176:177] neg_lo:[0,1] neg_hi:[0,1]
	v_mov_b32_e32 v184, v182
	v_pk_add_f32 v[172:173], v[178:179], v[176:177] neg_lo:[0,1] neg_hi:[0,1]
	v_mov_b32_e32 v183, v175
	v_pk_add_f32 v[176:177], v[184:185], v[172:173]
	s_nop 0
	v_pk_add_f32 v[178:179], v[176:177], v[176:177] op_sel:[0,1] op_sel_hi:[1,0]
	s_nop 0
	v_pk_add_f32 v[174:175], v[174:175], v[178:179] op_sel:[1,0] op_sel_hi:[0,1]
	v_mov_b32_e32 v177, v174
	v_pk_add_f32 v[180:181], v[176:177], v[182:183] neg_lo:[0,1] neg_hi:[0,1]
	v_mov_b32_e32 v173, v178
	v_sub_f32_e32 v151, v176, v180
	v_pk_add_f32 v[172:173], v[172:173], v[180:181] neg_lo:[0,1] neg_hi:[0,1]
	v_sub_f32_e32 v151, v182, v151
	v_add_f32_e32 v151, v172, v151
	v_add_f32_e32 v151, v151, v173
	v_add_f32_e32 v151, v174, v151
	v_cndmask_b32_e32 v151, v167, v151, vcc
	v_cmp_ngt_f32_e32 vcc, -1.0, v136
	s_nop 1
	v_cndmask_b32_e32 v151, v168, v151, vcc
	v_cmp_neq_f32_e32 vcc, -1.0, v136
	s_nop 1
	v_cndmask_b32_e32 v151, v169, v151, vcc
	v_cmp_lt_f32_e64 vcc, |v136|, s71
	s_nop 1
	v_cndmask_b32_e32 v136, v151, v136, vcc
;     __device__ __forceinline__ void operator()(const f32x4 (&acc)[2][2][4][2], const Unit& u, int wr, int wc, int fr, int fq) const {
;     ...
;                     for (int m = 0; m < 4; ++m) { const int r = row0 + ai * HALF + m * 16;
;                         const f32x4 v0 = acc[ai][0][m][0], v1 = acc[ai][0][m][1]; float* dp = DT + (size_t)r * 32 + c0;
; #pragma unroll
;                         for (int i = 0; i < 4; ++i) { float x0 = v0[i] + dt_bias[c0 + i], x1 = v1[i] + dt_bias[c0 + 4 + i];
;                             dp[i] = x0 > 20.f ? x0 : log1pf(__expf(x0)); dp[4 + i] = x1 > 20.f ? x1 : log1pf(__expf(x1)); }
.LBB0_803:
	s_or_b64 exec, exec, s[24:25]
	flat_store_dword v[154:155], v136 offset:16
	v_mov_b32_e32 v136, v201
	v_add_f32_e32 v151, v109, v136
	v_mov_b32_e32 v136, v205
	v_cmp_nlt_f32_e32 vcc, s67, v151
	s_and_saveexec_b64 s[24:25], vcc
	s_cbranch_execz .LBB0_805
	v_mul_f32_e32 v151, 0x3fb8aa3b, v151
	v_exp_f32_e32 v156, v151
	s_nop 0
	v_add_f32_e32 v151, 1.0, v156
	v_frexp_mant_f32_e32 v175, v151
	v_cvt_f64_f32_e32 v[172:173], v151
	v_add_f32_e32 v174, -1.0, v151
	v_frexp_exp_i32_f64_e32 v172, v[172:173]
	v_cmp_gt_f32_e32 vcc, s68, v175
	v_sub_f32_e32 v176, v174, v151
	v_sub_f32_e32 v174, v156, v174
	v_subbrev_co_u32_e32 v180, vcc, 0, v172, vcc
	v_add_f32_e32 v176, 1.0, v176
	v_sub_u32_e32 v172, 0, v180
	v_add_f32_e32 v174, v174, v176
	v_ldexp_f32 v151, v151, v172
	v_ldexp_f32 v172, v174, v172
	v_add_f32_e32 v174, -1.0, v151
	v_add_f32_e32 v173, 1.0, v174
	v_sub_f32_e32 v173, v151, v173
	v_add_f32_e32 v175, v172, v173
	v_add_f32_e32 v173, 1.0, v151
	v_add_f32_e32 v176, -1.0, v173
	v_sub_f32_e32 v151, v151, v176
	v_add_f32_e32 v151, v172, v151
	v_add_f32_e32 v181, v173, v151
	v_rcp_f32_e32 v182, v181
	v_sub_f32_e32 v172, v181, v173
	v_add_f32_e32 v173, v174, v175
	v_sub_f32_e32 v151, v151, v172
	v_mul_f32_e32 v184, v173, v182
	v_sub_f32_e32 v172, v173, v174
	v_mul_f32_e32 v174, v181, v184
	v_fma_f32 v176, v184, v181, -v174
	v_fmac_f32_e32 v176, v184, v151
	v_sub_f32_e32 v183, v175, v172
	v_add_f32_e32 v172, v174, v176
	v_sub_f32_e32 v175, v173, v172
	v_pk_add_f32 v[178:179], v[172:173], v[174:175] neg_lo:[0,1] neg_hi:[0,1]
	v_mov_b32_e32 v177, v172
	v_pk_add_f32 v[172:173], v[178:179], v[176:177] neg_lo:[0,1] neg_hi:[0,1]
	v_cmp_neq_f32_e32 vcc, s70, v156
	v_add_f32_e32 v173, v183, v173
	v_add_f32_e32 v172, v172, v173
	v_add_f32_e32 v173, v175, v172
	v_mul_f32_e32 v183, v182, v173
	v_mul_f32_e32 v174, v181, v183
	v_fma_f32 v176, v183, v181, -v174
	v_fmac_f32_e32 v176, v183, v151
	v_sub_f32_e32 v151, v175, v173
	v_add_f32_e32 v151, v172, v151
	v_add_f32_e32 v172, v174, v176
	v_sub_f32_e32 v175, v173, v172
	v_pk_add_f32 v[178:179], v[172:173], v[174:175] neg_lo:[0,1] neg_hi:[0,1]
	v_mov_b32_e32 v177, v172
	v_pk_add_f32 v[172:173], v[178:179], v[176:177] neg_lo:[0,1] neg_hi:[0,1]
	s_nop 0
	v_add_f32_e32 v151, v151, v173
	v_add_f32_e32 v151, v172, v151
	v_add_f32_e32 v173, v184, v183
	v_add_f32_e32 v151, v175, v151
	v_sub_f32_e32 v172, v173, v184
	v_mul_f32_e32 v151, v182, v151
	v_sub_f32_e32 v172, v183, v172
	v_add_f32_e32 v174, v172, v151
	v_add_f32_e32 v176, v173, v174
	v_cvt_f32_i32_e32 v172, v180
	v_mul_f32_e32 v177, v176, v176
	v_sub_f32_e32 v173, v176, v173
	v_fmamk_f32 v151, v177, 0x3e9b6dac, v166
	v_sub_f32_e32 v173, v174, v173
	v_fmaak_f32 v151, v177, v151, 0x3f2aaada
	v_ldexp_f32 v178, v173, 1
	v_mul_f32_e32 v173, v176, v177
	v_ldexp_f32 v175, v176, 1
	v_pk_mul_f32 v[176:177], v[172:173], v[150:151]
	s_nop 0
	v_fma_f32 v174, v172, s69, -v176
	v_fmac_f32_e32 v174, 0xb102e308, v172
	v_pk_add_f32 v[172:173], v[176:177], v[174:175]
	s_nop 0
	v_sub_f32_e32 v151, v173, v175
	v_sub_f32_e32 v151, v177, v151
	v_add_f32_e32 v179, v178, v151
	v_mov_b32_e32 v178, v176
	v_pk_add_f32 v[176:177], v[172:173], v[176:177] neg_lo:[0,1] neg_hi:[0,1]
	v_pk_add_f32 v[180:181], v[172:173], v[178:179]
	v_mov_b32_e32 v175, v172
	v_mov_b32_e32 v177, v181
	v_pk_add_f32 v[182:183], v[174:175], v[176:177] neg_lo:[0,1] neg_hi:[0,1]
	v_pk_add_f32 v[174:175], v[174:175], v[176:177]
	v_mov_b32_e32 v178, v179
	v_pk_add_f32 v[176:177], v[174:175], v[172:173] op_sel:[1,0] op_sel_hi:[0,1] neg_lo:[0,1] neg_hi:[0,1]
	v_pk_add_f32 v[184:185], v[180:181], v[176:177] op_sel_hi:[1,0] neg_lo:[0,1] neg_hi:[0,1]
	v_mov_b32_e32 v180, v181
	v_mov_b32_e32 v181, v175
	v_pk_mov_b32 v[176:177], v[172:173], v[176:177] op_sel:[1,0]
	v_mov_b32_e32 v179, v172
	v_pk_add_f32 v[176:177], v[180:181], v[176:177] neg_lo:[0,1] neg_hi:[0,1]
	v_mov_b32_e32 v184, v182
	v_pk_add_f32 v[172:173], v[178:179], v[176:177] neg_lo:[0,1] neg_hi:[0,1]
	v_mov_b32_e32 v183, v175
	v_pk_add_f32 v[176:177], v[184:185], v[172:173]
	s_nop 0
	v_pk_add_f32 v[178:179], v[176:177], v[176:177] op_sel:[0,1] op_sel_hi:[1,0]
	s_nop 0
	v_pk_add_f32 v[174:175], v[174:175], v[178:179] op_sel:[1,0] op_sel_hi:[0,1]
	v_mov_b32_e32 v177, v174
	v_pk_add_f32 v[180:181], v[176:177], v[182:183] neg_lo:[0,1] neg_hi:[0,1]
	v_mov_b32_e32 v173, v178
	v_sub_f32_e32 v151, v176, v180
	v_pk_add_f32 v[172:173], v[172:173], v[180:181] neg_lo:[0,1] neg_hi:[0,1]
	v_sub_f32_e32 v151, v182, v151
	v_add_f32_e32 v151, v172, v151
	v_add_f32_e32 v151, v151, v173
	v_add_f32_e32 v151, v174, v151
	v_cndmask_b32_e32 v151, v167, v151, vcc
	v_cmp_ngt_f32_e32 vcc, -1.0, v156
	s_nop 1
	v_cndmask_b32_e32 v151, v168, v151, vcc
	v_cmp_neq_f32_e32 vcc, -1.0, v156
	s_nop 1
	v_cndmask_b32_e32 v151, v169, v151, vcc
	v_cmp_lt_f32_e64 vcc, |v156|, s71
	s_nop 1
	v_cndmask_b32_e32 v151, v151, v156, vcc
;     __device__ __forceinline__ void operator()(const f32x4 (&acc)[2][2][4][2], const Unit& u, int wr, int wc, int fr, int fq) const {
;     ...
;                     for (int m = 0; m < 4; ++m) { const int r = row0 + ai * HALF + m * 16;
;                         const f32x4 v0 = acc[ai][0][m][0], v1 = acc[ai][0][m][1]; float* dp = DT + (size_t)r * 32 + c0;
; #pragma unroll
;                         for (int i = 0; i < 4; ++i) { float x0 = v0[i] + dt_bias[c0 + i], x1 = v1[i] + dt_bias[c0 + 4 + i];
;                             dp[i] = x0 > 20.f ? x0 : log1pf(__expf(x0)); dp[4 + i] = x1 > 20.f ? x1 : log1pf(__expf(x1)); }
.LBB0_805:
	s_or_b64 exec, exec, s[24:25]
	v_add_f32_e32 v136, v105, v136
	v_cmp_nlt_f32_e32 vcc, s67, v136
	flat_store_dword v[154:155], v151 offset:4
	s_and_saveexec_b64 s[24:25], vcc
	s_cbranch_execz .LBB0_807
	v_mul_f32_e32 v136, 0x3fb8aa3b, v136
	v_exp_f32_e32 v136, v136
	s_nop 0
	v_add_f32_e32 v151, 1.0, v136
	v_frexp_mant_f32_e32 v174, v151
	v_cvt_f64_f32_e32 v[172:173], v151
	v_add_f32_e32 v156, -1.0, v151
	v_frexp_exp_i32_f64_e32 v172, v[172:173]
	v_cmp_gt_f32_e32 vcc, s68, v174
	v_sub_f32_e32 v175, v156, v151
	v_sub_f32_e32 v156, v136, v156
	v_subbrev_co_u32_e32 v180, vcc, 0, v172, vcc
	v_add_f32_e32 v175, 1.0, v175
	v_sub_u32_e32 v172, 0, v180
	v_add_f32_e32 v156, v156, v175
	v_ldexp_f32 v151, v151, v172
	v_ldexp_f32 v156, v156, v172
	v_add_f32_e32 v172, -1.0, v151
	v_add_f32_e32 v173, 1.0, v172
	v_sub_f32_e32 v173, v151, v173
	v_add_f32_e32 v174, v156, v173
	v_add_f32_e32 v173, 1.0, v151
	v_add_f32_e32 v175, -1.0, v173
	v_sub_f32_e32 v151, v151, v175
	v_add_f32_e32 v151, v156, v151
	v_add_f32_e32 v156, v173, v151
	v_rcp_f32_e32 v181, v156
	v_sub_f32_e32 v173, v156, v173
	v_sub_f32_e32 v151, v151, v173
	v_add_f32_e32 v173, v172, v174
	v_sub_f32_e32 v172, v173, v172
	v_mul_f32_e32 v183, v173, v181
	v_sub_f32_e32 v182, v174, v172
	v_mul_f32_e32 v174, v156, v183
	v_fma_f32 v176, v183, v156, -v174
	v_fmac_f32_e32 v176, v183, v151
	v_add_f32_e32 v172, v174, v176
	v_sub_f32_e32 v175, v173, v172
	v_pk_add_f32 v[178:179], v[172:173], v[174:175] neg_lo:[0,1] neg_hi:[0,1]
	v_mov_b32_e32 v177, v172
	v_pk_add_f32 v[172:173], v[178:179], v[176:177] neg_lo:[0,1] neg_hi:[0,1]
	v_cmp_neq_f32_e32 vcc, s70, v136
	v_add_f32_e32 v173, v182, v173
	v_add_f32_e32 v172, v172, v173
	v_add_f32_e32 v173, v175, v172
	v_mul_f32_e32 v182, v181, v173
	v_mul_f32_e32 v174, v156, v182
	v_fma_f32 v176, v182, v156, -v174
	v_fmac_f32_e32 v176, v182, v151
	v_sub_f32_e32 v151, v175, v173
	v_add_f32_e32 v151, v172, v151
	v_add_f32_e32 v172, v174, v176
	v_sub_f32_e32 v175, v173, v172
	v_pk_add_f32 v[178:179], v[172:173], v[174:175] neg_lo:[0,1] neg_hi:[0,1]
	v_mov_b32_e32 v177, v172
	v_pk_add_f32 v[172:173], v[178:179], v[176:177] neg_lo:[0,1] neg_hi:[0,1]
	v_add_f32_e32 v156, v183, v182
	v_add_f32_e32 v151, v151, v173
	v_add_f32_e32 v151, v172, v151
	v_add_f32_e32 v151, v175, v151
	v_sub_f32_e32 v172, v156, v183
	v_mul_f32_e32 v151, v181, v151
	v_sub_f32_e32 v172, v182, v172
	v_add_f32_e32 v173, v172, v151
	v_add_f32_e32 v174, v156, v173
	v_cvt_f32_i32_e32 v172, v180
	v_mul_f32_e32 v176, v174, v174
	v_fmamk_f32 v151, v176, 0x3e9b6dac, v166
	v_sub_f32_e32 v156, v174, v156
	v_fmaak_f32 v151, v176, v151, 0x3f2aaada
	v_sub_f32_e32 v156, v173, v156
	v_mul_f32_e32 v173, v174, v176
	v_pk_mul_f32 v[176:177], v[172:173], v[150:151]
	v_ldexp_f32 v175, v174, 1
	v_fma_f32 v174, v172, s69, -v176
	v_fmac_f32_e32 v174, 0xb102e308, v172
	v_pk_add_f32 v[172:173], v[176:177], v[174:175]
	v_ldexp_f32 v156, v156, 1
	v_sub_f32_e32 v151, v173, v175
	v_sub_f32_e32 v151, v177, v151
	v_add_f32_e32 v179, v156, v151
	v_mov_b32_e32 v178, v176
	v_pk_add_f32 v[176:177], v[172:173], v[176:177] neg_lo:[0,1] neg_hi:[0,1]
	v_pk_add_f32 v[180:181], v[172:173], v[178:179]
	v_mov_b32_e32 v175, v172
	v_mov_b32_e32 v177, v181
	v_pk_add_f32 v[182:183], v[174:175], v[176:177] neg_lo:[0,1] neg_hi:[0,1]
	v_pk_add_f32 v[174:175], v[174:175], v[176:177]
	v_mov_b32_e32 v178, v179
	v_pk_add_f32 v[176:177], v[174:175], v[172:173] op_sel:[1,0] op_sel_hi:[0,1] neg_lo:[0,1] neg_hi:[0,1]
	v_pk_add_f32 v[184:185], v[180:181], v[176:177] op_sel_hi:[1,0] neg_lo:[0,1] neg_hi:[0,1]
	v_mov_b32_e32 v180, v181
	v_mov_b32_e32 v181, v175
	v_pk_mov_b32 v[176:177], v[172:173], v[176:177] op_sel:[1,0]
	v_mov_b32_e32 v179, v172
	v_pk_add_f32 v[176:177], v[180:181], v[176:177] neg_lo:[0,1] neg_hi:[0,1]
	v_mov_b32_e32 v184, v182
	v_pk_add_f32 v[172:173], v[178:179], v[176:177] neg_lo:[0,1] neg_hi:[0,1]
	v_mov_b32_e32 v183, v175
	v_pk_add_f32 v[176:177], v[184:185], v[172:173]
	s_nop 0
	v_pk_add_f32 v[178:179], v[176:177], v[176:177] op_sel:[0,1] op_sel_hi:[1,0]
	s_nop 0
	v_pk_add_f32 v[174:175], v[174:175], v[178:179] op_sel:[1,0] op_sel_hi:[0,1]
	v_mov_b32_e32 v177, v174
	v_pk_add_f32 v[180:181], v[176:177], v[182:183] neg_lo:[0,1] neg_hi:[0,1]
	v_mov_b32_e32 v173, v178
	v_sub_f32_e32 v151, v176, v180
	v_pk_add_f32 v[172:173], v[172:173], v[180:181] neg_lo:[0,1] neg_hi:[0,1]
	v_sub_f32_e32 v151, v182, v151
	v_add_f32_e32 v151, v172, v151
	v_add_f32_e32 v151, v151, v173
	v_add_f32_e32 v151, v174, v151
	v_cndmask_b32_e32 v151, v167, v151, vcc
	v_cmp_ngt_f32_e32 vcc, -1.0, v136
	s_nop 1
	v_cndmask_b32_e32 v151, v168, v151, vcc
	v_cmp_neq_f32_e32 vcc, -1.0, v136
	s_nop 1
	v_cndmask_b32_e32 v151, v169, v151, vcc
	v_cmp_lt_f32_e64 vcc, |v136|, s71
	s_nop 1
	v_cndmask_b32_e32 v136, v151, v136, vcc
;     __device__ __forceinline__ void operator()(const f32x4 (&acc)[2][2][4][2], const Unit& u, int wr, int wc, int fr, int fq) const {
;     ...
;                     for (int m = 0; m < 4; ++m) { const int r = row0 + ai * HALF + m * 16;
;                         const f32x4 v0 = acc[ai][0][m][0], v1 = acc[ai][0][m][1]; float* dp = DT + (size_t)r * 32 + c0;
; #pragma unroll
;                         for (int i = 0; i < 4; ++i) { float x0 = v0[i] + dt_bias[c0 + i], x1 = v1[i] + dt_bias[c0 + 4 + i];
;                             dp[i] = x0 > 20.f ? x0 : log1pf(__expf(x0)); dp[4 + i] = x1 > 20.f ? x1 : log1pf(__expf(x1)); }
.LBB0_807:
	s_or_b64 exec, exec, s[24:25]
	flat_store_dword v[154:155], v136 offset:20
	v_mov_b32_e32 v136, v202
	v_add_f32_e32 v151, v110, v136
	v_mov_b32_e32 v136, v206
	v_cmp_nlt_f32_e32 vcc, s67, v151
	s_and_saveexec_b64 s[24:25], vcc
	s_cbranch_execz .LBB0_809
	v_mul_f32_e32 v151, 0x3fb8aa3b, v151
	v_exp_f32_e32 v156, v151
	s_nop 0
	v_add_f32_e32 v151, 1.0, v156
	v_frexp_mant_f32_e32 v175, v151
	v_cvt_f64_f32_e32 v[172:173], v151
	v_add_f32_e32 v174, -1.0, v151
	v_frexp_exp_i32_f64_e32 v172, v[172:173]
	v_cmp_gt_f32_e32 vcc, s68, v175
	v_sub_f32_e32 v176, v174, v151
	v_sub_f32_e32 v174, v156, v174
	v_subbrev_co_u32_e32 v180, vcc, 0, v172, vcc
	v_add_f32_e32 v176, 1.0, v176
	v_sub_u32_e32 v172, 0, v180
	v_add_f32_e32 v174, v174, v176
	v_ldexp_f32 v151, v151, v172
	v_ldexp_f32 v172, v174, v172
	v_add_f32_e32 v174, -1.0, v151
	v_add_f32_e32 v173, 1.0, v174
	v_sub_f32_e32 v173, v151, v173
	v_add_f32_e32 v175, v172, v173
	v_add_f32_e32 v173, 1.0, v151
	v_add_f32_e32 v176, -1.0, v173
	v_sub_f32_e32 v151, v151, v176
	v_add_f32_e32 v151, v172, v151
	v_add_f32_e32 v181, v173, v151
	v_rcp_f32_e32 v182, v181
	v_sub_f32_e32 v172, v181, v173
	v_add_f32_e32 v173, v174, v175
	v_sub_f32_e32 v151, v151, v172
	v_mul_f32_e32 v184, v173, v182
	v_sub_f32_e32 v172, v173, v174
	v_mul_f32_e32 v174, v181, v184
	v_fma_f32 v176, v184, v181, -v174
	v_fmac_f32_e32 v176, v184, v151
	v_sub_f32_e32 v183, v175, v172
	v_add_f32_e32 v172, v174, v176
	v_sub_f32_e32 v175, v173, v172
	v_pk_add_f32 v[178:179], v[172:173], v[174:175] neg_lo:[0,1] neg_hi:[0,1]
	v_mov_b32_e32 v177, v172
	v_pk_add_f32 v[172:173], v[178:179], v[176:177] neg_lo:[0,1] neg_hi:[0,1]
	v_cmp_neq_f32_e32 vcc, s70, v156
	v_add_f32_e32 v173, v183, v173
	v_add_f32_e32 v172, v172, v173
	v_add_f32_e32 v173, v175, v172
	v_mul_f32_e32 v183, v182, v173
	v_mul_f32_e32 v174, v181, v183
	v_fma_f32 v176, v183, v181, -v174
	v_fmac_f32_e32 v176, v183, v151
	v_sub_f32_e32 v151, v175, v173
	v_add_f32_e32 v151, v172, v151
	v_add_f32_e32 v172, v174, v176
	v_sub_f32_e32 v175, v173, v172
	v_pk_add_f32 v[178:179], v[172:173], v[174:175] neg_lo:[0,1] neg_hi:[0,1]
	v_mov_b32_e32 v177, v172
	v_pk_add_f32 v[172:173], v[178:179], v[176:177] neg_lo:[0,1] neg_hi:[0,1]
	s_nop 0
	v_add_f32_e32 v151, v151, v173
	v_add_f32_e32 v151, v172, v151
	v_add_f32_e32 v173, v184, v183
	v_add_f32_e32 v151, v175, v151
	v_sub_f32_e32 v172, v173, v184
	v_mul_f32_e32 v151, v182, v151
	v_sub_f32_e32 v172, v183, v172
	v_add_f32_e32 v174, v172, v151
	v_add_f32_e32 v176, v173, v174
	v_cvt_f32_i32_e32 v172, v180
	v_mul_f32_e32 v177, v176, v176
	v_sub_f32_e32 v173, v176, v173
	v_fmamk_f32 v151, v177, 0x3e9b6dac, v166
	v_sub_f32_e32 v173, v174, v173
	v_fmaak_f32 v151, v177, v151, 0x3f2aaada
	v_ldexp_f32 v178, v173, 1
	v_mul_f32_e32 v173, v176, v177
	v_ldexp_f32 v175, v176, 1
	v_pk_mul_f32 v[176:177], v[172:173], v[150:151]
	s_nop 0
	v_fma_f32 v174, v172, s69, -v176
	v_fmac_f32_e32 v174, 0xb102e308, v172
	v_pk_add_f32 v[172:173], v[176:177], v[174:175]
	s_nop 0
	v_sub_f32_e32 v151, v173, v175
	v_sub_f32_e32 v151, v177, v151
	v_add_f32_e32 v179, v178, v151
	v_mov_b32_e32 v178, v176
	v_pk_add_f32 v[176:177], v[172:173], v[176:177] neg_lo:[0,1] neg_hi:[0,1]
	v_pk_add_f32 v[180:181], v[172:173], v[178:179]
	v_mov_b32_e32 v175, v172
	v_mov_b32_e32 v177, v181
	v_pk_add_f32 v[182:183], v[174:175], v[176:177] neg_lo:[0,1] neg_hi:[0,1]
	v_pk_add_f32 v[174:175], v[174:175], v[176:177]
	v_mov_b32_e32 v178, v179
	v_pk_add_f32 v[176:177], v[174:175], v[172:173] op_sel:[1,0] op_sel_hi:[0,1] neg_lo:[0,1] neg_hi:[0,1]
	v_pk_add_f32 v[184:185], v[180:181], v[176:177] op_sel_hi:[1,0] neg_lo:[0,1] neg_hi:[0,1]
	v_mov_b32_e32 v180, v181
	v_mov_b32_e32 v181, v175
	v_pk_mov_b32 v[176:177], v[172:173], v[176:177] op_sel:[1,0]
	v_mov_b32_e32 v179, v172
	v_pk_add_f32 v[176:177], v[180:181], v[176:177] neg_lo:[0,1] neg_hi:[0,1]
	v_mov_b32_e32 v184, v182
	v_pk_add_f32 v[172:173], v[178:179], v[176:177] neg_lo:[0,1] neg_hi:[0,1]
	v_mov_b32_e32 v183, v175
	v_pk_add_f32 v[176:177], v[184:185], v[172:173]
	s_nop 0
	v_pk_add_f32 v[178:179], v[176:177], v[176:177] op_sel:[0,1] op_sel_hi:[1,0]
	s_nop 0
	v_pk_add_f32 v[174:175], v[174:175], v[178:179] op_sel:[1,0] op_sel_hi:[0,1]
	v_mov_b32_e32 v177, v174
	v_pk_add_f32 v[180:181], v[176:177], v[182:183] neg_lo:[0,1] neg_hi:[0,1]
	v_mov_b32_e32 v173, v178
	v_sub_f32_e32 v151, v176, v180
	v_pk_add_f32 v[172:173], v[172:173], v[180:181] neg_lo:[0,1] neg_hi:[0,1]
	v_sub_f32_e32 v151, v182, v151
	v_add_f32_e32 v151, v172, v151
	v_add_f32_e32 v151, v151, v173
	v_add_f32_e32 v151, v174, v151
	v_cndmask_b32_e32 v151, v167, v151, vcc
	v_cmp_ngt_f32_e32 vcc, -1.0, v156
	s_nop 1
	v_cndmask_b32_e32 v151, v168, v151, vcc
	v_cmp_neq_f32_e32 vcc, -1.0, v156
	s_nop 1
	v_cndmask_b32_e32 v151, v169, v151, vcc
	v_cmp_lt_f32_e64 vcc, |v156|, s71
	s_nop 1
	v_cndmask_b32_e32 v151, v151, v156, vcc
;     __device__ __forceinline__ void operator()(const f32x4 (&acc)[2][2][4][2], const Unit& u, int wr, int wc, int fr, int fq) const {
;     ...
;                     for (int m = 0; m < 4; ++m) { const int r = row0 + ai * HALF + m * 16;
;                         const f32x4 v0 = acc[ai][0][m][0], v1 = acc[ai][0][m][1]; float* dp = DT + (size_t)r * 32 + c0;
; #pragma unroll
;                         for (int i = 0; i < 4; ++i) { float x0 = v0[i] + dt_bias[c0 + i], x1 = v1[i] + dt_bias[c0 + 4 + i];
;                             dp[i] = x0 > 20.f ? x0 : log1pf(__expf(x0)); dp[4 + i] = x1 > 20.f ? x1 : log1pf(__expf(x1)); }
.LBB0_809:
	s_or_b64 exec, exec, s[24:25]
	v_add_f32_e32 v136, v106, v136
	v_cmp_nlt_f32_e32 vcc, s67, v136
	flat_store_dword v[154:155], v151 offset:8
	s_and_saveexec_b64 s[24:25], vcc
	s_cbranch_execz .LBB0_811
	v_mul_f32_e32 v136, 0x3fb8aa3b, v136
	v_exp_f32_e32 v136, v136
	s_nop 0
	v_add_f32_e32 v151, 1.0, v136
	v_frexp_mant_f32_e32 v174, v151
	v_cvt_f64_f32_e32 v[172:173], v151
	v_add_f32_e32 v156, -1.0, v151
	v_frexp_exp_i32_f64_e32 v172, v[172:173]
	v_cmp_gt_f32_e32 vcc, s68, v174
	v_sub_f32_e32 v175, v156, v151
	v_sub_f32_e32 v156, v136, v156
	v_subbrev_co_u32_e32 v180, vcc, 0, v172, vcc
	v_add_f32_e32 v175, 1.0, v175
	v_sub_u32_e32 v172, 0, v180
	v_add_f32_e32 v156, v156, v175
	v_ldexp_f32 v151, v151, v172
	v_ldexp_f32 v156, v156, v172
	v_add_f32_e32 v172, -1.0, v151
	v_add_f32_e32 v173, 1.0, v172
	v_sub_f32_e32 v173, v151, v173
	v_add_f32_e32 v174, v156, v173
	v_add_f32_e32 v173, 1.0, v151
	v_add_f32_e32 v175, -1.0, v173
	v_sub_f32_e32 v151, v151, v175
	v_add_f32_e32 v151, v156, v151
	v_add_f32_e32 v156, v173, v151
	v_rcp_f32_e32 v181, v156
	v_sub_f32_e32 v173, v156, v173
	v_sub_f32_e32 v151, v151, v173
	v_add_f32_e32 v173, v172, v174
	v_sub_f32_e32 v172, v173, v172
	v_mul_f32_e32 v183, v173, v181
	v_sub_f32_e32 v182, v174, v172
	v_mul_f32_e32 v174, v156, v183
	v_fma_f32 v176, v183, v156, -v174
	v_fmac_f32_e32 v176, v183, v151
	v_add_f32_e32 v172, v174, v176
	v_sub_f32_e32 v175, v173, v172
	v_pk_add_f32 v[178:179], v[172:173], v[174:175] neg_lo:[0,1] neg_hi:[0,1]
	v_mov_b32_e32 v177, v172
	v_pk_add_f32 v[172:173], v[178:179], v[176:177] neg_lo:[0,1] neg_hi:[0,1]
	v_cmp_neq_f32_e32 vcc, s70, v136
	v_add_f32_e32 v173, v182, v173
	v_add_f32_e32 v172, v172, v173
	v_add_f32_e32 v173, v175, v172
	v_mul_f32_e32 v182, v181, v173
	v_mul_f32_e32 v174, v156, v182
	v_fma_f32 v176, v182, v156, -v174
	v_fmac_f32_e32 v176, v182, v151
	v_sub_f32_e32 v151, v175, v173
	v_add_f32_e32 v151, v172, v151
	v_add_f32_e32 v172, v174, v176
	v_sub_f32_e32 v175, v173, v172
	v_pk_add_f32 v[178:179], v[172:173], v[174:175] neg_lo:[0,1] neg_hi:[0,1]
	v_mov_b32_e32 v177, v172
	v_pk_add_f32 v[172:173], v[178:179], v[176:177] neg_lo:[0,1] neg_hi:[0,1]
	v_add_f32_e32 v156, v183, v182
	v_add_f32_e32 v151, v151, v173
	v_add_f32_e32 v151, v172, v151
	v_add_f32_e32 v151, v175, v151
	v_sub_f32_e32 v172, v156, v183
	v_mul_f32_e32 v151, v181, v151
	v_sub_f32_e32 v172, v182, v172
	v_add_f32_e32 v173, v172, v151
	v_add_f32_e32 v174, v156, v173
	v_cvt_f32_i32_e32 v172, v180
	v_mul_f32_e32 v176, v174, v174
	v_fmamk_f32 v151, v176, 0x3e9b6dac, v166
	v_sub_f32_e32 v156, v174, v156
	v_fmaak_f32 v151, v176, v151, 0x3f2aaada
	v_sub_f32_e32 v156, v173, v156
	v_mul_f32_e32 v173, v174, v176
	v_pk_mul_f32 v[176:177], v[172:173], v[150:151]
	v_ldexp_f32 v175, v174, 1
	v_fma_f32 v174, v172, s69, -v176
	v_fmac_f32_e32 v174, 0xb102e308, v172
	v_pk_add_f32 v[172:173], v[176:177], v[174:175]
	v_ldexp_f32 v156, v156, 1
	v_sub_f32_e32 v151, v173, v175
	v_sub_f32_e32 v151, v177, v151
	v_add_f32_e32 v179, v156, v151
	v_mov_b32_e32 v178, v176
	v_pk_add_f32 v[176:177], v[172:173], v[176:177] neg_lo:[0,1] neg_hi:[0,1]
	v_pk_add_f32 v[180:181], v[172:173], v[178:179]
	v_mov_b32_e32 v175, v172
	v_mov_b32_e32 v177, v181
	v_pk_add_f32 v[182:183], v[174:175], v[176:177] neg_lo:[0,1] neg_hi:[0,1]
	v_pk_add_f32 v[174:175], v[174:175], v[176:177]
	v_mov_b32_e32 v178, v179
	v_pk_add_f32 v[176:177], v[174:175], v[172:173] op_sel:[1,0] op_sel_hi:[0,1] neg_lo:[0,1] neg_hi:[0,1]
	v_pk_add_f32 v[184:185], v[180:181], v[176:177] op_sel_hi:[1,0] neg_lo:[0,1] neg_hi:[0,1]
	v_mov_b32_e32 v180, v181
	v_mov_b32_e32 v181, v175
	v_pk_mov_b32 v[176:177], v[172:173], v[176:177] op_sel:[1,0]
	v_mov_b32_e32 v179, v172
	v_pk_add_f32 v[176:177], v[180:181], v[176:177] neg_lo:[0,1] neg_hi:[0,1]
	v_mov_b32_e32 v184, v182
	v_pk_add_f32 v[172:173], v[178:179], v[176:177] neg_lo:[0,1] neg_hi:[0,1]
	v_mov_b32_e32 v183, v175
	v_pk_add_f32 v[176:177], v[184:185], v[172:173]
	s_nop 0
	v_pk_add_f32 v[178:179], v[176:177], v[176:177] op_sel:[0,1] op_sel_hi:[1,0]
	s_nop 0
	v_pk_add_f32 v[174:175], v[174:175], v[178:179] op_sel:[1,0] op_sel_hi:[0,1]
	v_mov_b32_e32 v177, v174
	v_pk_add_f32 v[180:181], v[176:177], v[182:183] neg_lo:[0,1] neg_hi:[0,1]
	v_mov_b32_e32 v173, v178
	v_sub_f32_e32 v151, v176, v180
	v_pk_add_f32 v[172:173], v[172:173], v[180:181] neg_lo:[0,1] neg_hi:[0,1]
	v_sub_f32_e32 v151, v182, v151
	v_add_f32_e32 v151, v172, v151
	v_add_f32_e32 v151, v151, v173
	v_add_f32_e32 v151, v174, v151
	v_cndmask_b32_e32 v151, v167, v151, vcc
	v_cmp_ngt_f32_e32 vcc, -1.0, v136
	s_nop 1
	v_cndmask_b32_e32 v151, v168, v151, vcc
	v_cmp_neq_f32_e32 vcc, -1.0, v136
	s_nop 1
	v_cndmask_b32_e32 v151, v169, v151, vcc
	v_cmp_lt_f32_e64 vcc, |v136|, s71
	s_nop 1
	v_cndmask_b32_e32 v136, v151, v136, vcc
;     __device__ __forceinline__ void operator()(const f32x4 (&acc)[2][2][4][2], const Unit& u, int wr, int wc, int fr, int fq) const {
;     ...
;                     for (int m = 0; m < 4; ++m) { const int r = row0 + ai * HALF + m * 16;
;                         const f32x4 v0 = acc[ai][0][m][0], v1 = acc[ai][0][m][1]; float* dp = DT + (size_t)r * 32 + c0;
; #pragma unroll
;                         for (int i = 0; i < 4; ++i) { float x0 = v0[i] + dt_bias[c0 + i], x1 = v1[i] + dt_bias[c0 + 4 + i];
;                             dp[i] = x0 > 20.f ? x0 : log1pf(__expf(x0)); dp[4 + i] = x1 > 20.f ? x1 : log1pf(__expf(x1)); }
.LBB0_811:
	s_or_b64 exec, exec, s[24:25]
	flat_store_dword v[154:155], v136 offset:24
	v_mov_b32_e32 v136, v203
	v_add_f32_e32 v151, v111, v136
	v_mov_b32_e32 v136, v207
	v_cmp_nlt_f32_e32 vcc, s67, v151
	s_and_saveexec_b64 s[24:25], vcc
	s_cbranch_execz .LBB0_813
	v_mul_f32_e32 v151, 0x3fb8aa3b, v151
	v_exp_f32_e32 v156, v151
	s_nop 0
	v_add_f32_e32 v151, 1.0, v156
	v_frexp_mant_f32_e32 v175, v151
	v_cvt_f64_f32_e32 v[172:173], v151
	v_add_f32_e32 v174, -1.0, v151
	v_frexp_exp_i32_f64_e32 v172, v[172:173]
	v_cmp_gt_f32_e32 vcc, s68, v175
	v_sub_f32_e32 v176, v174, v151
	v_sub_f32_e32 v174, v156, v174
	v_subbrev_co_u32_e32 v180, vcc, 0, v172, vcc
	v_add_f32_e32 v176, 1.0, v176
	v_sub_u32_e32 v172, 0, v180
	v_add_f32_e32 v174, v174, v176
	v_ldexp_f32 v151, v151, v172
	v_ldexp_f32 v172, v174, v172
	v_add_f32_e32 v174, -1.0, v151
	v_add_f32_e32 v173, 1.0, v174
	v_sub_f32_e32 v173, v151, v173
	v_add_f32_e32 v175, v172, v173
	v_add_f32_e32 v173, 1.0, v151
	v_add_f32_e32 v176, -1.0, v173
	v_sub_f32_e32 v151, v151, v176
	v_add_f32_e32 v151, v172, v151
	v_add_f32_e32 v181, v173, v151
	v_rcp_f32_e32 v182, v181
	v_sub_f32_e32 v172, v181, v173
	v_add_f32_e32 v173, v174, v175
	v_sub_f32_e32 v151, v151, v172
	v_mul_f32_e32 v184, v173, v182
	v_sub_f32_e32 v172, v173, v174
	v_mul_f32_e32 v174, v181, v184
	v_fma_f32 v176, v184, v181, -v174
	v_fmac_f32_e32 v176, v184, v151
	v_sub_f32_e32 v183, v175, v172
	v_add_f32_e32 v172, v174, v176
	v_sub_f32_e32 v175, v173, v172
	v_pk_add_f32 v[178:179], v[172:173], v[174:175] neg_lo:[0,1] neg_hi:[0,1]
	v_mov_b32_e32 v177, v172
	v_pk_add_f32 v[172:173], v[178:179], v[176:177] neg_lo:[0,1] neg_hi:[0,1]
	v_cmp_neq_f32_e32 vcc, s70, v156
	v_add_f32_e32 v173, v183, v173
	v_add_f32_e32 v172, v172, v173
	v_add_f32_e32 v173, v175, v172
	v_mul_f32_e32 v183, v182, v173
	v_mul_f32_e32 v174, v181, v183
	v_fma_f32 v176, v183, v181, -v174
	v_fmac_f32_e32 v176, v183, v151
	v_sub_f32_e32 v151, v175, v173
	v_add_f32_e32 v151, v172, v151
	v_add_f32_e32 v172, v174, v176
	v_sub_f32_e32 v175, v173, v172
	v_pk_add_f32 v[178:179], v[172:173], v[174:175] neg_lo:[0,1] neg_hi:[0,1]
	v_mov_b32_e32 v177, v172
	v_pk_add_f32 v[172:173], v[178:179], v[176:177] neg_lo:[0,1] neg_hi:[0,1]
	s_nop 0
	v_add_f32_e32 v151, v151, v173
	v_add_f32_e32 v151, v172, v151
	v_add_f32_e32 v173, v184, v183
	v_add_f32_e32 v151, v175, v151
	v_sub_f32_e32 v172, v173, v184
	v_mul_f32_e32 v151, v182, v151
	v_sub_f32_e32 v172, v183, v172
	v_add_f32_e32 v174, v172, v151
	v_add_f32_e32 v176, v173, v174
	v_cvt_f32_i32_e32 v172, v180
	v_mul_f32_e32 v177, v176, v176
	v_sub_f32_e32 v173, v176, v173
	v_fmamk_f32 v151, v177, 0x3e9b6dac, v166
	v_sub_f32_e32 v173, v174, v173
	v_fmaak_f32 v151, v177, v151, 0x3f2aaada
	v_ldexp_f32 v178, v173, 1
	v_mul_f32_e32 v173, v176, v177
	v_ldexp_f32 v175, v176, 1
	v_pk_mul_f32 v[176:177], v[172:173], v[150:151]
	s_nop 0
	v_fma_f32 v174, v172, s69, -v176
	v_fmac_f32_e32 v174, 0xb102e308, v172
	v_pk_add_f32 v[172:173], v[176:177], v[174:175]
	s_nop 0
	v_sub_f32_e32 v151, v173, v175
	v_sub_f32_e32 v151, v177, v151
	v_add_f32_e32 v179, v178, v151
	v_mov_b32_e32 v178, v176
	v_pk_add_f32 v[176:177], v[172:173], v[176:177] neg_lo:[0,1] neg_hi:[0,1]
	v_pk_add_f32 v[180:181], v[172:173], v[178:179]
	v_mov_b32_e32 v175, v172
	v_mov_b32_e32 v177, v181
	v_pk_add_f32 v[182:183], v[174:175], v[176:177] neg_lo:[0,1] neg_hi:[0,1]
	v_pk_add_f32 v[174:175], v[174:175], v[176:177]
	v_mov_b32_e32 v178, v179
	v_pk_add_f32 v[176:177], v[174:175], v[172:173] op_sel:[1,0] op_sel_hi:[0,1] neg_lo:[0,1] neg_hi:[0,1]
	v_pk_add_f32 v[184:185], v[180:181], v[176:177] op_sel_hi:[1,0] neg_lo:[0,1] neg_hi:[0,1]
	v_mov_b32_e32 v180, v181
	v_mov_b32_e32 v181, v175
	v_pk_mov_b32 v[176:177], v[172:173], v[176:177] op_sel:[1,0]
	v_mov_b32_e32 v179, v172
	v_pk_add_f32 v[176:177], v[180:181], v[176:177] neg_lo:[0,1] neg_hi:[0,1]
	v_mov_b32_e32 v184, v182
	v_pk_add_f32 v[172:173], v[178:179], v[176:177] neg_lo:[0,1] neg_hi:[0,1]
	v_mov_b32_e32 v183, v175
	v_pk_add_f32 v[176:177], v[184:185], v[172:173]
	s_nop 0
	v_pk_add_f32 v[178:179], v[176:177], v[176:177] op_sel:[0,1] op_sel_hi:[1,0]
	s_nop 0
	v_pk_add_f32 v[174:175], v[174:175], v[178:179] op_sel:[1,0] op_sel_hi:[0,1]
	v_mov_b32_e32 v177, v174
	v_pk_add_f32 v[180:181], v[176:177], v[182:183] neg_lo:[0,1] neg_hi:[0,1]
	v_mov_b32_e32 v173, v178
	v_sub_f32_e32 v151, v176, v180
	v_pk_add_f32 v[172:173], v[172:173], v[180:181] neg_lo:[0,1] neg_hi:[0,1]
	v_sub_f32_e32 v151, v182, v151
	v_add_f32_e32 v151, v172, v151
	v_add_f32_e32 v151, v151, v173
	v_add_f32_e32 v151, v174, v151
	v_cndmask_b32_e32 v151, v167, v151, vcc
	v_cmp_ngt_f32_e32 vcc, -1.0, v156
	s_nop 1
	v_cndmask_b32_e32 v151, v168, v151, vcc
	v_cmp_neq_f32_e32 vcc, -1.0, v156
	s_nop 1
	v_cndmask_b32_e32 v151, v169, v151, vcc
	v_cmp_lt_f32_e64 vcc, |v156|, s71
	s_nop 1
	v_cndmask_b32_e32 v151, v151, v156, vcc
;     __device__ __forceinline__ void operator()(const f32x4 (&acc)[2][2][4][2], const Unit& u, int wr, int wc, int fr, int fq) const {
;     ...
;                     for (int m = 0; m < 4; ++m) { const int r = row0 + ai * HALF + m * 16;
;                         const f32x4 v0 = acc[ai][0][m][0], v1 = acc[ai][0][m][1]; float* dp = DT + (size_t)r * 32 + c0;
; #pragma unroll
;                         for (int i = 0; i < 4; ++i) { float x0 = v0[i] + dt_bias[c0 + i], x1 = v1[i] + dt_bias[c0 + 4 + i];
;                             dp[i] = x0 > 20.f ? x0 : log1pf(__expf(x0)); dp[4 + i] = x1 > 20.f ? x1 : log1pf(__expf(x1)); }
.LBB0_813:
	s_or_b64 exec, exec, s[24:25]
	v_add_f32_e32 v136, v107, v136
	v_cmp_nlt_f32_e32 vcc, s67, v136
	flat_store_dword v[154:155], v151 offset:12
	s_and_saveexec_b64 s[24:25], vcc
	s_cbranch_execz .LBB0_815
	v_mul_f32_e32 v136, 0x3fb8aa3b, v136
	v_exp_f32_e32 v136, v136
	s_nop 0
	v_add_f32_e32 v151, 1.0, v136
	v_frexp_mant_f32_e32 v174, v151
	v_cvt_f64_f32_e32 v[172:173], v151
	v_add_f32_e32 v156, -1.0, v151
	v_frexp_exp_i32_f64_e32 v172, v[172:173]
	v_cmp_gt_f32_e32 vcc, s68, v174
	v_sub_f32_e32 v175, v156, v151
	v_sub_f32_e32 v156, v136, v156
	v_subbrev_co_u32_e32 v180, vcc, 0, v172, vcc
	v_add_f32_e32 v175, 1.0, v175
	v_sub_u32_e32 v172, 0, v180
	v_add_f32_e32 v156, v156, v175
	v_ldexp_f32 v151, v151, v172
	v_ldexp_f32 v156, v156, v172
	v_add_f32_e32 v172, -1.0, v151
	v_add_f32_e32 v173, 1.0, v172
	v_sub_f32_e32 v173, v151, v173
	v_add_f32_e32 v174, v156, v173
	v_add_f32_e32 v173, 1.0, v151
	v_add_f32_e32 v175, -1.0, v173
	v_sub_f32_e32 v151, v151, v175
	v_add_f32_e32 v151, v156, v151
	v_add_f32_e32 v156, v173, v151
	v_rcp_f32_e32 v181, v156
	v_sub_f32_e32 v173, v156, v173
	v_sub_f32_e32 v151, v151, v173
	v_add_f32_e32 v173, v172, v174
	v_sub_f32_e32 v172, v173, v172
	v_mul_f32_e32 v183, v173, v181
	v_sub_f32_e32 v182, v174, v172
	v_mul_f32_e32 v174, v156, v183
	v_fma_f32 v176, v183, v156, -v174
	v_fmac_f32_e32 v176, v183, v151
	v_add_f32_e32 v172, v174, v176
	v_sub_f32_e32 v175, v173, v172
	v_pk_add_f32 v[178:179], v[172:173], v[174:175] neg_lo:[0,1] neg_hi:[0,1]
	v_mov_b32_e32 v177, v172
	v_pk_add_f32 v[172:173], v[178:179], v[176:177] neg_lo:[0,1] neg_hi:[0,1]
	v_cmp_neq_f32_e32 vcc, s70, v136
	v_add_f32_e32 v173, v182, v173
	v_add_f32_e32 v172, v172, v173
	v_add_f32_e32 v173, v175, v172
	v_mul_f32_e32 v182, v181, v173
	v_mul_f32_e32 v174, v156, v182
	v_fma_f32 v176, v182, v156, -v174
	v_fmac_f32_e32 v176, v182, v151
	v_sub_f32_e32 v151, v175, v173
	v_add_f32_e32 v151, v172, v151
	v_add_f32_e32 v172, v174, v176
	v_sub_f32_e32 v175, v173, v172
	v_pk_add_f32 v[178:179], v[172:173], v[174:175] neg_lo:[0,1] neg_hi:[0,1]
	v_mov_b32_e32 v177, v172
	v_pk_add_f32 v[172:173], v[178:179], v[176:177] neg_lo:[0,1] neg_hi:[0,1]
	v_add_f32_e32 v156, v183, v182
	v_add_f32_e32 v151, v151, v173
	v_add_f32_e32 v151, v172, v151
	v_add_f32_e32 v151, v175, v151
	v_sub_f32_e32 v172, v156, v183
	v_mul_f32_e32 v151, v181, v151
	v_sub_f32_e32 v172, v182, v172
	v_add_f32_e32 v173, v172, v151
	v_add_f32_e32 v174, v156, v173
	v_cvt_f32_i32_e32 v172, v180
	v_mul_f32_e32 v176, v174, v174
	v_fmamk_f32 v151, v176, 0x3e9b6dac, v166
	v_sub_f32_e32 v156, v174, v156
	v_fmaak_f32 v151, v176, v151, 0x3f2aaada
	v_sub_f32_e32 v156, v173, v156
	v_mul_f32_e32 v173, v174, v176
	v_pk_mul_f32 v[176:177], v[172:173], v[150:151]
	v_ldexp_f32 v175, v174, 1
	v_fma_f32 v174, v172, s69, -v176
	v_fmac_f32_e32 v174, 0xb102e308, v172
	v_pk_add_f32 v[172:173], v[176:177], v[174:175]
	v_ldexp_f32 v156, v156, 1
	v_sub_f32_e32 v151, v173, v175
	v_sub_f32_e32 v151, v177, v151
	v_add_f32_e32 v179, v156, v151
	v_mov_b32_e32 v178, v176
	v_pk_add_f32 v[176:177], v[172:173], v[176:177] neg_lo:[0,1] neg_hi:[0,1]
	v_pk_add_f32 v[180:181], v[172:173], v[178:179]
	v_mov_b32_e32 v175, v172
	v_mov_b32_e32 v177, v181
	v_pk_add_f32 v[182:183], v[174:175], v[176:177] neg_lo:[0,1] neg_hi:[0,1]
	v_pk_add_f32 v[174:175], v[174:175], v[176:177]
	v_mov_b32_e32 v178, v179
	v_pk_add_f32 v[176:177], v[174:175], v[172:173] op_sel:[1,0] op_sel_hi:[0,1] neg_lo:[0,1] neg_hi:[0,1]
	v_pk_add_f32 v[184:185], v[180:181], v[176:177] op_sel_hi:[1,0] neg_lo:[0,1] neg_hi:[0,1]
	v_mov_b32_e32 v180, v181
	v_mov_b32_e32 v181, v175
	v_pk_mov_b32 v[176:177], v[172:173], v[176:177] op_sel:[1,0]
	v_mov_b32_e32 v179, v172
	v_pk_add_f32 v[176:177], v[180:181], v[176:177] neg_lo:[0,1] neg_hi:[0,1]
	v_mov_b32_e32 v184, v182
	v_pk_add_f32 v[172:173], v[178:179], v[176:177] neg_lo:[0,1] neg_hi:[0,1]
	v_mov_b32_e32 v183, v175
	v_pk_add_f32 v[176:177], v[184:185], v[172:173]
	s_nop 0
	v_pk_add_f32 v[178:179], v[176:177], v[176:177] op_sel:[0,1] op_sel_hi:[1,0]
	s_nop 0
	v_pk_add_f32 v[174:175], v[174:175], v[178:179] op_sel:[1,0] op_sel_hi:[0,1]
	v_mov_b32_e32 v177, v174
	v_pk_add_f32 v[180:181], v[176:177], v[182:183] neg_lo:[0,1] neg_hi:[0,1]
	v_mov_b32_e32 v173, v178
	v_sub_f32_e32 v151, v176, v180
	v_pk_add_f32 v[172:173], v[172:173], v[180:181] neg_lo:[0,1] neg_hi:[0,1]
	v_sub_f32_e32 v151, v182, v151
	v_add_f32_e32 v151, v172, v151
	v_add_f32_e32 v151, v151, v173
	v_add_f32_e32 v151, v174, v151
	v_cndmask_b32_e32 v151, v167, v151, vcc
	v_cmp_ngt_f32_e32 vcc, -1.0, v136
	s_nop 1
	v_cndmask_b32_e32 v151, v168, v151, vcc
	v_cmp_neq_f32_e32 vcc, -1.0, v136
	s_nop 1
	v_cndmask_b32_e32 v151, v169, v151, vcc
	v_cmp_lt_f32_e64 vcc, |v136|, s71
	s_nop 1
	v_cndmask_b32_e32 v136, v151, v136, vcc
;     __device__ __forceinline__ void operator()(const f32x4 (&acc)[2][2][4][2], const Unit& u, int wr, int wc, int fr, int fq) const {
;     ...
;                     for (int m = 0; m < 4; ++m) { const int r = row0 + ai * HALF + m * 16;
;                         const f32x4 v0 = acc[ai][0][m][0], v1 = acc[ai][0][m][1]; float* dp = DT + (size_t)r * 32 + c0;
; #pragma unroll
;                         for (int i = 0; i < 4; ++i) { float x0 = v0[i] + dt_bias[c0 + i], x1 = v1[i] + dt_bias[c0 + 4 + i];
;                             dp[i] = x0 > 20.f ? x0 : log1pf(__expf(x0)); dp[4 + i] = x1 > 20.f ? x1 : log1pf(__expf(x1)); }
;                         __builtin_amdgcn_sched_barrier(0); }
.LBB0_815:
	s_or_b64 exec, exec, s[24:25]
	flat_store_dword v[154:155], v136 offset:28
	v_mov_b32_e32 v136, v200
	v_add_f32_e32 v151, v92, v136
	v_mov_b32_e32 v136, v204
	v_cmp_nlt_f32_e32 vcc, s67, v151
	s_and_saveexec_b64 s[24:25], vcc
	s_cbranch_execz .LBB0_817
	v_mul_f32_e32 v151, 0x3fb8aa3b, v151
	v_exp_f32_e32 v156, v151
	s_nop 0
	v_add_f32_e32 v151, 1.0, v156
	v_frexp_mant_f32_e32 v173, v151
	v_cvt_f64_f32_e32 v[154:155], v151
	v_add_f32_e32 v172, -1.0, v151
	v_frexp_exp_i32_f64_e32 v154, v[154:155]
	v_cmp_gt_f32_e32 vcc, s68, v173
	v_sub_f32_e32 v174, v172, v151
	v_sub_f32_e32 v172, v156, v172
	v_subbrev_co_u32_e32 v178, vcc, 0, v154, vcc
	v_add_f32_e32 v174, 1.0, v174
	v_sub_u32_e32 v154, 0, v178
	v_add_f32_e32 v172, v172, v174
	v_ldexp_f32 v151, v151, v154
	v_ldexp_f32 v154, v172, v154
	v_add_f32_e32 v172, -1.0, v151
	v_add_f32_e32 v155, 1.0, v172
	v_sub_f32_e32 v155, v151, v155
	v_add_f32_e32 v173, v154, v155
	v_add_f32_e32 v155, 1.0, v151
	v_add_f32_e32 v174, -1.0, v155
	v_sub_f32_e32 v151, v151, v174
	v_add_f32_e32 v151, v154, v151
	v_add_f32_e32 v179, v155, v151
	v_rcp_f32_e32 v180, v179
	v_sub_f32_e32 v154, v179, v155
	v_add_f32_e32 v155, v172, v173
	v_sub_f32_e32 v151, v151, v154
	v_mul_f32_e32 v182, v155, v180
	v_sub_f32_e32 v154, v155, v172
	v_mul_f32_e32 v172, v179, v182
	v_fma_f32 v174, v182, v179, -v172
	v_fmac_f32_e32 v174, v182, v151
	v_sub_f32_e32 v181, v173, v154
	v_add_f32_e32 v154, v172, v174
	v_sub_f32_e32 v173, v155, v154
	v_pk_add_f32 v[176:177], v[154:155], v[172:173] neg_lo:[0,1] neg_hi:[0,1]
	v_mov_b32_e32 v175, v154
	v_pk_add_f32 v[154:155], v[176:177], v[174:175] neg_lo:[0,1] neg_hi:[0,1]
	v_cmp_neq_f32_e32 vcc, s70, v156
	v_add_f32_e32 v155, v181, v155
	v_add_f32_e32 v154, v154, v155
	v_add_f32_e32 v155, v173, v154
	v_mul_f32_e32 v181, v180, v155
	v_mul_f32_e32 v172, v179, v181
	v_fma_f32 v174, v181, v179, -v172
	v_fmac_f32_e32 v174, v181, v151
	v_sub_f32_e32 v151, v173, v155
	v_add_f32_e32 v151, v154, v151
	v_add_f32_e32 v154, v172, v174
	v_sub_f32_e32 v173, v155, v154
	v_pk_add_f32 v[176:177], v[154:155], v[172:173] neg_lo:[0,1] neg_hi:[0,1]
	v_mov_b32_e32 v175, v154
	v_pk_add_f32 v[154:155], v[176:177], v[174:175] neg_lo:[0,1] neg_hi:[0,1]
	s_nop 0
	v_add_f32_e32 v151, v151, v155
	v_add_f32_e32 v151, v154, v151
	v_add_f32_e32 v155, v182, v181
	v_add_f32_e32 v151, v173, v151
	v_sub_f32_e32 v154, v155, v182
	v_mul_f32_e32 v151, v180, v151
	v_sub_f32_e32 v154, v181, v154
	v_add_f32_e32 v172, v154, v151
	v_add_f32_e32 v174, v155, v172
	v_cvt_f32_i32_e32 v154, v178
	v_mul_f32_e32 v175, v174, v174
	v_sub_f32_e32 v155, v174, v155
	v_fmamk_f32 v151, v175, 0x3e9b6dac, v166
	v_sub_f32_e32 v155, v172, v155
	v_fmaak_f32 v151, v175, v151, 0x3f2aaada
	v_ldexp_f32 v176, v155, 1
	v_mul_f32_e32 v155, v174, v175
	v_ldexp_f32 v173, v174, 1
	v_pk_mul_f32 v[174:175], v[154:155], v[150:151]
	s_nop 0
	v_fma_f32 v172, v154, s69, -v174
	v_fmac_f32_e32 v172, 0xb102e308, v154
	v_pk_add_f32 v[154:155], v[174:175], v[172:173]
	s_nop 0
	v_sub_f32_e32 v151, v155, v173
	v_sub_f32_e32 v151, v175, v151
	v_add_f32_e32 v177, v176, v151
	v_mov_b32_e32 v176, v174
	v_pk_add_f32 v[174:175], v[154:155], v[174:175] neg_lo:[0,1] neg_hi:[0,1]
	v_pk_add_f32 v[178:179], v[154:155], v[176:177]
	v_mov_b32_e32 v173, v154
	v_mov_b32_e32 v175, v179
	v_pk_add_f32 v[180:181], v[172:173], v[174:175] neg_lo:[0,1] neg_hi:[0,1]
	v_pk_add_f32 v[172:173], v[172:173], v[174:175]
	v_mov_b32_e32 v176, v177
	v_pk_add_f32 v[174:175], v[172:173], v[154:155] op_sel:[1,0] op_sel_hi:[0,1] neg_lo:[0,1] neg_hi:[0,1]
	v_pk_add_f32 v[182:183], v[178:179], v[174:175] op_sel_hi:[1,0] neg_lo:[0,1] neg_hi:[0,1]
	v_mov_b32_e32 v178, v179
	v_mov_b32_e32 v179, v173
	v_pk_mov_b32 v[174:175], v[154:155], v[174:175] op_sel:[1,0]
	v_mov_b32_e32 v177, v154
	v_pk_add_f32 v[174:175], v[178:179], v[174:175] neg_lo:[0,1] neg_hi:[0,1]
	v_mov_b32_e32 v182, v180
	v_pk_add_f32 v[154:155], v[176:177], v[174:175] neg_lo:[0,1] neg_hi:[0,1]
	v_mov_b32_e32 v181, v173
	v_pk_add_f32 v[174:175], v[182:183], v[154:155]
	s_nop 0
	v_pk_add_f32 v[176:177], v[174:175], v[174:175] op_sel:[0,1] op_sel_hi:[1,0]
	s_nop 0
	v_pk_add_f32 v[172:173], v[172:173], v[176:177] op_sel:[1,0] op_sel_hi:[0,1]
	v_mov_b32_e32 v175, v172
	v_pk_add_f32 v[178:179], v[174:175], v[180:181] neg_lo:[0,1] neg_hi:[0,1]
	v_mov_b32_e32 v155, v176
	v_sub_f32_e32 v151, v174, v178
	v_pk_add_f32 v[154:155], v[154:155], v[178:179] neg_lo:[0,1] neg_hi:[0,1]
	v_sub_f32_e32 v151, v180, v151
	v_add_f32_e32 v151, v154, v151
	v_add_f32_e32 v151, v151, v155
	v_add_f32_e32 v151, v172, v151
	v_cndmask_b32_e32 v151, v167, v151, vcc
	v_cmp_ngt_f32_e32 vcc, -1.0, v156
	s_nop 1
	v_cndmask_b32_e32 v151, v168, v151, vcc
	v_cmp_neq_f32_e32 vcc, -1.0, v156
	s_nop 1
	v_cndmask_b32_e32 v151, v169, v151, vcc
	v_cmp_lt_f32_e64 vcc, |v156|, s71
	s_nop 1
	v_cndmask_b32_e32 v151, v151, v156, vcc
;     __device__ __forceinline__ void operator()(const f32x4 (&acc)[2][2][4][2], const Unit& u, int wr, int wc, int fr, int fq) const {
;     ...
;                     for (int m = 0; m < 4; ++m) { const int r = row0 + ai * HALF + m * 16;
;                         const f32x4 v0 = acc[ai][0][m][0], v1 = acc[ai][0][m][1]; float* dp = DT + (size_t)r * 32 + c0;
; #pragma unroll
;                         for (int i = 0; i < 4; ++i) { float x0 = v0[i] + dt_bias[c0 + i], x1 = v1[i] + dt_bias[c0 + 4 + i];
;                             dp[i] = x0 > 20.f ? x0 : log1pf(__expf(x0)); dp[4 + i] = x1 > 20.f ? x1 : log1pf(__expf(x1)); }
.LBB0_817:
	s_or_b64 exec, exec, s[24:25]
	v_or_b32_e32 v154, 32, v152
	v_ashrrev_i32_e32 v155, 31, v154
	v_lshlrev_b64 v[154:155], 7, v[154:155]
	v_add_f32_e32 v136, v88, v136
	v_lshl_add_u64 v[154:155], v[138:139], 0, v[154:155]
	v_cmp_nlt_f32_e32 vcc, s67, v136
	flat_store_dword v[154:155], v151
	s_and_saveexec_b64 s[24:25], vcc
	s_cbranch_execz .LBB0_819
	v_mul_f32_e32 v136, 0x3fb8aa3b, v136
	v_exp_f32_e32 v136, v136
	s_nop 0
	v_add_f32_e32 v151, 1.0, v136
	v_frexp_mant_f32_e32 v174, v151
	v_cvt_f64_f32_e32 v[172:173], v151
	v_add_f32_e32 v156, -1.0, v151
	v_frexp_exp_i32_f64_e32 v172, v[172:173]
	v_cmp_gt_f32_e32 vcc, s68, v174
	v_sub_f32_e32 v175, v156, v151
	v_sub_f32_e32 v156, v136, v156
	v_subbrev_co_u32_e32 v180, vcc, 0, v172, vcc
	v_add_f32_e32 v175, 1.0, v175
	v_sub_u32_e32 v172, 0, v180
	v_add_f32_e32 v156, v156, v175
	v_ldexp_f32 v151, v151, v172
	v_ldexp_f32 v156, v156, v172
	v_add_f32_e32 v172, -1.0, v151
	v_add_f32_e32 v173, 1.0, v172
	v_sub_f32_e32 v173, v151, v173
	v_add_f32_e32 v174, v156, v173
	v_add_f32_e32 v173, 1.0, v151
	v_add_f32_e32 v175, -1.0, v173
	v_sub_f32_e32 v151, v151, v175
	v_add_f32_e32 v151, v156, v151
	v_add_f32_e32 v156, v173, v151
	v_rcp_f32_e32 v181, v156
	v_sub_f32_e32 v173, v156, v173
	v_sub_f32_e32 v151, v151, v173
	v_add_f32_e32 v173, v172, v174
	v_sub_f32_e32 v172, v173, v172
	v_mul_f32_e32 v183, v173, v181
	v_sub_f32_e32 v182, v174, v172
	v_mul_f32_e32 v174, v156, v183
	v_fma_f32 v176, v183, v156, -v174
	v_fmac_f32_e32 v176, v183, v151
	v_add_f32_e32 v172, v174, v176
	v_sub_f32_e32 v175, v173, v172
	v_pk_add_f32 v[178:179], v[172:173], v[174:175] neg_lo:[0,1] neg_hi:[0,1]
	v_mov_b32_e32 v177, v172
	v_pk_add_f32 v[172:173], v[178:179], v[176:177] neg_lo:[0,1] neg_hi:[0,1]
	v_cmp_neq_f32_e32 vcc, s70, v136
	v_add_f32_e32 v173, v182, v173
	v_add_f32_e32 v172, v172, v173
	v_add_f32_e32 v173, v175, v172
	v_mul_f32_e32 v182, v181, v173
	v_mul_f32_e32 v174, v156, v182
	v_fma_f32 v176, v182, v156, -v174
	v_fmac_f32_e32 v176, v182, v151
	v_sub_f32_e32 v151, v175, v173
	v_add_f32_e32 v151, v172, v151
	v_add_f32_e32 v172, v174, v176
	v_sub_f32_e32 v175, v173, v172
	v_pk_add_f32 v[178:179], v[172:173], v[174:175] neg_lo:[0,1] neg_hi:[0,1]
	v_mov_b32_e32 v177, v172
	v_pk_add_f32 v[172:173], v[178:179], v[176:177] neg_lo:[0,1] neg_hi:[0,1]
	v_add_f32_e32 v156, v183, v182
	v_add_f32_e32 v151, v151, v173
	v_add_f32_e32 v151, v172, v151
	v_add_f32_e32 v151, v175, v151
	v_sub_f32_e32 v172, v156, v183
	v_mul_f32_e32 v151, v181, v151
	v_sub_f32_e32 v172, v182, v172
	v_add_f32_e32 v173, v172, v151
	v_add_f32_e32 v174, v156, v173
	v_cvt_f32_i32_e32 v172, v180
	v_mul_f32_e32 v176, v174, v174
	v_fmamk_f32 v151, v176, 0x3e9b6dac, v166
	v_sub_f32_e32 v156, v174, v156
	v_fmaak_f32 v151, v176, v151, 0x3f2aaada
	v_sub_f32_e32 v156, v173, v156
	v_mul_f32_e32 v173, v174, v176
	v_pk_mul_f32 v[176:177], v[172:173], v[150:151]
	v_ldexp_f32 v175, v174, 1
	v_fma_f32 v174, v172, s69, -v176
	v_fmac_f32_e32 v174, 0xb102e308, v172
	v_pk_add_f32 v[172:173], v[176:177], v[174:175]
	v_ldexp_f32 v156, v156, 1
	v_sub_f32_e32 v151, v173, v175
	v_sub_f32_e32 v151, v177, v151
	v_add_f32_e32 v179, v156, v151
	v_mov_b32_e32 v178, v176
	v_pk_add_f32 v[176:177], v[172:173], v[176:177] neg_lo:[0,1] neg_hi:[0,1]
	v_pk_add_f32 v[180:181], v[172:173], v[178:179]
	v_mov_b32_e32 v175, v172
	v_mov_b32_e32 v177, v181
	v_pk_add_f32 v[182:183], v[174:175], v[176:177] neg_lo:[0,1] neg_hi:[0,1]
	v_pk_add_f32 v[174:175], v[174:175], v[176:177]
	v_mov_b32_e32 v178, v179
	v_pk_add_f32 v[176:177], v[174:175], v[172:173] op_sel:[1,0] op_sel_hi:[0,1] neg_lo:[0,1] neg_hi:[0,1]
	v_pk_add_f32 v[184:185], v[180:181], v[176:177] op_sel_hi:[1,0] neg_lo:[0,1] neg_hi:[0,1]
	v_mov_b32_e32 v180, v181
	v_mov_b32_e32 v181, v175
	v_pk_mov_b32 v[176:177], v[172:173], v[176:177] op_sel:[1,0]
	v_mov_b32_e32 v179, v172
	v_pk_add_f32 v[176:177], v[180:181], v[176:177] neg_lo:[0,1] neg_hi:[0,1]
	v_mov_b32_e32 v184, v182
	v_pk_add_f32 v[172:173], v[178:179], v[176:177] neg_lo:[0,1] neg_hi:[0,1]
	v_mov_b32_e32 v183, v175
	v_pk_add_f32 v[176:177], v[184:185], v[172:173]
	s_nop 0
	v_pk_add_f32 v[178:179], v[176:177], v[176:177] op_sel:[0,1] op_sel_hi:[1,0]
	s_nop 0
	v_pk_add_f32 v[174:175], v[174:175], v[178:179] op_sel:[1,0] op_sel_hi:[0,1]
	v_mov_b32_e32 v177, v174
	v_pk_add_f32 v[180:181], v[176:177], v[182:183] neg_lo:[0,1] neg_hi:[0,1]
	v_mov_b32_e32 v173, v178
	v_sub_f32_e32 v151, v176, v180
	v_pk_add_f32 v[172:173], v[172:173], v[180:181] neg_lo:[0,1] neg_hi:[0,1]
	v_sub_f32_e32 v151, v182, v151
	v_add_f32_e32 v151, v172, v151
	v_add_f32_e32 v151, v151, v173
	v_add_f32_e32 v151, v174, v151
	v_cndmask_b32_e32 v151, v167, v151, vcc
	v_cmp_ngt_f32_e32 vcc, -1.0, v136
	s_nop 1
	v_cndmask_b32_e32 v151, v168, v151, vcc
	v_cmp_neq_f32_e32 vcc, -1.0, v136
	s_nop 1
	v_cndmask_b32_e32 v151, v169, v151, vcc
	v_cmp_lt_f32_e64 vcc, |v136|, s71
	s_nop 1
	v_cndmask_b32_e32 v136, v151, v136, vcc
;     __device__ __forceinline__ void operator()(const f32x4 (&acc)[2][2][4][2], const Unit& u, int wr, int wc, int fr, int fq) const {
;     ...
;                     for (int m = 0; m < 4; ++m) { const int r = row0 + ai * HALF + m * 16;
;                         const f32x4 v0 = acc[ai][0][m][0], v1 = acc[ai][0][m][1]; float* dp = DT + (size_t)r * 32 + c0;
; #pragma unroll
;                         for (int i = 0; i < 4; ++i) { float x0 = v0[i] + dt_bias[c0 + i], x1 = v1[i] + dt_bias[c0 + 4 + i];
;                             dp[i] = x0 > 20.f ? x0 : log1pf(__expf(x0)); dp[4 + i] = x1 > 20.f ? x1 : log1pf(__expf(x1)); }
.LBB0_819:
	s_or_b64 exec, exec, s[24:25]
	flat_store_dword v[154:155], v136 offset:16
	v_mov_b32_e32 v136, v201
	v_add_f32_e32 v151, v93, v136
	v_mov_b32_e32 v136, v205
	v_cmp_nlt_f32_e32 vcc, s67, v151
	s_and_saveexec_b64 s[24:25], vcc
	s_cbranch_execz .LBB0_821
	v_mul_f32_e32 v151, 0x3fb8aa3b, v151
	v_exp_f32_e32 v156, v151
	s_nop 0
	v_add_f32_e32 v151, 1.0, v156
	v_frexp_mant_f32_e32 v175, v151
	v_cvt_f64_f32_e32 v[172:173], v151
	v_add_f32_e32 v174, -1.0, v151
	v_frexp_exp_i32_f64_e32 v172, v[172:173]
	v_cmp_gt_f32_e32 vcc, s68, v175
	v_sub_f32_e32 v176, v174, v151
	v_sub_f32_e32 v174, v156, v174
	v_subbrev_co_u32_e32 v180, vcc, 0, v172, vcc
	v_add_f32_e32 v176, 1.0, v176
	v_sub_u32_e32 v172, 0, v180
	v_add_f32_e32 v174, v174, v176
	v_ldexp_f32 v151, v151, v172
	v_ldexp_f32 v172, v174, v172
	v_add_f32_e32 v174, -1.0, v151
	v_add_f32_e32 v173, 1.0, v174
	v_sub_f32_e32 v173, v151, v173
	v_add_f32_e32 v175, v172, v173
	v_add_f32_e32 v173, 1.0, v151
	v_add_f32_e32 v176, -1.0, v173
	v_sub_f32_e32 v151, v151, v176
	v_add_f32_e32 v151, v172, v151
	v_add_f32_e32 v181, v173, v151
	v_rcp_f32_e32 v182, v181
	v_sub_f32_e32 v172, v181, v173
	v_add_f32_e32 v173, v174, v175
	v_sub_f32_e32 v151, v151, v172
	v_mul_f32_e32 v184, v173, v182
	v_sub_f32_e32 v172, v173, v174
	v_mul_f32_e32 v174, v181, v184
	v_fma_f32 v176, v184, v181, -v174
	v_fmac_f32_e32 v176, v184, v151
	v_sub_f32_e32 v183, v175, v172
	v_add_f32_e32 v172, v174, v176
	v_sub_f32_e32 v175, v173, v172
	v_pk_add_f32 v[178:179], v[172:173], v[174:175] neg_lo:[0,1] neg_hi:[0,1]
	v_mov_b32_e32 v177, v172
	v_pk_add_f32 v[172:173], v[178:179], v[176:177] neg_lo:[0,1] neg_hi:[0,1]
	v_cmp_neq_f32_e32 vcc, s70, v156
	v_add_f32_e32 v173, v183, v173
	v_add_f32_e32 v172, v172, v173
	v_add_f32_e32 v173, v175, v172
	v_mul_f32_e32 v183, v182, v173
	v_mul_f32_e32 v174, v181, v183
	v_fma_f32 v176, v183, v181, -v174
	v_fmac_f32_e32 v176, v183, v151
	v_sub_f32_e32 v151, v175, v173
	v_add_f32_e32 v151, v172, v151
	v_add_f32_e32 v172, v174, v176
	v_sub_f32_e32 v175, v173, v172
	v_pk_add_f32 v[178:179], v[172:173], v[174:175] neg_lo:[0,1] neg_hi:[0,1]
	v_mov_b32_e32 v177, v172
	v_pk_add_f32 v[172:173], v[178:179], v[176:177] neg_lo:[0,1] neg_hi:[0,1]
	s_nop 0
	v_add_f32_e32 v151, v151, v173
	v_add_f32_e32 v151, v172, v151
	v_add_f32_e32 v173, v184, v183
	v_add_f32_e32 v151, v175, v151
	v_sub_f32_e32 v172, v173, v184
	v_mul_f32_e32 v151, v182, v151
	v_sub_f32_e32 v172, v183, v172
	v_add_f32_e32 v174, v172, v151
	v_add_f32_e32 v176, v173, v174
	v_cvt_f32_i32_e32 v172, v180
	v_mul_f32_e32 v177, v176, v176
	v_sub_f32_e32 v173, v176, v173
	v_fmamk_f32 v151, v177, 0x3e9b6dac, v166
	v_sub_f32_e32 v173, v174, v173
	v_fmaak_f32 v151, v177, v151, 0x3f2aaada
	v_ldexp_f32 v178, v173, 1
	v_mul_f32_e32 v173, v176, v177
	v_ldexp_f32 v175, v176, 1
	v_pk_mul_f32 v[176:177], v[172:173], v[150:151]
	s_nop 0
	v_fma_f32 v174, v172, s69, -v176
	v_fmac_f32_e32 v174, 0xb102e308, v172
	v_pk_add_f32 v[172:173], v[176:177], v[174:175]
	s_nop 0
	v_sub_f32_e32 v151, v173, v175
	v_sub_f32_e32 v151, v177, v151
	v_add_f32_e32 v179, v178, v151
	v_mov_b32_e32 v178, v176
	v_pk_add_f32 v[176:177], v[172:173], v[176:177] neg_lo:[0,1] neg_hi:[0,1]
	v_pk_add_f32 v[180:181], v[172:173], v[178:179]
	v_mov_b32_e32 v175, v172
	v_mov_b32_e32 v177, v181
	v_pk_add_f32 v[182:183], v[174:175], v[176:177] neg_lo:[0,1] neg_hi:[0,1]
	v_pk_add_f32 v[174:175], v[174:175], v[176:177]
	v_mov_b32_e32 v178, v179
	v_pk_add_f32 v[176:177], v[174:175], v[172:173] op_sel:[1,0] op_sel_hi:[0,1] neg_lo:[0,1] neg_hi:[0,1]
	v_pk_add_f32 v[184:185], v[180:181], v[176:177] op_sel_hi:[1,0] neg_lo:[0,1] neg_hi:[0,1]
	v_mov_b32_e32 v180, v181
	v_mov_b32_e32 v181, v175
	v_pk_mov_b32 v[176:177], v[172:173], v[176:177] op_sel:[1,0]
	v_mov_b32_e32 v179, v172
	v_pk_add_f32 v[176:177], v[180:181], v[176:177] neg_lo:[0,1] neg_hi:[0,1]
	v_mov_b32_e32 v184, v182
	v_pk_add_f32 v[172:173], v[178:179], v[176:177] neg_lo:[0,1] neg_hi:[0,1]
	v_mov_b32_e32 v183, v175
	v_pk_add_f32 v[176:177], v[184:185], v[172:173]
	s_nop 0
	v_pk_add_f32 v[178:179], v[176:177], v[176:177] op_sel:[0,1] op_sel_hi:[1,0]
	s_nop 0
	v_pk_add_f32 v[174:175], v[174:175], v[178:179] op_sel:[1,0] op_sel_hi:[0,1]
	v_mov_b32_e32 v177, v174
	v_pk_add_f32 v[180:181], v[176:177], v[182:183] neg_lo:[0,1] neg_hi:[0,1]
	v_mov_b32_e32 v173, v178
	v_sub_f32_e32 v151, v176, v180
	v_pk_add_f32 v[172:173], v[172:173], v[180:181] neg_lo:[0,1] neg_hi:[0,1]
	v_sub_f32_e32 v151, v182, v151
	v_add_f32_e32 v151, v172, v151
	v_add_f32_e32 v151, v151, v173
	v_add_f32_e32 v151, v174, v151
	v_cndmask_b32_e32 v151, v167, v151, vcc
	v_cmp_ngt_f32_e32 vcc, -1.0, v156
	s_nop 1
	v_cndmask_b32_e32 v151, v168, v151, vcc
	v_cmp_neq_f32_e32 vcc, -1.0, v156
	s_nop 1
	v_cndmask_b32_e32 v151, v169, v151, vcc
	v_cmp_lt_f32_e64 vcc, |v156|, s71
	s_nop 1
	v_cndmask_b32_e32 v151, v151, v156, vcc
;     __device__ __forceinline__ void operator()(const f32x4 (&acc)[2][2][4][2], const Unit& u, int wr, int wc, int fr, int fq) const {
;     ...
;                     for (int m = 0; m < 4; ++m) { const int r = row0 + ai * HALF + m * 16;
;                         const f32x4 v0 = acc[ai][0][m][0], v1 = acc[ai][0][m][1]; float* dp = DT + (size_t)r * 32 + c0;
; #pragma unroll
;                         for (int i = 0; i < 4; ++i) { float x0 = v0[i] + dt_bias[c0 + i], x1 = v1[i] + dt_bias[c0 + 4 + i];
;                             dp[i] = x0 > 20.f ? x0 : log1pf(__expf(x0)); dp[4 + i] = x1 > 20.f ? x1 : log1pf(__expf(x1)); }
.LBB0_821:
	s_or_b64 exec, exec, s[24:25]
	v_add_f32_e32 v136, v89, v136
	v_cmp_nlt_f32_e32 vcc, s67, v136
	flat_store_dword v[154:155], v151 offset:4
	s_and_saveexec_b64 s[24:25], vcc
	s_cbranch_execz .LBB0_823
	v_mul_f32_e32 v136, 0x3fb8aa3b, v136
	v_exp_f32_e32 v136, v136
	s_nop 0
	v_add_f32_e32 v151, 1.0, v136
	v_frexp_mant_f32_e32 v174, v151
	v_cvt_f64_f32_e32 v[172:173], v151
	v_add_f32_e32 v156, -1.0, v151
	v_frexp_exp_i32_f64_e32 v172, v[172:173]
	v_cmp_gt_f32_e32 vcc, s68, v174
	v_sub_f32_e32 v175, v156, v151
	v_sub_f32_e32 v156, v136, v156
	v_subbrev_co_u32_e32 v180, vcc, 0, v172, vcc
	v_add_f32_e32 v175, 1.0, v175
	v_sub_u32_e32 v172, 0, v180
	v_add_f32_e32 v156, v156, v175
	v_ldexp_f32 v151, v151, v172
	v_ldexp_f32 v156, v156, v172
	v_add_f32_e32 v172, -1.0, v151
	v_add_f32_e32 v173, 1.0, v172
	v_sub_f32_e32 v173, v151, v173
	v_add_f32_e32 v174, v156, v173
	v_add_f32_e32 v173, 1.0, v151
	v_add_f32_e32 v175, -1.0, v173
	v_sub_f32_e32 v151, v151, v175
	v_add_f32_e32 v151, v156, v151
	v_add_f32_e32 v156, v173, v151
	v_rcp_f32_e32 v181, v156
	v_sub_f32_e32 v173, v156, v173
	v_sub_f32_e32 v151, v151, v173
	v_add_f32_e32 v173, v172, v174
	v_sub_f32_e32 v172, v173, v172
	v_mul_f32_e32 v183, v173, v181
	v_sub_f32_e32 v182, v174, v172
	v_mul_f32_e32 v174, v156, v183
	v_fma_f32 v176, v183, v156, -v174
	v_fmac_f32_e32 v176, v183, v151
	v_add_f32_e32 v172, v174, v176
	v_sub_f32_e32 v175, v173, v172
	v_pk_add_f32 v[178:179], v[172:173], v[174:175] neg_lo:[0,1] neg_hi:[0,1]
	v_mov_b32_e32 v177, v172
	v_pk_add_f32 v[172:173], v[178:179], v[176:177] neg_lo:[0,1] neg_hi:[0,1]
	v_cmp_neq_f32_e32 vcc, s70, v136
	v_add_f32_e32 v173, v182, v173
	v_add_f32_e32 v172, v172, v173
	v_add_f32_e32 v173, v175, v172
	v_mul_f32_e32 v182, v181, v173
	v_mul_f32_e32 v174, v156, v182
	v_fma_f32 v176, v182, v156, -v174
	v_fmac_f32_e32 v176, v182, v151
	v_sub_f32_e32 v151, v175, v173
	v_add_f32_e32 v151, v172, v151
	v_add_f32_e32 v172, v174, v176
	v_sub_f32_e32 v175, v173, v172
	v_pk_add_f32 v[178:179], v[172:173], v[174:175] neg_lo:[0,1] neg_hi:[0,1]
	v_mov_b32_e32 v177, v172
	v_pk_add_f32 v[172:173], v[178:179], v[176:177] neg_lo:[0,1] neg_hi:[0,1]
	v_add_f32_e32 v156, v183, v182
	v_add_f32_e32 v151, v151, v173
	v_add_f32_e32 v151, v172, v151
	v_add_f32_e32 v151, v175, v151
	v_sub_f32_e32 v172, v156, v183
	v_mul_f32_e32 v151, v181, v151
	v_sub_f32_e32 v172, v182, v172
	v_add_f32_e32 v173, v172, v151
	v_add_f32_e32 v174, v156, v173
	v_cvt_f32_i32_e32 v172, v180
	v_mul_f32_e32 v176, v174, v174
	v_fmamk_f32 v151, v176, 0x3e9b6dac, v166
	v_sub_f32_e32 v156, v174, v156
	v_fmaak_f32 v151, v176, v151, 0x3f2aaada
	v_sub_f32_e32 v156, v173, v156
	v_mul_f32_e32 v173, v174, v176
	v_pk_mul_f32 v[176:177], v[172:173], v[150:151]
	v_ldexp_f32 v175, v174, 1
	v_fma_f32 v174, v172, s69, -v176
	v_fmac_f32_e32 v174, 0xb102e308, v172
	v_pk_add_f32 v[172:173], v[176:177], v[174:175]
	v_ldexp_f32 v156, v156, 1
	v_sub_f32_e32 v151, v173, v175
	v_sub_f32_e32 v151, v177, v151
	v_add_f32_e32 v179, v156, v151
	v_mov_b32_e32 v178, v176
	v_pk_add_f32 v[176:177], v[172:173], v[176:177] neg_lo:[0,1] neg_hi:[0,1]
	v_pk_add_f32 v[180:181], v[172:173], v[178:179]
	v_mov_b32_e32 v175, v172
	v_mov_b32_e32 v177, v181
	v_pk_add_f32 v[182:183], v[174:175], v[176:177] neg_lo:[0,1] neg_hi:[0,1]
	v_pk_add_f32 v[174:175], v[174:175], v[176:177]
	v_mov_b32_e32 v178, v179
	v_pk_add_f32 v[176:177], v[174:175], v[172:173] op_sel:[1,0] op_sel_hi:[0,1] neg_lo:[0,1] neg_hi:[0,1]
	v_pk_add_f32 v[184:185], v[180:181], v[176:177] op_sel_hi:[1,0] neg_lo:[0,1] neg_hi:[0,1]
	v_mov_b32_e32 v180, v181
	v_mov_b32_e32 v181, v175
	v_pk_mov_b32 v[176:177], v[172:173], v[176:177] op_sel:[1,0]
	v_mov_b32_e32 v179, v172
	v_pk_add_f32 v[176:177], v[180:181], v[176:177] neg_lo:[0,1] neg_hi:[0,1]
	v_mov_b32_e32 v184, v182
	v_pk_add_f32 v[172:173], v[178:179], v[176:177] neg_lo:[0,1] neg_hi:[0,1]
	v_mov_b32_e32 v183, v175
	v_pk_add_f32 v[176:177], v[184:185], v[172:173]
	s_nop 0
	v_pk_add_f32 v[178:179], v[176:177], v[176:177] op_sel:[0,1] op_sel_hi:[1,0]
	s_nop 0
	v_pk_add_f32 v[174:175], v[174:175], v[178:179] op_sel:[1,0] op_sel_hi:[0,1]
	v_mov_b32_e32 v177, v174
	v_pk_add_f32 v[180:181], v[176:177], v[182:183] neg_lo:[0,1] neg_hi:[0,1]
	v_mov_b32_e32 v173, v178
	v_sub_f32_e32 v151, v176, v180
	v_pk_add_f32 v[172:173], v[172:173], v[180:181] neg_lo:[0,1] neg_hi:[0,1]
	v_sub_f32_e32 v151, v182, v151
	v_add_f32_e32 v151, v172, v151
	v_add_f32_e32 v151, v151, v173
	v_add_f32_e32 v151, v174, v151
	v_cndmask_b32_e32 v151, v167, v151, vcc
	v_cmp_ngt_f32_e32 vcc, -1.0, v136
	s_nop 1
	v_cndmask_b32_e32 v151, v168, v151, vcc
	v_cmp_neq_f32_e32 vcc, -1.0, v136
	s_nop 1
	v_cndmask_b32_e32 v151, v169, v151, vcc
	v_cmp_lt_f32_e64 vcc, |v136|, s71
	s_nop 1
	v_cndmask_b32_e32 v136, v151, v136, vcc
;     __device__ __forceinline__ void operator()(const f32x4 (&acc)[2][2][4][2], const Unit& u, int wr, int wc, int fr, int fq) const {
;     ...
;                         for (int i = 0; i < 4; ++i) { float x0 = v0[i] + dt_bias[c0 + i], x1 = v1[i] + dt_bias[c0 + 4 + i];
;                             dp[i] = x0 > 20.f ? x0 : log1pf(__expf(x0)); dp[4 + i] = x1 > 20.f ? x1 : log1pf(__expf(x1)); }
.LBB0_823:
	s_or_b64 exec, exec, s[24:25]
	flat_store_dword v[154:155], v136 offset:20
	v_mov_b32_e32 v136, v202
	v_add_f32_e32 v151, v94, v136
	v_mov_b32_e32 v136, v206
	v_cmp_nlt_f32_e32 vcc, s67, v151
	s_and_saveexec_b64 s[24:25], vcc
	s_cbranch_execz .LBB0_825
	v_mul_f32_e32 v151, 0x3fb8aa3b, v151
	v_exp_f32_e32 v156, v151
	s_nop 0
	v_add_f32_e32 v151, 1.0, v156
	v_frexp_mant_f32_e32 v175, v151
	v_cvt_f64_f32_e32 v[172:173], v151
	v_add_f32_e32 v174, -1.0, v151
	v_frexp_exp_i32_f64_e32 v172, v[172:173]
	v_cmp_gt_f32_e32 vcc, s68, v175
	v_sub_f32_e32 v176, v174, v151
	v_sub_f32_e32 v174, v156, v174
	v_subbrev_co_u32_e32 v180, vcc, 0, v172, vcc
	v_add_f32_e32 v176, 1.0, v176
	v_sub_u32_e32 v172, 0, v180
	v_add_f32_e32 v174, v174, v176
	v_ldexp_f32 v151, v151, v172
	v_ldexp_f32 v172, v174, v172
	v_add_f32_e32 v174, -1.0, v151
	v_add_f32_e32 v173, 1.0, v174
	v_sub_f32_e32 v173, v151, v173
	v_add_f32_e32 v175, v172, v173
	v_add_f32_e32 v173, 1.0, v151
	v_add_f32_e32 v176, -1.0, v173
	v_sub_f32_e32 v151, v151, v176
	v_add_f32_e32 v151, v172, v151
	v_add_f32_e32 v181, v173, v151
	v_rcp_f32_e32 v182, v181
	v_sub_f32_e32 v172, v181, v173
	v_add_f32_e32 v173, v174, v175
	v_sub_f32_e32 v151, v151, v172
	v_mul_f32_e32 v184, v173, v182
	v_sub_f32_e32 v172, v173, v174
	v_mul_f32_e32 v174, v181, v184
	v_fma_f32 v176, v184, v181, -v174
	v_fmac_f32_e32 v176, v184, v151
	v_sub_f32_e32 v183, v175, v172
	v_add_f32_e32 v172, v174, v176
	v_sub_f32_e32 v175, v173, v172
	v_pk_add_f32 v[178:179], v[172:173], v[174:175] neg_lo:[0,1] neg_hi:[0,1]
	v_mov_b32_e32 v177, v172
	v_pk_add_f32 v[172:173], v[178:179], v[176:177] neg_lo:[0,1] neg_hi:[0,1]
	v_cmp_neq_f32_e32 vcc, s70, v156
	v_add_f32_e32 v173, v183, v173
	v_add_f32_e32 v172, v172, v173
	v_add_f32_e32 v173, v175, v172
	v_mul_f32_e32 v183, v182, v173
	v_mul_f32_e32 v174, v181, v183
	v_fma_f32 v176, v183, v181, -v174
	v_fmac_f32_e32 v176, v183, v151
	v_sub_f32_e32 v151, v175, v173
	v_add_f32_e32 v151, v172, v151
	v_add_f32_e32 v172, v174, v176
	v_sub_f32_e32 v175, v173, v172
	v_pk_add_f32 v[178:179], v[172:173], v[174:175] neg_lo:[0,1] neg_hi:[0,1]
	v_mov_b32_e32 v177, v172
	v_pk_add_f32 v[172:173], v[178:179], v[176:177] neg_lo:[0,1] neg_hi:[0,1]
	s_nop 0
	v_add_f32_e32 v151, v151, v173
	v_add_f32_e32 v151, v172, v151
	v_add_f32_e32 v173, v184, v183
	v_add_f32_e32 v151, v175, v151
	v_sub_f32_e32 v172, v173, v184
	v_mul_f32_e32 v151, v182, v151
	v_sub_f32_e32 v172, v183, v172
	v_add_f32_e32 v174, v172, v151
	v_add_f32_e32 v176, v173, v174
	v_cvt_f32_i32_e32 v172, v180
	v_mul_f32_e32 v177, v176, v176
	v_sub_f32_e32 v173, v176, v173
	v_fmamk_f32 v151, v177, 0x3e9b6dac, v166
	v_sub_f32_e32 v173, v174, v173
	v_fmaak_f32 v151, v177, v151, 0x3f2aaada
	v_ldexp_f32 v178, v173, 1
	v_mul_f32_e32 v173, v176, v177
	v_ldexp_f32 v175, v176, 1
	v_pk_mul_f32 v[176:177], v[172:173], v[150:151]
	s_nop 0
	v_fma_f32 v174, v172, s69, -v176
	v_fmac_f32_e32 v174, 0xb102e308, v172
	v_pk_add_f32 v[172:173], v[176:177], v[174:175]
	s_nop 0
	v_sub_f32_e32 v151, v173, v175
	v_sub_f32_e32 v151, v177, v151
	v_add_f32_e32 v179, v178, v151
	v_mov_b32_e32 v178, v176
	v_pk_add_f32 v[176:177], v[172:173], v[176:177] neg_lo:[0,1] neg_hi:[0,1]
	v_pk_add_f32 v[180:181], v[172:173], v[178:179]
	v_mov_b32_e32 v175, v172
	v_mov_b32_e32 v177, v181
	v_pk_add_f32 v[182:183], v[174:175], v[176:177] neg_lo:[0,1] neg_hi:[0,1]
	v_pk_add_f32 v[174:175], v[174:175], v[176:177]
	v_mov_b32_e32 v178, v179
	v_pk_add_f32 v[176:177], v[174:175], v[172:173] op_sel:[1,0] op_sel_hi:[0,1] neg_lo:[0,1] neg_hi:[0,1]
	v_pk_add_f32 v[184:185], v[180:181], v[176:177] op_sel_hi:[1,0] neg_lo:[0,1] neg_hi:[0,1]
	v_mov_b32_e32 v180, v181
	v_mov_b32_e32 v181, v175
	v_pk_mov_b32 v[176:177], v[172:173], v[176:177] op_sel:[1,0]
	v_mov_b32_e32 v179, v172
	v_pk_add_f32 v[176:177], v[180:181], v[176:177] neg_lo:[0,1] neg_hi:[0,1]
	v_mov_b32_e32 v184, v182
	v_pk_add_f32 v[172:173], v[178:179], v[176:177] neg_lo:[0,1] neg_hi:[0,1]
	v_mov_b32_e32 v183, v175
	v_pk_add_f32 v[176:177], v[184:185], v[172:173]
	s_nop 0
	v_pk_add_f32 v[178:179], v[176:177], v[176:177] op_sel:[0,1] op_sel_hi:[1,0]
	s_nop 0
	v_pk_add_f32 v[174:175], v[174:175], v[178:179] op_sel:[1,0] op_sel_hi:[0,1]
	v_mov_b32_e32 v177, v174
	v_pk_add_f32 v[180:181], v[176:177], v[182:183] neg_lo:[0,1] neg_hi:[0,1]
	v_mov_b32_e32 v173, v178
	v_sub_f32_e32 v151, v176, v180
	v_pk_add_f32 v[172:173], v[172:173], v[180:181] neg_lo:[0,1] neg_hi:[0,1]
	v_sub_f32_e32 v151, v182, v151
	v_add_f32_e32 v151, v172, v151
	v_add_f32_e32 v151, v151, v173
	v_add_f32_e32 v151, v174, v151
	v_cndmask_b32_e32 v151, v167, v151, vcc
	v_cmp_ngt_f32_e32 vcc, -1.0, v156
	s_nop 1
	v_cndmask_b32_e32 v151, v168, v151, vcc
	v_cmp_neq_f32_e32 vcc, -1.0, v156
	s_nop 1
	v_cndmask_b32_e32 v151, v169, v151, vcc
	v_cmp_lt_f32_e64 vcc, |v156|, s71
	s_nop 1
	v_cndmask_b32_e32 v151, v151, v156, vcc
;     __device__ __forceinline__ void operator()(const f32x4 (&acc)[2][2][4][2], const Unit& u, int wr, int wc, int fr, int fq) const {
;     ...
;                         for (int i = 0; i < 4; ++i) { float x0 = v0[i] + dt_bias[c0 + i], x1 = v1[i] + dt_bias[c0 + 4 + i];
;                             dp[i] = x0 > 20.f ? x0 : log1pf(__expf(x0)); dp[4 + i] = x1 > 20.f ? x1 : log1pf(__expf(x1)); }
.LBB0_825:
	s_or_b64 exec, exec, s[24:25]
	v_add_f32_e32 v136, v90, v136
	v_cmp_nlt_f32_e32 vcc, s67, v136
	flat_store_dword v[154:155], v151 offset:8
	s_and_saveexec_b64 s[24:25], vcc
	s_cbranch_execz .LBB0_827
	v_mul_f32_e32 v136, 0x3fb8aa3b, v136
	v_exp_f32_e32 v136, v136
	s_nop 0
	v_add_f32_e32 v151, 1.0, v136
	v_frexp_mant_f32_e32 v174, v151
	v_cvt_f64_f32_e32 v[172:173], v151
	v_add_f32_e32 v156, -1.0, v151
	v_frexp_exp_i32_f64_e32 v172, v[172:173]
	v_cmp_gt_f32_e32 vcc, s68, v174
	v_sub_f32_e32 v175, v156, v151
	v_sub_f32_e32 v156, v136, v156
	v_subbrev_co_u32_e32 v180, vcc, 0, v172, vcc
	v_add_f32_e32 v175, 1.0, v175
	v_sub_u32_e32 v172, 0, v180
	v_add_f32_e32 v156, v156, v175
	v_ldexp_f32 v151, v151, v172
	v_ldexp_f32 v156, v156, v172
	v_add_f32_e32 v172, -1.0, v151
	v_add_f32_e32 v173, 1.0, v172
	v_sub_f32_e32 v173, v151, v173
	v_add_f32_e32 v174, v156, v173
	v_add_f32_e32 v173, 1.0, v151
	v_add_f32_e32 v175, -1.0, v173
	v_sub_f32_e32 v151, v151, v175
	v_add_f32_e32 v151, v156, v151
	v_add_f32_e32 v156, v173, v151
	v_rcp_f32_e32 v181, v156
	v_sub_f32_e32 v173, v156, v173
	v_sub_f32_e32 v151, v151, v173
	v_add_f32_e32 v173, v172, v174
	v_sub_f32_e32 v172, v173, v172
	v_mul_f32_e32 v183, v173, v181
	v_sub_f32_e32 v182, v174, v172
	v_mul_f32_e32 v174, v156, v183
	v_fma_f32 v176, v183, v156, -v174
	v_fmac_f32_e32 v176, v183, v151
	v_add_f32_e32 v172, v174, v176
	v_sub_f32_e32 v175, v173, v172
	v_pk_add_f32 v[178:179], v[172:173], v[174:175] neg_lo:[0,1] neg_hi:[0,1]
	v_mov_b32_e32 v177, v172
	v_pk_add_f32 v[172:173], v[178:179], v[176:177] neg_lo:[0,1] neg_hi:[0,1]
	v_cmp_neq_f32_e32 vcc, s70, v136
	v_add_f32_e32 v173, v182, v173
	v_add_f32_e32 v172, v172, v173
	v_add_f32_e32 v173, v175, v172
	v_mul_f32_e32 v182, v181, v173
	v_mul_f32_e32 v174, v156, v182
	v_fma_f32 v176, v182, v156, -v174
	v_fmac_f32_e32 v176, v182, v151
	v_sub_f32_e32 v151, v175, v173
	v_add_f32_e32 v151, v172, v151
	v_add_f32_e32 v172, v174, v176
	v_sub_f32_e32 v175, v173, v172
	v_pk_add_f32 v[178:179], v[172:173], v[174:175] neg_lo:[0,1] neg_hi:[0,1]
	v_mov_b32_e32 v177, v172
	v_pk_add_f32 v[172:173], v[178:179], v[176:177] neg_lo:[0,1] neg_hi:[0,1]
	v_add_f32_e32 v156, v183, v182
	v_add_f32_e32 v151, v151, v173
	v_add_f32_e32 v151, v172, v151
	v_add_f32_e32 v151, v175, v151
	v_sub_f32_e32 v172, v156, v183
	v_mul_f32_e32 v151, v181, v151
	v_sub_f32_e32 v172, v182, v172
	v_add_f32_e32 v173, v172, v151
	v_add_f32_e32 v174, v156, v173
	v_cvt_f32_i32_e32 v172, v180
	v_mul_f32_e32 v176, v174, v174
	v_fmamk_f32 v151, v176, 0x3e9b6dac, v166
	v_sub_f32_e32 v156, v174, v156
	v_fmaak_f32 v151, v176, v151, 0x3f2aaada
	v_sub_f32_e32 v156, v173, v156
	v_mul_f32_e32 v173, v174, v176
	v_pk_mul_f32 v[176:177], v[172:173], v[150:151]
	v_ldexp_f32 v175, v174, 1
	v_fma_f32 v174, v172, s69, -v176
	v_fmac_f32_e32 v174, 0xb102e308, v172
	v_pk_add_f32 v[172:173], v[176:177], v[174:175]
	v_ldexp_f32 v156, v156, 1
	v_sub_f32_e32 v151, v173, v175
	v_sub_f32_e32 v151, v177, v151
	v_add_f32_e32 v179, v156, v151
	v_mov_b32_e32 v178, v176
	v_pk_add_f32 v[176:177], v[172:173], v[176:177] neg_lo:[0,1] neg_hi:[0,1]
	v_pk_add_f32 v[180:181], v[172:173], v[178:179]
	v_mov_b32_e32 v175, v172
	v_mov_b32_e32 v177, v181
	v_pk_add_f32 v[182:183], v[174:175], v[176:177] neg_lo:[0,1] neg_hi:[0,1]
	v_pk_add_f32 v[174:175], v[174:175], v[176:177]
	v_mov_b32_e32 v178, v179
	v_pk_add_f32 v[176:177], v[174:175], v[172:173] op_sel:[1,0] op_sel_hi:[0,1] neg_lo:[0,1] neg_hi:[0,1]
	v_pk_add_f32 v[184:185], v[180:181], v[176:177] op_sel_hi:[1,0] neg_lo:[0,1] neg_hi:[0,1]
	v_mov_b32_e32 v180, v181
	v_mov_b32_e32 v181, v175
	v_pk_mov_b32 v[176:177], v[172:173], v[176:177] op_sel:[1,0]
	v_mov_b32_e32 v179, v172
	v_pk_add_f32 v[176:177], v[180:181], v[176:177] neg_lo:[0,1] neg_hi:[0,1]
	v_mov_b32_e32 v184, v182
	v_pk_add_f32 v[172:173], v[178:179], v[176:177] neg_lo:[0,1] neg_hi:[0,1]
	v_mov_b32_e32 v183, v175
	v_pk_add_f32 v[176:177], v[184:185], v[172:173]
	s_nop 0
	v_pk_add_f32 v[178:179], v[176:177], v[176:177] op_sel:[0,1] op_sel_hi:[1,0]
	s_nop 0
	v_pk_add_f32 v[174:175], v[174:175], v[178:179] op_sel:[1,0] op_sel_hi:[0,1]
	v_mov_b32_e32 v177, v174
	v_pk_add_f32 v[180:181], v[176:177], v[182:183] neg_lo:[0,1] neg_hi:[0,1]
	v_mov_b32_e32 v173, v178
	v_sub_f32_e32 v151, v176, v180
	v_pk_add_f32 v[172:173], v[172:173], v[180:181] neg_lo:[0,1] neg_hi:[0,1]
	v_sub_f32_e32 v151, v182, v151
	v_add_f32_e32 v151, v172, v151
	v_add_f32_e32 v151, v151, v173
	v_add_f32_e32 v151, v174, v151
	v_cndmask_b32_e32 v151, v167, v151, vcc
	v_cmp_ngt_f32_e32 vcc, -1.0, v136
	s_nop 1
	v_cndmask_b32_e32 v151, v168, v151, vcc
	v_cmp_neq_f32_e32 vcc, -1.0, v136
	s_nop 1
	v_cndmask_b32_e32 v151, v169, v151, vcc
	v_cmp_lt_f32_e64 vcc, |v136|, s71
	s_nop 1
	v_cndmask_b32_e32 v136, v151, v136, vcc
;     __device__ __forceinline__ void operator()(const f32x4 (&acc)[2][2][4][2], const Unit& u, int wr, int wc, int fr, int fq) const {
;     ...
;                         for (int i = 0; i < 4; ++i) { float x0 = v0[i] + dt_bias[c0 + i], x1 = v1[i] + dt_bias[c0 + 4 + i];
;                             dp[i] = x0 > 20.f ? x0 : log1pf(__expf(x0)); dp[4 + i] = x1 > 20.f ? x1 : log1pf(__expf(x1)); }
.LBB0_827:
	s_or_b64 exec, exec, s[24:25]
	flat_store_dword v[154:155], v136 offset:24
	v_mov_b32_e32 v136, v203
	v_add_f32_e32 v151, v95, v136
	v_mov_b32_e32 v136, v207
	v_cmp_nlt_f32_e32 vcc, s67, v151
	s_and_saveexec_b64 s[24:25], vcc
	s_cbranch_execz .LBB0_829
	v_mul_f32_e32 v151, 0x3fb8aa3b, v151
	v_exp_f32_e32 v156, v151
	s_nop 0
	v_add_f32_e32 v151, 1.0, v156
	v_frexp_mant_f32_e32 v175, v151
	v_cvt_f64_f32_e32 v[172:173], v151
	v_add_f32_e32 v174, -1.0, v151
	v_frexp_exp_i32_f64_e32 v172, v[172:173]
	v_cmp_gt_f32_e32 vcc, s68, v175
	v_sub_f32_e32 v176, v174, v151
	v_sub_f32_e32 v174, v156, v174
	v_subbrev_co_u32_e32 v180, vcc, 0, v172, vcc
	v_add_f32_e32 v176, 1.0, v176
	v_sub_u32_e32 v172, 0, v180
	v_add_f32_e32 v174, v174, v176
	v_ldexp_f32 v151, v151, v172
	v_ldexp_f32 v172, v174, v172
	v_add_f32_e32 v174, -1.0, v151
	v_add_f32_e32 v173, 1.0, v174
	v_sub_f32_e32 v173, v151, v173
	v_add_f32_e32 v175, v172, v173
	v_add_f32_e32 v173, 1.0, v151
	v_add_f32_e32 v176, -1.0, v173
	v_sub_f32_e32 v151, v151, v176
	v_add_f32_e32 v151, v172, v151
	v_add_f32_e32 v181, v173, v151
	v_rcp_f32_e32 v182, v181
	v_sub_f32_e32 v172, v181, v173
	v_add_f32_e32 v173, v174, v175
	v_sub_f32_e32 v151, v151, v172
	v_mul_f32_e32 v184, v173, v182
	v_sub_f32_e32 v172, v173, v174
	v_mul_f32_e32 v174, v181, v184
	v_fma_f32 v176, v184, v181, -v174
	v_fmac_f32_e32 v176, v184, v151
	v_sub_f32_e32 v183, v175, v172
	v_add_f32_e32 v172, v174, v176
	v_sub_f32_e32 v175, v173, v172
	v_pk_add_f32 v[178:179], v[172:173], v[174:175] neg_lo:[0,1] neg_hi:[0,1]
	v_mov_b32_e32 v177, v172
	v_pk_add_f32 v[172:173], v[178:179], v[176:177] neg_lo:[0,1] neg_hi:[0,1]
	v_cmp_neq_f32_e32 vcc, s70, v156
	v_add_f32_e32 v173, v183, v173
	v_add_f32_e32 v172, v172, v173
	v_add_f32_e32 v173, v175, v172
	v_mul_f32_e32 v183, v182, v173
	v_mul_f32_e32 v174, v181, v183
	v_fma_f32 v176, v183, v181, -v174
	v_fmac_f32_e32 v176, v183, v151
	v_sub_f32_e32 v151, v175, v173
	v_add_f32_e32 v151, v172, v151
	v_add_f32_e32 v172, v174, v176
	v_sub_f32_e32 v175, v173, v172
	v_pk_add_f32 v[178:179], v[172:173], v[174:175] neg_lo:[0,1] neg_hi:[0,1]
	v_mov_b32_e32 v177, v172
	v_pk_add_f32 v[172:173], v[178:179], v[176:177] neg_lo:[0,1] neg_hi:[0,1]
	s_nop 0
	v_add_f32_e32 v151, v151, v173
	v_add_f32_e32 v151, v172, v151
	v_add_f32_e32 v173, v184, v183
	v_add_f32_e32 v151, v175, v151
	v_sub_f32_e32 v172, v173, v184
	v_mul_f32_e32 v151, v182, v151
	v_sub_f32_e32 v172, v183, v172
	v_add_f32_e32 v174, v172, v151
	v_add_f32_e32 v176, v173, v174
	v_cvt_f32_i32_e32 v172, v180
	v_mul_f32_e32 v177, v176, v176
	v_sub_f32_e32 v173, v176, v173
	v_fmamk_f32 v151, v177, 0x3e9b6dac, v166
	v_sub_f32_e32 v173, v174, v173
	v_fmaak_f32 v151, v177, v151, 0x3f2aaada
	v_ldexp_f32 v178, v173, 1
	v_mul_f32_e32 v173, v176, v177
	v_ldexp_f32 v175, v176, 1
	v_pk_mul_f32 v[176:177], v[172:173], v[150:151]
	s_nop 0
	v_fma_f32 v174, v172, s69, -v176
	v_fmac_f32_e32 v174, 0xb102e308, v172
	v_pk_add_f32 v[172:173], v[176:177], v[174:175]
	s_nop 0
	v_sub_f32_e32 v151, v173, v175
	v_sub_f32_e32 v151, v177, v151
	v_add_f32_e32 v179, v178, v151
	v_mov_b32_e32 v178, v176
	v_pk_add_f32 v[176:177], v[172:173], v[176:177] neg_lo:[0,1] neg_hi:[0,1]
	v_pk_add_f32 v[180:181], v[172:173], v[178:179]
	v_mov_b32_e32 v175, v172
	v_mov_b32_e32 v177, v181
	v_pk_add_f32 v[182:183], v[174:175], v[176:177] neg_lo:[0,1] neg_hi:[0,1]
	v_pk_add_f32 v[174:175], v[174:175], v[176:177]
	v_mov_b32_e32 v178, v179
	v_pk_add_f32 v[176:177], v[174:175], v[172:173] op_sel:[1,0] op_sel_hi:[0,1] neg_lo:[0,1] neg_hi:[0,1]
	v_pk_add_f32 v[184:185], v[180:181], v[176:177] op_sel_hi:[1,0] neg_lo:[0,1] neg_hi:[0,1]
	v_mov_b32_e32 v180, v181
	v_mov_b32_e32 v181, v175
	v_pk_mov_b32 v[176:177], v[172:173], v[176:177] op_sel:[1,0]
	v_mov_b32_e32 v179, v172
	v_pk_add_f32 v[176:177], v[180:181], v[176:177] neg_lo:[0,1] neg_hi:[0,1]
	v_mov_b32_e32 v184, v182
	v_pk_add_f32 v[172:173], v[178:179], v[176:177] neg_lo:[0,1] neg_hi:[0,1]
	v_mov_b32_e32 v183, v175
	v_pk_add_f32 v[176:177], v[184:185], v[172:173]
	s_nop 0
	v_pk_add_f32 v[178:179], v[176:177], v[176:177] op_sel:[0,1] op_sel_hi:[1,0]
	s_nop 0
	v_pk_add_f32 v[174:175], v[174:175], v[178:179] op_sel:[1,0] op_sel_hi:[0,1]
	v_mov_b32_e32 v177, v174
	v_pk_add_f32 v[180:181], v[176:177], v[182:183] neg_lo:[0,1] neg_hi:[0,1]
	v_mov_b32_e32 v173, v178
	v_sub_f32_e32 v151, v176, v180
	v_pk_add_f32 v[172:173], v[172:173], v[180:181] neg_lo:[0,1] neg_hi:[0,1]
	v_sub_f32_e32 v151, v182, v151
	v_add_f32_e32 v151, v172, v151
	v_add_f32_e32 v151, v151, v173
	v_add_f32_e32 v151, v174, v151
	v_cndmask_b32_e32 v151, v167, v151, vcc
	v_cmp_ngt_f32_e32 vcc, -1.0, v156
	s_nop 1
	v_cndmask_b32_e32 v151, v168, v151, vcc
	v_cmp_neq_f32_e32 vcc, -1.0, v156
	s_nop 1
	v_cndmask_b32_e32 v151, v169, v151, vcc
	v_cmp_lt_f32_e64 vcc, |v156|, s71
	s_nop 1
	v_cndmask_b32_e32 v151, v151, v156, vcc
;     __device__ __forceinline__ void operator()(const f32x4 (&acc)[2][2][4][2], const Unit& u, int wr, int wc, int fr, int fq) const {
;     ...
;                         for (int i = 0; i < 4; ++i) { float x0 = v0[i] + dt_bias[c0 + i], x1 = v1[i] + dt_bias[c0 + 4 + i];
;                             dp[i] = x0 > 20.f ? x0 : log1pf(__expf(x0)); dp[4 + i] = x1 > 20.f ? x1 : log1pf(__expf(x1)); }
.LBB0_829:
	s_or_b64 exec, exec, s[24:25]
	v_add_f32_e32 v136, v91, v136
	v_cmp_nlt_f32_e32 vcc, s67, v136
	flat_store_dword v[154:155], v151 offset:12
	s_and_saveexec_b64 s[24:25], vcc
	s_cbranch_execz .LBB0_831
	v_mul_f32_e32 v136, 0x3fb8aa3b, v136
	v_exp_f32_e32 v136, v136
	s_nop 0
	v_add_f32_e32 v151, 1.0, v136
	v_frexp_mant_f32_e32 v174, v151
	v_cvt_f64_f32_e32 v[172:173], v151
	v_add_f32_e32 v156, -1.0, v151
	v_frexp_exp_i32_f64_e32 v172, v[172:173]
	v_cmp_gt_f32_e32 vcc, s68, v174
	v_sub_f32_e32 v175, v156, v151
	v_sub_f32_e32 v156, v136, v156
	v_subbrev_co_u32_e32 v180, vcc, 0, v172, vcc
	v_add_f32_e32 v175, 1.0, v175
	v_sub_u32_e32 v172, 0, v180
	v_add_f32_e32 v156, v156, v175
	v_ldexp_f32 v151, v151, v172
	v_ldexp_f32 v156, v156, v172
	v_add_f32_e32 v172, -1.0, v151
	v_add_f32_e32 v173, 1.0, v172
	v_sub_f32_e32 v173, v151, v173
	v_add_f32_e32 v174, v156, v173
	v_add_f32_e32 v173, 1.0, v151
	v_add_f32_e32 v175, -1.0, v173
	v_sub_f32_e32 v151, v151, v175
	v_add_f32_e32 v151, v156, v151
	v_add_f32_e32 v156, v173, v151
	v_rcp_f32_e32 v181, v156
	v_sub_f32_e32 v173, v156, v173
	v_sub_f32_e32 v151, v151, v173
	v_add_f32_e32 v173, v172, v174
	v_sub_f32_e32 v172, v173, v172
	v_mul_f32_e32 v183, v173, v181
	v_sub_f32_e32 v182, v174, v172
	v_mul_f32_e32 v174, v156, v183
	v_fma_f32 v176, v183, v156, -v174
	v_fmac_f32_e32 v176, v183, v151
	v_add_f32_e32 v172, v174, v176
	v_sub_f32_e32 v175, v173, v172
	v_pk_add_f32 v[178:179], v[172:173], v[174:175] neg_lo:[0,1] neg_hi:[0,1]
	v_mov_b32_e32 v177, v172
	v_pk_add_f32 v[172:173], v[178:179], v[176:177] neg_lo:[0,1] neg_hi:[0,1]
	v_cmp_neq_f32_e32 vcc, s70, v136
	v_add_f32_e32 v173, v182, v173
	v_add_f32_e32 v172, v172, v173
	v_add_f32_e32 v173, v175, v172
	v_mul_f32_e32 v182, v181, v173
	v_mul_f32_e32 v174, v156, v182
	v_fma_f32 v176, v182, v156, -v174
	v_fmac_f32_e32 v176, v182, v151
	v_sub_f32_e32 v151, v175, v173
	v_add_f32_e32 v151, v172, v151
	v_add_f32_e32 v172, v174, v176
	v_sub_f32_e32 v175, v173, v172
	v_pk_add_f32 v[178:179], v[172:173], v[174:175] neg_lo:[0,1] neg_hi:[0,1]
	v_mov_b32_e32 v177, v172
	v_pk_add_f32 v[172:173], v[178:179], v[176:177] neg_lo:[0,1] neg_hi:[0,1]
	v_add_f32_e32 v156, v183, v182
	v_add_f32_e32 v151, v151, v173
	v_add_f32_e32 v151, v172, v151
	v_add_f32_e32 v151, v175, v151
	v_sub_f32_e32 v172, v156, v183
	v_mul_f32_e32 v151, v181, v151
	v_sub_f32_e32 v172, v182, v172
	v_add_f32_e32 v173, v172, v151
	v_add_f32_e32 v174, v156, v173
	v_cvt_f32_i32_e32 v172, v180
	v_mul_f32_e32 v176, v174, v174
	v_fmamk_f32 v151, v176, 0x3e9b6dac, v166
	v_sub_f32_e32 v156, v174, v156
	v_fmaak_f32 v151, v176, v151, 0x3f2aaada
	v_sub_f32_e32 v156, v173, v156
	v_mul_f32_e32 v173, v174, v176
	v_pk_mul_f32 v[176:177], v[172:173], v[150:151]
	v_ldexp_f32 v175, v174, 1
	v_fma_f32 v174, v172, s69, -v176
	v_fmac_f32_e32 v174, 0xb102e308, v172
	v_pk_add_f32 v[172:173], v[176:177], v[174:175]
	v_ldexp_f32 v156, v156, 1
	v_sub_f32_e32 v151, v173, v175
	v_sub_f32_e32 v151, v177, v151
	v_add_f32_e32 v179, v156, v151
	v_mov_b32_e32 v178, v176
	v_pk_add_f32 v[176:177], v[172:173], v[176:177] neg_lo:[0,1] neg_hi:[0,1]
	v_pk_add_f32 v[180:181], v[172:173], v[178:179]
	v_mov_b32_e32 v175, v172
	v_mov_b32_e32 v177, v181
	v_pk_add_f32 v[182:183], v[174:175], v[176:177] neg_lo:[0,1] neg_hi:[0,1]
	v_pk_add_f32 v[174:175], v[174:175], v[176:177]
	v_mov_b32_e32 v178, v179
	v_pk_add_f32 v[176:177], v[174:175], v[172:173] op_sel:[1,0] op_sel_hi:[0,1] neg_lo:[0,1] neg_hi:[0,1]
	v_pk_add_f32 v[184:185], v[180:181], v[176:177] op_sel_hi:[1,0] neg_lo:[0,1] neg_hi:[0,1]
	v_mov_b32_e32 v180, v181
	v_mov_b32_e32 v181, v175
	v_pk_mov_b32 v[176:177], v[172:173], v[176:177] op_sel:[1,0]
	v_mov_b32_e32 v179, v172
	v_pk_add_f32 v[176:177], v[180:181], v[176:177] neg_lo:[0,1] neg_hi:[0,1]
	v_mov_b32_e32 v184, v182
	v_pk_add_f32 v[172:173], v[178:179], v[176:177] neg_lo:[0,1] neg_hi:[0,1]
	v_mov_b32_e32 v183, v175
	v_pk_add_f32 v[176:177], v[184:185], v[172:173]
	s_nop 0
	v_pk_add_f32 v[178:179], v[176:177], v[176:177] op_sel:[0,1] op_sel_hi:[1,0]
	s_nop 0
	v_pk_add_f32 v[174:175], v[174:175], v[178:179] op_sel:[1,0] op_sel_hi:[0,1]
	v_mov_b32_e32 v177, v174
	v_pk_add_f32 v[180:181], v[176:177], v[182:183] neg_lo:[0,1] neg_hi:[0,1]
	v_mov_b32_e32 v173, v178
	v_sub_f32_e32 v151, v176, v180
	v_pk_add_f32 v[172:173], v[172:173], v[180:181] neg_lo:[0,1] neg_hi:[0,1]
	v_sub_f32_e32 v151, v182, v151
	v_add_f32_e32 v151, v172, v151
	v_add_f32_e32 v151, v151, v173
	v_add_f32_e32 v151, v174, v151
	v_cndmask_b32_e32 v151, v167, v151, vcc
	v_cmp_ngt_f32_e32 vcc, -1.0, v136
	s_nop 1
	v_cndmask_b32_e32 v151, v168, v151, vcc
	v_cmp_neq_f32_e32 vcc, -1.0, v136
	s_nop 1
	v_cndmask_b32_e32 v151, v169, v151, vcc
	v_cmp_lt_f32_e64 vcc, |v136|, s71
	s_nop 1
	v_cndmask_b32_e32 v136, v151, v136, vcc
;     __device__ __forceinline__ void operator()(const f32x4 (&acc)[2][2][4][2], const Unit& u, int wr, int wc, int fr, int fq) const {
;     ...
;                         for (int i = 0; i < 4; ++i) { float x0 = v0[i] + dt_bias[c0 + i], x1 = v1[i] + dt_bias[c0 + 4 + i];
;                             dp[i] = x0 > 20.f ? x0 : log1pf(__expf(x0)); dp[4 + i] = x1 > 20.f ? x1 : log1pf(__expf(x1)); }
.LBB0_831:
	s_or_b64 exec, exec, s[24:25]
	flat_store_dword v[154:155], v136 offset:28
	v_mov_b32_e32 v136, v200
	v_add_f32_e32 v151, v76, v136
	v_mov_b32_e32 v136, v204
	v_cmp_nlt_f32_e32 vcc, s67, v151
	s_and_saveexec_b64 s[24:25], vcc
	s_cbranch_execz .LBB0_833
	v_mul_f32_e32 v151, 0x3fb8aa3b, v151
	v_exp_f32_e32 v156, v151
	s_nop 0
	v_add_f32_e32 v151, 1.0, v156
	v_frexp_mant_f32_e32 v173, v151
	v_cvt_f64_f32_e32 v[154:155], v151
	v_add_f32_e32 v172, -1.0, v151
	v_frexp_exp_i32_f64_e32 v154, v[154:155]
	v_cmp_gt_f32_e32 vcc, s68, v173
	v_sub_f32_e32 v174, v172, v151
	v_sub_f32_e32 v172, v156, v172
	v_subbrev_co_u32_e32 v178, vcc, 0, v154, vcc
	v_add_f32_e32 v174, 1.0, v174
	v_sub_u32_e32 v154, 0, v178
	v_add_f32_e32 v172, v172, v174
	v_ldexp_f32 v151, v151, v154
	v_ldexp_f32 v154, v172, v154
	v_add_f32_e32 v172, -1.0, v151
	v_add_f32_e32 v155, 1.0, v172
	v_sub_f32_e32 v155, v151, v155
	v_add_f32_e32 v173, v154, v155
	v_add_f32_e32 v155, 1.0, v151
	v_add_f32_e32 v174, -1.0, v155
	v_sub_f32_e32 v151, v151, v174
	v_add_f32_e32 v151, v154, v151
	v_add_f32_e32 v179, v155, v151
	v_rcp_f32_e32 v180, v179
	v_sub_f32_e32 v154, v179, v155
	v_add_f32_e32 v155, v172, v173
	v_sub_f32_e32 v151, v151, v154
	v_mul_f32_e32 v182, v155, v180
	v_sub_f32_e32 v154, v155, v172
	v_mul_f32_e32 v172, v179, v182
	v_fma_f32 v174, v182, v179, -v172
	v_fmac_f32_e32 v174, v182, v151
	v_sub_f32_e32 v181, v173, v154
	v_add_f32_e32 v154, v172, v174
	v_sub_f32_e32 v173, v155, v154
	v_pk_add_f32 v[176:177], v[154:155], v[172:173] neg_lo:[0,1] neg_hi:[0,1]
	v_mov_b32_e32 v175, v154
	v_pk_add_f32 v[154:155], v[176:177], v[174:175] neg_lo:[0,1] neg_hi:[0,1]
	v_cmp_neq_f32_e32 vcc, s70, v156
	v_add_f32_e32 v155, v181, v155
	v_add_f32_e32 v154, v154, v155
	v_add_f32_e32 v155, v173, v154
	v_mul_f32_e32 v181, v180, v155
	v_mul_f32_e32 v172, v179, v181
	v_fma_f32 v174, v181, v179, -v172
	v_fmac_f32_e32 v174, v181, v151
	v_sub_f32_e32 v151, v173, v155
	v_add_f32_e32 v151, v154, v151
	v_add_f32_e32 v154, v172, v174
	v_sub_f32_e32 v173, v155, v154
	v_pk_add_f32 v[176:177], v[154:155], v[172:173] neg_lo:[0,1] neg_hi:[0,1]
	v_mov_b32_e32 v175, v154
	v_pk_add_f32 v[154:155], v[176:177], v[174:175] neg_lo:[0,1] neg_hi:[0,1]
	s_nop 0
	v_add_f32_e32 v151, v151, v155
	v_add_f32_e32 v151, v154, v151
	v_add_f32_e32 v155, v182, v181
	v_add_f32_e32 v151, v173, v151
	v_sub_f32_e32 v154, v155, v182
	v_mul_f32_e32 v151, v180, v151
	v_sub_f32_e32 v154, v181, v154
	v_add_f32_e32 v172, v154, v151
	v_add_f32_e32 v174, v155, v172
	v_cvt_f32_i32_e32 v154, v178
	v_mul_f32_e32 v175, v174, v174
	v_sub_f32_e32 v155, v174, v155
	v_fmamk_f32 v151, v175, 0x3e9b6dac, v166
	v_sub_f32_e32 v155, v172, v155
	v_fmaak_f32 v151, v175, v151, 0x3f2aaada
	v_ldexp_f32 v176, v155, 1
	v_mul_f32_e32 v155, v174, v175
	v_ldexp_f32 v173, v174, 1
	v_pk_mul_f32 v[174:175], v[154:155], v[150:151]
	s_nop 0
	v_fma_f32 v172, v154, s69, -v174
	v_fmac_f32_e32 v172, 0xb102e308, v154
	v_pk_add_f32 v[154:155], v[174:175], v[172:173]
	s_nop 0
	v_sub_f32_e32 v151, v155, v173
	v_sub_f32_e32 v151, v175, v151
	v_add_f32_e32 v177, v176, v151
	v_mov_b32_e32 v176, v174
	v_pk_add_f32 v[174:175], v[154:155], v[174:175] neg_lo:[0,1] neg_hi:[0,1]
	v_pk_add_f32 v[178:179], v[154:155], v[176:177]
	v_mov_b32_e32 v173, v154
	v_mov_b32_e32 v175, v179
	v_pk_add_f32 v[180:181], v[172:173], v[174:175] neg_lo:[0,1] neg_hi:[0,1]
	v_pk_add_f32 v[172:173], v[172:173], v[174:175]
	v_mov_b32_e32 v176, v177
	v_pk_add_f32 v[174:175], v[172:173], v[154:155] op_sel:[1,0] op_sel_hi:[0,1] neg_lo:[0,1] neg_hi:[0,1]
	v_pk_add_f32 v[182:183], v[178:179], v[174:175] op_sel_hi:[1,0] neg_lo:[0,1] neg_hi:[0,1]
	v_mov_b32_e32 v178, v179
	v_mov_b32_e32 v179, v173
	v_pk_mov_b32 v[174:175], v[154:155], v[174:175] op_sel:[1,0]
	v_mov_b32_e32 v177, v154
	v_pk_add_f32 v[174:175], v[178:179], v[174:175] neg_lo:[0,1] neg_hi:[0,1]
	v_mov_b32_e32 v182, v180
	v_pk_add_f32 v[154:155], v[176:177], v[174:175] neg_lo:[0,1] neg_hi:[0,1]
	v_mov_b32_e32 v181, v173
	v_pk_add_f32 v[174:175], v[182:183], v[154:155]
	s_nop 0
	v_pk_add_f32 v[176:177], v[174:175], v[174:175] op_sel:[0,1] op_sel_hi:[1,0]
	s_nop 0
	v_pk_add_f32 v[172:173], v[172:173], v[176:177] op_sel:[1,0] op_sel_hi:[0,1]
	v_mov_b32_e32 v175, v172
	v_pk_add_f32 v[178:179], v[174:175], v[180:181] neg_lo:[0,1] neg_hi:[0,1]
	v_mov_b32_e32 v155, v176
	v_sub_f32_e32 v151, v174, v178
	v_pk_add_f32 v[154:155], v[154:155], v[178:179] neg_lo:[0,1] neg_hi:[0,1]
	v_sub_f32_e32 v151, v180, v151
	v_add_f32_e32 v151, v154, v151
	v_add_f32_e32 v151, v151, v155
	v_add_f32_e32 v151, v172, v151
	v_cndmask_b32_e32 v151, v167, v151, vcc
	v_cmp_ngt_f32_e32 vcc, -1.0, v156
	s_nop 1
	v_cndmask_b32_e32 v151, v168, v151, vcc
	v_cmp_neq_f32_e32 vcc, -1.0, v156
	s_nop 1
	v_cndmask_b32_e32 v151, v169, v151, vcc
	v_cmp_lt_f32_e64 vcc, |v156|, s71
	s_nop 1
	v_cndmask_b32_e32 v151, v151, v156, vcc
;     __device__ __forceinline__ void operator()(const f32x4 (&acc)[2][2][4][2], const Unit& u, int wr, int wc, int fr, int fq) const {
;     ...
;                     for (int m = 0; m < 4; ++m) { const int r = row0 + ai * HALF + m * 16;
;                         const f32x4 v0 = acc[ai][0][m][0], v1 = acc[ai][0][m][1]; float* dp = DT + (size_t)r * 32 + c0;
; #pragma unroll
;                         for (int i = 0; i < 4; ++i) { float x0 = v0[i] + dt_bias[c0 + i], x1 = v1[i] + dt_bias[c0 + 4 + i];
;                             dp[i] = x0 > 20.f ? x0 : log1pf(__expf(x0)); dp[4 + i] = x1 > 20.f ? x1 : log1pf(__expf(x1)); }
.LBB0_833:
	s_or_b64 exec, exec, s[24:25]
	v_or_b32_e32 v154, 48, v152
	v_ashrrev_i32_e32 v155, 31, v154
	v_lshlrev_b64 v[154:155], 7, v[154:155]
	v_add_f32_e32 v136, v72, v136
	v_lshl_add_u64 v[154:155], v[138:139], 0, v[154:155]
	v_cmp_nlt_f32_e32 vcc, s67, v136
	flat_store_dword v[154:155], v151
	s_and_saveexec_b64 s[24:25], vcc
	s_cbranch_execz .LBB0_835
	v_mul_f32_e32 v136, 0x3fb8aa3b, v136
	v_exp_f32_e32 v136, v136
	s_nop 0
	v_add_f32_e32 v151, 1.0, v136
	v_frexp_mant_f32_e32 v174, v151
	v_cvt_f64_f32_e32 v[172:173], v151
	v_add_f32_e32 v156, -1.0, v151
	v_frexp_exp_i32_f64_e32 v172, v[172:173]
	v_cmp_gt_f32_e32 vcc, s68, v174
	v_sub_f32_e32 v175, v156, v151
	v_sub_f32_e32 v156, v136, v156
	v_subbrev_co_u32_e32 v180, vcc, 0, v172, vcc
	v_add_f32_e32 v175, 1.0, v175
	v_sub_u32_e32 v172, 0, v180
	v_add_f32_e32 v156, v156, v175
	v_ldexp_f32 v151, v151, v172
	v_ldexp_f32 v156, v156, v172
	v_add_f32_e32 v172, -1.0, v151
	v_add_f32_e32 v173, 1.0, v172
	v_sub_f32_e32 v173, v151, v173
	v_add_f32_e32 v174, v156, v173
	v_add_f32_e32 v173, 1.0, v151
	v_add_f32_e32 v175, -1.0, v173
	v_sub_f32_e32 v151, v151, v175
	v_add_f32_e32 v151, v156, v151
	v_add_f32_e32 v156, v173, v151
	v_rcp_f32_e32 v181, v156
	v_sub_f32_e32 v173, v156, v173
	v_sub_f32_e32 v151, v151, v173
	v_add_f32_e32 v173, v172, v174
	v_sub_f32_e32 v172, v173, v172
	v_mul_f32_e32 v183, v173, v181
	v_sub_f32_e32 v182, v174, v172
	v_mul_f32_e32 v174, v156, v183
	v_fma_f32 v176, v183, v156, -v174
	v_fmac_f32_e32 v176, v183, v151
	v_add_f32_e32 v172, v174, v176
	v_sub_f32_e32 v175, v173, v172
	v_pk_add_f32 v[178:179], v[172:173], v[174:175] neg_lo:[0,1] neg_hi:[0,1]
	v_mov_b32_e32 v177, v172
	v_pk_add_f32 v[172:173], v[178:179], v[176:177] neg_lo:[0,1] neg_hi:[0,1]
	v_cmp_neq_f32_e32 vcc, s70, v136
	v_add_f32_e32 v173, v182, v173
	v_add_f32_e32 v172, v172, v173
	v_add_f32_e32 v173, v175, v172
	v_mul_f32_e32 v182, v181, v173
	v_mul_f32_e32 v174, v156, v182
	v_fma_f32 v176, v182, v156, -v174
	v_fmac_f32_e32 v176, v182, v151
	v_sub_f32_e32 v151, v175, v173
	v_add_f32_e32 v151, v172, v151
	v_add_f32_e32 v172, v174, v176
	v_sub_f32_e32 v175, v173, v172
	v_pk_add_f32 v[178:179], v[172:173], v[174:175] neg_lo:[0,1] neg_hi:[0,1]
	v_mov_b32_e32 v177, v172
	v_pk_add_f32 v[172:173], v[178:179], v[176:177] neg_lo:[0,1] neg_hi:[0,1]
	v_add_f32_e32 v156, v183, v182
	v_add_f32_e32 v151, v151, v173
	v_add_f32_e32 v151, v172, v151
	v_add_f32_e32 v151, v175, v151
	v_sub_f32_e32 v172, v156, v183
	v_mul_f32_e32 v151, v181, v151
	v_sub_f32_e32 v172, v182, v172
	v_add_f32_e32 v173, v172, v151
	v_add_f32_e32 v174, v156, v173
	v_cvt_f32_i32_e32 v172, v180
	v_mul_f32_e32 v176, v174, v174
	v_fmamk_f32 v151, v176, 0x3e9b6dac, v166
	v_sub_f32_e32 v156, v174, v156
	v_fmaak_f32 v151, v176, v151, 0x3f2aaada
	v_sub_f32_e32 v156, v173, v156
	v_mul_f32_e32 v173, v174, v176
	v_pk_mul_f32 v[176:177], v[172:173], v[150:151]
	v_ldexp_f32 v175, v174, 1
	v_fma_f32 v174, v172, s69, -v176
	v_fmac_f32_e32 v174, 0xb102e308, v172
	v_pk_add_f32 v[172:173], v[176:177], v[174:175]
	v_ldexp_f32 v156, v156, 1
	v_sub_f32_e32 v151, v173, v175
	v_sub_f32_e32 v151, v177, v151
	v_add_f32_e32 v179, v156, v151
	v_mov_b32_e32 v178, v176
	v_pk_add_f32 v[176:177], v[172:173], v[176:177] neg_lo:[0,1] neg_hi:[0,1]
	v_pk_add_f32 v[180:181], v[172:173], v[178:179]
	v_mov_b32_e32 v175, v172
	v_mov_b32_e32 v177, v181
	v_pk_add_f32 v[182:183], v[174:175], v[176:177] neg_lo:[0,1] neg_hi:[0,1]
	v_pk_add_f32 v[174:175], v[174:175], v[176:177]
	v_mov_b32_e32 v178, v179
	v_pk_add_f32 v[176:177], v[174:175], v[172:173] op_sel:[1,0] op_sel_hi:[0,1] neg_lo:[0,1] neg_hi:[0,1]
	v_pk_add_f32 v[184:185], v[180:181], v[176:177] op_sel_hi:[1,0] neg_lo:[0,1] neg_hi:[0,1]
	v_mov_b32_e32 v180, v181
	v_mov_b32_e32 v181, v175
	v_pk_mov_b32 v[176:177], v[172:173], v[176:177] op_sel:[1,0]
	v_mov_b32_e32 v179, v172
	v_pk_add_f32 v[176:177], v[180:181], v[176:177] neg_lo:[0,1] neg_hi:[0,1]
	v_mov_b32_e32 v184, v182
	v_pk_add_f32 v[172:173], v[178:179], v[176:177] neg_lo:[0,1] neg_hi:[0,1]
	v_mov_b32_e32 v183, v175
	v_pk_add_f32 v[176:177], v[184:185], v[172:173]
	s_nop 0
	v_pk_add_f32 v[178:179], v[176:177], v[176:177] op_sel:[0,1] op_sel_hi:[1,0]
	s_nop 0
	v_pk_add_f32 v[174:175], v[174:175], v[178:179] op_sel:[1,0] op_sel_hi:[0,1]
	v_mov_b32_e32 v177, v174
	v_pk_add_f32 v[180:181], v[176:177], v[182:183] neg_lo:[0,1] neg_hi:[0,1]
	v_mov_b32_e32 v173, v178
	v_sub_f32_e32 v151, v176, v180
	v_pk_add_f32 v[172:173], v[172:173], v[180:181] neg_lo:[0,1] neg_hi:[0,1]
	v_sub_f32_e32 v151, v182, v151
	v_add_f32_e32 v151, v172, v151
	v_add_f32_e32 v151, v151, v173
	v_add_f32_e32 v151, v174, v151
	v_cndmask_b32_e32 v151, v167, v151, vcc
	v_cmp_ngt_f32_e32 vcc, -1.0, v136
	s_nop 1
	v_cndmask_b32_e32 v151, v168, v151, vcc
	v_cmp_neq_f32_e32 vcc, -1.0, v136
	s_nop 1
	v_cndmask_b32_e32 v151, v169, v151, vcc
	v_cmp_lt_f32_e64 vcc, |v136|, s71
	s_nop 1
	v_cndmask_b32_e32 v136, v151, v136, vcc
;     __device__ __forceinline__ void operator()(const f32x4 (&acc)[2][2][4][2], const Unit& u, int wr, int wc, int fr, int fq) const {
;     ...
;                         for (int i = 0; i < 4; ++i) { float x0 = v0[i] + dt_bias[c0 + i], x1 = v1[i] + dt_bias[c0 + 4 + i];
;                             dp[i] = x0 > 20.f ? x0 : log1pf(__expf(x0)); dp[4 + i] = x1 > 20.f ? x1 : log1pf(__expf(x1)); }
.LBB0_835:
	s_or_b64 exec, exec, s[24:25]
	flat_store_dword v[154:155], v136 offset:16
	v_mov_b32_e32 v136, v201
	v_add_f32_e32 v151, v77, v136
	v_mov_b32_e32 v136, v205
	v_cmp_nlt_f32_e32 vcc, s67, v151
	s_and_saveexec_b64 s[24:25], vcc
	s_cbranch_execz .LBB0_837
	v_mul_f32_e32 v151, 0x3fb8aa3b, v151
	v_exp_f32_e32 v156, v151
	s_nop 0
	v_add_f32_e32 v151, 1.0, v156
	v_frexp_mant_f32_e32 v175, v151
	v_cvt_f64_f32_e32 v[172:173], v151
	v_add_f32_e32 v174, -1.0, v151
	v_frexp_exp_i32_f64_e32 v172, v[172:173]
	v_cmp_gt_f32_e32 vcc, s68, v175
	v_sub_f32_e32 v176, v174, v151
	v_sub_f32_e32 v174, v156, v174
	v_subbrev_co_u32_e32 v180, vcc, 0, v172, vcc
	v_add_f32_e32 v176, 1.0, v176
	v_sub_u32_e32 v172, 0, v180
	v_add_f32_e32 v174, v174, v176
	v_ldexp_f32 v151, v151, v172
	v_ldexp_f32 v172, v174, v172
	v_add_f32_e32 v174, -1.0, v151
	v_add_f32_e32 v173, 1.0, v174
	v_sub_f32_e32 v173, v151, v173
	v_add_f32_e32 v175, v172, v173
	v_add_f32_e32 v173, 1.0, v151
	v_add_f32_e32 v176, -1.0, v173
	v_sub_f32_e32 v151, v151, v176
	v_add_f32_e32 v151, v172, v151
	v_add_f32_e32 v181, v173, v151
	v_rcp_f32_e32 v182, v181
	v_sub_f32_e32 v172, v181, v173
	v_add_f32_e32 v173, v174, v175
	v_sub_f32_e32 v151, v151, v172
	v_mul_f32_e32 v184, v173, v182
	v_sub_f32_e32 v172, v173, v174
	v_mul_f32_e32 v174, v181, v184
	v_fma_f32 v176, v184, v181, -v174
	v_fmac_f32_e32 v176, v184, v151
	v_sub_f32_e32 v183, v175, v172
	v_add_f32_e32 v172, v174, v176
	v_sub_f32_e32 v175, v173, v172
	v_pk_add_f32 v[178:179], v[172:173], v[174:175] neg_lo:[0,1] neg_hi:[0,1]
	v_mov_b32_e32 v177, v172
	v_pk_add_f32 v[172:173], v[178:179], v[176:177] neg_lo:[0,1] neg_hi:[0,1]
	v_cmp_neq_f32_e32 vcc, s70, v156
	v_add_f32_e32 v173, v183, v173
	v_add_f32_e32 v172, v172, v173
	v_add_f32_e32 v173, v175, v172
	v_mul_f32_e32 v183, v182, v173
	v_mul_f32_e32 v174, v181, v183
	v_fma_f32 v176, v183, v181, -v174
	v_fmac_f32_e32 v176, v183, v151
	v_sub_f32_e32 v151, v175, v173
	v_add_f32_e32 v151, v172, v151
	v_add_f32_e32 v172, v174, v176
	v_sub_f32_e32 v175, v173, v172
	v_pk_add_f32 v[178:179], v[172:173], v[174:175] neg_lo:[0,1] neg_hi:[0,1]
	v_mov_b32_e32 v177, v172
	v_pk_add_f32 v[172:173], v[178:179], v[176:177] neg_lo:[0,1] neg_hi:[0,1]
	s_nop 0
	v_add_f32_e32 v151, v151, v173
	v_add_f32_e32 v151, v172, v151
	v_add_f32_e32 v173, v184, v183
	v_add_f32_e32 v151, v175, v151
	v_sub_f32_e32 v172, v173, v184
	v_mul_f32_e32 v151, v182, v151
	v_sub_f32_e32 v172, v183, v172
	v_add_f32_e32 v174, v172, v151
	v_add_f32_e32 v176, v173, v174
	v_cvt_f32_i32_e32 v172, v180
	v_mul_f32_e32 v177, v176, v176
	v_sub_f32_e32 v173, v176, v173
	v_fmamk_f32 v151, v177, 0x3e9b6dac, v166
	v_sub_f32_e32 v173, v174, v173
	v_fmaak_f32 v151, v177, v151, 0x3f2aaada
	v_ldexp_f32 v178, v173, 1
	v_mul_f32_e32 v173, v176, v177
	v_ldexp_f32 v175, v176, 1
	v_pk_mul_f32 v[176:177], v[172:173], v[150:151]
	s_nop 0
	v_fma_f32 v174, v172, s69, -v176
	v_fmac_f32_e32 v174, 0xb102e308, v172
	v_pk_add_f32 v[172:173], v[176:177], v[174:175]
	s_nop 0
	v_sub_f32_e32 v151, v173, v175
	v_sub_f32_e32 v151, v177, v151
	v_add_f32_e32 v179, v178, v151
	v_mov_b32_e32 v178, v176
	v_pk_add_f32 v[176:177], v[172:173], v[176:177] neg_lo:[0,1] neg_hi:[0,1]
	v_pk_add_f32 v[180:181], v[172:173], v[178:179]
	v_mov_b32_e32 v175, v172
	v_mov_b32_e32 v177, v181
	v_pk_add_f32 v[182:183], v[174:175], v[176:177] neg_lo:[0,1] neg_hi:[0,1]
	v_pk_add_f32 v[174:175], v[174:175], v[176:177]
	v_mov_b32_e32 v178, v179
	v_pk_add_f32 v[176:177], v[174:175], v[172:173] op_sel:[1,0] op_sel_hi:[0,1] neg_lo:[0,1] neg_hi:[0,1]
	v_pk_add_f32 v[184:185], v[180:181], v[176:177] op_sel_hi:[1,0] neg_lo:[0,1] neg_hi:[0,1]
	v_mov_b32_e32 v180, v181
	v_mov_b32_e32 v181, v175
	v_pk_mov_b32 v[176:177], v[172:173], v[176:177] op_sel:[1,0]
	v_mov_b32_e32 v179, v172
	v_pk_add_f32 v[176:177], v[180:181], v[176:177] neg_lo:[0,1] neg_hi:[0,1]
	v_mov_b32_e32 v184, v182
	v_pk_add_f32 v[172:173], v[178:179], v[176:177] neg_lo:[0,1] neg_hi:[0,1]
	v_mov_b32_e32 v183, v175
	v_pk_add_f32 v[176:177], v[184:185], v[172:173]
	s_nop 0
	v_pk_add_f32 v[178:179], v[176:177], v[176:177] op_sel:[0,1] op_sel_hi:[1,0]
	s_nop 0
	v_pk_add_f32 v[174:175], v[174:175], v[178:179] op_sel:[1,0] op_sel_hi:[0,1]
	v_mov_b32_e32 v177, v174
	v_pk_add_f32 v[180:181], v[176:177], v[182:183] neg_lo:[0,1] neg_hi:[0,1]
	v_mov_b32_e32 v173, v178
	v_sub_f32_e32 v151, v176, v180
	v_pk_add_f32 v[172:173], v[172:173], v[180:181] neg_lo:[0,1] neg_hi:[0,1]
	v_sub_f32_e32 v151, v182, v151
	v_add_f32_e32 v151, v172, v151
	v_add_f32_e32 v151, v151, v173
	v_add_f32_e32 v151, v174, v151
	v_cndmask_b32_e32 v151, v167, v151, vcc
	v_cmp_ngt_f32_e32 vcc, -1.0, v156
	s_nop 1
	v_cndmask_b32_e32 v151, v168, v151, vcc
	v_cmp_neq_f32_e32 vcc, -1.0, v156
	s_nop 1
	v_cndmask_b32_e32 v151, v169, v151, vcc
	v_cmp_lt_f32_e64 vcc, |v156|, s71
	s_nop 1
	v_cndmask_b32_e32 v151, v151, v156, vcc
;     __device__ __forceinline__ void operator()(const f32x4 (&acc)[2][2][4][2], const Unit& u, int wr, int wc, int fr, int fq) const {
;     ...
;                         for (int i = 0; i < 4; ++i) { float x0 = v0[i] + dt_bias[c0 + i], x1 = v1[i] + dt_bias[c0 + 4 + i];
;                             dp[i] = x0 > 20.f ? x0 : log1pf(__expf(x0)); dp[4 + i] = x1 > 20.f ? x1 : log1pf(__expf(x1)); }
.LBB0_837:
	s_or_b64 exec, exec, s[24:25]
	v_add_f32_e32 v136, v73, v136
	v_cmp_nlt_f32_e32 vcc, s67, v136
	flat_store_dword v[154:155], v151 offset:4
	s_and_saveexec_b64 s[24:25], vcc
	s_cbranch_execz .LBB0_839
	v_mul_f32_e32 v136, 0x3fb8aa3b, v136
	v_exp_f32_e32 v136, v136
	s_nop 0
	v_add_f32_e32 v151, 1.0, v136
	v_frexp_mant_f32_e32 v174, v151
	v_cvt_f64_f32_e32 v[172:173], v151
	v_add_f32_e32 v156, -1.0, v151
	v_frexp_exp_i32_f64_e32 v172, v[172:173]
	v_cmp_gt_f32_e32 vcc, s68, v174
	v_sub_f32_e32 v175, v156, v151
	v_sub_f32_e32 v156, v136, v156
	v_subbrev_co_u32_e32 v180, vcc, 0, v172, vcc
	v_add_f32_e32 v175, 1.0, v175
	v_sub_u32_e32 v172, 0, v180
	v_add_f32_e32 v156, v156, v175
	v_ldexp_f32 v151, v151, v172
	v_ldexp_f32 v156, v156, v172
	v_add_f32_e32 v172, -1.0, v151
	v_add_f32_e32 v173, 1.0, v172
	v_sub_f32_e32 v173, v151, v173
	v_add_f32_e32 v174, v156, v173
	v_add_f32_e32 v173, 1.0, v151
	v_add_f32_e32 v175, -1.0, v173
	v_sub_f32_e32 v151, v151, v175
	v_add_f32_e32 v151, v156, v151
	v_add_f32_e32 v156, v173, v151
	v_rcp_f32_e32 v181, v156
	v_sub_f32_e32 v173, v156, v173
	v_sub_f32_e32 v151, v151, v173
	v_add_f32_e32 v173, v172, v174
	v_sub_f32_e32 v172, v173, v172
	v_mul_f32_e32 v183, v173, v181
	v_sub_f32_e32 v182, v174, v172
	v_mul_f32_e32 v174, v156, v183
	v_fma_f32 v176, v183, v156, -v174
	v_fmac_f32_e32 v176, v183, v151
	v_add_f32_e32 v172, v174, v176
	v_sub_f32_e32 v175, v173, v172
	v_pk_add_f32 v[178:179], v[172:173], v[174:175] neg_lo:[0,1] neg_hi:[0,1]
	v_mov_b32_e32 v177, v172
	v_pk_add_f32 v[172:173], v[178:179], v[176:177] neg_lo:[0,1] neg_hi:[0,1]
	v_cmp_neq_f32_e32 vcc, s70, v136
	v_add_f32_e32 v173, v182, v173
	v_add_f32_e32 v172, v172, v173
	v_add_f32_e32 v173, v175, v172
	v_mul_f32_e32 v182, v181, v173
	v_mul_f32_e32 v174, v156, v182
	v_fma_f32 v176, v182, v156, -v174
	v_fmac_f32_e32 v176, v182, v151
	v_sub_f32_e32 v151, v175, v173
	v_add_f32_e32 v151, v172, v151
	v_add_f32_e32 v172, v174, v176
	v_sub_f32_e32 v175, v173, v172
	v_pk_add_f32 v[178:179], v[172:173], v[174:175] neg_lo:[0,1] neg_hi:[0,1]
	v_mov_b32_e32 v177, v172
	v_pk_add_f32 v[172:173], v[178:179], v[176:177] neg_lo:[0,1] neg_hi:[0,1]
	v_add_f32_e32 v156, v183, v182
	v_add_f32_e32 v151, v151, v173
	v_add_f32_e32 v151, v172, v151
	v_add_f32_e32 v151, v175, v151
	v_sub_f32_e32 v172, v156, v183
	v_mul_f32_e32 v151, v181, v151
	v_sub_f32_e32 v172, v182, v172
	v_add_f32_e32 v173, v172, v151
	v_add_f32_e32 v174, v156, v173
	v_cvt_f32_i32_e32 v172, v180
	v_mul_f32_e32 v176, v174, v174
	v_fmamk_f32 v151, v176, 0x3e9b6dac, v166
	v_sub_f32_e32 v156, v174, v156
	v_fmaak_f32 v151, v176, v151, 0x3f2aaada
	v_sub_f32_e32 v156, v173, v156
	v_mul_f32_e32 v173, v174, v176
	v_pk_mul_f32 v[176:177], v[172:173], v[150:151]
	v_ldexp_f32 v175, v174, 1
	v_fma_f32 v174, v172, s69, -v176
	v_fmac_f32_e32 v174, 0xb102e308, v172
	v_pk_add_f32 v[172:173], v[176:177], v[174:175]
	v_ldexp_f32 v156, v156, 1
	v_sub_f32_e32 v151, v173, v175
	v_sub_f32_e32 v151, v177, v151
	v_add_f32_e32 v179, v156, v151
	v_mov_b32_e32 v178, v176
	v_pk_add_f32 v[176:177], v[172:173], v[176:177] neg_lo:[0,1] neg_hi:[0,1]
	v_pk_add_f32 v[180:181], v[172:173], v[178:179]
	v_mov_b32_e32 v175, v172
	v_mov_b32_e32 v177, v181
	v_pk_add_f32 v[182:183], v[174:175], v[176:177] neg_lo:[0,1] neg_hi:[0,1]
	v_pk_add_f32 v[174:175], v[174:175], v[176:177]
	v_mov_b32_e32 v178, v179
	v_pk_add_f32 v[176:177], v[174:175], v[172:173] op_sel:[1,0] op_sel_hi:[0,1] neg_lo:[0,1] neg_hi:[0,1]
	v_pk_add_f32 v[184:185], v[180:181], v[176:177] op_sel_hi:[1,0] neg_lo:[0,1] neg_hi:[0,1]
	v_mov_b32_e32 v180, v181
	v_mov_b32_e32 v181, v175
	v_pk_mov_b32 v[176:177], v[172:173], v[176:177] op_sel:[1,0]
	v_mov_b32_e32 v179, v172
	v_pk_add_f32 v[176:177], v[180:181], v[176:177] neg_lo:[0,1] neg_hi:[0,1]
	v_mov_b32_e32 v184, v182
	v_pk_add_f32 v[172:173], v[178:179], v[176:177] neg_lo:[0,1] neg_hi:[0,1]
	v_mov_b32_e32 v183, v175
	v_pk_add_f32 v[176:177], v[184:185], v[172:173]
	s_nop 0
	v_pk_add_f32 v[178:179], v[176:177], v[176:177] op_sel:[0,1] op_sel_hi:[1,0]
	s_nop 0
	v_pk_add_f32 v[174:175], v[174:175], v[178:179] op_sel:[1,0] op_sel_hi:[0,1]
	v_mov_b32_e32 v177, v174
	v_pk_add_f32 v[180:181], v[176:177], v[182:183] neg_lo:[0,1] neg_hi:[0,1]
	v_mov_b32_e32 v173, v178
	v_sub_f32_e32 v151, v176, v180
	v_pk_add_f32 v[172:173], v[172:173], v[180:181] neg_lo:[0,1] neg_hi:[0,1]
	v_sub_f32_e32 v151, v182, v151
	v_add_f32_e32 v151, v172, v151
	v_add_f32_e32 v151, v151, v173
	v_add_f32_e32 v151, v174, v151
	v_cndmask_b32_e32 v151, v167, v151, vcc
	v_cmp_ngt_f32_e32 vcc, -1.0, v136
	s_nop 1
	v_cndmask_b32_e32 v151, v168, v151, vcc
	v_cmp_neq_f32_e32 vcc, -1.0, v136
	s_nop 1
	v_cndmask_b32_e32 v151, v169, v151, vcc
	v_cmp_lt_f32_e64 vcc, |v136|, s71
	s_nop 1
	v_cndmask_b32_e32 v136, v151, v136, vcc
;     __device__ __forceinline__ void operator()(const f32x4 (&acc)[2][2][4][2], const Unit& u, int wr, int wc, int fr, int fq) const {
;     ...
;                         for (int i = 0; i < 4; ++i) { float x0 = v0[i] + dt_bias[c0 + i], x1 = v1[i] + dt_bias[c0 + 4 + i];
;                             dp[i] = x0 > 20.f ? x0 : log1pf(__expf(x0)); dp[4 + i] = x1 > 20.f ? x1 : log1pf(__expf(x1)); }
.LBB0_839:
	s_or_b64 exec, exec, s[24:25]
	flat_store_dword v[154:155], v136 offset:20
	v_mov_b32_e32 v136, v202
	v_add_f32_e32 v151, v78, v136
	v_mov_b32_e32 v136, v206
	v_cmp_nlt_f32_e32 vcc, s67, v151
	s_and_saveexec_b64 s[24:25], vcc
	s_cbranch_execz .LBB0_841
	v_mul_f32_e32 v151, 0x3fb8aa3b, v151
	v_exp_f32_e32 v156, v151
	s_nop 0
	v_add_f32_e32 v151, 1.0, v156
	v_frexp_mant_f32_e32 v175, v151
	v_cvt_f64_f32_e32 v[172:173], v151
	v_add_f32_e32 v174, -1.0, v151
	v_frexp_exp_i32_f64_e32 v172, v[172:173]
	v_cmp_gt_f32_e32 vcc, s68, v175
	v_sub_f32_e32 v176, v174, v151
	v_sub_f32_e32 v174, v156, v174
	v_subbrev_co_u32_e32 v180, vcc, 0, v172, vcc
	v_add_f32_e32 v176, 1.0, v176
	v_sub_u32_e32 v172, 0, v180
	v_add_f32_e32 v174, v174, v176
	v_ldexp_f32 v151, v151, v172
	v_ldexp_f32 v172, v174, v172
	v_add_f32_e32 v174, -1.0, v151
	v_add_f32_e32 v173, 1.0, v174
	v_sub_f32_e32 v173, v151, v173
	v_add_f32_e32 v175, v172, v173
	v_add_f32_e32 v173, 1.0, v151
	v_add_f32_e32 v176, -1.0, v173
	v_sub_f32_e32 v151, v151, v176
	v_add_f32_e32 v151, v172, v151
	v_add_f32_e32 v181, v173, v151
	v_rcp_f32_e32 v182, v181
	v_sub_f32_e32 v172, v181, v173
	v_add_f32_e32 v173, v174, v175
	v_sub_f32_e32 v151, v151, v172
	v_mul_f32_e32 v184, v173, v182
	v_sub_f32_e32 v172, v173, v174
	v_mul_f32_e32 v174, v181, v184
	v_fma_f32 v176, v184, v181, -v174
	v_fmac_f32_e32 v176, v184, v151
	v_sub_f32_e32 v183, v175, v172
	v_add_f32_e32 v172, v174, v176
	v_sub_f32_e32 v175, v173, v172
	v_pk_add_f32 v[178:179], v[172:173], v[174:175] neg_lo:[0,1] neg_hi:[0,1]
	v_mov_b32_e32 v177, v172
	v_pk_add_f32 v[172:173], v[178:179], v[176:177] neg_lo:[0,1] neg_hi:[0,1]
	v_cmp_neq_f32_e32 vcc, s70, v156
	v_add_f32_e32 v173, v183, v173
	v_add_f32_e32 v172, v172, v173
	v_add_f32_e32 v173, v175, v172
	v_mul_f32_e32 v183, v182, v173
	v_mul_f32_e32 v174, v181, v183
	v_fma_f32 v176, v183, v181, -v174
	v_fmac_f32_e32 v176, v183, v151
	v_sub_f32_e32 v151, v175, v173
	v_add_f32_e32 v151, v172, v151
	v_add_f32_e32 v172, v174, v176
	v_sub_f32_e32 v175, v173, v172
	v_pk_add_f32 v[178:179], v[172:173], v[174:175] neg_lo:[0,1] neg_hi:[0,1]
	v_mov_b32_e32 v177, v172
	v_pk_add_f32 v[172:173], v[178:179], v[176:177] neg_lo:[0,1] neg_hi:[0,1]
	s_nop 0
	v_add_f32_e32 v151, v151, v173
	v_add_f32_e32 v151, v172, v151
	v_add_f32_e32 v173, v184, v183
	v_add_f32_e32 v151, v175, v151
	v_sub_f32_e32 v172, v173, v184
	v_mul_f32_e32 v151, v182, v151
	v_sub_f32_e32 v172, v183, v172
	v_add_f32_e32 v174, v172, v151
	v_add_f32_e32 v176, v173, v174
	v_cvt_f32_i32_e32 v172, v180
	v_mul_f32_e32 v177, v176, v176
	v_sub_f32_e32 v173, v176, v173
	v_fmamk_f32 v151, v177, 0x3e9b6dac, v166
	v_sub_f32_e32 v173, v174, v173
	v_fmaak_f32 v151, v177, v151, 0x3f2aaada
	v_ldexp_f32 v178, v173, 1
	v_mul_f32_e32 v173, v176, v177
	v_ldexp_f32 v175, v176, 1
	v_pk_mul_f32 v[176:177], v[172:173], v[150:151]
	s_nop 0
	v_fma_f32 v174, v172, s69, -v176
	v_fmac_f32_e32 v174, 0xb102e308, v172
	v_pk_add_f32 v[172:173], v[176:177], v[174:175]
	s_nop 0
	v_sub_f32_e32 v151, v173, v175
	v_sub_f32_e32 v151, v177, v151
	v_add_f32_e32 v179, v178, v151
	v_mov_b32_e32 v178, v176
	v_pk_add_f32 v[176:177], v[172:173], v[176:177] neg_lo:[0,1] neg_hi:[0,1]
	v_pk_add_f32 v[180:181], v[172:173], v[178:179]
	v_mov_b32_e32 v175, v172
	v_mov_b32_e32 v177, v181
	v_pk_add_f32 v[182:183], v[174:175], v[176:177] neg_lo:[0,1] neg_hi:[0,1]
	v_pk_add_f32 v[174:175], v[174:175], v[176:177]
	v_mov_b32_e32 v178, v179
	v_pk_add_f32 v[176:177], v[174:175], v[172:173] op_sel:[1,0] op_sel_hi:[0,1] neg_lo:[0,1] neg_hi:[0,1]
	v_pk_add_f32 v[184:185], v[180:181], v[176:177] op_sel_hi:[1,0] neg_lo:[0,1] neg_hi:[0,1]
	v_mov_b32_e32 v180, v181
	v_mov_b32_e32 v181, v175
	v_pk_mov_b32 v[176:177], v[172:173], v[176:177] op_sel:[1,0]
	v_mov_b32_e32 v179, v172
	v_pk_add_f32 v[176:177], v[180:181], v[176:177] neg_lo:[0,1] neg_hi:[0,1]
	v_mov_b32_e32 v184, v182
	v_pk_add_f32 v[172:173], v[178:179], v[176:177] neg_lo:[0,1] neg_hi:[0,1]
	v_mov_b32_e32 v183, v175
	v_pk_add_f32 v[176:177], v[184:185], v[172:173]
	s_nop 0
	v_pk_add_f32 v[178:179], v[176:177], v[176:177] op_sel:[0,1] op_sel_hi:[1,0]
	s_nop 0
	v_pk_add_f32 v[174:175], v[174:175], v[178:179] op_sel:[1,0] op_sel_hi:[0,1]
	v_mov_b32_e32 v177, v174
	v_pk_add_f32 v[180:181], v[176:177], v[182:183] neg_lo:[0,1] neg_hi:[0,1]
	v_mov_b32_e32 v173, v178
	v_sub_f32_e32 v151, v176, v180
	v_pk_add_f32 v[172:173], v[172:173], v[180:181] neg_lo:[0,1] neg_hi:[0,1]
	v_sub_f32_e32 v151, v182, v151
	v_add_f32_e32 v151, v172, v151
	v_add_f32_e32 v151, v151, v173
	v_add_f32_e32 v151, v174, v151
	v_cndmask_b32_e32 v151, v167, v151, vcc
	v_cmp_ngt_f32_e32 vcc, -1.0, v156
	s_nop 1
	v_cndmask_b32_e32 v151, v168, v151, vcc
	v_cmp_neq_f32_e32 vcc, -1.0, v156
	s_nop 1
	v_cndmask_b32_e32 v151, v169, v151, vcc
	v_cmp_lt_f32_e64 vcc, |v156|, s71
	s_nop 1
	v_cndmask_b32_e32 v151, v151, v156, vcc
;     __device__ __forceinline__ void operator()(const f32x4 (&acc)[2][2][4][2], const Unit& u, int wr, int wc, int fr, int fq) const {
;     ...
;                         for (int i = 0; i < 4; ++i) { float x0 = v0[i] + dt_bias[c0 + i], x1 = v1[i] + dt_bias[c0 + 4 + i];
;                             dp[i] = x0 > 20.f ? x0 : log1pf(__expf(x0)); dp[4 + i] = x1 > 20.f ? x1 : log1pf(__expf(x1)); }
.LBB0_841:
	s_or_b64 exec, exec, s[24:25]
	v_add_f32_e32 v136, v74, v136
	v_cmp_nlt_f32_e32 vcc, s67, v136
	flat_store_dword v[154:155], v151 offset:8
	s_and_saveexec_b64 s[24:25], vcc
	s_cbranch_execz .LBB0_843
	v_mul_f32_e32 v136, 0x3fb8aa3b, v136
	v_exp_f32_e32 v136, v136
	s_nop 0
	v_add_f32_e32 v151, 1.0, v136
	v_frexp_mant_f32_e32 v174, v151
	v_cvt_f64_f32_e32 v[172:173], v151
	v_add_f32_e32 v156, -1.0, v151
	v_frexp_exp_i32_f64_e32 v172, v[172:173]
	v_cmp_gt_f32_e32 vcc, s68, v174
	v_sub_f32_e32 v175, v156, v151
	v_sub_f32_e32 v156, v136, v156
	v_subbrev_co_u32_e32 v180, vcc, 0, v172, vcc
	v_add_f32_e32 v175, 1.0, v175
	v_sub_u32_e32 v172, 0, v180
	v_add_f32_e32 v156, v156, v175
	v_ldexp_f32 v151, v151, v172
	v_ldexp_f32 v156, v156, v172
	v_add_f32_e32 v172, -1.0, v151
	v_add_f32_e32 v173, 1.0, v172
	v_sub_f32_e32 v173, v151, v173
	v_add_f32_e32 v174, v156, v173
	v_add_f32_e32 v173, 1.0, v151
	v_add_f32_e32 v175, -1.0, v173
	v_sub_f32_e32 v151, v151, v175
	v_add_f32_e32 v151, v156, v151
	v_add_f32_e32 v156, v173, v151
	v_rcp_f32_e32 v181, v156
	v_sub_f32_e32 v173, v156, v173
	v_sub_f32_e32 v151, v151, v173
	v_add_f32_e32 v173, v172, v174
	v_sub_f32_e32 v172, v173, v172
	v_mul_f32_e32 v183, v173, v181
	v_sub_f32_e32 v182, v174, v172
	v_mul_f32_e32 v174, v156, v183
	v_fma_f32 v176, v183, v156, -v174
	v_fmac_f32_e32 v176, v183, v151
	v_add_f32_e32 v172, v174, v176
	v_sub_f32_e32 v175, v173, v172
	v_pk_add_f32 v[178:179], v[172:173], v[174:175] neg_lo:[0,1] neg_hi:[0,1]
	v_mov_b32_e32 v177, v172
	v_pk_add_f32 v[172:173], v[178:179], v[176:177] neg_lo:[0,1] neg_hi:[0,1]
	v_cmp_neq_f32_e32 vcc, s70, v136
	v_add_f32_e32 v173, v182, v173
	v_add_f32_e32 v172, v172, v173
	v_add_f32_e32 v173, v175, v172
	v_mul_f32_e32 v182, v181, v173
	v_mul_f32_e32 v174, v156, v182
	v_fma_f32 v176, v182, v156, -v174
	v_fmac_f32_e32 v176, v182, v151
	v_sub_f32_e32 v151, v175, v173
	v_add_f32_e32 v151, v172, v151
	v_add_f32_e32 v172, v174, v176
	v_sub_f32_e32 v175, v173, v172
	v_pk_add_f32 v[178:179], v[172:173], v[174:175] neg_lo:[0,1] neg_hi:[0,1]
	v_mov_b32_e32 v177, v172
	v_pk_add_f32 v[172:173], v[178:179], v[176:177] neg_lo:[0,1] neg_hi:[0,1]
	v_add_f32_e32 v156, v183, v182
	v_add_f32_e32 v151, v151, v173
	v_add_f32_e32 v151, v172, v151
	v_add_f32_e32 v151, v175, v151
	v_sub_f32_e32 v172, v156, v183
	v_mul_f32_e32 v151, v181, v151
	v_sub_f32_e32 v172, v182, v172
	v_add_f32_e32 v173, v172, v151
	v_add_f32_e32 v174, v156, v173
	v_cvt_f32_i32_e32 v172, v180
	v_mul_f32_e32 v176, v174, v174
	v_fmamk_f32 v151, v176, 0x3e9b6dac, v166
	v_sub_f32_e32 v156, v174, v156
	v_fmaak_f32 v151, v176, v151, 0x3f2aaada
	v_sub_f32_e32 v156, v173, v156
	v_mul_f32_e32 v173, v174, v176
	v_pk_mul_f32 v[176:177], v[172:173], v[150:151]
	v_ldexp_f32 v175, v174, 1
	v_fma_f32 v174, v172, s69, -v176
	v_fmac_f32_e32 v174, 0xb102e308, v172
	v_pk_add_f32 v[172:173], v[176:177], v[174:175]
	v_ldexp_f32 v156, v156, 1
	v_sub_f32_e32 v151, v173, v175
	v_sub_f32_e32 v151, v177, v151
	v_add_f32_e32 v179, v156, v151
	v_mov_b32_e32 v178, v176
	v_pk_add_f32 v[176:177], v[172:173], v[176:177] neg_lo:[0,1] neg_hi:[0,1]
	v_pk_add_f32 v[180:181], v[172:173], v[178:179]
	v_mov_b32_e32 v175, v172
	v_mov_b32_e32 v177, v181
	v_pk_add_f32 v[182:183], v[174:175], v[176:177] neg_lo:[0,1] neg_hi:[0,1]
	v_pk_add_f32 v[174:175], v[174:175], v[176:177]
	v_mov_b32_e32 v178, v179
	v_pk_add_f32 v[176:177], v[174:175], v[172:173] op_sel:[1,0] op_sel_hi:[0,1] neg_lo:[0,1] neg_hi:[0,1]
	v_pk_add_f32 v[184:185], v[180:181], v[176:177] op_sel_hi:[1,0] neg_lo:[0,1] neg_hi:[0,1]
	v_mov_b32_e32 v180, v181
	v_mov_b32_e32 v181, v175
	v_pk_mov_b32 v[176:177], v[172:173], v[176:177] op_sel:[1,0]
	v_mov_b32_e32 v179, v172
	v_pk_add_f32 v[176:177], v[180:181], v[176:177] neg_lo:[0,1] neg_hi:[0,1]
	v_mov_b32_e32 v184, v182
	v_pk_add_f32 v[172:173], v[178:179], v[176:177] neg_lo:[0,1] neg_hi:[0,1]
	v_mov_b32_e32 v183, v175
	v_pk_add_f32 v[176:177], v[184:185], v[172:173]
	s_nop 0
	v_pk_add_f32 v[178:179], v[176:177], v[176:177] op_sel:[0,1] op_sel_hi:[1,0]
	s_nop 0
	v_pk_add_f32 v[174:175], v[174:175], v[178:179] op_sel:[1,0] op_sel_hi:[0,1]
	v_mov_b32_e32 v177, v174
	v_pk_add_f32 v[180:181], v[176:177], v[182:183] neg_lo:[0,1] neg_hi:[0,1]
	v_mov_b32_e32 v173, v178
	v_sub_f32_e32 v151, v176, v180
	v_pk_add_f32 v[172:173], v[172:173], v[180:181] neg_lo:[0,1] neg_hi:[0,1]
	v_sub_f32_e32 v151, v182, v151
	v_add_f32_e32 v151, v172, v151
	v_add_f32_e32 v151, v151, v173
	v_add_f32_e32 v151, v174, v151
	v_cndmask_b32_e32 v151, v167, v151, vcc
	v_cmp_ngt_f32_e32 vcc, -1.0, v136
	s_nop 1
	v_cndmask_b32_e32 v151, v168, v151, vcc
	v_cmp_neq_f32_e32 vcc, -1.0, v136
	s_nop 1
	v_cndmask_b32_e32 v151, v169, v151, vcc
	v_cmp_lt_f32_e64 vcc, |v136|, s71
	s_nop 1
	v_cndmask_b32_e32 v136, v151, v136, vcc
;     __device__ __forceinline__ void operator()(const f32x4 (&acc)[2][2][4][2], const Unit& u, int wr, int wc, int fr, int fq) const {
;     ...
;                         for (int i = 0; i < 4; ++i) { float x0 = v0[i] + dt_bias[c0 + i], x1 = v1[i] + dt_bias[c0 + 4 + i];
;                             dp[i] = x0 > 20.f ? x0 : log1pf(__expf(x0)); dp[4 + i] = x1 > 20.f ? x1 : log1pf(__expf(x1)); }
.LBB0_843:
	s_or_b64 exec, exec, s[24:25]
	flat_store_dword v[154:155], v136 offset:24
	v_mov_b32_e32 v136, v203
	v_add_f32_e32 v151, v79, v136
	v_mov_b32_e32 v136, v207
	v_cmp_nlt_f32_e32 vcc, s67, v151
	s_and_saveexec_b64 s[24:25], vcc
	s_cbranch_execz .LBB0_845
	v_mul_f32_e32 v151, 0x3fb8aa3b, v151
	v_exp_f32_e32 v156, v151
	s_nop 0
	v_add_f32_e32 v151, 1.0, v156
	v_frexp_mant_f32_e32 v175, v151
	v_cvt_f64_f32_e32 v[172:173], v151
	v_add_f32_e32 v174, -1.0, v151
	v_frexp_exp_i32_f64_e32 v172, v[172:173]
	v_cmp_gt_f32_e32 vcc, s68, v175
	v_sub_f32_e32 v176, v174, v151
	v_sub_f32_e32 v174, v156, v174
	v_subbrev_co_u32_e32 v180, vcc, 0, v172, vcc
	v_add_f32_e32 v176, 1.0, v176
	v_sub_u32_e32 v172, 0, v180
	v_add_f32_e32 v174, v174, v176
	v_ldexp_f32 v151, v151, v172
	v_ldexp_f32 v172, v174, v172
	v_add_f32_e32 v174, -1.0, v151
	v_add_f32_e32 v173, 1.0, v174
	v_sub_f32_e32 v173, v151, v173
	v_add_f32_e32 v175, v172, v173
	v_add_f32_e32 v173, 1.0, v151
	v_add_f32_e32 v176, -1.0, v173
	v_sub_f32_e32 v151, v151, v176
	v_add_f32_e32 v151, v172, v151
	v_add_f32_e32 v181, v173, v151
	v_rcp_f32_e32 v182, v181
	v_sub_f32_e32 v172, v181, v173
	v_add_f32_e32 v173, v174, v175
	v_sub_f32_e32 v151, v151, v172
	v_mul_f32_e32 v184, v173, v182
	v_sub_f32_e32 v172, v173, v174
	v_mul_f32_e32 v174, v181, v184
	v_fma_f32 v176, v184, v181, -v174
	v_fmac_f32_e32 v176, v184, v151
	v_sub_f32_e32 v183, v175, v172
	v_add_f32_e32 v172, v174, v176
	v_sub_f32_e32 v175, v173, v172
	v_pk_add_f32 v[178:179], v[172:173], v[174:175] neg_lo:[0,1] neg_hi:[0,1]
	v_mov_b32_e32 v177, v172
	v_pk_add_f32 v[172:173], v[178:179], v[176:177] neg_lo:[0,1] neg_hi:[0,1]
	v_cmp_neq_f32_e32 vcc, s70, v156
	v_add_f32_e32 v173, v183, v173
	v_add_f32_e32 v172, v172, v173
	v_add_f32_e32 v173, v175, v172
	v_mul_f32_e32 v183, v182, v173
	v_mul_f32_e32 v174, v181, v183
	v_fma_f32 v176, v183, v181, -v174
	v_fmac_f32_e32 v176, v183, v151
	v_sub_f32_e32 v151, v175, v173
	v_add_f32_e32 v151, v172, v151
	v_add_f32_e32 v172, v174, v176
	v_sub_f32_e32 v175, v173, v172
	v_pk_add_f32 v[178:179], v[172:173], v[174:175] neg_lo:[0,1] neg_hi:[0,1]
	v_mov_b32_e32 v177, v172
	v_pk_add_f32 v[172:173], v[178:179], v[176:177] neg_lo:[0,1] neg_hi:[0,1]
	s_nop 0
	v_add_f32_e32 v151, v151, v173
	v_add_f32_e32 v151, v172, v151
	v_add_f32_e32 v173, v184, v183
	v_add_f32_e32 v151, v175, v151
	v_sub_f32_e32 v172, v173, v184
	v_mul_f32_e32 v151, v182, v151
	v_sub_f32_e32 v172, v183, v172
	v_add_f32_e32 v174, v172, v151
	v_add_f32_e32 v176, v173, v174
	v_cvt_f32_i32_e32 v172, v180
	v_mul_f32_e32 v177, v176, v176
	v_sub_f32_e32 v173, v176, v173
	v_fmamk_f32 v151, v177, 0x3e9b6dac, v166
	v_sub_f32_e32 v173, v174, v173
	v_fmaak_f32 v151, v177, v151, 0x3f2aaada
	v_ldexp_f32 v178, v173, 1
	v_mul_f32_e32 v173, v176, v177
	v_ldexp_f32 v175, v176, 1
	v_pk_mul_f32 v[176:177], v[172:173], v[150:151]
	s_nop 0
	v_fma_f32 v174, v172, s69, -v176
	v_fmac_f32_e32 v174, 0xb102e308, v172
	v_pk_add_f32 v[172:173], v[176:177], v[174:175]
	s_nop 0
	v_sub_f32_e32 v151, v173, v175
	v_sub_f32_e32 v151, v177, v151
	v_add_f32_e32 v179, v178, v151
	v_mov_b32_e32 v178, v176
	v_pk_add_f32 v[176:177], v[172:173], v[176:177] neg_lo:[0,1] neg_hi:[0,1]
	v_pk_add_f32 v[180:181], v[172:173], v[178:179]
	v_mov_b32_e32 v175, v172
	v_mov_b32_e32 v177, v181
	v_pk_add_f32 v[182:183], v[174:175], v[176:177] neg_lo:[0,1] neg_hi:[0,1]
	v_pk_add_f32 v[174:175], v[174:175], v[176:177]
	v_mov_b32_e32 v178, v179
	v_pk_add_f32 v[176:177], v[174:175], v[172:173] op_sel:[1,0] op_sel_hi:[0,1] neg_lo:[0,1] neg_hi:[0,1]
	v_pk_add_f32 v[184:185], v[180:181], v[176:177] op_sel_hi:[1,0] neg_lo:[0,1] neg_hi:[0,1]
	v_mov_b32_e32 v180, v181
	v_mov_b32_e32 v181, v175
	v_pk_mov_b32 v[176:177], v[172:173], v[176:177] op_sel:[1,0]
	v_mov_b32_e32 v179, v172
	v_pk_add_f32 v[176:177], v[180:181], v[176:177] neg_lo:[0,1] neg_hi:[0,1]
	v_mov_b32_e32 v184, v182
	v_pk_add_f32 v[172:173], v[178:179], v[176:177] neg_lo:[0,1] neg_hi:[0,1]
	v_mov_b32_e32 v183, v175
	v_pk_add_f32 v[176:177], v[184:185], v[172:173]
	s_nop 0
	v_pk_add_f32 v[178:179], v[176:177], v[176:177] op_sel:[0,1] op_sel_hi:[1,0]
	s_nop 0
	v_pk_add_f32 v[174:175], v[174:175], v[178:179] op_sel:[1,0] op_sel_hi:[0,1]
	v_mov_b32_e32 v177, v174
	v_pk_add_f32 v[180:181], v[176:177], v[182:183] neg_lo:[0,1] neg_hi:[0,1]
	v_mov_b32_e32 v173, v178
	v_sub_f32_e32 v151, v176, v180
	v_pk_add_f32 v[172:173], v[172:173], v[180:181] neg_lo:[0,1] neg_hi:[0,1]
	v_sub_f32_e32 v151, v182, v151
	v_add_f32_e32 v151, v172, v151
	v_add_f32_e32 v151, v151, v173
	v_add_f32_e32 v151, v174, v151
	v_cndmask_b32_e32 v151, v167, v151, vcc
	v_cmp_ngt_f32_e32 vcc, -1.0, v156
	s_nop 1
	v_cndmask_b32_e32 v151, v168, v151, vcc
	v_cmp_neq_f32_e32 vcc, -1.0, v156
	s_nop 1
	v_cndmask_b32_e32 v151, v169, v151, vcc
	v_cmp_lt_f32_e64 vcc, |v156|, s71
	s_nop 1
	v_cndmask_b32_e32 v151, v151, v156, vcc
;     __device__ __forceinline__ void operator()(const f32x4 (&acc)[2][2][4][2], const Unit& u, int wr, int wc, int fr, int fq) const {
;     ...
;                         for (int i = 0; i < 4; ++i) { float x0 = v0[i] + dt_bias[c0 + i], x1 = v1[i] + dt_bias[c0 + 4 + i];
;                             dp[i] = x0 > 20.f ? x0 : log1pf(__expf(x0)); dp[4 + i] = x1 > 20.f ? x1 : log1pf(__expf(x1)); }
.LBB0_845:
	s_or_b64 exec, exec, s[24:25]
	v_add_f32_e32 v136, v75, v136
	v_cmp_nlt_f32_e32 vcc, s67, v136
	flat_store_dword v[154:155], v151 offset:12
	s_and_saveexec_b64 s[24:25], vcc
	s_cbranch_execz .LBB0_847
	v_mul_f32_e32 v136, 0x3fb8aa3b, v136
	v_exp_f32_e32 v136, v136
	s_nop 0
	v_add_f32_e32 v151, 1.0, v136
	v_frexp_mant_f32_e32 v174, v151
	v_cvt_f64_f32_e32 v[172:173], v151
	v_add_f32_e32 v156, -1.0, v151
	v_frexp_exp_i32_f64_e32 v172, v[172:173]
	v_cmp_gt_f32_e32 vcc, s68, v174
	v_sub_f32_e32 v175, v156, v151
	v_sub_f32_e32 v156, v136, v156
	v_subbrev_co_u32_e32 v180, vcc, 0, v172, vcc
	v_add_f32_e32 v175, 1.0, v175
	v_sub_u32_e32 v172, 0, v180
	v_add_f32_e32 v156, v156, v175
	v_ldexp_f32 v151, v151, v172
	v_ldexp_f32 v156, v156, v172
	v_add_f32_e32 v172, -1.0, v151
	v_add_f32_e32 v173, 1.0, v172
	v_sub_f32_e32 v173, v151, v173
	v_add_f32_e32 v174, v156, v173
	v_add_f32_e32 v173, 1.0, v151
	v_add_f32_e32 v175, -1.0, v173
	v_sub_f32_e32 v151, v151, v175
	v_add_f32_e32 v151, v156, v151
	v_add_f32_e32 v156, v173, v151
	v_rcp_f32_e32 v181, v156
	v_sub_f32_e32 v173, v156, v173
	v_sub_f32_e32 v151, v151, v173
	v_add_f32_e32 v173, v172, v174
	v_sub_f32_e32 v172, v173, v172
	v_mul_f32_e32 v183, v173, v181
	v_sub_f32_e32 v182, v174, v172
	v_mul_f32_e32 v174, v156, v183
	v_fma_f32 v176, v183, v156, -v174
	v_fmac_f32_e32 v176, v183, v151
	v_add_f32_e32 v172, v174, v176
	v_sub_f32_e32 v175, v173, v172
	v_pk_add_f32 v[178:179], v[172:173], v[174:175] neg_lo:[0,1] neg_hi:[0,1]
	v_mov_b32_e32 v177, v172
	v_pk_add_f32 v[172:173], v[178:179], v[176:177] neg_lo:[0,1] neg_hi:[0,1]
	v_cmp_neq_f32_e32 vcc, s70, v136
	v_add_f32_e32 v173, v182, v173
	v_add_f32_e32 v172, v172, v173
	v_add_f32_e32 v173, v175, v172
	v_mul_f32_e32 v182, v181, v173
	v_mul_f32_e32 v174, v156, v182
	v_fma_f32 v176, v182, v156, -v174
	v_fmac_f32_e32 v176, v182, v151
	v_sub_f32_e32 v151, v175, v173
	v_add_f32_e32 v151, v172, v151
	v_add_f32_e32 v172, v174, v176
	v_sub_f32_e32 v175, v173, v172
	v_pk_add_f32 v[178:179], v[172:173], v[174:175] neg_lo:[0,1] neg_hi:[0,1]
	v_mov_b32_e32 v177, v172
	v_pk_add_f32 v[172:173], v[178:179], v[176:177] neg_lo:[0,1] neg_hi:[0,1]
	v_add_f32_e32 v156, v183, v182
	v_add_f32_e32 v151, v151, v173
	v_add_f32_e32 v151, v172, v151
	v_add_f32_e32 v151, v175, v151
	v_sub_f32_e32 v172, v156, v183
	v_mul_f32_e32 v151, v181, v151
	v_sub_f32_e32 v172, v182, v172
	v_add_f32_e32 v173, v172, v151
	v_add_f32_e32 v174, v156, v173
	v_cvt_f32_i32_e32 v172, v180
	v_mul_f32_e32 v176, v174, v174
	v_fmamk_f32 v151, v176, 0x3e9b6dac, v166
	v_sub_f32_e32 v156, v174, v156
	v_fmaak_f32 v151, v176, v151, 0x3f2aaada
	v_sub_f32_e32 v156, v173, v156
	v_mul_f32_e32 v173, v174, v176
	v_pk_mul_f32 v[176:177], v[172:173], v[150:151]
	v_ldexp_f32 v175, v174, 1
	v_fma_f32 v174, v172, s69, -v176
	v_fmac_f32_e32 v174, 0xb102e308, v172
	v_pk_add_f32 v[172:173], v[176:177], v[174:175]
	v_ldexp_f32 v156, v156, 1
	v_sub_f32_e32 v151, v173, v175
	v_sub_f32_e32 v151, v177, v151
	v_add_f32_e32 v179, v156, v151
	v_mov_b32_e32 v178, v176
	v_pk_add_f32 v[176:177], v[172:173], v[176:177] neg_lo:[0,1] neg_hi:[0,1]
	v_pk_add_f32 v[180:181], v[172:173], v[178:179]
	v_mov_b32_e32 v175, v172
	v_mov_b32_e32 v177, v181
	v_pk_add_f32 v[182:183], v[174:175], v[176:177] neg_lo:[0,1] neg_hi:[0,1]
	v_pk_add_f32 v[174:175], v[174:175], v[176:177]
	v_mov_b32_e32 v178, v179
	v_pk_add_f32 v[176:177], v[174:175], v[172:173] op_sel:[1,0] op_sel_hi:[0,1] neg_lo:[0,1] neg_hi:[0,1]
	v_pk_add_f32 v[184:185], v[180:181], v[176:177] op_sel_hi:[1,0] neg_lo:[0,1] neg_hi:[0,1]
	v_mov_b32_e32 v180, v181
	v_mov_b32_e32 v181, v175
	v_pk_mov_b32 v[176:177], v[172:173], v[176:177] op_sel:[1,0]
	v_mov_b32_e32 v179, v172
	v_pk_add_f32 v[176:177], v[180:181], v[176:177] neg_lo:[0,1] neg_hi:[0,1]
	v_mov_b32_e32 v184, v182
	v_pk_add_f32 v[172:173], v[178:179], v[176:177] neg_lo:[0,1] neg_hi:[0,1]
	v_mov_b32_e32 v183, v175
	v_pk_add_f32 v[176:177], v[184:185], v[172:173]
	s_nop 0
	v_pk_add_f32 v[178:179], v[176:177], v[176:177] op_sel:[0,1] op_sel_hi:[1,0]
	s_nop 0
	v_pk_add_f32 v[174:175], v[174:175], v[178:179] op_sel:[1,0] op_sel_hi:[0,1]
	v_mov_b32_e32 v177, v174
	v_pk_add_f32 v[180:181], v[176:177], v[182:183] neg_lo:[0,1] neg_hi:[0,1]
	v_mov_b32_e32 v173, v178
	v_sub_f32_e32 v151, v176, v180
	v_pk_add_f32 v[172:173], v[172:173], v[180:181] neg_lo:[0,1] neg_hi:[0,1]
	v_sub_f32_e32 v151, v182, v151
	v_add_f32_e32 v151, v172, v151
	v_add_f32_e32 v151, v151, v173
	v_add_f32_e32 v151, v174, v151
	v_cndmask_b32_e32 v151, v167, v151, vcc
	v_cmp_ngt_f32_e32 vcc, -1.0, v136
	s_nop 1
	v_cndmask_b32_e32 v151, v168, v151, vcc
	v_cmp_neq_f32_e32 vcc, -1.0, v136
	s_nop 1
	v_cndmask_b32_e32 v151, v169, v151, vcc
	v_cmp_lt_f32_e64 vcc, |v136|, s71
	s_nop 1
	v_cndmask_b32_e32 v136, v151, v136, vcc
;     __device__ __forceinline__ void operator()(const f32x4 (&acc)[2][2][4][2], const Unit& u, int wr, int wc, int fr, int fq) const {
;     ...
;                         for (int i = 0; i < 4; ++i) { float x0 = v0[i] + dt_bias[c0 + i], x1 = v1[i] + dt_bias[c0 + 4 + i];
;                             dp[i] = x0 > 20.f ? x0 : log1pf(__expf(x0)); dp[4 + i] = x1 > 20.f ? x1 : log1pf(__expf(x1)); }
.LBB0_847:
	s_or_b64 exec, exec, s[24:25]
	flat_store_dword v[154:155], v136 offset:28
	v_mov_b32_e32 v136, v200
	v_add_f32_e32 v151, v60, v136
	v_mov_b32_e32 v136, v204
	v_cmp_nlt_f32_e32 vcc, s67, v151
	s_and_saveexec_b64 s[24:25], vcc
	s_cbranch_execz .LBB0_849
	v_mul_f32_e32 v151, 0x3fb8aa3b, v151
	v_exp_f32_e32 v156, v151
	s_nop 0
	v_add_f32_e32 v151, 1.0, v156
	v_frexp_mant_f32_e32 v173, v151
	v_cvt_f64_f32_e32 v[154:155], v151
	v_add_f32_e32 v172, -1.0, v151
	v_frexp_exp_i32_f64_e32 v154, v[154:155]
	v_cmp_gt_f32_e32 vcc, s68, v173
	v_sub_f32_e32 v174, v172, v151
	v_sub_f32_e32 v172, v156, v172
	v_subbrev_co_u32_e32 v178, vcc, 0, v154, vcc
	v_add_f32_e32 v174, 1.0, v174
	v_sub_u32_e32 v154, 0, v178
	v_add_f32_e32 v172, v172, v174
	v_ldexp_f32 v151, v151, v154
	v_ldexp_f32 v154, v172, v154
	v_add_f32_e32 v172, -1.0, v151
	v_add_f32_e32 v155, 1.0, v172
	v_sub_f32_e32 v155, v151, v155
	v_add_f32_e32 v173, v154, v155
	v_add_f32_e32 v155, 1.0, v151
	v_add_f32_e32 v174, -1.0, v155
	v_sub_f32_e32 v151, v151, v174
	v_add_f32_e32 v151, v154, v151
	v_add_f32_e32 v179, v155, v151
	v_rcp_f32_e32 v180, v179
	v_sub_f32_e32 v154, v179, v155
	v_add_f32_e32 v155, v172, v173
	v_sub_f32_e32 v151, v151, v154
	v_mul_f32_e32 v182, v155, v180
	v_sub_f32_e32 v154, v155, v172
	v_mul_f32_e32 v172, v179, v182
	v_fma_f32 v174, v182, v179, -v172
	v_fmac_f32_e32 v174, v182, v151
	v_sub_f32_e32 v181, v173, v154
	v_add_f32_e32 v154, v172, v174
	v_sub_f32_e32 v173, v155, v154
	v_pk_add_f32 v[176:177], v[154:155], v[172:173] neg_lo:[0,1] neg_hi:[0,1]
	v_mov_b32_e32 v175, v154
	v_pk_add_f32 v[154:155], v[176:177], v[174:175] neg_lo:[0,1] neg_hi:[0,1]
	v_cmp_neq_f32_e32 vcc, s70, v156
	v_add_f32_e32 v155, v181, v155
	v_add_f32_e32 v154, v154, v155
	v_add_f32_e32 v155, v173, v154
	v_mul_f32_e32 v181, v180, v155
	v_mul_f32_e32 v172, v179, v181
	v_fma_f32 v174, v181, v179, -v172
	v_fmac_f32_e32 v174, v181, v151
	v_sub_f32_e32 v151, v173, v155
	v_add_f32_e32 v151, v154, v151
	v_add_f32_e32 v154, v172, v174
	v_sub_f32_e32 v173, v155, v154
	v_pk_add_f32 v[176:177], v[154:155], v[172:173] neg_lo:[0,1] neg_hi:[0,1]
	v_mov_b32_e32 v175, v154
	v_pk_add_f32 v[154:155], v[176:177], v[174:175] neg_lo:[0,1] neg_hi:[0,1]
	s_nop 0
	v_add_f32_e32 v151, v151, v155
	v_add_f32_e32 v151, v154, v151
	v_add_f32_e32 v155, v182, v181
	v_add_f32_e32 v151, v173, v151
	v_sub_f32_e32 v154, v155, v182
	v_mul_f32_e32 v151, v180, v151
	v_sub_f32_e32 v154, v181, v154
	v_add_f32_e32 v172, v154, v151
	v_add_f32_e32 v174, v155, v172
	v_cvt_f32_i32_e32 v154, v178
	v_mul_f32_e32 v175, v174, v174
	v_sub_f32_e32 v155, v174, v155
	v_fmamk_f32 v151, v175, 0x3e9b6dac, v166
	v_sub_f32_e32 v155, v172, v155
	v_fmaak_f32 v151, v175, v151, 0x3f2aaada
	v_ldexp_f32 v176, v155, 1
	v_mul_f32_e32 v155, v174, v175
	v_ldexp_f32 v173, v174, 1
	v_pk_mul_f32 v[174:175], v[154:155], v[150:151]
	s_nop 0
	v_fma_f32 v172, v154, s69, -v174
	v_fmac_f32_e32 v172, 0xb102e308, v154
	v_pk_add_f32 v[154:155], v[174:175], v[172:173]
	s_nop 0
	v_sub_f32_e32 v151, v155, v173
	v_sub_f32_e32 v151, v175, v151
	v_add_f32_e32 v177, v176, v151
	v_mov_b32_e32 v176, v174
	v_pk_add_f32 v[174:175], v[154:155], v[174:175] neg_lo:[0,1] neg_hi:[0,1]
	v_pk_add_f32 v[178:179], v[154:155], v[176:177]
	v_mov_b32_e32 v173, v154
	v_mov_b32_e32 v175, v179
	v_pk_add_f32 v[180:181], v[172:173], v[174:175] neg_lo:[0,1] neg_hi:[0,1]
	v_pk_add_f32 v[172:173], v[172:173], v[174:175]
	v_mov_b32_e32 v176, v177
	v_pk_add_f32 v[174:175], v[172:173], v[154:155] op_sel:[1,0] op_sel_hi:[0,1] neg_lo:[0,1] neg_hi:[0,1]
	v_pk_add_f32 v[182:183], v[178:179], v[174:175] op_sel_hi:[1,0] neg_lo:[0,1] neg_hi:[0,1]
	v_mov_b32_e32 v178, v179
	v_mov_b32_e32 v179, v173
	v_pk_mov_b32 v[174:175], v[154:155], v[174:175] op_sel:[1,0]
	v_mov_b32_e32 v177, v154
	v_pk_add_f32 v[174:175], v[178:179], v[174:175] neg_lo:[0,1] neg_hi:[0,1]
	v_mov_b32_e32 v182, v180
	v_pk_add_f32 v[154:155], v[176:177], v[174:175] neg_lo:[0,1] neg_hi:[0,1]
	v_mov_b32_e32 v181, v173
	v_pk_add_f32 v[174:175], v[182:183], v[154:155]
	s_nop 0
	v_pk_add_f32 v[176:177], v[174:175], v[174:175] op_sel:[0,1] op_sel_hi:[1,0]
	s_nop 0
	v_pk_add_f32 v[172:173], v[172:173], v[176:177] op_sel:[1,0] op_sel_hi:[0,1]
	v_mov_b32_e32 v175, v172
	v_pk_add_f32 v[178:179], v[174:175], v[180:181] neg_lo:[0,1] neg_hi:[0,1]
	v_mov_b32_e32 v155, v176
	v_sub_f32_e32 v151, v174, v178
	v_pk_add_f32 v[154:155], v[154:155], v[178:179] neg_lo:[0,1] neg_hi:[0,1]
	v_sub_f32_e32 v151, v180, v151
	v_add_f32_e32 v151, v154, v151
	v_add_f32_e32 v151, v151, v155
	v_add_f32_e32 v151, v172, v151
	v_cndmask_b32_e32 v151, v167, v151, vcc
	v_cmp_ngt_f32_e32 vcc, -1.0, v156
	s_nop 1
	v_cndmask_b32_e32 v151, v168, v151, vcc
	v_cmp_neq_f32_e32 vcc, -1.0, v156
	s_nop 1
	v_cndmask_b32_e32 v151, v169, v151, vcc
	v_cmp_lt_f32_e64 vcc, |v156|, s71
	s_nop 1
	v_cndmask_b32_e32 v151, v151, v156, vcc
;     __device__ __forceinline__ void operator()(const f32x4 (&acc)[2][2][4][2], const Unit& u, int wr, int wc, int fr, int fq) const {
;     ...
;                     for (int m = 0; m < 4; ++m) { const int r = row0 + ai * HALF + m * 16;
;                         const f32x4 v0 = acc[ai][0][m][0], v1 = acc[ai][0][m][1]; float* dp = DT + (size_t)r * 32 + c0;
; #pragma unroll
;                         for (int i = 0; i < 4; ++i) { float x0 = v0[i] + dt_bias[c0 + i], x1 = v1[i] + dt_bias[c0 + 4 + i];
;                             dp[i] = x0 > 20.f ? x0 : log1pf(__expf(x0)); dp[4 + i] = x1 > 20.f ? x1 : log1pf(__expf(x1)); }
.LBB0_849:
	s_or_b64 exec, exec, s[24:25]
	v_lshlrev_b64 v[154:155], 7, v[152:153]
	v_lshl_add_u64 v[154:155], v[138:139], 0, v[154:155]
	v_add_co_u32_e32 v172, vcc, 0x4000, v154
	v_add_f32_e32 v136, v56, v136
	v_addc_co_u32_e32 v173, vcc, 0, v155, vcc
	v_cmp_nlt_f32_e32 vcc, s67, v136
	flat_store_dword v[172:173], v151
	s_and_saveexec_b64 s[24:25], vcc
	s_cbranch_execz .LBB0_851
	v_mul_f32_e32 v136, 0x3fb8aa3b, v136
	v_exp_f32_e32 v136, v136
	s_nop 0
	v_add_f32_e32 v151, 1.0, v136
	v_frexp_mant_f32_e32 v174, v151
	v_cvt_f64_f32_e32 v[172:173], v151
	v_add_f32_e32 v156, -1.0, v151
	v_frexp_exp_i32_f64_e32 v172, v[172:173]
	v_cmp_gt_f32_e32 vcc, s68, v174
	v_sub_f32_e32 v175, v156, v151
	v_sub_f32_e32 v156, v136, v156
	v_subbrev_co_u32_e32 v180, vcc, 0, v172, vcc
	v_add_f32_e32 v175, 1.0, v175
	v_sub_u32_e32 v172, 0, v180
	v_add_f32_e32 v156, v156, v175
	v_ldexp_f32 v151, v151, v172
	v_ldexp_f32 v156, v156, v172
	v_add_f32_e32 v172, -1.0, v151
	v_add_f32_e32 v173, 1.0, v172
	v_sub_f32_e32 v173, v151, v173
	v_add_f32_e32 v174, v156, v173
	v_add_f32_e32 v173, 1.0, v151
	v_add_f32_e32 v175, -1.0, v173
	v_sub_f32_e32 v151, v151, v175
	v_add_f32_e32 v151, v156, v151
	v_add_f32_e32 v156, v173, v151
	v_rcp_f32_e32 v181, v156
	v_sub_f32_e32 v173, v156, v173
	v_sub_f32_e32 v151, v151, v173
	v_add_f32_e32 v173, v172, v174
	v_sub_f32_e32 v172, v173, v172
	v_mul_f32_e32 v183, v173, v181
	v_sub_f32_e32 v182, v174, v172
	v_mul_f32_e32 v174, v156, v183
	v_fma_f32 v176, v183, v156, -v174
	v_fmac_f32_e32 v176, v183, v151
	v_add_f32_e32 v172, v174, v176
	v_sub_f32_e32 v175, v173, v172
	v_pk_add_f32 v[178:179], v[172:173], v[174:175] neg_lo:[0,1] neg_hi:[0,1]
	v_mov_b32_e32 v177, v172
	v_pk_add_f32 v[172:173], v[178:179], v[176:177] neg_lo:[0,1] neg_hi:[0,1]
	v_cmp_neq_f32_e32 vcc, s70, v136
	v_add_f32_e32 v173, v182, v173
	v_add_f32_e32 v172, v172, v173
	v_add_f32_e32 v173, v175, v172
	v_mul_f32_e32 v182, v181, v173
	v_mul_f32_e32 v174, v156, v182
	v_fma_f32 v176, v182, v156, -v174
	v_fmac_f32_e32 v176, v182, v151
	v_sub_f32_e32 v151, v175, v173
	v_add_f32_e32 v151, v172, v151
	v_add_f32_e32 v172, v174, v176
	v_sub_f32_e32 v175, v173, v172
	v_pk_add_f32 v[178:179], v[172:173], v[174:175] neg_lo:[0,1] neg_hi:[0,1]
	v_mov_b32_e32 v177, v172
	v_pk_add_f32 v[172:173], v[178:179], v[176:177] neg_lo:[0,1] neg_hi:[0,1]
	v_add_f32_e32 v156, v183, v182
	v_add_f32_e32 v151, v151, v173
	v_add_f32_e32 v151, v172, v151
	v_add_f32_e32 v151, v175, v151
	v_sub_f32_e32 v172, v156, v183
	v_mul_f32_e32 v151, v181, v151
	v_sub_f32_e32 v172, v182, v172
	v_add_f32_e32 v173, v172, v151
	v_add_f32_e32 v174, v156, v173
	v_cvt_f32_i32_e32 v172, v180
	v_mul_f32_e32 v176, v174, v174
	v_fmamk_f32 v151, v176, 0x3e9b6dac, v166
	v_sub_f32_e32 v156, v174, v156
	v_fmaak_f32 v151, v176, v151, 0x3f2aaada
	v_sub_f32_e32 v156, v173, v156
	v_mul_f32_e32 v173, v174, v176
	v_pk_mul_f32 v[176:177], v[172:173], v[150:151]
	v_ldexp_f32 v175, v174, 1
	v_fma_f32 v174, v172, s69, -v176
	v_fmac_f32_e32 v174, 0xb102e308, v172
	v_pk_add_f32 v[172:173], v[176:177], v[174:175]
	v_ldexp_f32 v156, v156, 1
	v_sub_f32_e32 v151, v173, v175
	v_sub_f32_e32 v151, v177, v151
	v_add_f32_e32 v179, v156, v151
	v_mov_b32_e32 v178, v176
	v_pk_add_f32 v[176:177], v[172:173], v[176:177] neg_lo:[0,1] neg_hi:[0,1]
	v_pk_add_f32 v[180:181], v[172:173], v[178:179]
	v_mov_b32_e32 v175, v172
	v_mov_b32_e32 v177, v181
	v_pk_add_f32 v[182:183], v[174:175], v[176:177] neg_lo:[0,1] neg_hi:[0,1]
	v_pk_add_f32 v[174:175], v[174:175], v[176:177]
	v_mov_b32_e32 v178, v179
	v_pk_add_f32 v[176:177], v[174:175], v[172:173] op_sel:[1,0] op_sel_hi:[0,1] neg_lo:[0,1] neg_hi:[0,1]
	v_pk_add_f32 v[184:185], v[180:181], v[176:177] op_sel_hi:[1,0] neg_lo:[0,1] neg_hi:[0,1]
	v_mov_b32_e32 v180, v181
	v_mov_b32_e32 v181, v175
	v_pk_mov_b32 v[176:177], v[172:173], v[176:177] op_sel:[1,0]
	v_mov_b32_e32 v179, v172
	v_pk_add_f32 v[176:177], v[180:181], v[176:177] neg_lo:[0,1] neg_hi:[0,1]
	v_mov_b32_e32 v184, v182
	v_pk_add_f32 v[172:173], v[178:179], v[176:177] neg_lo:[0,1] neg_hi:[0,1]
	v_mov_b32_e32 v183, v175
	v_pk_add_f32 v[176:177], v[184:185], v[172:173]
	s_nop 0
	v_pk_add_f32 v[178:179], v[176:177], v[176:177] op_sel:[0,1] op_sel_hi:[1,0]
	s_nop 0
	v_pk_add_f32 v[174:175], v[174:175], v[178:179] op_sel:[1,0] op_sel_hi:[0,1]
	v_mov_b32_e32 v177, v174
	v_pk_add_f32 v[180:181], v[176:177], v[182:183] neg_lo:[0,1] neg_hi:[0,1]
	v_mov_b32_e32 v173, v178
	v_sub_f32_e32 v151, v176, v180
	v_pk_add_f32 v[172:173], v[172:173], v[180:181] neg_lo:[0,1] neg_hi:[0,1]
	v_sub_f32_e32 v151, v182, v151
	v_add_f32_e32 v151, v172, v151
	v_add_f32_e32 v151, v151, v173
	v_add_f32_e32 v151, v174, v151
	v_cndmask_b32_e32 v151, v167, v151, vcc
	v_cmp_ngt_f32_e32 vcc, -1.0, v136
	s_nop 1
	v_cndmask_b32_e32 v151, v168, v151, vcc
	v_cmp_neq_f32_e32 vcc, -1.0, v136
	s_nop 1
	v_cndmask_b32_e32 v151, v169, v151, vcc
	v_cmp_lt_f32_e64 vcc, |v136|, s71
	s_nop 1
	v_cndmask_b32_e32 v136, v151, v136, vcc
;     __device__ __forceinline__ void operator()(const f32x4 (&acc)[2][2][4][2], const Unit& u, int wr, int wc, int fr, int fq) const {
;     ...
;                         for (int i = 0; i < 4; ++i) { float x0 = v0[i] + dt_bias[c0 + i], x1 = v1[i] + dt_bias[c0 + 4 + i];
;                             dp[i] = x0 > 20.f ? x0 : log1pf(__expf(x0)); dp[4 + i] = x1 > 20.f ? x1 : log1pf(__expf(x1)); }
.LBB0_851:
	s_or_b64 exec, exec, s[24:25]
	s_mov_b64 s[24:25], 0x4000
	v_lshl_add_u64 v[154:155], v[154:155], 0, s[24:25]
	flat_store_dword v[154:155], v136 offset:16
	v_mov_b32_e32 v151, v201
	s_nop 0
	v_mov_b32_e32 v136, v205
	v_add_f32_e32 v151, v61, v151
	v_cmp_nlt_f32_e32 vcc, s67, v151
	s_and_saveexec_b64 s[24:25], vcc
	s_cbranch_execz .LBB0_853
	v_mul_f32_e32 v151, 0x3fb8aa3b, v151
	v_exp_f32_e32 v156, v151
	s_nop 0
	v_add_f32_e32 v151, 1.0, v156
	v_frexp_mant_f32_e32 v175, v151
	v_cvt_f64_f32_e32 v[172:173], v151
	v_add_f32_e32 v174, -1.0, v151
	v_frexp_exp_i32_f64_e32 v172, v[172:173]
	v_cmp_gt_f32_e32 vcc, s68, v175
	v_sub_f32_e32 v176, v174, v151
	v_sub_f32_e32 v174, v156, v174
	v_subbrev_co_u32_e32 v180, vcc, 0, v172, vcc
	v_add_f32_e32 v176, 1.0, v176
	v_sub_u32_e32 v172, 0, v180
	v_add_f32_e32 v174, v174, v176
	v_ldexp_f32 v151, v151, v172
	v_ldexp_f32 v172, v174, v172
	v_add_f32_e32 v174, -1.0, v151
	v_add_f32_e32 v173, 1.0, v174
	v_sub_f32_e32 v173, v151, v173
	v_add_f32_e32 v175, v172, v173
	v_add_f32_e32 v173, 1.0, v151
	v_add_f32_e32 v176, -1.0, v173
	v_sub_f32_e32 v151, v151, v176
	v_add_f32_e32 v151, v172, v151
	v_add_f32_e32 v181, v173, v151
	v_rcp_f32_e32 v182, v181
	v_sub_f32_e32 v172, v181, v173
	v_add_f32_e32 v173, v174, v175
	v_sub_f32_e32 v151, v151, v172
	v_mul_f32_e32 v184, v173, v182
	v_sub_f32_e32 v172, v173, v174
	v_mul_f32_e32 v174, v181, v184
	v_fma_f32 v176, v184, v181, -v174
	v_fmac_f32_e32 v176, v184, v151
	v_sub_f32_e32 v183, v175, v172
	v_add_f32_e32 v172, v174, v176
	v_sub_f32_e32 v175, v173, v172
	v_pk_add_f32 v[178:179], v[172:173], v[174:175] neg_lo:[0,1] neg_hi:[0,1]
	v_mov_b32_e32 v177, v172
	v_pk_add_f32 v[172:173], v[178:179], v[176:177] neg_lo:[0,1] neg_hi:[0,1]
	v_cmp_neq_f32_e32 vcc, s70, v156
	v_add_f32_e32 v173, v183, v173
	v_add_f32_e32 v172, v172, v173
	v_add_f32_e32 v173, v175, v172
	v_mul_f32_e32 v183, v182, v173
	v_mul_f32_e32 v174, v181, v183
	v_fma_f32 v176, v183, v181, -v174
	v_fmac_f32_e32 v176, v183, v151
	v_sub_f32_e32 v151, v175, v173
	v_add_f32_e32 v151, v172, v151
	v_add_f32_e32 v172, v174, v176
	v_sub_f32_e32 v175, v173, v172
	v_pk_add_f32 v[178:179], v[172:173], v[174:175] neg_lo:[0,1] neg_hi:[0,1]
	v_mov_b32_e32 v177, v172
	v_pk_add_f32 v[172:173], v[178:179], v[176:177] neg_lo:[0,1] neg_hi:[0,1]
	s_nop 0
	v_add_f32_e32 v151, v151, v173
	v_add_f32_e32 v151, v172, v151
	v_add_f32_e32 v173, v184, v183
	v_add_f32_e32 v151, v175, v151
	v_sub_f32_e32 v172, v173, v184
	v_mul_f32_e32 v151, v182, v151
	v_sub_f32_e32 v172, v183, v172
	v_add_f32_e32 v174, v172, v151
	v_add_f32_e32 v176, v173, v174
	v_cvt_f32_i32_e32 v172, v180
	v_mul_f32_e32 v177, v176, v176
	v_sub_f32_e32 v173, v176, v173
	v_fmamk_f32 v151, v177, 0x3e9b6dac, v166
	v_sub_f32_e32 v173, v174, v173
	v_fmaak_f32 v151, v177, v151, 0x3f2aaada
	v_ldexp_f32 v178, v173, 1
	v_mul_f32_e32 v173, v176, v177
	v_ldexp_f32 v175, v176, 1
	v_pk_mul_f32 v[176:177], v[172:173], v[150:151]
	s_nop 0
	v_fma_f32 v174, v172, s69, -v176
	v_fmac_f32_e32 v174, 0xb102e308, v172
	v_pk_add_f32 v[172:173], v[176:177], v[174:175]
	s_nop 0
	v_sub_f32_e32 v151, v173, v175
	v_sub_f32_e32 v151, v177, v151
	v_add_f32_e32 v179, v178, v151
	v_mov_b32_e32 v178, v176
	v_pk_add_f32 v[176:177], v[172:173], v[176:177] neg_lo:[0,1] neg_hi:[0,1]
	v_pk_add_f32 v[180:181], v[172:173], v[178:179]
	v_mov_b32_e32 v175, v172
	v_mov_b32_e32 v177, v181
	v_pk_add_f32 v[182:183], v[174:175], v[176:177] neg_lo:[0,1] neg_hi:[0,1]
	v_pk_add_f32 v[174:175], v[174:175], v[176:177]
	v_mov_b32_e32 v178, v179
	v_pk_add_f32 v[176:177], v[174:175], v[172:173] op_sel:[1,0] op_sel_hi:[0,1] neg_lo:[0,1] neg_hi:[0,1]
	v_pk_add_f32 v[184:185], v[180:181], v[176:177] op_sel_hi:[1,0] neg_lo:[0,1] neg_hi:[0,1]
	v_mov_b32_e32 v180, v181
	v_mov_b32_e32 v181, v175
	v_pk_mov_b32 v[176:177], v[172:173], v[176:177] op_sel:[1,0]
	v_mov_b32_e32 v179, v172
	v_pk_add_f32 v[176:177], v[180:181], v[176:177] neg_lo:[0,1] neg_hi:[0,1]
	v_mov_b32_e32 v184, v182
	v_pk_add_f32 v[172:173], v[178:179], v[176:177] neg_lo:[0,1] neg_hi:[0,1]
	v_mov_b32_e32 v183, v175
	v_pk_add_f32 v[176:177], v[184:185], v[172:173]
	s_nop 0
	v_pk_add_f32 v[178:179], v[176:177], v[176:177] op_sel:[0,1] op_sel_hi:[1,0]
	s_nop 0
	v_pk_add_f32 v[174:175], v[174:175], v[178:179] op_sel:[1,0] op_sel_hi:[0,1]
	v_mov_b32_e32 v177, v174
	v_pk_add_f32 v[180:181], v[176:177], v[182:183] neg_lo:[0,1] neg_hi:[0,1]
	v_mov_b32_e32 v173, v178
	v_sub_f32_e32 v151, v176, v180
	v_pk_add_f32 v[172:173], v[172:173], v[180:181] neg_lo:[0,1] neg_hi:[0,1]
	v_sub_f32_e32 v151, v182, v151
	v_add_f32_e32 v151, v172, v151
	v_add_f32_e32 v151, v151, v173
	v_add_f32_e32 v151, v174, v151
	v_cndmask_b32_e32 v151, v167, v151, vcc
	v_cmp_ngt_f32_e32 vcc, -1.0, v156
	s_nop 1
	v_cndmask_b32_e32 v151, v168, v151, vcc
	v_cmp_neq_f32_e32 vcc, -1.0, v156
	s_nop 1
	v_cndmask_b32_e32 v151, v169, v151, vcc
	v_cmp_lt_f32_e64 vcc, |v156|, s71
	s_nop 1
	v_cndmask_b32_e32 v151, v151, v156, vcc

;     __device__ __forceinline__ void operator()(const f32x4 (&acc)[2][2][4][2], const Unit& u, int wr, int wc, int fr, int fq) const {
;     ...
;                         for (int i = 0; i < 4; ++i) { float x0 = v0[i] + dt_bias[c0 + i], x1 = v1[i] + dt_bias[c0 + 4 + i];
;                             dp[i] = x0 > 20.f ? x0 : log1pf(__expf(x0)); dp[4 + i] = x1 > 20.f ? x1 : log1pf(__expf(x1)); }
.LBB0_855:
	s_or_b64 exec, exec, s[24:25]
	flat_store_dword v[154:155], v136 offset:20
	v_mov_b32_e32 v136, v202
	v_add_f32_e32 v151, v62, v136
	v_mov_b32_e32 v136, v206
	v_cmp_nlt_f32_e32 vcc, s67, v151
	s_and_saveexec_b64 s[24:25], vcc
	s_cbranch_execz .LBB0_857
	v_mul_f32_e32 v151, 0x3fb8aa3b, v151
	v_exp_f32_e32 v156, v151
	s_nop 0
	v_add_f32_e32 v151, 1.0, v156
	v_frexp_mant_f32_e32 v175, v151
	v_cvt_f64_f32_e32 v[172:173], v151
	v_add_f32_e32 v174, -1.0, v151
	v_frexp_exp_i32_f64_e32 v172, v[172:173]
	v_cmp_gt_f32_e32 vcc, s68, v175
	v_sub_f32_e32 v176, v174, v151
	v_sub_f32_e32 v174, v156, v174
	v_subbrev_co_u32_e32 v180, vcc, 0, v172, vcc
	v_add_f32_e32 v176, 1.0, v176
	v_sub_u32_e32 v172, 0, v180
	v_add_f32_e32 v174, v174, v176
	v_ldexp_f32 v151, v151, v172
	v_ldexp_f32 v172, v174, v172
	v_add_f32_e32 v174, -1.0, v151
	v_add_f32_e32 v173, 1.0, v174
	v_sub_f32_e32 v173, v151, v173
	v_add_f32_e32 v175, v172, v173
	v_add_f32_e32 v173, 1.0, v151
	v_add_f32_e32 v176, -1.0, v173
	v_sub_f32_e32 v151, v151, v176
	v_add_f32_e32 v151, v172, v151
	v_add_f32_e32 v181, v173, v151
	v_rcp_f32_e32 v182, v181
	v_sub_f32_e32 v172, v181, v173
	v_add_f32_e32 v173, v174, v175
	v_sub_f32_e32 v151, v151, v172
	v_mul_f32_e32 v184, v173, v182
	v_sub_f32_e32 v172, v173, v174
	v_mul_f32_e32 v174, v181, v184
	v_fma_f32 v176, v184, v181, -v174
	v_fmac_f32_e32 v176, v184, v151
	v_sub_f32_e32 v183, v175, v172
	v_add_f32_e32 v172, v174, v176
	v_sub_f32_e32 v175, v173, v172
	v_pk_add_f32 v[178:179], v[172:173], v[174:175] neg_lo:[0,1] neg_hi:[0,1]
	v_mov_b32_e32 v177, v172
	v_pk_add_f32 v[172:173], v[178:179], v[176:177] neg_lo:[0,1] neg_hi:[0,1]
	v_cmp_neq_f32_e32 vcc, s70, v156
	v_add_f32_e32 v173, v183, v173
	v_add_f32_e32 v172, v172, v173
	v_add_f32_e32 v173, v175, v172
	v_mul_f32_e32 v183, v182, v173
	v_mul_f32_e32 v174, v181, v183
	v_fma_f32 v176, v183, v181, -v174
	v_fmac_f32_e32 v176, v183, v151
	v_sub_f32_e32 v151, v175, v173
	v_add_f32_e32 v151, v172, v151
	v_add_f32_e32 v172, v174, v176
	v_sub_f32_e32 v175, v173, v172
	v_pk_add_f32 v[178:179], v[172:173], v[174:175] neg_lo:[0,1] neg_hi:[0,1]
	v_mov_b32_e32 v177, v172
	v_pk_add_f32 v[172:173], v[178:179], v[176:177] neg_lo:[0,1] neg_hi:[0,1]
	s_nop 0
	v_add_f32_e32 v151, v151, v173
	v_add_f32_e32 v151, v172, v151
	v_add_f32_e32 v173, v184, v183
	v_add_f32_e32 v151, v175, v151
	v_sub_f32_e32 v172, v173, v184
	v_mul_f32_e32 v151, v182, v151
	v_sub_f32_e32 v172, v183, v172
	v_add_f32_e32 v174, v172, v151
	v_add_f32_e32 v176, v173, v174
	v_cvt_f32_i32_e32 v172, v180
	v_mul_f32_e32 v177, v176, v176
	v_sub_f32_e32 v173, v176, v173
	v_fmamk_f32 v151, v177, 0x3e9b6dac, v166
	v_sub_f32_e32 v173, v174, v173
	v_fmaak_f32 v151, v177, v151, 0x3f2aaada
	v_ldexp_f32 v178, v173, 1
	v_mul_f32_e32 v173, v176, v177
	v_ldexp_f32 v175, v176, 1
	v_pk_mul_f32 v[176:177], v[172:173], v[150:151]
	s_nop 0
	v_fma_f32 v174, v172, s69, -v176
	v_fmac_f32_e32 v174, 0xb102e308, v172
	v_pk_add_f32 v[172:173], v[176:177], v[174:175]
	s_nop 0
	v_sub_f32_e32 v151, v173, v175
	v_sub_f32_e32 v151, v177, v151
	v_add_f32_e32 v179, v178, v151
	v_mov_b32_e32 v178, v176
	v_pk_add_f32 v[176:177], v[172:173], v[176:177] neg_lo:[0,1] neg_hi:[0,1]
	v_pk_add_f32 v[180:181], v[172:173], v[178:179]
	v_mov_b32_e32 v175, v172
	v_mov_b32_e32 v177, v181
	v_pk_add_f32 v[182:183], v[174:175], v[176:177] neg_lo:[0,1] neg_hi:[0,1]
	v_pk_add_f32 v[174:175], v[174:175], v[176:177]
	v_mov_b32_e32 v178, v179
	v_pk_add_f32 v[176:177], v[174:175], v[172:173] op_sel:[1,0] op_sel_hi:[0,1] neg_lo:[0,1] neg_hi:[0,1]
	v_pk_add_f32 v[184:185], v[180:181], v[176:177] op_sel_hi:[1,0] neg_lo:[0,1] neg_hi:[0,1]
	v_mov_b32_e32 v180, v181
	v_mov_b32_e32 v181, v175
	v_pk_mov_b32 v[176:177], v[172:173], v[176:177] op_sel:[1,0]
	v_mov_b32_e32 v179, v172
	v_pk_add_f32 v[176:177], v[180:181], v[176:177] neg_lo:[0,1] neg_hi:[0,1]
	v_mov_b32_e32 v184, v182
	v_pk_add_f32 v[172:173], v[178:179], v[176:177] neg_lo:[0,1] neg_hi:[0,1]
	v_mov_b32_e32 v183, v175
	v_pk_add_f32 v[176:177], v[184:185], v[172:173]
	s_nop 0
	v_pk_add_f32 v[178:179], v[176:177], v[176:177] op_sel:[0,1] op_sel_hi:[1,0]
	s_nop 0
	v_pk_add_f32 v[174:175], v[174:175], v[178:179] op_sel:[1,0] op_sel_hi:[0,1]
	v_mov_b32_e32 v177, v174
	v_pk_add_f32 v[180:181], v[176:177], v[182:183] neg_lo:[0,1] neg_hi:[0,1]
	v_mov_b32_e32 v173, v178
	v_sub_f32_e32 v151, v176, v180
	v_pk_add_f32 v[172:173], v[172:173], v[180:181] neg_lo:[0,1] neg_hi:[0,1]
	v_sub_f32_e32 v151, v182, v151
	v_add_f32_e32 v151, v172, v151
	v_add_f32_e32 v151, v151, v173
	v_add_f32_e32 v151, v174, v151
	v_cndmask_b32_e32 v151, v167, v151, vcc
	v_cmp_ngt_f32_e32 vcc, -1.0, v156
	s_nop 1
	v_cndmask_b32_e32 v151, v168, v151, vcc
	v_cmp_neq_f32_e32 vcc, -1.0, v156
	s_nop 1
	v_cndmask_b32_e32 v151, v169, v151, vcc
	v_cmp_lt_f32_e64 vcc, |v156|, s71
	s_nop 1
	v_cndmask_b32_e32 v151, v151, v156, vcc
;     __device__ __forceinline__ void operator()(const f32x4 (&acc)[2][2][4][2], const Unit& u, int wr, int wc, int fr, int fq) const {
;     ...
;                         for (int i = 0; i < 4; ++i) { float x0 = v0[i] + dt_bias[c0 + i], x1 = v1[i] + dt_bias[c0 + 4 + i];
;                             dp[i] = x0 > 20.f ? x0 : log1pf(__expf(x0)); dp[4 + i] = x1 > 20.f ? x1 : log1pf(__expf(x1)); }
.LBB0_857:
	s_or_b64 exec, exec, s[24:25]
	v_add_f32_e32 v136, v58, v136
	v_cmp_nlt_f32_e32 vcc, s67, v136
	flat_store_dword v[154:155], v151 offset:8
	s_and_saveexec_b64 s[24:25], vcc
	s_cbranch_execz .LBB0_859
	v_mul_f32_e32 v136, 0x3fb8aa3b, v136
	v_exp_f32_e32 v136, v136
	s_nop 0
	v_add_f32_e32 v151, 1.0, v136
	v_frexp_mant_f32_e32 v174, v151
	v_cvt_f64_f32_e32 v[172:173], v151
	v_add_f32_e32 v156, -1.0, v151
	v_frexp_exp_i32_f64_e32 v172, v[172:173]
	v_cmp_gt_f32_e32 vcc, s68, v174
	v_sub_f32_e32 v175, v156, v151
	v_sub_f32_e32 v156, v136, v156
	v_subbrev_co_u32_e32 v180, vcc, 0, v172, vcc
	v_add_f32_e32 v175, 1.0, v175
	v_sub_u32_e32 v172, 0, v180
	v_add_f32_e32 v156, v156, v175
	v_ldexp_f32 v151, v151, v172
	v_ldexp_f32 v156, v156, v172
	v_add_f32_e32 v172, -1.0, v151
	v_add_f32_e32 v173, 1.0, v172
	v_sub_f32_e32 v173, v151, v173
	v_add_f32_e32 v174, v156, v173
	v_add_f32_e32 v173, 1.0, v151
	v_add_f32_e32 v175, -1.0, v173
	v_sub_f32_e32 v151, v151, v175
	v_add_f32_e32 v151, v156, v151
	v_add_f32_e32 v156, v173, v151
	v_rcp_f32_e32 v181, v156
	v_sub_f32_e32 v173, v156, v173
	v_sub_f32_e32 v151, v151, v173
	v_add_f32_e32 v173, v172, v174
	v_sub_f32_e32 v172, v173, v172
	v_mul_f32_e32 v183, v173, v181
	v_sub_f32_e32 v182, v174, v172
	v_mul_f32_e32 v174, v156, v183
	v_fma_f32 v176, v183, v156, -v174
	v_fmac_f32_e32 v176, v183, v151
	v_add_f32_e32 v172, v174, v176
	v_sub_f32_e32 v175, v173, v172
	v_pk_add_f32 v[178:179], v[172:173], v[174:175] neg_lo:[0,1] neg_hi:[0,1]
	v_mov_b32_e32 v177, v172
	v_pk_add_f32 v[172:173], v[178:179], v[176:177] neg_lo:[0,1] neg_hi:[0,1]
	v_cmp_neq_f32_e32 vcc, s70, v136
	v_add_f32_e32 v173, v182, v173
	v_add_f32_e32 v172, v172, v173
	v_add_f32_e32 v173, v175, v172
	v_mul_f32_e32 v182, v181, v173
	v_mul_f32_e32 v174, v156, v182
	v_fma_f32 v176, v182, v156, -v174
	v_fmac_f32_e32 v176, v182, v151
	v_sub_f32_e32 v151, v175, v173
	v_add_f32_e32 v151, v172, v151
	v_add_f32_e32 v172, v174, v176
	v_sub_f32_e32 v175, v173, v172
	v_pk_add_f32 v[178:179], v[172:173], v[174:175] neg_lo:[0,1] neg_hi:[0,1]
	v_mov_b32_e32 v177, v172
	v_pk_add_f32 v[172:173], v[178:179], v[176:177] neg_lo:[0,1] neg_hi:[0,1]
	v_add_f32_e32 v156, v183, v182
	v_add_f32_e32 v151, v151, v173
	v_add_f32_e32 v151, v172, v151
	v_add_f32_e32 v151, v175, v151
	v_sub_f32_e32 v172, v156, v183
	v_mul_f32_e32 v151, v181, v151
	v_sub_f32_e32 v172, v182, v172
	v_add_f32_e32 v173, v172, v151
	v_add_f32_e32 v174, v156, v173
	v_cvt_f32_i32_e32 v172, v180
	v_mul_f32_e32 v176, v174, v174
	v_fmamk_f32 v151, v176, 0x3e9b6dac, v166
	v_sub_f32_e32 v156, v174, v156
	v_fmaak_f32 v151, v176, v151, 0x3f2aaada
	v_sub_f32_e32 v156, v173, v156
	v_mul_f32_e32 v173, v174, v176
	v_pk_mul_f32 v[176:177], v[172:173], v[150:151]
	v_ldexp_f32 v175, v174, 1
	v_fma_f32 v174, v172, s69, -v176
	v_fmac_f32_e32 v174, 0xb102e308, v172
	v_pk_add_f32 v[172:173], v[176:177], v[174:175]
	v_ldexp_f32 v156, v156, 1
	v_sub_f32_e32 v151, v173, v175
	v_sub_f32_e32 v151, v177, v151
	v_add_f32_e32 v179, v156, v151
	v_mov_b32_e32 v178, v176
	v_pk_add_f32 v[176:177], v[172:173], v[176:177] neg_lo:[0,1] neg_hi:[0,1]
	v_pk_add_f32 v[180:181], v[172:173], v[178:179]
	v_mov_b32_e32 v175, v172
	v_mov_b32_e32 v177, v181
	v_pk_add_f32 v[182:183], v[174:175], v[176:177] neg_lo:[0,1] neg_hi:[0,1]
	v_pk_add_f32 v[174:175], v[174:175], v[176:177]
	v_mov_b32_e32 v178, v179
	v_pk_add_f32 v[176:177], v[174:175], v[172:173] op_sel:[1,0] op_sel_hi:[0,1] neg_lo:[0,1] neg_hi:[0,1]
	v_pk_add_f32 v[184:185], v[180:181], v[176:177] op_sel_hi:[1,0] neg_lo:[0,1] neg_hi:[0,1]
	v_mov_b32_e32 v180, v181
	v_mov_b32_e32 v181, v175
	v_pk_mov_b32 v[176:177], v[172:173], v[176:177] op_sel:[1,0]
	v_mov_b32_e32 v179, v172
	v_pk_add_f32 v[176:177], v[180:181], v[176:177] neg_lo:[0,1] neg_hi:[0,1]
	v_mov_b32_e32 v184, v182
	v_pk_add_f32 v[172:173], v[178:179], v[176:177] neg_lo:[0,1] neg_hi:[0,1]
	v_mov_b32_e32 v183, v175
	v_pk_add_f32 v[176:177], v[184:185], v[172:173]
	s_nop 0
	v_pk_add_f32 v[178:179], v[176:177], v[176:177] op_sel:[0,1] op_sel_hi:[1,0]
	s_nop 0
	v_pk_add_f32 v[174:175], v[174:175], v[178:179] op_sel:[1,0] op_sel_hi:[0,1]
	v_mov_b32_e32 v177, v174
	v_pk_add_f32 v[180:181], v[176:177], v[182:183] neg_lo:[0,1] neg_hi:[0,1]
	v_mov_b32_e32 v173, v178
	v_sub_f32_e32 v151, v176, v180
	v_pk_add_f32 v[172:173], v[172:173], v[180:181] neg_lo:[0,1] neg_hi:[0,1]
	v_sub_f32_e32 v151, v182, v151
	v_add_f32_e32 v151, v172, v151
	v_add_f32_e32 v151, v151, v173
	v_add_f32_e32 v151, v174, v151
	v_cndmask_b32_e32 v151, v167, v151, vcc
	v_cmp_ngt_f32_e32 vcc, -1.0, v136
	s_nop 1
	v_cndmask_b32_e32 v151, v168, v151, vcc
	v_cmp_neq_f32_e32 vcc, -1.0, v136
	s_nop 1
	v_cndmask_b32_e32 v151, v169, v151, vcc
	v_cmp_lt_f32_e64 vcc, |v136|, s71
	s_nop 1
	v_cndmask_b32_e32 v136, v151, v136, vcc
;     __device__ __forceinline__ void operator()(const f32x4 (&acc)[2][2][4][2], const Unit& u, int wr, int wc, int fr, int fq) const {
;     ...
;                         for (int i = 0; i < 4; ++i) { float x0 = v0[i] + dt_bias[c0 + i], x1 = v1[i] + dt_bias[c0 + 4 + i];
;                             dp[i] = x0 > 20.f ? x0 : log1pf(__expf(x0)); dp[4 + i] = x1 > 20.f ? x1 : log1pf(__expf(x1)); }
.LBB0_859:
	s_or_b64 exec, exec, s[24:25]
	flat_store_dword v[154:155], v136 offset:24
	v_mov_b32_e32 v136, v203
	v_add_f32_e32 v151, v63, v136
	v_mov_b32_e32 v136, v207
	v_cmp_nlt_f32_e32 vcc, s67, v151
	s_and_saveexec_b64 s[24:25], vcc
	s_cbranch_execz .LBB0_861
	v_mul_f32_e32 v151, 0x3fb8aa3b, v151
	v_exp_f32_e32 v156, v151
	s_nop 0
	v_add_f32_e32 v151, 1.0, v156
	v_frexp_mant_f32_e32 v175, v151
	v_cvt_f64_f32_e32 v[172:173], v151
	v_add_f32_e32 v174, -1.0, v151
	v_frexp_exp_i32_f64_e32 v172, v[172:173]
	v_cmp_gt_f32_e32 vcc, s68, v175
	v_sub_f32_e32 v176, v174, v151
	v_sub_f32_e32 v174, v156, v174
	v_subbrev_co_u32_e32 v180, vcc, 0, v172, vcc
	v_add_f32_e32 v176, 1.0, v176
	v_sub_u32_e32 v172, 0, v180
	v_add_f32_e32 v174, v174, v176
	v_ldexp_f32 v151, v151, v172
	v_ldexp_f32 v172, v174, v172
	v_add_f32_e32 v174, -1.0, v151
	v_add_f32_e32 v173, 1.0, v174
	v_sub_f32_e32 v173, v151, v173
	v_add_f32_e32 v175, v172, v173
	v_add_f32_e32 v173, 1.0, v151
	v_add_f32_e32 v176, -1.0, v173
	v_sub_f32_e32 v151, v151, v176
	v_add_f32_e32 v151, v172, v151
	v_add_f32_e32 v181, v173, v151
	v_rcp_f32_e32 v182, v181
	v_sub_f32_e32 v172, v181, v173
	v_add_f32_e32 v173, v174, v175
	v_sub_f32_e32 v151, v151, v172
	v_mul_f32_e32 v184, v173, v182
	v_sub_f32_e32 v172, v173, v174
	v_mul_f32_e32 v174, v181, v184
	v_fma_f32 v176, v184, v181, -v174
	v_fmac_f32_e32 v176, v184, v151
	v_sub_f32_e32 v183, v175, v172
	v_add_f32_e32 v172, v174, v176
	v_sub_f32_e32 v175, v173, v172
	v_pk_add_f32 v[178:179], v[172:173], v[174:175] neg_lo:[0,1] neg_hi:[0,1]
	v_mov_b32_e32 v177, v172
	v_pk_add_f32 v[172:173], v[178:179], v[176:177] neg_lo:[0,1] neg_hi:[0,1]
	v_cmp_neq_f32_e32 vcc, s70, v156
	v_add_f32_e32 v173, v183, v173
	v_add_f32_e32 v172, v172, v173
	v_add_f32_e32 v173, v175, v172
	v_mul_f32_e32 v183, v182, v173
	v_mul_f32_e32 v174, v181, v183
	v_fma_f32 v176, v183, v181, -v174
	v_fmac_f32_e32 v176, v183, v151
	v_sub_f32_e32 v151, v175, v173
	v_add_f32_e32 v151, v172, v151
	v_add_f32_e32 v172, v174, v176
	v_sub_f32_e32 v175, v173, v172
	v_pk_add_f32 v[178:179], v[172:173], v[174:175] neg_lo:[0,1] neg_hi:[0,1]
	v_mov_b32_e32 v177, v172
	v_pk_add_f32 v[172:173], v[178:179], v[176:177] neg_lo:[0,1] neg_hi:[0,1]
	s_nop 0
	v_add_f32_e32 v151, v151, v173
	v_add_f32_e32 v151, v172, v151
	v_add_f32_e32 v173, v184, v183
	v_add_f32_e32 v151, v175, v151
	v_sub_f32_e32 v172, v173, v184
	v_mul_f32_e32 v151, v182, v151
	v_sub_f32_e32 v172, v183, v172
	v_add_f32_e32 v174, v172, v151
	v_add_f32_e32 v176, v173, v174
	v_cvt_f32_i32_e32 v172, v180
	v_mul_f32_e32 v177, v176, v176
	v_sub_f32_e32 v173, v176, v173
	v_fmamk_f32 v151, v177, 0x3e9b6dac, v166
	v_sub_f32_e32 v173, v174, v173
	v_fmaak_f32 v151, v177, v151, 0x3f2aaada
	v_ldexp_f32 v178, v173, 1
	v_mul_f32_e32 v173, v176, v177
	v_ldexp_f32 v175, v176, 1
	v_pk_mul_f32 v[176:177], v[172:173], v[150:151]
	s_nop 0
	v_fma_f32 v174, v172, s69, -v176
	v_fmac_f32_e32 v174, 0xb102e308, v172
	v_pk_add_f32 v[172:173], v[176:177], v[174:175]
	s_nop 0
	v_sub_f32_e32 v151, v173, v175
	v_sub_f32_e32 v151, v177, v151
	v_add_f32_e32 v179, v178, v151
	v_mov_b32_e32 v178, v176
	v_pk_add_f32 v[176:177], v[172:173], v[176:177] neg_lo:[0,1] neg_hi:[0,1]
	v_pk_add_f32 v[180:181], v[172:173], v[178:179]
	v_mov_b32_e32 v175, v172
	v_mov_b32_e32 v177, v181
	v_pk_add_f32 v[182:183], v[174:175], v[176:177] neg_lo:[0,1] neg_hi:[0,1]
	v_pk_add_f32 v[174:175], v[174:175], v[176:177]
	v_mov_b32_e32 v178, v179
	v_pk_add_f32 v[176:177], v[174:175], v[172:173] op_sel:[1,0] op_sel_hi:[0,1] neg_lo:[0,1] neg_hi:[0,1]
	v_pk_add_f32 v[184:185], v[180:181], v[176:177] op_sel_hi:[1,0] neg_lo:[0,1] neg_hi:[0,1]
	v_mov_b32_e32 v180, v181
	v_mov_b32_e32 v181, v175
	v_pk_mov_b32 v[176:177], v[172:173], v[176:177] op_sel:[1,0]
	v_mov_b32_e32 v179, v172
	v_pk_add_f32 v[176:177], v[180:181], v[176:177] neg_lo:[0,1] neg_hi:[0,1]
	v_mov_b32_e32 v184, v182
	v_pk_add_f32 v[172:173], v[178:179], v[176:177] neg_lo:[0,1] neg_hi:[0,1]
	v_mov_b32_e32 v183, v175
	v_pk_add_f32 v[176:177], v[184:185], v[172:173]
	s_nop 0
	v_pk_add_f32 v[178:179], v[176:177], v[176:177] op_sel:[0,1] op_sel_hi:[1,0]
	s_nop 0
	v_pk_add_f32 v[174:175], v[174:175], v[178:179] op_sel:[1,0] op_sel_hi:[0,1]
	v_mov_b32_e32 v177, v174
	v_pk_add_f32 v[180:181], v[176:177], v[182:183] neg_lo:[0,1] neg_hi:[0,1]
	v_mov_b32_e32 v173, v178
	v_sub_f32_e32 v151, v176, v180
	v_pk_add_f32 v[172:173], v[172:173], v[180:181] neg_lo:[0,1] neg_hi:[0,1]
	v_sub_f32_e32 v151, v182, v151
	v_add_f32_e32 v151, v172, v151
	v_add_f32_e32 v151, v151, v173
	v_add_f32_e32 v151, v174, v151
	v_cndmask_b32_e32 v151, v167, v151, vcc
	v_cmp_ngt_f32_e32 vcc, -1.0, v156
	s_nop 1
	v_cndmask_b32_e32 v151, v168, v151, vcc
	v_cmp_neq_f32_e32 vcc, -1.0, v156
	s_nop 1
	v_cndmask_b32_e32 v151, v169, v151, vcc
	v_cmp_lt_f32_e64 vcc, |v156|, s71
	s_nop 1
	v_cndmask_b32_e32 v151, v151, v156, vcc
;     __device__ __forceinline__ void operator()(const f32x4 (&acc)[2][2][4][2], const Unit& u, int wr, int wc, int fr, int fq) const {
;     ...
;                         for (int i = 0; i < 4; ++i) { float x0 = v0[i] + dt_bias[c0 + i], x1 = v1[i] + dt_bias[c0 + 4 + i];
;                             dp[i] = x0 > 20.f ? x0 : log1pf(__expf(x0)); dp[4 + i] = x1 > 20.f ? x1 : log1pf(__expf(x1)); }
.LBB0_861:
	s_or_b64 exec, exec, s[24:25]
	v_add_f32_e32 v136, v59, v136
	v_cmp_nlt_f32_e32 vcc, s67, v136
	flat_store_dword v[154:155], v151 offset:12
	s_and_saveexec_b64 s[24:25], vcc
	s_cbranch_execz .LBB0_863
	v_mul_f32_e32 v136, 0x3fb8aa3b, v136
	v_exp_f32_e32 v136, v136
	s_nop 0
	v_add_f32_e32 v151, 1.0, v136
	v_frexp_mant_f32_e32 v174, v151
	v_cvt_f64_f32_e32 v[172:173], v151
	v_add_f32_e32 v156, -1.0, v151
	v_frexp_exp_i32_f64_e32 v172, v[172:173]
	v_cmp_gt_f32_e32 vcc, s68, v174
	v_sub_f32_e32 v175, v156, v151
	v_sub_f32_e32 v156, v136, v156
	v_subbrev_co_u32_e32 v180, vcc, 0, v172, vcc
	v_add_f32_e32 v175, 1.0, v175
	v_sub_u32_e32 v172, 0, v180
	v_add_f32_e32 v156, v156, v175
	v_ldexp_f32 v151, v151, v172
	v_ldexp_f32 v156, v156, v172
	v_add_f32_e32 v172, -1.0, v151
	v_add_f32_e32 v173, 1.0, v172
	v_sub_f32_e32 v173, v151, v173
	v_add_f32_e32 v174, v156, v173
	v_add_f32_e32 v173, 1.0, v151
	v_add_f32_e32 v175, -1.0, v173
	v_sub_f32_e32 v151, v151, v175
	v_add_f32_e32 v151, v156, v151
	v_add_f32_e32 v156, v173, v151
	v_rcp_f32_e32 v181, v156
	v_sub_f32_e32 v173, v156, v173
	v_sub_f32_e32 v151, v151, v173
	v_add_f32_e32 v173, v172, v174
	v_sub_f32_e32 v172, v173, v172
	v_mul_f32_e32 v183, v173, v181
	v_sub_f32_e32 v182, v174, v172
	v_mul_f32_e32 v174, v156, v183
	v_fma_f32 v176, v183, v156, -v174
	v_fmac_f32_e32 v176, v183, v151
	v_add_f32_e32 v172, v174, v176
	v_sub_f32_e32 v175, v173, v172
	v_pk_add_f32 v[178:179], v[172:173], v[174:175] neg_lo:[0,1] neg_hi:[0,1]
	v_mov_b32_e32 v177, v172
	v_pk_add_f32 v[172:173], v[178:179], v[176:177] neg_lo:[0,1] neg_hi:[0,1]
	v_cmp_neq_f32_e32 vcc, s70, v136
	v_add_f32_e32 v173, v182, v173
	v_add_f32_e32 v172, v172, v173
	v_add_f32_e32 v173, v175, v172
	v_mul_f32_e32 v182, v181, v173
	v_mul_f32_e32 v174, v156, v182
	v_fma_f32 v176, v182, v156, -v174
	v_fmac_f32_e32 v176, v182, v151
	v_sub_f32_e32 v151, v175, v173
	v_add_f32_e32 v151, v172, v151
	v_add_f32_e32 v172, v174, v176
	v_sub_f32_e32 v175, v173, v172
	v_pk_add_f32 v[178:179], v[172:173], v[174:175] neg_lo:[0,1] neg_hi:[0,1]
	v_mov_b32_e32 v177, v172
	v_pk_add_f32 v[172:173], v[178:179], v[176:177] neg_lo:[0,1] neg_hi:[0,1]
	v_add_f32_e32 v156, v183, v182
	v_add_f32_e32 v151, v151, v173
	v_add_f32_e32 v151, v172, v151
	v_add_f32_e32 v151, v175, v151
	v_sub_f32_e32 v172, v156, v183
	v_mul_f32_e32 v151, v181, v151
	v_sub_f32_e32 v172, v182, v172
	v_add_f32_e32 v173, v172, v151
	v_add_f32_e32 v174, v156, v173
	v_cvt_f32_i32_e32 v172, v180
	v_mul_f32_e32 v176, v174, v174
	v_fmamk_f32 v151, v176, 0x3e9b6dac, v166
	v_sub_f32_e32 v156, v174, v156
	v_fmaak_f32 v151, v176, v151, 0x3f2aaada
	v_sub_f32_e32 v156, v173, v156
	v_mul_f32_e32 v173, v174, v176
	v_pk_mul_f32 v[176:177], v[172:173], v[150:151]
	v_ldexp_f32 v175, v174, 1
	v_fma_f32 v174, v172, s69, -v176
	v_fmac_f32_e32 v174, 0xb102e308, v172
	v_pk_add_f32 v[172:173], v[176:177], v[174:175]
	v_ldexp_f32 v156, v156, 1
	v_sub_f32_e32 v151, v173, v175
	v_sub_f32_e32 v151, v177, v151
	v_add_f32_e32 v179, v156, v151
	v_mov_b32_e32 v178, v176
	v_pk_add_f32 v[176:177], v[172:173], v[176:177] neg_lo:[0,1] neg_hi:[0,1]
	v_pk_add_f32 v[180:181], v[172:173], v[178:179]
	v_mov_b32_e32 v175, v172
	v_mov_b32_e32 v177, v181
	v_pk_add_f32 v[182:183], v[174:175], v[176:177] neg_lo:[0,1] neg_hi:[0,1]
	v_pk_add_f32 v[174:175], v[174:175], v[176:177]
	v_mov_b32_e32 v178, v179
	v_pk_add_f32 v[176:177], v[174:175], v[172:173] op_sel:[1,0] op_sel_hi:[0,1] neg_lo:[0,1] neg_hi:[0,1]
	v_pk_add_f32 v[184:185], v[180:181], v[176:177] op_sel_hi:[1,0] neg_lo:[0,1] neg_hi:[0,1]
	v_mov_b32_e32 v180, v181
	v_mov_b32_e32 v181, v175
	v_pk_mov_b32 v[176:177], v[172:173], v[176:177] op_sel:[1,0]
	v_mov_b32_e32 v179, v172
	v_pk_add_f32 v[176:177], v[180:181], v[176:177] neg_lo:[0,1] neg_hi:[0,1]
	v_mov_b32_e32 v184, v182
	v_pk_add_f32 v[172:173], v[178:179], v[176:177] neg_lo:[0,1] neg_hi:[0,1]
	v_mov_b32_e32 v183, v175
	v_pk_add_f32 v[176:177], v[184:185], v[172:173]
	s_nop 0
	v_pk_add_f32 v[178:179], v[176:177], v[176:177] op_sel:[0,1] op_sel_hi:[1,0]
	s_nop 0
	v_pk_add_f32 v[174:175], v[174:175], v[178:179] op_sel:[1,0] op_sel_hi:[0,1]
	v_mov_b32_e32 v177, v174
	v_pk_add_f32 v[180:181], v[176:177], v[182:183] neg_lo:[0,1] neg_hi:[0,1]
	v_mov_b32_e32 v173, v178
	v_sub_f32_e32 v151, v176, v180
	v_pk_add_f32 v[172:173], v[172:173], v[180:181] neg_lo:[0,1] neg_hi:[0,1]
	v_sub_f32_e32 v151, v182, v151
	v_add_f32_e32 v151, v172, v151
	v_add_f32_e32 v151, v151, v173
	v_add_f32_e32 v151, v174, v151
	v_cndmask_b32_e32 v151, v167, v151, vcc
	v_cmp_ngt_f32_e32 vcc, -1.0, v136
	s_nop 1
	v_cndmask_b32_e32 v151, v168, v151, vcc
	v_cmp_neq_f32_e32 vcc, -1.0, v136
	s_nop 1
	v_cndmask_b32_e32 v151, v169, v151, vcc
	v_cmp_lt_f32_e64 vcc, |v136|, s71
	s_nop 1
	v_cndmask_b32_e32 v136, v151, v136, vcc
;     __device__ __forceinline__ void operator()(const f32x4 (&acc)[2][2][4][2], const Unit& u, int wr, int wc, int fr, int fq) const {
;     ...
;                         for (int i = 0; i < 4; ++i) { float x0 = v0[i] + dt_bias[c0 + i], x1 = v1[i] + dt_bias[c0 + 4 + i];
;                             dp[i] = x0 > 20.f ? x0 : log1pf(__expf(x0)); dp[4 + i] = x1 > 20.f ? x1 : log1pf(__expf(x1)); }
.LBB0_863:
	s_or_b64 exec, exec, s[24:25]
	flat_store_dword v[154:155], v136 offset:28
	v_mov_b32_e32 v136, v200
	v_add_f32_e32 v151, v44, v136
	v_mov_b32_e32 v136, v204
	v_cmp_nlt_f32_e32 vcc, s67, v151
	s_and_saveexec_b64 s[24:25], vcc
	s_cbranch_execz .LBB0_865
	v_mul_f32_e32 v151, 0x3fb8aa3b, v151
	v_exp_f32_e32 v156, v151
	s_nop 0
	v_add_f32_e32 v151, 1.0, v156
	v_frexp_mant_f32_e32 v173, v151
	v_cvt_f64_f32_e32 v[154:155], v151
	v_add_f32_e32 v172, -1.0, v151
	v_frexp_exp_i32_f64_e32 v154, v[154:155]
	v_cmp_gt_f32_e32 vcc, s68, v173
	v_sub_f32_e32 v174, v172, v151
	v_sub_f32_e32 v172, v156, v172
	v_subbrev_co_u32_e32 v178, vcc, 0, v154, vcc
	v_add_f32_e32 v174, 1.0, v174
	v_sub_u32_e32 v154, 0, v178
	v_add_f32_e32 v172, v172, v174
	v_ldexp_f32 v151, v151, v154
	v_ldexp_f32 v154, v172, v154
	v_add_f32_e32 v172, -1.0, v151
	v_add_f32_e32 v155, 1.0, v172
	v_sub_f32_e32 v155, v151, v155
	v_add_f32_e32 v173, v154, v155
	v_add_f32_e32 v155, 1.0, v151
	v_add_f32_e32 v174, -1.0, v155
	v_sub_f32_e32 v151, v151, v174
	v_add_f32_e32 v151, v154, v151
	v_add_f32_e32 v179, v155, v151
	v_rcp_f32_e32 v180, v179
	v_sub_f32_e32 v154, v179, v155
	v_add_f32_e32 v155, v172, v173
	v_sub_f32_e32 v151, v151, v154
	v_mul_f32_e32 v182, v155, v180
	v_sub_f32_e32 v154, v155, v172
	v_mul_f32_e32 v172, v179, v182
	v_fma_f32 v174, v182, v179, -v172
	v_fmac_f32_e32 v174, v182, v151
	v_sub_f32_e32 v181, v173, v154
	v_add_f32_e32 v154, v172, v174
	v_sub_f32_e32 v173, v155, v154
	v_pk_add_f32 v[176:177], v[154:155], v[172:173] neg_lo:[0,1] neg_hi:[0,1]
	v_mov_b32_e32 v175, v154
	v_pk_add_f32 v[154:155], v[176:177], v[174:175] neg_lo:[0,1] neg_hi:[0,1]
	v_cmp_neq_f32_e32 vcc, s70, v156
	v_add_f32_e32 v155, v181, v155
	v_add_f32_e32 v154, v154, v155
	v_add_f32_e32 v155, v173, v154
	v_mul_f32_e32 v181, v180, v155
	v_mul_f32_e32 v172, v179, v181
	v_fma_f32 v174, v181, v179, -v172
	v_fmac_f32_e32 v174, v181, v151
	v_sub_f32_e32 v151, v173, v155
	v_add_f32_e32 v151, v154, v151
	v_add_f32_e32 v154, v172, v174
	v_sub_f32_e32 v173, v155, v154
	v_pk_add_f32 v[176:177], v[154:155], v[172:173] neg_lo:[0,1] neg_hi:[0,1]
	v_mov_b32_e32 v175, v154
	v_pk_add_f32 v[154:155], v[176:177], v[174:175] neg_lo:[0,1] neg_hi:[0,1]
	s_nop 0
	v_add_f32_e32 v151, v151, v155
	v_add_f32_e32 v151, v154, v151
	v_add_f32_e32 v155, v182, v181
	v_add_f32_e32 v151, v173, v151
	v_sub_f32_e32 v154, v155, v182
	v_mul_f32_e32 v151, v180, v151
	v_sub_f32_e32 v154, v181, v154
	v_add_f32_e32 v172, v154, v151
	v_add_f32_e32 v174, v155, v172
	v_cvt_f32_i32_e32 v154, v178
	v_mul_f32_e32 v175, v174, v174
	v_sub_f32_e32 v155, v174, v155
	v_fmamk_f32 v151, v175, 0x3e9b6dac, v166
	v_sub_f32_e32 v155, v172, v155
	v_fmaak_f32 v151, v175, v151, 0x3f2aaada
	v_ldexp_f32 v176, v155, 1
	v_mul_f32_e32 v155, v174, v175
	v_ldexp_f32 v173, v174, 1
	v_pk_mul_f32 v[174:175], v[154:155], v[150:151]
	s_nop 0
	v_fma_f32 v172, v154, s69, -v174
	v_fmac_f32_e32 v172, 0xb102e308, v154
	v_pk_add_f32 v[154:155], v[174:175], v[172:173]
	s_nop 0
	v_sub_f32_e32 v151, v155, v173
	v_sub_f32_e32 v151, v175, v151
	v_add_f32_e32 v177, v176, v151
	v_mov_b32_e32 v176, v174
	v_pk_add_f32 v[174:175], v[154:155], v[174:175] neg_lo:[0,1] neg_hi:[0,1]
	v_pk_add_f32 v[178:179], v[154:155], v[176:177]
	v_mov_b32_e32 v173, v154
	v_mov_b32_e32 v175, v179
	v_pk_add_f32 v[180:181], v[172:173], v[174:175] neg_lo:[0,1] neg_hi:[0,1]
	v_pk_add_f32 v[172:173], v[172:173], v[174:175]
	v_mov_b32_e32 v176, v177
	v_pk_add_f32 v[174:175], v[172:173], v[154:155] op_sel:[1,0] op_sel_hi:[0,1] neg_lo:[0,1] neg_hi:[0,1]
	v_pk_add_f32 v[182:183], v[178:179], v[174:175] op_sel_hi:[1,0] neg_lo:[0,1] neg_hi:[0,1]
	v_mov_b32_e32 v178, v179
	v_mov_b32_e32 v179, v173
	v_pk_mov_b32 v[174:175], v[154:155], v[174:175] op_sel:[1,0]
	v_mov_b32_e32 v177, v154
	v_pk_add_f32 v[174:175], v[178:179], v[174:175] neg_lo:[0,1] neg_hi:[0,1]
	v_mov_b32_e32 v182, v180
	v_pk_add_f32 v[154:155], v[176:177], v[174:175] neg_lo:[0,1] neg_hi:[0,1]
	v_mov_b32_e32 v181, v173
	v_pk_add_f32 v[174:175], v[182:183], v[154:155]
	s_nop 0
	v_pk_add_f32 v[176:177], v[174:175], v[174:175] op_sel:[0,1] op_sel_hi:[1,0]
	s_nop 0
	v_pk_add_f32 v[172:173], v[172:173], v[176:177] op_sel:[1,0] op_sel_hi:[0,1]
	v_mov_b32_e32 v175, v172
	v_pk_add_f32 v[178:179], v[174:175], v[180:181] neg_lo:[0,1] neg_hi:[0,1]
	v_mov_b32_e32 v155, v176
	v_sub_f32_e32 v151, v174, v178
	v_pk_add_f32 v[154:155], v[154:155], v[178:179] neg_lo:[0,1] neg_hi:[0,1]
	v_sub_f32_e32 v151, v180, v151
	v_add_f32_e32 v151, v154, v151
	v_add_f32_e32 v151, v151, v155
	v_add_f32_e32 v151, v172, v151
	v_cndmask_b32_e32 v151, v167, v151, vcc
	v_cmp_ngt_f32_e32 vcc, -1.0, v156
	s_nop 1
	v_cndmask_b32_e32 v151, v168, v151, vcc
	v_cmp_neq_f32_e32 vcc, -1.0, v156
	s_nop 1
	v_cndmask_b32_e32 v151, v169, v151, vcc
	v_cmp_lt_f32_e64 vcc, |v156|, s71
	s_nop 1
	v_cndmask_b32_e32 v151, v151, v156, vcc
;     __device__ __forceinline__ void operator()(const f32x4 (&acc)[2][2][4][2], const Unit& u, int wr, int wc, int fr, int fq) const {
;     ...
;                     for (int m = 0; m < 4; ++m) { const int r = row0 + ai * HALF + m * 16;
;                         const f32x4 v0 = acc[ai][0][m][0], v1 = acc[ai][0][m][1]; float* dp = DT + (size_t)r * 32 + c0;
; #pragma unroll
;                         for (int i = 0; i < 4; ++i) { float x0 = v0[i] + dt_bias[c0 + i], x1 = v1[i] + dt_bias[c0 + 4 + i];
;                             dp[i] = x0 > 20.f ? x0 : log1pf(__expf(x0)); dp[4 + i] = x1 > 20.f ? x1 : log1pf(__expf(x1)); }
.LBB0_865:
	s_or_b64 exec, exec, s[24:25]
	v_lshlrev_b64 v[154:155], 7, v[152:153]
	v_lshl_add_u64 v[154:155], v[138:139], 0, v[154:155]
	v_add_co_u32_e32 v172, vcc, 0x4000, v154
	v_add_f32_e32 v136, v40, v136
	v_addc_co_u32_e32 v173, vcc, 0, v155, vcc
	v_cmp_nlt_f32_e32 vcc, s67, v136
	flat_store_dword v[172:173], v151 offset:2048
	s_and_saveexec_b64 s[24:25], vcc
	s_cbranch_execz .LBB0_867
	v_mul_f32_e32 v136, 0x3fb8aa3b, v136
	v_exp_f32_e32 v136, v136
	s_nop 0
	v_add_f32_e32 v151, 1.0, v136
	v_frexp_mant_f32_e32 v174, v151
	v_cvt_f64_f32_e32 v[172:173], v151
	v_add_f32_e32 v156, -1.0, v151
	v_frexp_exp_i32_f64_e32 v172, v[172:173]
	v_cmp_gt_f32_e32 vcc, s68, v174
	v_sub_f32_e32 v175, v156, v151
	v_sub_f32_e32 v156, v136, v156
	v_subbrev_co_u32_e32 v180, vcc, 0, v172, vcc
	v_add_f32_e32 v175, 1.0, v175
	v_sub_u32_e32 v172, 0, v180
	v_add_f32_e32 v156, v156, v175
	v_ldexp_f32 v151, v151, v172
	v_ldexp_f32 v156, v156, v172
	v_add_f32_e32 v172, -1.0, v151
	v_add_f32_e32 v173, 1.0, v172
	v_sub_f32_e32 v173, v151, v173
	v_add_f32_e32 v174, v156, v173
	v_add_f32_e32 v173, 1.0, v151
	v_add_f32_e32 v175, -1.0, v173
	v_sub_f32_e32 v151, v151, v175
	v_add_f32_e32 v151, v156, v151
	v_add_f32_e32 v156, v173, v151
	v_rcp_f32_e32 v181, v156
	v_sub_f32_e32 v173, v156, v173
	v_sub_f32_e32 v151, v151, v173
	v_add_f32_e32 v173, v172, v174
	v_sub_f32_e32 v172, v173, v172
	v_mul_f32_e32 v183, v173, v181
	v_sub_f32_e32 v182, v174, v172
	v_mul_f32_e32 v174, v156, v183
	v_fma_f32 v176, v183, v156, -v174
	v_fmac_f32_e32 v176, v183, v151
	v_add_f32_e32 v172, v174, v176
	v_sub_f32_e32 v175, v173, v172
	v_pk_add_f32 v[178:179], v[172:173], v[174:175] neg_lo:[0,1] neg_hi:[0,1]
	v_mov_b32_e32 v177, v172
	v_pk_add_f32 v[172:173], v[178:179], v[176:177] neg_lo:[0,1] neg_hi:[0,1]
	v_cmp_neq_f32_e32 vcc, s70, v136
	v_add_f32_e32 v173, v182, v173
	v_add_f32_e32 v172, v172, v173
	v_add_f32_e32 v173, v175, v172
	v_mul_f32_e32 v182, v181, v173
	v_mul_f32_e32 v174, v156, v182
	v_fma_f32 v176, v182, v156, -v174
	v_fmac_f32_e32 v176, v182, v151
	v_sub_f32_e32 v151, v175, v173
	v_add_f32_e32 v151, v172, v151
	v_add_f32_e32 v172, v174, v176
	v_sub_f32_e32 v175, v173, v172
	v_pk_add_f32 v[178:179], v[172:173], v[174:175] neg_lo:[0,1] neg_hi:[0,1]
	v_mov_b32_e32 v177, v172
	v_pk_add_f32 v[172:173], v[178:179], v[176:177] neg_lo:[0,1] neg_hi:[0,1]
	v_add_f32_e32 v156, v183, v182
	v_add_f32_e32 v151, v151, v173
	v_add_f32_e32 v151, v172, v151
	v_add_f32_e32 v151, v175, v151
	v_sub_f32_e32 v172, v156, v183
	v_mul_f32_e32 v151, v181, v151
	v_sub_f32_e32 v172, v182, v172
	v_add_f32_e32 v173, v172, v151
	v_add_f32_e32 v174, v156, v173
	v_cvt_f32_i32_e32 v172, v180
	v_mul_f32_e32 v176, v174, v174
	v_fmamk_f32 v151, v176, 0x3e9b6dac, v166
	v_sub_f32_e32 v156, v174, v156
	v_fmaak_f32 v151, v176, v151, 0x3f2aaada
	v_sub_f32_e32 v156, v173, v156
	v_mul_f32_e32 v173, v174, v176
	v_pk_mul_f32 v[176:177], v[172:173], v[150:151]
	v_ldexp_f32 v175, v174, 1
	v_fma_f32 v174, v172, s69, -v176
	v_fmac_f32_e32 v174, 0xb102e308, v172
	v_pk_add_f32 v[172:173], v[176:177], v[174:175]
	v_ldexp_f32 v156, v156, 1
	v_sub_f32_e32 v151, v173, v175
	v_sub_f32_e32 v151, v177, v151
	v_add_f32_e32 v179, v156, v151
	v_mov_b32_e32 v178, v176
	v_pk_add_f32 v[176:177], v[172:173], v[176:177] neg_lo:[0,1] neg_hi:[0,1]
	v_pk_add_f32 v[180:181], v[172:173], v[178:179]
	v_mov_b32_e32 v175, v172
	v_mov_b32_e32 v177, v181
	v_pk_add_f32 v[182:183], v[174:175], v[176:177] neg_lo:[0,1] neg_hi:[0,1]
	v_pk_add_f32 v[174:175], v[174:175], v[176:177]
	v_mov_b32_e32 v178, v179
	v_pk_add_f32 v[176:177], v[174:175], v[172:173] op_sel:[1,0] op_sel_hi:[0,1] neg_lo:[0,1] neg_hi:[0,1]
	v_pk_add_f32 v[184:185], v[180:181], v[176:177] op_sel_hi:[1,0] neg_lo:[0,1] neg_hi:[0,1]
	v_mov_b32_e32 v180, v181
	v_mov_b32_e32 v181, v175
	v_pk_mov_b32 v[176:177], v[172:173], v[176:177] op_sel:[1,0]
	v_mov_b32_e32 v179, v172
	v_pk_add_f32 v[176:177], v[180:181], v[176:177] neg_lo:[0,1] neg_hi:[0,1]
	v_mov_b32_e32 v184, v182
	v_pk_add_f32 v[172:173], v[178:179], v[176:177] neg_lo:[0,1] neg_hi:[0,1]
	v_mov_b32_e32 v183, v175
	v_pk_add_f32 v[176:177], v[184:185], v[172:173]
	s_nop 0
	v_pk_add_f32 v[178:179], v[176:177], v[176:177] op_sel:[0,1] op_sel_hi:[1,0]
	s_nop 0
	v_pk_add_f32 v[174:175], v[174:175], v[178:179] op_sel:[1,0] op_sel_hi:[0,1]
	v_mov_b32_e32 v177, v174
	v_pk_add_f32 v[180:181], v[176:177], v[182:183] neg_lo:[0,1] neg_hi:[0,1]
	v_mov_b32_e32 v173, v178
	v_sub_f32_e32 v151, v176, v180
	v_pk_add_f32 v[172:173], v[172:173], v[180:181] neg_lo:[0,1] neg_hi:[0,1]
	v_sub_f32_e32 v151, v182, v151
	v_add_f32_e32 v151, v172, v151
	v_add_f32_e32 v151, v151, v173
	v_add_f32_e32 v151, v174, v151
	v_cndmask_b32_e32 v151, v167, v151, vcc
	v_cmp_ngt_f32_e32 vcc, -1.0, v136
	s_nop 1
	v_cndmask_b32_e32 v151, v168, v151, vcc
	v_cmp_neq_f32_e32 vcc, -1.0, v136
	s_nop 1
	v_cndmask_b32_e32 v151, v169, v151, vcc
	v_cmp_lt_f32_e64 vcc, |v136|, s71
	s_nop 1
	v_cndmask_b32_e32 v136, v151, v136, vcc
;     __device__ __forceinline__ void operator()(const f32x4 (&acc)[2][2][4][2], const Unit& u, int wr, int wc, int fr, int fq) const {
;     ...
;                         for (int i = 0; i < 4; ++i) { float x0 = v0[i] + dt_bias[c0 + i], x1 = v1[i] + dt_bias[c0 + 4 + i];
;                             dp[i] = x0 > 20.f ? x0 : log1pf(__expf(x0)); dp[4 + i] = x1 > 20.f ? x1 : log1pf(__expf(x1)); }
.LBB0_867:
	s_or_b64 exec, exec, s[24:25]
	s_mov_b64 s[24:25], 0x4800
	v_lshl_add_u64 v[154:155], v[154:155], 0, s[24:25]
	flat_store_dword v[154:155], v136 offset:16
	v_mov_b32_e32 v151, v201
	s_nop 0
	v_mov_b32_e32 v136, v205
	v_add_f32_e32 v151, v45, v151
	v_cmp_nlt_f32_e32 vcc, s67, v151
	s_and_saveexec_b64 s[24:25], vcc
	s_cbranch_execz .LBB0_869
	v_mul_f32_e32 v151, 0x3fb8aa3b, v151
	v_exp_f32_e32 v156, v151
	s_nop 0
	v_add_f32_e32 v151, 1.0, v156
	v_frexp_mant_f32_e32 v175, v151
	v_cvt_f64_f32_e32 v[172:173], v151
	v_add_f32_e32 v174, -1.0, v151
	v_frexp_exp_i32_f64_e32 v172, v[172:173]
	v_cmp_gt_f32_e32 vcc, s68, v175
	v_sub_f32_e32 v176, v174, v151
	v_sub_f32_e32 v174, v156, v174
	v_subbrev_co_u32_e32 v180, vcc, 0, v172, vcc
	v_add_f32_e32 v176, 1.0, v176
	v_sub_u32_e32 v172, 0, v180
	v_add_f32_e32 v174, v174, v176
	v_ldexp_f32 v151, v151, v172
	v_ldexp_f32 v172, v174, v172
	v_add_f32_e32 v174, -1.0, v151
	v_add_f32_e32 v173, 1.0, v174
	v_sub_f32_e32 v173, v151, v173
	v_add_f32_e32 v175, v172, v173
	v_add_f32_e32 v173, 1.0, v151
	v_add_f32_e32 v176, -1.0, v173
	v_sub_f32_e32 v151, v151, v176
	v_add_f32_e32 v151, v172, v151
	v_add_f32_e32 v181, v173, v151
	v_rcp_f32_e32 v182, v181
	v_sub_f32_e32 v172, v181, v173
	v_add_f32_e32 v173, v174, v175
	v_sub_f32_e32 v151, v151, v172
	v_mul_f32_e32 v184, v173, v182
	v_sub_f32_e32 v172, v173, v174
	v_mul_f32_e32 v174, v181, v184
	v_fma_f32 v176, v184, v181, -v174
	v_fmac_f32_e32 v176, v184, v151
	v_sub_f32_e32 v183, v175, v172
	v_add_f32_e32 v172, v174, v176
	v_sub_f32_e32 v175, v173, v172
	v_pk_add_f32 v[178:179], v[172:173], v[174:175] neg_lo:[0,1] neg_hi:[0,1]
	v_mov_b32_e32 v177, v172
	v_pk_add_f32 v[172:173], v[178:179], v[176:177] neg_lo:[0,1] neg_hi:[0,1]
	v_cmp_neq_f32_e32 vcc, s70, v156
	v_add_f32_e32 v173, v183, v173
	v_add_f32_e32 v172, v172, v173
	v_add_f32_e32 v173, v175, v172
	v_mul_f32_e32 v183, v182, v173
	v_mul_f32_e32 v174, v181, v183
	v_fma_f32 v176, v183, v181, -v174
	v_fmac_f32_e32 v176, v183, v151
	v_sub_f32_e32 v151, v175, v173
	v_add_f32_e32 v151, v172, v151
	v_add_f32_e32 v172, v174, v176
	v_sub_f32_e32 v175, v173, v172
	v_pk_add_f32 v[178:179], v[172:173], v[174:175] neg_lo:[0,1] neg_hi:[0,1]
	v_mov_b32_e32 v177, v172
	v_pk_add_f32 v[172:173], v[178:179], v[176:177] neg_lo:[0,1] neg_hi:[0,1]
	s_nop 0
	v_add_f32_e32 v151, v151, v173
	v_add_f32_e32 v151, v172, v151
	v_add_f32_e32 v173, v184, v183
	v_add_f32_e32 v151, v175, v151
	v_sub_f32_e32 v172, v173, v184
	v_mul_f32_e32 v151, v182, v151
	v_sub_f32_e32 v172, v183, v172
	v_add_f32_e32 v174, v172, v151
	v_add_f32_e32 v176, v173, v174
	v_cvt_f32_i32_e32 v172, v180
	v_mul_f32_e32 v177, v176, v176
	v_sub_f32_e32 v173, v176, v173
	v_fmamk_f32 v151, v177, 0x3e9b6dac, v166
	v_sub_f32_e32 v173, v174, v173
	v_fmaak_f32 v151, v177, v151, 0x3f2aaada
	v_ldexp_f32 v178, v173, 1
	v_mul_f32_e32 v173, v176, v177
	v_ldexp_f32 v175, v176, 1
	v_pk_mul_f32 v[176:177], v[172:173], v[150:151]
	s_nop 0
	v_fma_f32 v174, v172, s69, -v176
	v_fmac_f32_e32 v174, 0xb102e308, v172
	v_pk_add_f32 v[172:173], v[176:177], v[174:175]
	s_nop 0
	v_sub_f32_e32 v151, v173, v175
	v_sub_f32_e32 v151, v177, v151
	v_add_f32_e32 v179, v178, v151
	v_mov_b32_e32 v178, v176
	v_pk_add_f32 v[176:177], v[172:173], v[176:177] neg_lo:[0,1] neg_hi:[0,1]
	v_pk_add_f32 v[180:181], v[172:173], v[178:179]
	v_mov_b32_e32 v175, v172
	v_mov_b32_e32 v177, v181
	v_pk_add_f32 v[182:183], v[174:175], v[176:177] neg_lo:[0,1] neg_hi:[0,1]
	v_pk_add_f32 v[174:175], v[174:175], v[176:177]
	v_mov_b32_e32 v178, v179
	v_pk_add_f32 v[176:177], v[174:175], v[172:173] op_sel:[1,0] op_sel_hi:[0,1] neg_lo:[0,1] neg_hi:[0,1]
	v_pk_add_f32 v[184:185], v[180:181], v[176:177] op_sel_hi:[1,0] neg_lo:[0,1] neg_hi:[0,1]
	v_mov_b32_e32 v180, v181
	v_mov_b32_e32 v181, v175
	v_pk_mov_b32 v[176:177], v[172:173], v[176:177] op_sel:[1,0]
	v_mov_b32_e32 v179, v172
	v_pk_add_f32 v[176:177], v[180:181], v[176:177] neg_lo:[0,1] neg_hi:[0,1]
	v_mov_b32_e32 v184, v182
	v_pk_add_f32 v[172:173], v[178:179], v[176:177] neg_lo:[0,1] neg_hi:[0,1]
	v_mov_b32_e32 v183, v175
	v_pk_add_f32 v[176:177], v[184:185], v[172:173]
	s_nop 0
	v_pk_add_f32 v[178:179], v[176:177], v[176:177] op_sel:[0,1] op_sel_hi:[1,0]
	s_nop 0
	v_pk_add_f32 v[174:175], v[174:175], v[178:179] op_sel:[1,0] op_sel_hi:[0,1]
	v_mov_b32_e32 v177, v174
	v_pk_add_f32 v[180:181], v[176:177], v[182:183] neg_lo:[0,1] neg_hi:[0,1]
	v_mov_b32_e32 v173, v178
	v_sub_f32_e32 v151, v176, v180
	v_pk_add_f32 v[172:173], v[172:173], v[180:181] neg_lo:[0,1] neg_hi:[0,1]
	v_sub_f32_e32 v151, v182, v151
	v_add_f32_e32 v151, v172, v151
	v_add_f32_e32 v151, v151, v173
	v_add_f32_e32 v151, v174, v151
	v_cndmask_b32_e32 v151, v167, v151, vcc
	v_cmp_ngt_f32_e32 vcc, -1.0, v156
	s_nop 1
	v_cndmask_b32_e32 v151, v168, v151, vcc
	v_cmp_neq_f32_e32 vcc, -1.0, v156
	s_nop 1
	v_cndmask_b32_e32 v151, v169, v151, vcc
	v_cmp_lt_f32_e64 vcc, |v156|, s71
	s_nop 1
	v_cndmask_b32_e32 v151, v151, v156, vcc

;     __device__ __forceinline__ void operator()(const f32x4 (&acc)[2][2][4][2], const Unit& u, int wr, int wc, int fr, int fq) const {
;     ...
;                         for (int i = 0; i < 4; ++i) { float x0 = v0[i] + dt_bias[c0 + i], x1 = v1[i] + dt_bias[c0 + 4 + i];
;                             dp[i] = x0 > 20.f ? x0 : log1pf(__expf(x0)); dp[4 + i] = x1 > 20.f ? x1 : log1pf(__expf(x1)); }
.LBB0_871:
	s_or_b64 exec, exec, s[24:25]
	flat_store_dword v[154:155], v136 offset:20
	v_mov_b32_e32 v136, v202
	v_add_f32_e32 v151, v46, v136
	v_mov_b32_e32 v136, v206
	v_cmp_nlt_f32_e32 vcc, s67, v151
	s_and_saveexec_b64 s[24:25], vcc
	s_cbranch_execz .LBB0_873
	v_mul_f32_e32 v151, 0x3fb8aa3b, v151
	v_exp_f32_e32 v156, v151
	s_nop 0
	v_add_f32_e32 v151, 1.0, v156
	v_frexp_mant_f32_e32 v175, v151
	v_cvt_f64_f32_e32 v[172:173], v151
	v_add_f32_e32 v174, -1.0, v151
	v_frexp_exp_i32_f64_e32 v172, v[172:173]
	v_cmp_gt_f32_e32 vcc, s68, v175
	v_sub_f32_e32 v176, v174, v151
	v_sub_f32_e32 v174, v156, v174
	v_subbrev_co_u32_e32 v180, vcc, 0, v172, vcc
	v_add_f32_e32 v176, 1.0, v176
	v_sub_u32_e32 v172, 0, v180
	v_add_f32_e32 v174, v174, v176
	v_ldexp_f32 v151, v151, v172
	v_ldexp_f32 v172, v174, v172
	v_add_f32_e32 v174, -1.0, v151
	v_add_f32_e32 v173, 1.0, v174
	v_sub_f32_e32 v173, v151, v173
	v_add_f32_e32 v175, v172, v173
	v_add_f32_e32 v173, 1.0, v151
	v_add_f32_e32 v176, -1.0, v173
	v_sub_f32_e32 v151, v151, v176
	v_add_f32_e32 v151, v172, v151
	v_add_f32_e32 v181, v173, v151
	v_rcp_f32_e32 v182, v181
	v_sub_f32_e32 v172, v181, v173
	v_add_f32_e32 v173, v174, v175
	v_sub_f32_e32 v151, v151, v172
	v_mul_f32_e32 v184, v173, v182
	v_sub_f32_e32 v172, v173, v174
	v_mul_f32_e32 v174, v181, v184
	v_fma_f32 v176, v184, v181, -v174
	v_fmac_f32_e32 v176, v184, v151
	v_sub_f32_e32 v183, v175, v172
	v_add_f32_e32 v172, v174, v176
	v_sub_f32_e32 v175, v173, v172
	v_pk_add_f32 v[178:179], v[172:173], v[174:175] neg_lo:[0,1] neg_hi:[0,1]
	v_mov_b32_e32 v177, v172
	v_pk_add_f32 v[172:173], v[178:179], v[176:177] neg_lo:[0,1] neg_hi:[0,1]
	v_cmp_neq_f32_e32 vcc, s70, v156
	v_add_f32_e32 v173, v183, v173
	v_add_f32_e32 v172, v172, v173
	v_add_f32_e32 v173, v175, v172
	v_mul_f32_e32 v183, v182, v173
	v_mul_f32_e32 v174, v181, v183
	v_fma_f32 v176, v183, v181, -v174
	v_fmac_f32_e32 v176, v183, v151
	v_sub_f32_e32 v151, v175, v173
	v_add_f32_e32 v151, v172, v151
	v_add_f32_e32 v172, v174, v176
	v_sub_f32_e32 v175, v173, v172
	v_pk_add_f32 v[178:179], v[172:173], v[174:175] neg_lo:[0,1] neg_hi:[0,1]
	v_mov_b32_e32 v177, v172
	v_pk_add_f32 v[172:173], v[178:179], v[176:177] neg_lo:[0,1] neg_hi:[0,1]
	s_nop 0
	v_add_f32_e32 v151, v151, v173
	v_add_f32_e32 v151, v172, v151
	v_add_f32_e32 v173, v184, v183
	v_add_f32_e32 v151, v175, v151
	v_sub_f32_e32 v172, v173, v184
	v_mul_f32_e32 v151, v182, v151
	v_sub_f32_e32 v172, v183, v172
	v_add_f32_e32 v174, v172, v151
	v_add_f32_e32 v176, v173, v174
	v_cvt_f32_i32_e32 v172, v180
	v_mul_f32_e32 v177, v176, v176
	v_sub_f32_e32 v173, v176, v173
	v_fmamk_f32 v151, v177, 0x3e9b6dac, v166
	v_sub_f32_e32 v173, v174, v173
	v_fmaak_f32 v151, v177, v151, 0x3f2aaada
	v_ldexp_f32 v178, v173, 1
	v_mul_f32_e32 v173, v176, v177
	v_ldexp_f32 v175, v176, 1
	v_pk_mul_f32 v[176:177], v[172:173], v[150:151]
	s_nop 0
	v_fma_f32 v174, v172, s69, -v176
	v_fmac_f32_e32 v174, 0xb102e308, v172
	v_pk_add_f32 v[172:173], v[176:177], v[174:175]
	s_nop 0
	v_sub_f32_e32 v151, v173, v175
	v_sub_f32_e32 v151, v177, v151
	v_add_f32_e32 v179, v178, v151
	v_mov_b32_e32 v178, v176
	v_pk_add_f32 v[176:177], v[172:173], v[176:177] neg_lo:[0,1] neg_hi:[0,1]
	v_pk_add_f32 v[180:181], v[172:173], v[178:179]
	v_mov_b32_e32 v175, v172
	v_mov_b32_e32 v177, v181
	v_pk_add_f32 v[182:183], v[174:175], v[176:177] neg_lo:[0,1] neg_hi:[0,1]
	v_pk_add_f32 v[174:175], v[174:175], v[176:177]
	v_mov_b32_e32 v178, v179
	v_pk_add_f32 v[176:177], v[174:175], v[172:173] op_sel:[1,0] op_sel_hi:[0,1] neg_lo:[0,1] neg_hi:[0,1]
	v_pk_add_f32 v[184:185], v[180:181], v[176:177] op_sel_hi:[1,0] neg_lo:[0,1] neg_hi:[0,1]
	v_mov_b32_e32 v180, v181
	v_mov_b32_e32 v181, v175
	v_pk_mov_b32 v[176:177], v[172:173], v[176:177] op_sel:[1,0]
	v_mov_b32_e32 v179, v172
	v_pk_add_f32 v[176:177], v[180:181], v[176:177] neg_lo:[0,1] neg_hi:[0,1]
	v_mov_b32_e32 v184, v182
	v_pk_add_f32 v[172:173], v[178:179], v[176:177] neg_lo:[0,1] neg_hi:[0,1]
	v_mov_b32_e32 v183, v175
	v_pk_add_f32 v[176:177], v[184:185], v[172:173]
	s_nop 0
	v_pk_add_f32 v[178:179], v[176:177], v[176:177] op_sel:[0,1] op_sel_hi:[1,0]
	s_nop 0
	v_pk_add_f32 v[174:175], v[174:175], v[178:179] op_sel:[1,0] op_sel_hi:[0,1]
	v_mov_b32_e32 v177, v174
	v_pk_add_f32 v[180:181], v[176:177], v[182:183] neg_lo:[0,1] neg_hi:[0,1]
	v_mov_b32_e32 v173, v178
	v_sub_f32_e32 v151, v176, v180
	v_pk_add_f32 v[172:173], v[172:173], v[180:181] neg_lo:[0,1] neg_hi:[0,1]
	v_sub_f32_e32 v151, v182, v151
	v_add_f32_e32 v151, v172, v151
	v_add_f32_e32 v151, v151, v173
	v_add_f32_e32 v151, v174, v151
	v_cndmask_b32_e32 v151, v167, v151, vcc
	v_cmp_ngt_f32_e32 vcc, -1.0, v156
	s_nop 1
	v_cndmask_b32_e32 v151, v168, v151, vcc
	v_cmp_neq_f32_e32 vcc, -1.0, v156
	s_nop 1
	v_cndmask_b32_e32 v151, v169, v151, vcc
	v_cmp_lt_f32_e64 vcc, |v156|, s71
	s_nop 1
	v_cndmask_b32_e32 v151, v151, v156, vcc
;     __device__ __forceinline__ void operator()(const f32x4 (&acc)[2][2][4][2], const Unit& u, int wr, int wc, int fr, int fq) const {
;     ...
;                         for (int i = 0; i < 4; ++i) { float x0 = v0[i] + dt_bias[c0 + i], x1 = v1[i] + dt_bias[c0 + 4 + i];
;                             dp[i] = x0 > 20.f ? x0 : log1pf(__expf(x0)); dp[4 + i] = x1 > 20.f ? x1 : log1pf(__expf(x1)); }
.LBB0_873:
	s_or_b64 exec, exec, s[24:25]
	v_add_f32_e32 v136, v42, v136
	v_cmp_nlt_f32_e32 vcc, s67, v136
	flat_store_dword v[154:155], v151 offset:8
	s_and_saveexec_b64 s[24:25], vcc
	s_cbranch_execz .LBB0_875
	v_mul_f32_e32 v136, 0x3fb8aa3b, v136
	v_exp_f32_e32 v136, v136
	s_nop 0
	v_add_f32_e32 v151, 1.0, v136
	v_frexp_mant_f32_e32 v174, v151
	v_cvt_f64_f32_e32 v[172:173], v151
	v_add_f32_e32 v156, -1.0, v151
	v_frexp_exp_i32_f64_e32 v172, v[172:173]
	v_cmp_gt_f32_e32 vcc, s68, v174
	v_sub_f32_e32 v175, v156, v151
	v_sub_f32_e32 v156, v136, v156
	v_subbrev_co_u32_e32 v180, vcc, 0, v172, vcc
	v_add_f32_e32 v175, 1.0, v175
	v_sub_u32_e32 v172, 0, v180
	v_add_f32_e32 v156, v156, v175
	v_ldexp_f32 v151, v151, v172
	v_ldexp_f32 v156, v156, v172
	v_add_f32_e32 v172, -1.0, v151
	v_add_f32_e32 v173, 1.0, v172
	v_sub_f32_e32 v173, v151, v173
	v_add_f32_e32 v174, v156, v173
	v_add_f32_e32 v173, 1.0, v151
	v_add_f32_e32 v175, -1.0, v173
	v_sub_f32_e32 v151, v151, v175
	v_add_f32_e32 v151, v156, v151
	v_add_f32_e32 v156, v173, v151
	v_rcp_f32_e32 v181, v156
	v_sub_f32_e32 v173, v156, v173
	v_sub_f32_e32 v151, v151, v173
	v_add_f32_e32 v173, v172, v174
	v_sub_f32_e32 v172, v173, v172
	v_mul_f32_e32 v183, v173, v181
	v_sub_f32_e32 v182, v174, v172
	v_mul_f32_e32 v174, v156, v183
	v_fma_f32 v176, v183, v156, -v174
	v_fmac_f32_e32 v176, v183, v151
	v_add_f32_e32 v172, v174, v176
	v_sub_f32_e32 v175, v173, v172
	v_pk_add_f32 v[178:179], v[172:173], v[174:175] neg_lo:[0,1] neg_hi:[0,1]
	v_mov_b32_e32 v177, v172
	v_pk_add_f32 v[172:173], v[178:179], v[176:177] neg_lo:[0,1] neg_hi:[0,1]
	v_cmp_neq_f32_e32 vcc, s70, v136
	v_add_f32_e32 v173, v182, v173
	v_add_f32_e32 v172, v172, v173
	v_add_f32_e32 v173, v175, v172
	v_mul_f32_e32 v182, v181, v173
	v_mul_f32_e32 v174, v156, v182
	v_fma_f32 v176, v182, v156, -v174
	v_fmac_f32_e32 v176, v182, v151
	v_sub_f32_e32 v151, v175, v173
	v_add_f32_e32 v151, v172, v151
	v_add_f32_e32 v172, v174, v176
	v_sub_f32_e32 v175, v173, v172
	v_pk_add_f32 v[178:179], v[172:173], v[174:175] neg_lo:[0,1] neg_hi:[0,1]
	v_mov_b32_e32 v177, v172
	v_pk_add_f32 v[172:173], v[178:179], v[176:177] neg_lo:[0,1] neg_hi:[0,1]
	v_add_f32_e32 v156, v183, v182
	v_add_f32_e32 v151, v151, v173
	v_add_f32_e32 v151, v172, v151
	v_add_f32_e32 v151, v175, v151
	v_sub_f32_e32 v172, v156, v183
	v_mul_f32_e32 v151, v181, v151
	v_sub_f32_e32 v172, v182, v172
	v_add_f32_e32 v173, v172, v151
	v_add_f32_e32 v174, v156, v173
	v_cvt_f32_i32_e32 v172, v180
	v_mul_f32_e32 v176, v174, v174
	v_fmamk_f32 v151, v176, 0x3e9b6dac, v166
	v_sub_f32_e32 v156, v174, v156
	v_fmaak_f32 v151, v176, v151, 0x3f2aaada
	v_sub_f32_e32 v156, v173, v156
	v_mul_f32_e32 v173, v174, v176
	v_pk_mul_f32 v[176:177], v[172:173], v[150:151]
	v_ldexp_f32 v175, v174, 1
	v_fma_f32 v174, v172, s69, -v176
	v_fmac_f32_e32 v174, 0xb102e308, v172
	v_pk_add_f32 v[172:173], v[176:177], v[174:175]
	v_ldexp_f32 v156, v156, 1
	v_sub_f32_e32 v151, v173, v175
	v_sub_f32_e32 v151, v177, v151
	v_add_f32_e32 v179, v156, v151
	v_mov_b32_e32 v178, v176
	v_pk_add_f32 v[176:177], v[172:173], v[176:177] neg_lo:[0,1] neg_hi:[0,1]
	v_pk_add_f32 v[180:181], v[172:173], v[178:179]
	v_mov_b32_e32 v175, v172
	v_mov_b32_e32 v177, v181
	v_pk_add_f32 v[182:183], v[174:175], v[176:177] neg_lo:[0,1] neg_hi:[0,1]
	v_pk_add_f32 v[174:175], v[174:175], v[176:177]
	v_mov_b32_e32 v178, v179
	v_pk_add_f32 v[176:177], v[174:175], v[172:173] op_sel:[1,0] op_sel_hi:[0,1] neg_lo:[0,1] neg_hi:[0,1]
	v_pk_add_f32 v[184:185], v[180:181], v[176:177] op_sel_hi:[1,0] neg_lo:[0,1] neg_hi:[0,1]
	v_mov_b32_e32 v180, v181
	v_mov_b32_e32 v181, v175
	v_pk_mov_b32 v[176:177], v[172:173], v[176:177] op_sel:[1,0]
	v_mov_b32_e32 v179, v172
	v_pk_add_f32 v[176:177], v[180:181], v[176:177] neg_lo:[0,1] neg_hi:[0,1]
	v_mov_b32_e32 v184, v182
	v_pk_add_f32 v[172:173], v[178:179], v[176:177] neg_lo:[0,1] neg_hi:[0,1]
	v_mov_b32_e32 v183, v175
	v_pk_add_f32 v[176:177], v[184:185], v[172:173]
	s_nop 0
	v_pk_add_f32 v[178:179], v[176:177], v[176:177] op_sel:[0,1] op_sel_hi:[1,0]
	s_nop 0
	v_pk_add_f32 v[174:175], v[174:175], v[178:179] op_sel:[1,0] op_sel_hi:[0,1]
	v_mov_b32_e32 v177, v174
	v_pk_add_f32 v[180:181], v[176:177], v[182:183] neg_lo:[0,1] neg_hi:[0,1]
	v_mov_b32_e32 v173, v178
	v_sub_f32_e32 v151, v176, v180
	v_pk_add_f32 v[172:173], v[172:173], v[180:181] neg_lo:[0,1] neg_hi:[0,1]
	v_sub_f32_e32 v151, v182, v151
	v_add_f32_e32 v151, v172, v151
	v_add_f32_e32 v151, v151, v173
	v_add_f32_e32 v151, v174, v151
	v_cndmask_b32_e32 v151, v167, v151, vcc
	v_cmp_ngt_f32_e32 vcc, -1.0, v136
	s_nop 1
	v_cndmask_b32_e32 v151, v168, v151, vcc
	v_cmp_neq_f32_e32 vcc, -1.0, v136
	s_nop 1
	v_cndmask_b32_e32 v151, v169, v151, vcc
	v_cmp_lt_f32_e64 vcc, |v136|, s71
	s_nop 1
	v_cndmask_b32_e32 v136, v151, v136, vcc
;     __device__ __forceinline__ void operator()(const f32x4 (&acc)[2][2][4][2], const Unit& u, int wr, int wc, int fr, int fq) const {
;     ...
;                         for (int i = 0; i < 4; ++i) { float x0 = v0[i] + dt_bias[c0 + i], x1 = v1[i] + dt_bias[c0 + 4 + i];
;                             dp[i] = x0 > 20.f ? x0 : log1pf(__expf(x0)); dp[4 + i] = x1 > 20.f ? x1 : log1pf(__expf(x1)); }
.LBB0_875:
	s_or_b64 exec, exec, s[24:25]
	flat_store_dword v[154:155], v136 offset:24
	v_mov_b32_e32 v136, v203
	v_add_f32_e32 v151, v47, v136
	v_mov_b32_e32 v136, v207
	v_cmp_nlt_f32_e32 vcc, s67, v151
	s_and_saveexec_b64 s[24:25], vcc
	s_cbranch_execz .LBB0_877
	v_mul_f32_e32 v151, 0x3fb8aa3b, v151
	v_exp_f32_e32 v156, v151
	s_nop 0
	v_add_f32_e32 v151, 1.0, v156
	v_frexp_mant_f32_e32 v175, v151
	v_cvt_f64_f32_e32 v[172:173], v151
	v_add_f32_e32 v174, -1.0, v151
	v_frexp_exp_i32_f64_e32 v172, v[172:173]
	v_cmp_gt_f32_e32 vcc, s68, v175
	v_sub_f32_e32 v176, v174, v151
	v_sub_f32_e32 v174, v156, v174
	v_subbrev_co_u32_e32 v180, vcc, 0, v172, vcc
	v_add_f32_e32 v176, 1.0, v176
	v_sub_u32_e32 v172, 0, v180
	v_add_f32_e32 v174, v174, v176
	v_ldexp_f32 v151, v151, v172
	v_ldexp_f32 v172, v174, v172
	v_add_f32_e32 v174, -1.0, v151
	v_add_f32_e32 v173, 1.0, v174
	v_sub_f32_e32 v173, v151, v173
	v_add_f32_e32 v175, v172, v173
	v_add_f32_e32 v173, 1.0, v151
	v_add_f32_e32 v176, -1.0, v173
	v_sub_f32_e32 v151, v151, v176
	v_add_f32_e32 v151, v172, v151
	v_add_f32_e32 v181, v173, v151
	v_rcp_f32_e32 v182, v181
	v_sub_f32_e32 v172, v181, v173
	v_add_f32_e32 v173, v174, v175
	v_sub_f32_e32 v151, v151, v172
	v_mul_f32_e32 v184, v173, v182
	v_sub_f32_e32 v172, v173, v174
	v_mul_f32_e32 v174, v181, v184
	v_fma_f32 v176, v184, v181, -v174
	v_fmac_f32_e32 v176, v184, v151
	v_sub_f32_e32 v183, v175, v172
	v_add_f32_e32 v172, v174, v176
	v_sub_f32_e32 v175, v173, v172
	v_pk_add_f32 v[178:179], v[172:173], v[174:175] neg_lo:[0,1] neg_hi:[0,1]
	v_mov_b32_e32 v177, v172
	v_pk_add_f32 v[172:173], v[178:179], v[176:177] neg_lo:[0,1] neg_hi:[0,1]
	v_cmp_neq_f32_e32 vcc, s70, v156
	v_add_f32_e32 v173, v183, v173
	v_add_f32_e32 v172, v172, v173
	v_add_f32_e32 v173, v175, v172
	v_mul_f32_e32 v183, v182, v173
	v_mul_f32_e32 v174, v181, v183
	v_fma_f32 v176, v183, v181, -v174
	v_fmac_f32_e32 v176, v183, v151
	v_sub_f32_e32 v151, v175, v173
	v_add_f32_e32 v151, v172, v151
	v_add_f32_e32 v172, v174, v176
	v_sub_f32_e32 v175, v173, v172
	v_pk_add_f32 v[178:179], v[172:173], v[174:175] neg_lo:[0,1] neg_hi:[0,1]
	v_mov_b32_e32 v177, v172
	v_pk_add_f32 v[172:173], v[178:179], v[176:177] neg_lo:[0,1] neg_hi:[0,1]
	s_nop 0
	v_add_f32_e32 v151, v151, v173
	v_add_f32_e32 v151, v172, v151
	v_add_f32_e32 v173, v184, v183
	v_add_f32_e32 v151, v175, v151
	v_sub_f32_e32 v172, v173, v184
	v_mul_f32_e32 v151, v182, v151
	v_sub_f32_e32 v172, v183, v172
	v_add_f32_e32 v174, v172, v151
	v_add_f32_e32 v176, v173, v174
	v_cvt_f32_i32_e32 v172, v180
	v_mul_f32_e32 v177, v176, v176
	v_sub_f32_e32 v173, v176, v173
	v_fmamk_f32 v151, v177, 0x3e9b6dac, v166
	v_sub_f32_e32 v173, v174, v173
	v_fmaak_f32 v151, v177, v151, 0x3f2aaada
	v_ldexp_f32 v178, v173, 1
	v_mul_f32_e32 v173, v176, v177
	v_ldexp_f32 v175, v176, 1
	v_pk_mul_f32 v[176:177], v[172:173], v[150:151]
	s_nop 0
	v_fma_f32 v174, v172, s69, -v176
	v_fmac_f32_e32 v174, 0xb102e308, v172
	v_pk_add_f32 v[172:173], v[176:177], v[174:175]
	s_nop 0
	v_sub_f32_e32 v151, v173, v175
	v_sub_f32_e32 v151, v177, v151
	v_add_f32_e32 v179, v178, v151
	v_mov_b32_e32 v178, v176
	v_pk_add_f32 v[176:177], v[172:173], v[176:177] neg_lo:[0,1] neg_hi:[0,1]
	v_pk_add_f32 v[180:181], v[172:173], v[178:179]
	v_mov_b32_e32 v175, v172
	v_mov_b32_e32 v177, v181
	v_pk_add_f32 v[182:183], v[174:175], v[176:177] neg_lo:[0,1] neg_hi:[0,1]
	v_pk_add_f32 v[174:175], v[174:175], v[176:177]
	v_mov_b32_e32 v178, v179
	v_pk_add_f32 v[176:177], v[174:175], v[172:173] op_sel:[1,0] op_sel_hi:[0,1] neg_lo:[0,1] neg_hi:[0,1]
	v_pk_add_f32 v[184:185], v[180:181], v[176:177] op_sel_hi:[1,0] neg_lo:[0,1] neg_hi:[0,1]
	v_mov_b32_e32 v180, v181
	v_mov_b32_e32 v181, v175
	v_pk_mov_b32 v[176:177], v[172:173], v[176:177] op_sel:[1,0]
	v_mov_b32_e32 v179, v172
	v_pk_add_f32 v[176:177], v[180:181], v[176:177] neg_lo:[0,1] neg_hi:[0,1]
	v_mov_b32_e32 v184, v182
	v_pk_add_f32 v[172:173], v[178:179], v[176:177] neg_lo:[0,1] neg_hi:[0,1]
	v_mov_b32_e32 v183, v175
	v_pk_add_f32 v[176:177], v[184:185], v[172:173]
	s_nop 0
	v_pk_add_f32 v[178:179], v[176:177], v[176:177] op_sel:[0,1] op_sel_hi:[1,0]
	s_nop 0
	v_pk_add_f32 v[174:175], v[174:175], v[178:179] op_sel:[1,0] op_sel_hi:[0,1]
	v_mov_b32_e32 v177, v174
	v_pk_add_f32 v[180:181], v[176:177], v[182:183] neg_lo:[0,1] neg_hi:[0,1]
	v_mov_b32_e32 v173, v178
	v_sub_f32_e32 v151, v176, v180
	v_pk_add_f32 v[172:173], v[172:173], v[180:181] neg_lo:[0,1] neg_hi:[0,1]
	v_sub_f32_e32 v151, v182, v151
	v_add_f32_e32 v151, v172, v151
	v_add_f32_e32 v151, v151, v173
	v_add_f32_e32 v151, v174, v151
	v_cndmask_b32_e32 v151, v167, v151, vcc
	v_cmp_ngt_f32_e32 vcc, -1.0, v156
	s_nop 1
	v_cndmask_b32_e32 v151, v168, v151, vcc
	v_cmp_neq_f32_e32 vcc, -1.0, v156
	s_nop 1
	v_cndmask_b32_e32 v151, v169, v151, vcc
	v_cmp_lt_f32_e64 vcc, |v156|, s71
	s_nop 1
	v_cndmask_b32_e32 v151, v151, v156, vcc
;     __device__ __forceinline__ void operator()(const f32x4 (&acc)[2][2][4][2], const Unit& u, int wr, int wc, int fr, int fq) const {
;     ...
;                     for (int m = 0; m < 4; ++m) { const int r = row0 + ai * HALF + m * 16;
;                         const f32x4 v0 = acc[ai][0][m][0], v1 = acc[ai][0][m][1]; float* dp = DT + (size_t)r * 32 + c0;
; #pragma unroll
;                         for (int i = 0; i < 4; ++i) { float x0 = v0[i] + dt_bias[c0 + i], x1 = v1[i] + dt_bias[c0 + 4 + i];
;                             dp[i] = x0 > 20.f ? x0 : log1pf(__expf(x0)); dp[4 + i] = x1 > 20.f ? x1 : log1pf(__expf(x1)); }
;                         __builtin_amdgcn_sched_barrier(0); }
.LBB0_877:
	s_or_b64 exec, exec, s[24:25]
	v_add_f32_e32 v136, v43, v136
	v_cmp_nlt_f32_e32 vcc, s67, v136
	flat_store_dword v[154:155], v151 offset:12
	s_and_saveexec_b64 s[24:25], vcc
	s_cbranch_execz .LBB0_879
	v_mul_f32_e32 v136, 0x3fb8aa3b, v136
	v_exp_f32_e32 v136, v136
	s_nop 0
	v_add_f32_e32 v151, 1.0, v136
	v_frexp_mant_f32_e32 v174, v151
	v_cvt_f64_f32_e32 v[172:173], v151
	v_add_f32_e32 v156, -1.0, v151
	v_frexp_exp_i32_f64_e32 v172, v[172:173]
	v_cmp_gt_f32_e32 vcc, s68, v174
	v_sub_f32_e32 v175, v156, v151
	v_sub_f32_e32 v156, v136, v156
	v_subbrev_co_u32_e32 v180, vcc, 0, v172, vcc
	v_add_f32_e32 v175, 1.0, v175
	v_sub_u32_e32 v172, 0, v180
	v_add_f32_e32 v156, v156, v175
	v_ldexp_f32 v151, v151, v172
	v_ldexp_f32 v156, v156, v172
	v_add_f32_e32 v172, -1.0, v151
	v_add_f32_e32 v173, 1.0, v172
	v_sub_f32_e32 v173, v151, v173
	v_add_f32_e32 v174, v156, v173
	v_add_f32_e32 v173, 1.0, v151
	v_add_f32_e32 v175, -1.0, v173
	v_sub_f32_e32 v151, v151, v175
	v_add_f32_e32 v151, v156, v151
	v_add_f32_e32 v156, v173, v151
	v_rcp_f32_e32 v181, v156
	v_sub_f32_e32 v173, v156, v173
	v_sub_f32_e32 v151, v151, v173
	v_add_f32_e32 v173, v172, v174
	v_sub_f32_e32 v172, v173, v172
	v_mul_f32_e32 v183, v173, v181
	v_sub_f32_e32 v182, v174, v172
	v_mul_f32_e32 v174, v156, v183
	v_fma_f32 v176, v183, v156, -v174
	v_fmac_f32_e32 v176, v183, v151
	v_add_f32_e32 v172, v174, v176
	v_sub_f32_e32 v175, v173, v172
	v_pk_add_f32 v[178:179], v[172:173], v[174:175] neg_lo:[0,1] neg_hi:[0,1]
	v_mov_b32_e32 v177, v172
	v_pk_add_f32 v[172:173], v[178:179], v[176:177] neg_lo:[0,1] neg_hi:[0,1]
	v_cmp_neq_f32_e32 vcc, s70, v136
	v_add_f32_e32 v173, v182, v173
	v_add_f32_e32 v172, v172, v173
	v_add_f32_e32 v173, v175, v172
	v_mul_f32_e32 v182, v181, v173
	v_mul_f32_e32 v174, v156, v182
	v_fma_f32 v176, v182, v156, -v174
	v_fmac_f32_e32 v176, v182, v151
	v_sub_f32_e32 v151, v175, v173
	v_add_f32_e32 v151, v172, v151
	v_add_f32_e32 v172, v174, v176
	v_sub_f32_e32 v175, v173, v172
	v_pk_add_f32 v[178:179], v[172:173], v[174:175] neg_lo:[0,1] neg_hi:[0,1]
	v_mov_b32_e32 v177, v172
	v_pk_add_f32 v[172:173], v[178:179], v[176:177] neg_lo:[0,1] neg_hi:[0,1]
	v_add_f32_e32 v156, v183, v182
	v_add_f32_e32 v151, v151, v173
	v_add_f32_e32 v151, v172, v151
	v_add_f32_e32 v151, v175, v151
	v_sub_f32_e32 v172, v156, v183
	v_mul_f32_e32 v151, v181, v151
	v_sub_f32_e32 v172, v182, v172
	v_add_f32_e32 v173, v172, v151
	v_add_f32_e32 v174, v156, v173
	v_cvt_f32_i32_e32 v172, v180
	v_mul_f32_e32 v176, v174, v174
	v_fmamk_f32 v151, v176, 0x3e9b6dac, v166
	v_sub_f32_e32 v156, v174, v156
	v_fmaak_f32 v151, v176, v151, 0x3f2aaada
	v_sub_f32_e32 v156, v173, v156
	v_mul_f32_e32 v173, v174, v176
	v_pk_mul_f32 v[176:177], v[172:173], v[150:151]
	v_ldexp_f32 v175, v174, 1
	v_fma_f32 v174, v172, s69, -v176
	v_fmac_f32_e32 v174, 0xb102e308, v172
	v_pk_add_f32 v[172:173], v[176:177], v[174:175]
	v_ldexp_f32 v156, v156, 1
	v_sub_f32_e32 v151, v173, v175
	v_sub_f32_e32 v151, v177, v151
	v_add_f32_e32 v179, v156, v151
	v_mov_b32_e32 v178, v176
	v_pk_add_f32 v[176:177], v[172:173], v[176:177] neg_lo:[0,1] neg_hi:[0,1]
	v_pk_add_f32 v[180:181], v[172:173], v[178:179]
	v_mov_b32_e32 v175, v172
	v_mov_b32_e32 v177, v181
	v_pk_add_f32 v[182:183], v[174:175], v[176:177] neg_lo:[0,1] neg_hi:[0,1]
	v_pk_add_f32 v[174:175], v[174:175], v[176:177]
	v_mov_b32_e32 v178, v179
	v_pk_add_f32 v[176:177], v[174:175], v[172:173] op_sel:[1,0] op_sel_hi:[0,1] neg_lo:[0,1] neg_hi:[0,1]
	v_pk_add_f32 v[184:185], v[180:181], v[176:177] op_sel_hi:[1,0] neg_lo:[0,1] neg_hi:[0,1]
	v_mov_b32_e32 v180, v181
	v_mov_b32_e32 v181, v175
	v_pk_mov_b32 v[176:177], v[172:173], v[176:177] op_sel:[1,0]
	v_mov_b32_e32 v179, v172
	v_pk_add_f32 v[176:177], v[180:181], v[176:177] neg_lo:[0,1] neg_hi:[0,1]
	v_mov_b32_e32 v184, v182
	v_pk_add_f32 v[172:173], v[178:179], v[176:177] neg_lo:[0,1] neg_hi:[0,1]
	v_mov_b32_e32 v183, v175
	v_pk_add_f32 v[176:177], v[184:185], v[172:173]
	s_nop 0
	v_pk_add_f32 v[178:179], v[176:177], v[176:177] op_sel:[0,1] op_sel_hi:[1,0]
	s_nop 0
	v_pk_add_f32 v[174:175], v[174:175], v[178:179] op_sel:[1,0] op_sel_hi:[0,1]
	v_mov_b32_e32 v177, v174
	v_pk_add_f32 v[180:181], v[176:177], v[182:183] neg_lo:[0,1] neg_hi:[0,1]
	v_mov_b32_e32 v173, v178
	v_sub_f32_e32 v151, v176, v180
	v_pk_add_f32 v[172:173], v[172:173], v[180:181] neg_lo:[0,1] neg_hi:[0,1]
	v_sub_f32_e32 v151, v182, v151
	v_add_f32_e32 v151, v172, v151
	v_add_f32_e32 v151, v151, v173
	v_add_f32_e32 v151, v174, v151
	v_cndmask_b32_e32 v151, v167, v151, vcc
	v_cmp_ngt_f32_e32 vcc, -1.0, v136
	s_nop 1
	v_cndmask_b32_e32 v151, v168, v151, vcc
	v_cmp_neq_f32_e32 vcc, -1.0, v136
	s_nop 1
	v_cndmask_b32_e32 v151, v169, v151, vcc
	v_cmp_lt_f32_e64 vcc, |v136|, s71
	s_nop 1
	v_cndmask_b32_e32 v136, v151, v136, vcc
;     __device__ __forceinline__ void operator()(const f32x4 (&acc)[2][2][4][2], const Unit& u, int wr, int wc, int fr, int fq) const {
;     ...
;                     for (int m = 0; m < 4; ++m) { const int r = row0 + ai * HALF + m * 16;
;                         const f32x4 v0 = acc[ai][0][m][0], v1 = acc[ai][0][m][1]; float* dp = DT + (size_t)r * 32 + c0;
; #pragma unroll
;                         for (int i = 0; i < 4; ++i) { float x0 = v0[i] + dt_bias[c0 + i], x1 = v1[i] + dt_bias[c0 + 4 + i];
;                             dp[i] = x0 > 20.f ? x0 : log1pf(__expf(x0)); dp[4 + i] = x1 > 20.f ? x1 : log1pf(__expf(x1)); }
;                         __builtin_amdgcn_sched_barrier(0); }
.LBB0_879:
	s_or_b64 exec, exec, s[24:25]
	flat_store_dword v[154:155], v136 offset:28
	v_mov_b32_e32 v136, v200
	v_add_f32_e32 v151, v28, v136
	v_mov_b32_e32 v136, v204
	v_cmp_nlt_f32_e32 vcc, s67, v151
	s_and_saveexec_b64 s[24:25], vcc
	s_cbranch_execz .LBB0_881
	v_mul_f32_e32 v151, 0x3fb8aa3b, v151
	v_exp_f32_e32 v156, v151
	s_nop 0
	v_add_f32_e32 v151, 1.0, v156
	v_frexp_mant_f32_e32 v173, v151
	v_cvt_f64_f32_e32 v[154:155], v151
	v_add_f32_e32 v172, -1.0, v151
	v_frexp_exp_i32_f64_e32 v154, v[154:155]
	v_cmp_gt_f32_e32 vcc, s68, v173
	v_sub_f32_e32 v174, v172, v151
	v_sub_f32_e32 v172, v156, v172
	v_subbrev_co_u32_e32 v178, vcc, 0, v154, vcc
	v_add_f32_e32 v174, 1.0, v174
	v_sub_u32_e32 v154, 0, v178
	v_add_f32_e32 v172, v172, v174
	v_ldexp_f32 v151, v151, v154
	v_ldexp_f32 v154, v172, v154
	v_add_f32_e32 v172, -1.0, v151
	v_add_f32_e32 v155, 1.0, v172
	v_sub_f32_e32 v155, v151, v155
	v_add_f32_e32 v173, v154, v155
	v_add_f32_e32 v155, 1.0, v151
	v_add_f32_e32 v174, -1.0, v155
	v_sub_f32_e32 v151, v151, v174
	v_add_f32_e32 v151, v154, v151
	v_add_f32_e32 v179, v155, v151
	v_rcp_f32_e32 v180, v179
	v_sub_f32_e32 v154, v179, v155
	v_add_f32_e32 v155, v172, v173
	v_sub_f32_e32 v151, v151, v154
	v_mul_f32_e32 v182, v155, v180
	v_sub_f32_e32 v154, v155, v172
	v_mul_f32_e32 v172, v179, v182
	v_fma_f32 v174, v182, v179, -v172
	v_fmac_f32_e32 v174, v182, v151
	v_sub_f32_e32 v181, v173, v154
	v_add_f32_e32 v154, v172, v174
	v_sub_f32_e32 v173, v155, v154
	v_pk_add_f32 v[176:177], v[154:155], v[172:173] neg_lo:[0,1] neg_hi:[0,1]
	v_mov_b32_e32 v175, v154
	v_pk_add_f32 v[154:155], v[176:177], v[174:175] neg_lo:[0,1] neg_hi:[0,1]
	v_cmp_neq_f32_e32 vcc, s70, v156
	v_add_f32_e32 v155, v181, v155
	v_add_f32_e32 v154, v154, v155
	v_add_f32_e32 v155, v173, v154
	v_mul_f32_e32 v181, v180, v155
	v_mul_f32_e32 v172, v179, v181
	v_fma_f32 v174, v181, v179, -v172
	v_fmac_f32_e32 v174, v181, v151
	v_sub_f32_e32 v151, v173, v155
	v_add_f32_e32 v151, v154, v151
	v_add_f32_e32 v154, v172, v174
	v_sub_f32_e32 v173, v155, v154
	v_pk_add_f32 v[176:177], v[154:155], v[172:173] neg_lo:[0,1] neg_hi:[0,1]
	v_mov_b32_e32 v175, v154
	v_pk_add_f32 v[154:155], v[176:177], v[174:175] neg_lo:[0,1] neg_hi:[0,1]
	s_nop 0
	v_add_f32_e32 v151, v151, v155
	v_add_f32_e32 v151, v154, v151
	v_add_f32_e32 v155, v182, v181
	v_add_f32_e32 v151, v173, v151
	v_sub_f32_e32 v154, v155, v182
	v_mul_f32_e32 v151, v180, v151
	v_sub_f32_e32 v154, v181, v154
	v_add_f32_e32 v172, v154, v151
	v_add_f32_e32 v174, v155, v172
	v_cvt_f32_i32_e32 v154, v178
	v_mul_f32_e32 v175, v174, v174
	v_sub_f32_e32 v155, v174, v155
	v_fmamk_f32 v151, v175, 0x3e9b6dac, v166
	v_sub_f32_e32 v155, v172, v155
	v_fmaak_f32 v151, v175, v151, 0x3f2aaada
	v_ldexp_f32 v176, v155, 1
	v_mul_f32_e32 v155, v174, v175
	v_ldexp_f32 v173, v174, 1
	v_pk_mul_f32 v[174:175], v[154:155], v[150:151]
	s_nop 0
	v_fma_f32 v172, v154, s69, -v174
	v_fmac_f32_e32 v172, 0xb102e308, v154
	v_pk_add_f32 v[154:155], v[174:175], v[172:173]
	s_nop 0
	v_sub_f32_e32 v151, v155, v173
	v_sub_f32_e32 v151, v175, v151
	v_add_f32_e32 v177, v176, v151
	v_mov_b32_e32 v176, v174
	v_pk_add_f32 v[174:175], v[154:155], v[174:175] neg_lo:[0,1] neg_hi:[0,1]
	v_pk_add_f32 v[178:179], v[154:155], v[176:177]
	v_mov_b32_e32 v173, v154
	v_mov_b32_e32 v175, v179
	v_pk_add_f32 v[180:181], v[172:173], v[174:175] neg_lo:[0,1] neg_hi:[0,1]
	v_pk_add_f32 v[172:173], v[172:173], v[174:175]
	v_mov_b32_e32 v176, v177
	v_pk_add_f32 v[174:175], v[172:173], v[154:155] op_sel:[1,0] op_sel_hi:[0,1] neg_lo:[0,1] neg_hi:[0,1]
	v_pk_add_f32 v[182:183], v[178:179], v[174:175] op_sel_hi:[1,0] neg_lo:[0,1] neg_hi:[0,1]
	v_mov_b32_e32 v178, v179
	v_mov_b32_e32 v179, v173
	v_pk_mov_b32 v[174:175], v[154:155], v[174:175] op_sel:[1,0]
	v_mov_b32_e32 v177, v154
	v_pk_add_f32 v[174:175], v[178:179], v[174:175] neg_lo:[0,1] neg_hi:[0,1]
	v_mov_b32_e32 v182, v180
	v_pk_add_f32 v[154:155], v[176:177], v[174:175] neg_lo:[0,1] neg_hi:[0,1]
	v_mov_b32_e32 v181, v173
	v_pk_add_f32 v[174:175], v[182:183], v[154:155]
	s_nop 0
	v_pk_add_f32 v[176:177], v[174:175], v[174:175] op_sel:[0,1] op_sel_hi:[1,0]
	s_nop 0
	v_pk_add_f32 v[172:173], v[172:173], v[176:177] op_sel:[1,0] op_sel_hi:[0,1]
	v_mov_b32_e32 v175, v172
	v_pk_add_f32 v[178:179], v[174:175], v[180:181] neg_lo:[0,1] neg_hi:[0,1]
	v_mov_b32_e32 v155, v176
	v_sub_f32_e32 v151, v174, v178
	v_pk_add_f32 v[154:155], v[154:155], v[178:179] neg_lo:[0,1] neg_hi:[0,1]
	v_sub_f32_e32 v151, v180, v151
	v_add_f32_e32 v151, v154, v151
	v_add_f32_e32 v151, v151, v155
	v_add_f32_e32 v151, v172, v151
	v_cndmask_b32_e32 v151, v167, v151, vcc
	v_cmp_ngt_f32_e32 vcc, -1.0, v156
	s_nop 1
	v_cndmask_b32_e32 v151, v168, v151, vcc
	v_cmp_neq_f32_e32 vcc, -1.0, v156
	s_nop 1
	v_cndmask_b32_e32 v151, v169, v151, vcc
	v_cmp_lt_f32_e64 vcc, |v156|, s71
	s_nop 1
	v_cndmask_b32_e32 v151, v151, v156, vcc
;     __device__ __forceinline__ void operator()(const f32x4 (&acc)[2][2][4][2], const Unit& u, int wr, int wc, int fr, int fq) const {
;     ...
;                     for (int m = 0; m < 4; ++m) { const int r = row0 + ai * HALF + m * 16;
;                         const f32x4 v0 = acc[ai][0][m][0], v1 = acc[ai][0][m][1]; float* dp = DT + (size_t)r * 32 + c0;
; #pragma unroll
;                         for (int i = 0; i < 4; ++i) { float x0 = v0[i] + dt_bias[c0 + i], x1 = v1[i] + dt_bias[c0 + 4 + i];
;                             dp[i] = x0 > 20.f ? x0 : log1pf(__expf(x0)); dp[4 + i] = x1 > 20.f ? x1 : log1pf(__expf(x1)); }
;                         __builtin_amdgcn_sched_barrier(0); }
.LBB0_881:
	s_or_b64 exec, exec, s[24:25]
	v_lshlrev_b64 v[154:155], 7, v[152:153]
	v_lshl_add_u64 v[154:155], v[138:139], 0, v[154:155]
	v_add_co_u32_e32 v172, vcc, 0x5000, v154
	v_add_f32_e32 v136, v24, v136
	v_addc_co_u32_e32 v173, vcc, 0, v155, vcc
	v_cmp_nlt_f32_e32 vcc, s67, v136
	flat_store_dword v[172:173], v151
	s_and_saveexec_b64 s[24:25], vcc
	s_cbranch_execz .LBB0_883
	v_mul_f32_e32 v136, 0x3fb8aa3b, v136
	v_exp_f32_e32 v136, v136
	s_nop 0
	v_add_f32_e32 v151, 1.0, v136
	v_frexp_mant_f32_e32 v174, v151
	v_cvt_f64_f32_e32 v[172:173], v151
	v_add_f32_e32 v156, -1.0, v151
	v_frexp_exp_i32_f64_e32 v172, v[172:173]
	v_cmp_gt_f32_e32 vcc, s68, v174
	v_sub_f32_e32 v175, v156, v151
	v_sub_f32_e32 v156, v136, v156
	v_subbrev_co_u32_e32 v180, vcc, 0, v172, vcc
	v_add_f32_e32 v175, 1.0, v175
	v_sub_u32_e32 v172, 0, v180
	v_add_f32_e32 v156, v156, v175
	v_ldexp_f32 v151, v151, v172
	v_ldexp_f32 v156, v156, v172
	v_add_f32_e32 v172, -1.0, v151
	v_add_f32_e32 v173, 1.0, v172
	v_sub_f32_e32 v173, v151, v173
	v_add_f32_e32 v174, v156, v173
	v_add_f32_e32 v173, 1.0, v151
	v_add_f32_e32 v175, -1.0, v173
	v_sub_f32_e32 v151, v151, v175
	v_add_f32_e32 v151, v156, v151
	v_add_f32_e32 v156, v173, v151
	v_rcp_f32_e32 v181, v156
	v_sub_f32_e32 v173, v156, v173
	v_sub_f32_e32 v151, v151, v173
	v_add_f32_e32 v173, v172, v174
	v_sub_f32_e32 v172, v173, v172
	v_mul_f32_e32 v183, v173, v181
	v_sub_f32_e32 v182, v174, v172
	v_mul_f32_e32 v174, v156, v183
	v_fma_f32 v176, v183, v156, -v174
	v_fmac_f32_e32 v176, v183, v151
	v_add_f32_e32 v172, v174, v176
	v_sub_f32_e32 v175, v173, v172
	v_pk_add_f32 v[178:179], v[172:173], v[174:175] neg_lo:[0,1] neg_hi:[0,1]
	v_mov_b32_e32 v177, v172
	v_pk_add_f32 v[172:173], v[178:179], v[176:177] neg_lo:[0,1] neg_hi:[0,1]
	v_cmp_neq_f32_e32 vcc, s70, v136
	v_add_f32_e32 v173, v182, v173
	v_add_f32_e32 v172, v172, v173
	v_add_f32_e32 v173, v175, v172
	v_mul_f32_e32 v182, v181, v173
	v_mul_f32_e32 v174, v156, v182
	v_fma_f32 v176, v182, v156, -v174
	v_fmac_f32_e32 v176, v182, v151
	v_sub_f32_e32 v151, v175, v173
	v_add_f32_e32 v151, v172, v151
	v_add_f32_e32 v172, v174, v176
	v_sub_f32_e32 v175, v173, v172
	v_pk_add_f32 v[178:179], v[172:173], v[174:175] neg_lo:[0,1] neg_hi:[0,1]
	v_mov_b32_e32 v177, v172
	v_pk_add_f32 v[172:173], v[178:179], v[176:177] neg_lo:[0,1] neg_hi:[0,1]
	v_add_f32_e32 v156, v183, v182
	v_add_f32_e32 v151, v151, v173
	v_add_f32_e32 v151, v172, v151
	v_add_f32_e32 v151, v175, v151
	v_sub_f32_e32 v172, v156, v183
	v_mul_f32_e32 v151, v181, v151
	v_sub_f32_e32 v172, v182, v172
	v_add_f32_e32 v173, v172, v151
	v_add_f32_e32 v174, v156, v173
	v_cvt_f32_i32_e32 v172, v180
	v_mul_f32_e32 v176, v174, v174
	v_fmamk_f32 v151, v176, 0x3e9b6dac, v166
	v_sub_f32_e32 v156, v174, v156
	v_fmaak_f32 v151, v176, v151, 0x3f2aaada
	v_sub_f32_e32 v156, v173, v156
	v_mul_f32_e32 v173, v174, v176
	v_pk_mul_f32 v[176:177], v[172:173], v[150:151]
	v_ldexp_f32 v175, v174, 1
	v_fma_f32 v174, v172, s69, -v176
	v_fmac_f32_e32 v174, 0xb102e308, v172
	v_pk_add_f32 v[172:173], v[176:177], v[174:175]
	v_ldexp_f32 v156, v156, 1
	v_sub_f32_e32 v151, v173, v175
	v_sub_f32_e32 v151, v177, v151
	v_add_f32_e32 v179, v156, v151
	v_mov_b32_e32 v178, v176
	v_pk_add_f32 v[176:177], v[172:173], v[176:177] neg_lo:[0,1] neg_hi:[0,1]
	v_pk_add_f32 v[180:181], v[172:173], v[178:179]
	v_mov_b32_e32 v175, v172
	v_mov_b32_e32 v177, v181
	v_pk_add_f32 v[182:183], v[174:175], v[176:177] neg_lo:[0,1] neg_hi:[0,1]
	v_pk_add_f32 v[174:175], v[174:175], v[176:177]
	v_mov_b32_e32 v178, v179
	v_pk_add_f32 v[176:177], v[174:175], v[172:173] op_sel:[1,0] op_sel_hi:[0,1] neg_lo:[0,1] neg_hi:[0,1]
	v_pk_add_f32 v[184:185], v[180:181], v[176:177] op_sel_hi:[1,0] neg_lo:[0,1] neg_hi:[0,1]
	v_mov_b32_e32 v180, v181
	v_mov_b32_e32 v181, v175
	v_pk_mov_b32 v[176:177], v[172:173], v[176:177] op_sel:[1,0]
	v_mov_b32_e32 v179, v172
	v_pk_add_f32 v[176:177], v[180:181], v[176:177] neg_lo:[0,1] neg_hi:[0,1]
	v_mov_b32_e32 v184, v182
	v_pk_add_f32 v[172:173], v[178:179], v[176:177] neg_lo:[0,1] neg_hi:[0,1]
	v_mov_b32_e32 v183, v175
	v_pk_add_f32 v[176:177], v[184:185], v[172:173]
	s_nop 0
	v_pk_add_f32 v[178:179], v[176:177], v[176:177] op_sel:[0,1] op_sel_hi:[1,0]
	s_nop 0
	v_pk_add_f32 v[174:175], v[174:175], v[178:179] op_sel:[1,0] op_sel_hi:[0,1]
	v_mov_b32_e32 v177, v174
	v_pk_add_f32 v[180:181], v[176:177], v[182:183] neg_lo:[0,1] neg_hi:[0,1]
	v_mov_b32_e32 v173, v178
	v_sub_f32_e32 v151, v176, v180
	v_pk_add_f32 v[172:173], v[172:173], v[180:181] neg_lo:[0,1] neg_hi:[0,1]
	v_sub_f32_e32 v151, v182, v151
	v_add_f32_e32 v151, v172, v151
	v_add_f32_e32 v151, v151, v173
	v_add_f32_e32 v151, v174, v151
	v_cndmask_b32_e32 v151, v167, v151, vcc
	v_cmp_ngt_f32_e32 vcc, -1.0, v136
	s_nop 1
	v_cndmask_b32_e32 v151, v168, v151, vcc
	v_cmp_neq_f32_e32 vcc, -1.0, v136
	s_nop 1
	v_cndmask_b32_e32 v151, v169, v151, vcc
	v_cmp_lt_f32_e64 vcc, |v136|, s71
	s_nop 1
	v_cndmask_b32_e32 v136, v151, v136, vcc
;     __device__ __forceinline__ void operator()(const f32x4 (&acc)[2][2][4][2], const Unit& u, int wr, int wc, int fr, int fq) const {
;     ...
;                     for (int m = 0; m < 4; ++m) { const int r = row0 + ai * HALF + m * 16;
;                         const f32x4 v0 = acc[ai][0][m][0], v1 = acc[ai][0][m][1]; float* dp = DT + (size_t)r * 32 + c0;
; #pragma unroll
;                         for (int i = 0; i < 4; ++i) { float x0 = v0[i] + dt_bias[c0 + i], x1 = v1[i] + dt_bias[c0 + 4 + i];
;                             dp[i] = x0 > 20.f ? x0 : log1pf(__expf(x0)); dp[4 + i] = x1 > 20.f ? x1 : log1pf(__expf(x1)); }
;                         __builtin_amdgcn_sched_barrier(0); }
.LBB0_883:
	s_or_b64 exec, exec, s[24:25]
	s_mov_b64 s[24:25], 0x5000
	v_lshl_add_u64 v[154:155], v[154:155], 0, s[24:25]
	flat_store_dword v[154:155], v136 offset:16
	v_mov_b32_e32 v151, v201
	s_nop 0
	v_mov_b32_e32 v136, v205
	v_add_f32_e32 v151, v29, v151
	v_cmp_nlt_f32_e32 vcc, s67, v151
	s_and_saveexec_b64 s[24:25], vcc
	s_cbranch_execz .LBB0_885
	v_mul_f32_e32 v151, 0x3fb8aa3b, v151
	v_exp_f32_e32 v156, v151
	s_nop 0
	v_add_f32_e32 v151, 1.0, v156
	v_frexp_mant_f32_e32 v175, v151
	v_cvt_f64_f32_e32 v[172:173], v151
	v_add_f32_e32 v174, -1.0, v151
	v_frexp_exp_i32_f64_e32 v172, v[172:173]
	v_cmp_gt_f32_e32 vcc, s68, v175
	v_sub_f32_e32 v176, v174, v151
	v_sub_f32_e32 v174, v156, v174
	v_subbrev_co_u32_e32 v180, vcc, 0, v172, vcc
	v_add_f32_e32 v176, 1.0, v176
	v_sub_u32_e32 v172, 0, v180
	v_add_f32_e32 v174, v174, v176
	v_ldexp_f32 v151, v151, v172
	v_ldexp_f32 v172, v174, v172
	v_add_f32_e32 v174, -1.0, v151
	v_add_f32_e32 v173, 1.0, v174
	v_sub_f32_e32 v173, v151, v173
	v_add_f32_e32 v175, v172, v173
	v_add_f32_e32 v173, 1.0, v151
	v_add_f32_e32 v176, -1.0, v173
	v_sub_f32_e32 v151, v151, v176
	v_add_f32_e32 v151, v172, v151
	v_add_f32_e32 v181, v173, v151
	v_rcp_f32_e32 v182, v181
	v_sub_f32_e32 v172, v181, v173
	v_add_f32_e32 v173, v174, v175
	v_sub_f32_e32 v151, v151, v172
	v_mul_f32_e32 v184, v173, v182
	v_sub_f32_e32 v172, v173, v174
	v_mul_f32_e32 v174, v181, v184
	v_fma_f32 v176, v184, v181, -v174
	v_fmac_f32_e32 v176, v184, v151
	v_sub_f32_e32 v183, v175, v172
	v_add_f32_e32 v172, v174, v176
	v_sub_f32_e32 v175, v173, v172
	v_pk_add_f32 v[178:179], v[172:173], v[174:175] neg_lo:[0,1] neg_hi:[0,1]
	v_mov_b32_e32 v177, v172
	v_pk_add_f32 v[172:173], v[178:179], v[176:177] neg_lo:[0,1] neg_hi:[0,1]
	v_cmp_neq_f32_e32 vcc, s70, v156
	v_add_f32_e32 v173, v183, v173
	v_add_f32_e32 v172, v172, v173
	v_add_f32_e32 v173, v175, v172
	v_mul_f32_e32 v183, v182, v173
	v_mul_f32_e32 v174, v181, v183
	v_fma_f32 v176, v183, v181, -v174
	v_fmac_f32_e32 v176, v183, v151
	v_sub_f32_e32 v151, v175, v173
	v_add_f32_e32 v151, v172, v151
	v_add_f32_e32 v172, v174, v176
	v_sub_f32_e32 v175, v173, v172
	v_pk_add_f32 v[178:179], v[172:173], v[174:175] neg_lo:[0,1] neg_hi:[0,1]
	v_mov_b32_e32 v177, v172
	v_pk_add_f32 v[172:173], v[178:179], v[176:177] neg_lo:[0,1] neg_hi:[0,1]
	s_nop 0
	v_add_f32_e32 v151, v151, v173
	v_add_f32_e32 v151, v172, v151
	v_add_f32_e32 v173, v184, v183
	v_add_f32_e32 v151, v175, v151
	v_sub_f32_e32 v172, v173, v184
	v_mul_f32_e32 v151, v182, v151
	v_sub_f32_e32 v172, v183, v172
	v_add_f32_e32 v174, v172, v151
	v_add_f32_e32 v176, v173, v174
	v_cvt_f32_i32_e32 v172, v180
	v_mul_f32_e32 v177, v176, v176
	v_sub_f32_e32 v173, v176, v173
	v_fmamk_f32 v151, v177, 0x3e9b6dac, v166
	v_sub_f32_e32 v173, v174, v173
	v_fmaak_f32 v151, v177, v151, 0x3f2aaada
	v_ldexp_f32 v178, v173, 1
	v_mul_f32_e32 v173, v176, v177
	v_ldexp_f32 v175, v176, 1
	v_pk_mul_f32 v[176:177], v[172:173], v[150:151]
	s_nop 0
	v_fma_f32 v174, v172, s69, -v176
	v_fmac_f32_e32 v174, 0xb102e308, v172
	v_pk_add_f32 v[172:173], v[176:177], v[174:175]
	s_nop 0
	v_sub_f32_e32 v151, v173, v175
	v_sub_f32_e32 v151, v177, v151
	v_add_f32_e32 v179, v178, v151
	v_mov_b32_e32 v178, v176
	v_pk_add_f32 v[176:177], v[172:173], v[176:177] neg_lo:[0,1] neg_hi:[0,1]
	v_pk_add_f32 v[180:181], v[172:173], v[178:179]
	v_mov_b32_e32 v175, v172
	v_mov_b32_e32 v177, v181
	v_pk_add_f32 v[182:183], v[174:175], v[176:177] neg_lo:[0,1] neg_hi:[0,1]
	v_pk_add_f32 v[174:175], v[174:175], v[176:177]
	v_mov_b32_e32 v178, v179
	v_pk_add_f32 v[176:177], v[174:175], v[172:173] op_sel:[1,0] op_sel_hi:[0,1] neg_lo:[0,1] neg_hi:[0,1]
	v_pk_add_f32 v[184:185], v[180:181], v[176:177] op_sel_hi:[1,0] neg_lo:[0,1] neg_hi:[0,1]
	v_mov_b32_e32 v180, v181
	v_mov_b32_e32 v181, v175
	v_pk_mov_b32 v[176:177], v[172:173], v[176:177] op_sel:[1,0]
	v_mov_b32_e32 v179, v172
	v_pk_add_f32 v[176:177], v[180:181], v[176:177] neg_lo:[0,1] neg_hi:[0,1]
	v_mov_b32_e32 v184, v182
	v_pk_add_f32 v[172:173], v[178:179], v[176:177] neg_lo:[0,1] neg_hi:[0,1]
	v_mov_b32_e32 v183, v175
	v_pk_add_f32 v[176:177], v[184:185], v[172:173]
	s_nop 0
	v_pk_add_f32 v[178:179], v[176:177], v[176:177] op_sel:[0,1] op_sel_hi:[1,0]
	s_nop 0
	v_pk_add_f32 v[174:175], v[174:175], v[178:179] op_sel:[1,0] op_sel_hi:[0,1]
	v_mov_b32_e32 v177, v174
	v_pk_add_f32 v[180:181], v[176:177], v[182:183] neg_lo:[0,1] neg_hi:[0,1]
	v_mov_b32_e32 v173, v178
	v_sub_f32_e32 v151, v176, v180
	v_pk_add_f32 v[172:173], v[172:173], v[180:181] neg_lo:[0,1] neg_hi:[0,1]
	v_sub_f32_e32 v151, v182, v151
	v_add_f32_e32 v151, v172, v151
	v_add_f32_e32 v151, v151, v173
	v_add_f32_e32 v151, v174, v151
	v_cndmask_b32_e32 v151, v167, v151, vcc
	v_cmp_ngt_f32_e32 vcc, -1.0, v156
	s_nop 1
	v_cndmask_b32_e32 v151, v168, v151, vcc
	v_cmp_neq_f32_e32 vcc, -1.0, v156
	s_nop 1
	v_cndmask_b32_e32 v151, v169, v151, vcc
	v_cmp_lt_f32_e64 vcc, |v156|, s71
	s_nop 1
	v_cndmask_b32_e32 v151, v151, v156, vcc

;     __device__ __forceinline__ void operator()(const f32x4 (&acc)[2][2][4][2], const Unit& u, int wr, int wc, int fr, int fq) const {
;     ...
;                     for (int m = 0; m < 4; ++m) { const int r = row0 + ai * HALF + m * 16;
;                         const f32x4 v0 = acc[ai][0][m][0], v1 = acc[ai][0][m][1]; float* dp = DT + (size_t)r * 32 + c0;
; #pragma unroll
;                         for (int i = 0; i < 4; ++i) { float x0 = v0[i] + dt_bias[c0 + i], x1 = v1[i] + dt_bias[c0 + 4 + i];
;                             dp[i] = x0 > 20.f ? x0 : log1pf(__expf(x0)); dp[4 + i] = x1 > 20.f ? x1 : log1pf(__expf(x1)); }
;                         __builtin_amdgcn_sched_barrier(0); }
.LBB0_887:
	s_or_b64 exec, exec, s[24:25]
	flat_store_dword v[154:155], v136 offset:20
	v_mov_b32_e32 v136, v202
	v_add_f32_e32 v151, v30, v136
	v_mov_b32_e32 v136, v206
	v_cmp_nlt_f32_e32 vcc, s67, v151
	s_and_saveexec_b64 s[24:25], vcc
	s_cbranch_execz .LBB0_889
	v_mul_f32_e32 v151, 0x3fb8aa3b, v151
	v_exp_f32_e32 v156, v151
	s_nop 0
	v_add_f32_e32 v151, 1.0, v156
	v_frexp_mant_f32_e32 v175, v151
	v_cvt_f64_f32_e32 v[172:173], v151
	v_add_f32_e32 v174, -1.0, v151
	v_frexp_exp_i32_f64_e32 v172, v[172:173]
	v_cmp_gt_f32_e32 vcc, s68, v175
	v_sub_f32_e32 v176, v174, v151
	v_sub_f32_e32 v174, v156, v174
	v_subbrev_co_u32_e32 v180, vcc, 0, v172, vcc
	v_add_f32_e32 v176, 1.0, v176
	v_sub_u32_e32 v172, 0, v180
	v_add_f32_e32 v174, v174, v176
	v_ldexp_f32 v151, v151, v172
	v_ldexp_f32 v172, v174, v172
	v_add_f32_e32 v174, -1.0, v151
	v_add_f32_e32 v173, 1.0, v174
	v_sub_f32_e32 v173, v151, v173
	v_add_f32_e32 v175, v172, v173
	v_add_f32_e32 v173, 1.0, v151
	v_add_f32_e32 v176, -1.0, v173
	v_sub_f32_e32 v151, v151, v176
	v_add_f32_e32 v151, v172, v151
	v_add_f32_e32 v181, v173, v151
	v_rcp_f32_e32 v182, v181
	v_sub_f32_e32 v172, v181, v173
	v_add_f32_e32 v173, v174, v175
	v_sub_f32_e32 v151, v151, v172
	v_mul_f32_e32 v184, v173, v182
	v_sub_f32_e32 v172, v173, v174
	v_mul_f32_e32 v174, v181, v184
	v_fma_f32 v176, v184, v181, -v174
	v_fmac_f32_e32 v176, v184, v151
	v_sub_f32_e32 v183, v175, v172
	v_add_f32_e32 v172, v174, v176
	v_sub_f32_e32 v175, v173, v172
	v_pk_add_f32 v[178:179], v[172:173], v[174:175] neg_lo:[0,1] neg_hi:[0,1]
	v_mov_b32_e32 v177, v172
	v_pk_add_f32 v[172:173], v[178:179], v[176:177] neg_lo:[0,1] neg_hi:[0,1]
	v_cmp_neq_f32_e32 vcc, s70, v156
	v_add_f32_e32 v173, v183, v173
	v_add_f32_e32 v172, v172, v173
	v_add_f32_e32 v173, v175, v172
	v_mul_f32_e32 v183, v182, v173
	v_mul_f32_e32 v174, v181, v183
	v_fma_f32 v176, v183, v181, -v174
	v_fmac_f32_e32 v176, v183, v151
	v_sub_f32_e32 v151, v175, v173
	v_add_f32_e32 v151, v172, v151
	v_add_f32_e32 v172, v174, v176
	v_sub_f32_e32 v175, v173, v172
	v_pk_add_f32 v[178:179], v[172:173], v[174:175] neg_lo:[0,1] neg_hi:[0,1]
	v_mov_b32_e32 v177, v172
	v_pk_add_f32 v[172:173], v[178:179], v[176:177] neg_lo:[0,1] neg_hi:[0,1]
	s_nop 0
	v_add_f32_e32 v151, v151, v173
	v_add_f32_e32 v151, v172, v151
	v_add_f32_e32 v173, v184, v183
	v_add_f32_e32 v151, v175, v151
	v_sub_f32_e32 v172, v173, v184
	v_mul_f32_e32 v151, v182, v151
	v_sub_f32_e32 v172, v183, v172
	v_add_f32_e32 v174, v172, v151
	v_add_f32_e32 v176, v173, v174
	v_cvt_f32_i32_e32 v172, v180
	v_mul_f32_e32 v177, v176, v176
	v_sub_f32_e32 v173, v176, v173
	v_fmamk_f32 v151, v177, 0x3e9b6dac, v166
	v_sub_f32_e32 v173, v174, v173
	v_fmaak_f32 v151, v177, v151, 0x3f2aaada
	v_ldexp_f32 v178, v173, 1
	v_mul_f32_e32 v173, v176, v177
	v_ldexp_f32 v175, v176, 1
	v_pk_mul_f32 v[176:177], v[172:173], v[150:151]
	s_nop 0
	v_fma_f32 v174, v172, s69, -v176
	v_fmac_f32_e32 v174, 0xb102e308, v172
	v_pk_add_f32 v[172:173], v[176:177], v[174:175]
	s_nop 0
	v_sub_f32_e32 v151, v173, v175
	v_sub_f32_e32 v151, v177, v151
	v_add_f32_e32 v179, v178, v151
	v_mov_b32_e32 v178, v176
	v_pk_add_f32 v[176:177], v[172:173], v[176:177] neg_lo:[0,1] neg_hi:[0,1]
	v_pk_add_f32 v[180:181], v[172:173], v[178:179]
	v_mov_b32_e32 v175, v172
	v_mov_b32_e32 v177, v181
	v_pk_add_f32 v[182:183], v[174:175], v[176:177] neg_lo:[0,1] neg_hi:[0,1]
	v_pk_add_f32 v[174:175], v[174:175], v[176:177]
	v_mov_b32_e32 v178, v179
	v_pk_add_f32 v[176:177], v[174:175], v[172:173] op_sel:[1,0] op_sel_hi:[0,1] neg_lo:[0,1] neg_hi:[0,1]
	v_pk_add_f32 v[184:185], v[180:181], v[176:177] op_sel_hi:[1,0] neg_lo:[0,1] neg_hi:[0,1]
	v_mov_b32_e32 v180, v181
	v_mov_b32_e32 v181, v175
	v_pk_mov_b32 v[176:177], v[172:173], v[176:177] op_sel:[1,0]
	v_mov_b32_e32 v179, v172
	v_pk_add_f32 v[176:177], v[180:181], v[176:177] neg_lo:[0,1] neg_hi:[0,1]
	v_mov_b32_e32 v184, v182
	v_pk_add_f32 v[172:173], v[178:179], v[176:177] neg_lo:[0,1] neg_hi:[0,1]
	v_mov_b32_e32 v183, v175
	v_pk_add_f32 v[176:177], v[184:185], v[172:173]
	s_nop 0
	v_pk_add_f32 v[178:179], v[176:177], v[176:177] op_sel:[0,1] op_sel_hi:[1,0]
	s_nop 0
	v_pk_add_f32 v[174:175], v[174:175], v[178:179] op_sel:[1,0] op_sel_hi:[0,1]
	v_mov_b32_e32 v177, v174
	v_pk_add_f32 v[180:181], v[176:177], v[182:183] neg_lo:[0,1] neg_hi:[0,1]
	v_mov_b32_e32 v173, v178
	v_sub_f32_e32 v151, v176, v180
	v_pk_add_f32 v[172:173], v[172:173], v[180:181] neg_lo:[0,1] neg_hi:[0,1]
	v_sub_f32_e32 v151, v182, v151
	v_add_f32_e32 v151, v172, v151
	v_add_f32_e32 v151, v151, v173
	v_add_f32_e32 v151, v174, v151
	v_cndmask_b32_e32 v151, v167, v151, vcc
	v_cmp_ngt_f32_e32 vcc, -1.0, v156
	s_nop 1
	v_cndmask_b32_e32 v151, v168, v151, vcc
	v_cmp_neq_f32_e32 vcc, -1.0, v156
	s_nop 1
	v_cndmask_b32_e32 v151, v169, v151, vcc
	v_cmp_lt_f32_e64 vcc, |v156|, s71
	s_nop 1
	v_cndmask_b32_e32 v151, v151, v156, vcc
;     __device__ __forceinline__ void operator()(const f32x4 (&acc)[2][2][4][2], const Unit& u, int wr, int wc, int fr, int fq) const {
;     ...
;                     for (int m = 0; m < 4; ++m) { const int r = row0 + ai * HALF + m * 16;
;                         const f32x4 v0 = acc[ai][0][m][0], v1 = acc[ai][0][m][1]; float* dp = DT + (size_t)r * 32 + c0;
; #pragma unroll
;                         for (int i = 0; i < 4; ++i) { float x0 = v0[i] + dt_bias[c0 + i], x1 = v1[i] + dt_bias[c0 + 4 + i];
;                             dp[i] = x0 > 20.f ? x0 : log1pf(__expf(x0)); dp[4 + i] = x1 > 20.f ? x1 : log1pf(__expf(x1)); }
;                         __builtin_amdgcn_sched_barrier(0); }
.LBB0_889:
	s_or_b64 exec, exec, s[24:25]
	v_add_f32_e32 v136, v26, v136
	v_cmp_nlt_f32_e32 vcc, s67, v136
	flat_store_dword v[154:155], v151 offset:8
	s_and_saveexec_b64 s[24:25], vcc
	s_cbranch_execz .LBB0_891
	v_mul_f32_e32 v136, 0x3fb8aa3b, v136
	v_exp_f32_e32 v136, v136
	s_nop 0
	v_add_f32_e32 v151, 1.0, v136
	v_frexp_mant_f32_e32 v174, v151
	v_cvt_f64_f32_e32 v[172:173], v151
	v_add_f32_e32 v156, -1.0, v151
	v_frexp_exp_i32_f64_e32 v172, v[172:173]
	v_cmp_gt_f32_e32 vcc, s68, v174
	v_sub_f32_e32 v175, v156, v151
	v_sub_f32_e32 v156, v136, v156
	v_subbrev_co_u32_e32 v180, vcc, 0, v172, vcc
	v_add_f32_e32 v175, 1.0, v175
	v_sub_u32_e32 v172, 0, v180
	v_add_f32_e32 v156, v156, v175
	v_ldexp_f32 v151, v151, v172
	v_ldexp_f32 v156, v156, v172
	v_add_f32_e32 v172, -1.0, v151
	v_add_f32_e32 v173, 1.0, v172
	v_sub_f32_e32 v173, v151, v173
	v_add_f32_e32 v174, v156, v173
	v_add_f32_e32 v173, 1.0, v151
	v_add_f32_e32 v175, -1.0, v173
	v_sub_f32_e32 v151, v151, v175
	v_add_f32_e32 v151, v156, v151
	v_add_f32_e32 v156, v173, v151
	v_rcp_f32_e32 v181, v156
	v_sub_f32_e32 v173, v156, v173
	v_sub_f32_e32 v151, v151, v173
	v_add_f32_e32 v173, v172, v174
	v_sub_f32_e32 v172, v173, v172
	v_mul_f32_e32 v183, v173, v181
	v_sub_f32_e32 v182, v174, v172
	v_mul_f32_e32 v174, v156, v183
	v_fma_f32 v176, v183, v156, -v174
	v_fmac_f32_e32 v176, v183, v151
	v_add_f32_e32 v172, v174, v176
	v_sub_f32_e32 v175, v173, v172
	v_pk_add_f32 v[178:179], v[172:173], v[174:175] neg_lo:[0,1] neg_hi:[0,1]
	v_mov_b32_e32 v177, v172
	v_pk_add_f32 v[172:173], v[178:179], v[176:177] neg_lo:[0,1] neg_hi:[0,1]
	v_cmp_neq_f32_e32 vcc, s70, v136
	v_add_f32_e32 v173, v182, v173
	v_add_f32_e32 v172, v172, v173
	v_add_f32_e32 v173, v175, v172
	v_mul_f32_e32 v182, v181, v173
	v_mul_f32_e32 v174, v156, v182
	v_fma_f32 v176, v182, v156, -v174
	v_fmac_f32_e32 v176, v182, v151
	v_sub_f32_e32 v151, v175, v173
	v_add_f32_e32 v151, v172, v151
	v_add_f32_e32 v172, v174, v176
	v_sub_f32_e32 v175, v173, v172
	v_pk_add_f32 v[178:179], v[172:173], v[174:175] neg_lo:[0,1] neg_hi:[0,1]
	v_mov_b32_e32 v177, v172
	v_pk_add_f32 v[172:173], v[178:179], v[176:177] neg_lo:[0,1] neg_hi:[0,1]
	v_add_f32_e32 v156, v183, v182
	v_add_f32_e32 v151, v151, v173
	v_add_f32_e32 v151, v172, v151
	v_add_f32_e32 v151, v175, v151
	v_sub_f32_e32 v172, v156, v183
	v_mul_f32_e32 v151, v181, v151
	v_sub_f32_e32 v172, v182, v172
	v_add_f32_e32 v173, v172, v151
	v_add_f32_e32 v174, v156, v173
	v_cvt_f32_i32_e32 v172, v180
	v_mul_f32_e32 v176, v174, v174
	v_fmamk_f32 v151, v176, 0x3e9b6dac, v166
	v_sub_f32_e32 v156, v174, v156
	v_fmaak_f32 v151, v176, v151, 0x3f2aaada
	v_sub_f32_e32 v156, v173, v156
	v_mul_f32_e32 v173, v174, v176
	v_pk_mul_f32 v[176:177], v[172:173], v[150:151]
	v_ldexp_f32 v175, v174, 1
	v_fma_f32 v174, v172, s69, -v176
	v_fmac_f32_e32 v174, 0xb102e308, v172
	v_pk_add_f32 v[172:173], v[176:177], v[174:175]
	v_ldexp_f32 v156, v156, 1
	v_sub_f32_e32 v151, v173, v175
	v_sub_f32_e32 v151, v177, v151
	v_add_f32_e32 v179, v156, v151
	v_mov_b32_e32 v178, v176
	v_pk_add_f32 v[176:177], v[172:173], v[176:177] neg_lo:[0,1] neg_hi:[0,1]
	v_pk_add_f32 v[180:181], v[172:173], v[178:179]
	v_mov_b32_e32 v175, v172
	v_mov_b32_e32 v177, v181
	v_pk_add_f32 v[182:183], v[174:175], v[176:177] neg_lo:[0,1] neg_hi:[0,1]
	v_pk_add_f32 v[174:175], v[174:175], v[176:177]
	v_mov_b32_e32 v178, v179
	v_pk_add_f32 v[176:177], v[174:175], v[172:173] op_sel:[1,0] op_sel_hi:[0,1] neg_lo:[0,1] neg_hi:[0,1]
	v_pk_add_f32 v[184:185], v[180:181], v[176:177] op_sel_hi:[1,0] neg_lo:[0,1] neg_hi:[0,1]
	v_mov_b32_e32 v180, v181
	v_mov_b32_e32 v181, v175
	v_pk_mov_b32 v[176:177], v[172:173], v[176:177] op_sel:[1,0]
	v_mov_b32_e32 v179, v172
	v_pk_add_f32 v[176:177], v[180:181], v[176:177] neg_lo:[0,1] neg_hi:[0,1]
	v_mov_b32_e32 v184, v182
	v_pk_add_f32 v[172:173], v[178:179], v[176:177] neg_lo:[0,1] neg_hi:[0,1]
	v_mov_b32_e32 v183, v175
	v_pk_add_f32 v[176:177], v[184:185], v[172:173]
	s_nop 0
	v_pk_add_f32 v[178:179], v[176:177], v[176:177] op_sel:[0,1] op_sel_hi:[1,0]
	s_nop 0
	v_pk_add_f32 v[174:175], v[174:175], v[178:179] op_sel:[1,0] op_sel_hi:[0,1]
	v_mov_b32_e32 v177, v174
	v_pk_add_f32 v[180:181], v[176:177], v[182:183] neg_lo:[0,1] neg_hi:[0,1]
	v_mov_b32_e32 v173, v178
	v_sub_f32_e32 v151, v176, v180
	v_pk_add_f32 v[172:173], v[172:173], v[180:181] neg_lo:[0,1] neg_hi:[0,1]
	v_sub_f32_e32 v151, v182, v151
	v_add_f32_e32 v151, v172, v151
	v_add_f32_e32 v151, v151, v173
	v_add_f32_e32 v151, v174, v151
	v_cndmask_b32_e32 v151, v167, v151, vcc
	v_cmp_ngt_f32_e32 vcc, -1.0, v136
	s_nop 1
	v_cndmask_b32_e32 v151, v168, v151, vcc
	v_cmp_neq_f32_e32 vcc, -1.0, v136
	s_nop 1
	v_cndmask_b32_e32 v151, v169, v151, vcc
	v_cmp_lt_f32_e64 vcc, |v136|, s71
	s_nop 1
	v_cndmask_b32_e32 v136, v151, v136, vcc
;     __device__ __forceinline__ void operator()(const f32x4 (&acc)[2][2][4][2], const Unit& u, int wr, int wc, int fr, int fq) const {
;     ...
;                     for (int m = 0; m < 4; ++m) { const int r = row0 + ai * HALF + m * 16;
;                         const f32x4 v0 = acc[ai][0][m][0], v1 = acc[ai][0][m][1]; float* dp = DT + (size_t)r * 32 + c0;
; #pragma unroll
;                         for (int i = 0; i < 4; ++i) { float x0 = v0[i] + dt_bias[c0 + i], x1 = v1[i] + dt_bias[c0 + 4 + i];
;                             dp[i] = x0 > 20.f ? x0 : log1pf(__expf(x0)); dp[4 + i] = x1 > 20.f ? x1 : log1pf(__expf(x1)); }
;                         __builtin_amdgcn_sched_barrier(0); }
.LBB0_891:
	s_or_b64 exec, exec, s[24:25]
	flat_store_dword v[154:155], v136 offset:24
	v_mov_b32_e32 v136, v203
	v_add_f32_e32 v151, v31, v136
	v_mov_b32_e32 v136, v207
	v_cmp_nlt_f32_e32 vcc, s67, v151
	s_and_saveexec_b64 s[24:25], vcc
	s_cbranch_execz .LBB0_893
	v_mul_f32_e32 v151, 0x3fb8aa3b, v151
	v_exp_f32_e32 v156, v151
	s_nop 0
	v_add_f32_e32 v151, 1.0, v156
	v_frexp_mant_f32_e32 v175, v151
	v_cvt_f64_f32_e32 v[172:173], v151
	v_add_f32_e32 v174, -1.0, v151
	v_frexp_exp_i32_f64_e32 v172, v[172:173]
	v_cmp_gt_f32_e32 vcc, s68, v175
	v_sub_f32_e32 v176, v174, v151
	v_sub_f32_e32 v174, v156, v174
	v_subbrev_co_u32_e32 v180, vcc, 0, v172, vcc
	v_add_f32_e32 v176, 1.0, v176
	v_sub_u32_e32 v172, 0, v180
	v_add_f32_e32 v174, v174, v176
	v_ldexp_f32 v151, v151, v172
	v_ldexp_f32 v172, v174, v172
	v_add_f32_e32 v174, -1.0, v151
	v_add_f32_e32 v173, 1.0, v174
	v_sub_f32_e32 v173, v151, v173
	v_add_f32_e32 v175, v172, v173
	v_add_f32_e32 v173, 1.0, v151
	v_add_f32_e32 v176, -1.0, v173
	v_sub_f32_e32 v151, v151, v176
	v_add_f32_e32 v151, v172, v151
	v_add_f32_e32 v181, v173, v151
	v_rcp_f32_e32 v182, v181
	v_sub_f32_e32 v172, v181, v173
	v_add_f32_e32 v173, v174, v175
	v_sub_f32_e32 v151, v151, v172
	v_mul_f32_e32 v184, v173, v182
	v_sub_f32_e32 v172, v173, v174
	v_mul_f32_e32 v174, v181, v184
	v_fma_f32 v176, v184, v181, -v174
	v_fmac_f32_e32 v176, v184, v151
	v_sub_f32_e32 v183, v175, v172
	v_add_f32_e32 v172, v174, v176
	v_sub_f32_e32 v175, v173, v172
	v_pk_add_f32 v[178:179], v[172:173], v[174:175] neg_lo:[0,1] neg_hi:[0,1]
	v_mov_b32_e32 v177, v172
	v_pk_add_f32 v[172:173], v[178:179], v[176:177] neg_lo:[0,1] neg_hi:[0,1]
	v_cmp_neq_f32_e32 vcc, s70, v156
	v_add_f32_e32 v173, v183, v173
	v_add_f32_e32 v172, v172, v173
	v_add_f32_e32 v173, v175, v172
	v_mul_f32_e32 v183, v182, v173
	v_mul_f32_e32 v174, v181, v183
	v_fma_f32 v176, v183, v181, -v174
	v_fmac_f32_e32 v176, v183, v151
	v_sub_f32_e32 v151, v175, v173
	v_add_f32_e32 v151, v172, v151
	v_add_f32_e32 v172, v174, v176
	v_sub_f32_e32 v175, v173, v172
	v_pk_add_f32 v[178:179], v[172:173], v[174:175] neg_lo:[0,1] neg_hi:[0,1]
	v_mov_b32_e32 v177, v172
	v_pk_add_f32 v[172:173], v[178:179], v[176:177] neg_lo:[0,1] neg_hi:[0,1]
	s_nop 0
	v_add_f32_e32 v151, v151, v173
	v_add_f32_e32 v151, v172, v151
	v_add_f32_e32 v173, v184, v183
	v_add_f32_e32 v151, v175, v151
	v_sub_f32_e32 v172, v173, v184
	v_mul_f32_e32 v151, v182, v151
	v_sub_f32_e32 v172, v183, v172
	v_add_f32_e32 v174, v172, v151
	v_add_f32_e32 v176, v173, v174
	v_cvt_f32_i32_e32 v172, v180
	v_mul_f32_e32 v177, v176, v176
	v_sub_f32_e32 v173, v176, v173
	v_fmamk_f32 v151, v177, 0x3e9b6dac, v166
	v_sub_f32_e32 v173, v174, v173
	v_fmaak_f32 v151, v177, v151, 0x3f2aaada
	v_ldexp_f32 v178, v173, 1
	v_mul_f32_e32 v173, v176, v177
	v_ldexp_f32 v175, v176, 1
	v_pk_mul_f32 v[176:177], v[172:173], v[150:151]
	s_nop 0
	v_fma_f32 v174, v172, s69, -v176
	v_fmac_f32_e32 v174, 0xb102e308, v172
	v_pk_add_f32 v[172:173], v[176:177], v[174:175]
	s_nop 0
	v_sub_f32_e32 v151, v173, v175
	v_sub_f32_e32 v151, v177, v151
	v_add_f32_e32 v179, v178, v151
	v_mov_b32_e32 v178, v176
	v_pk_add_f32 v[176:177], v[172:173], v[176:177] neg_lo:[0,1] neg_hi:[0,1]
	v_pk_add_f32 v[180:181], v[172:173], v[178:179]
	v_mov_b32_e32 v175, v172
	v_mov_b32_e32 v177, v181
	v_pk_add_f32 v[182:183], v[174:175], v[176:177] neg_lo:[0,1] neg_hi:[0,1]
	v_pk_add_f32 v[174:175], v[174:175], v[176:177]
	v_mov_b32_e32 v178, v179
	v_pk_add_f32 v[176:177], v[174:175], v[172:173] op_sel:[1,0] op_sel_hi:[0,1] neg_lo:[0,1] neg_hi:[0,1]
	v_pk_add_f32 v[184:185], v[180:181], v[176:177] op_sel_hi:[1,0] neg_lo:[0,1] neg_hi:[0,1]
	v_mov_b32_e32 v180, v181
	v_mov_b32_e32 v181, v175
	v_pk_mov_b32 v[176:177], v[172:173], v[176:177] op_sel:[1,0]
	v_mov_b32_e32 v179, v172
	v_pk_add_f32 v[176:177], v[180:181], v[176:177] neg_lo:[0,1] neg_hi:[0,1]
	v_mov_b32_e32 v184, v182
	v_pk_add_f32 v[172:173], v[178:179], v[176:177] neg_lo:[0,1] neg_hi:[0,1]
	v_mov_b32_e32 v183, v175
	v_pk_add_f32 v[176:177], v[184:185], v[172:173]
	s_nop 0
	v_pk_add_f32 v[178:179], v[176:177], v[176:177] op_sel:[0,1] op_sel_hi:[1,0]
	s_nop 0
	v_pk_add_f32 v[174:175], v[174:175], v[178:179] op_sel:[1,0] op_sel_hi:[0,1]
	v_mov_b32_e32 v177, v174
	v_pk_add_f32 v[180:181], v[176:177], v[182:183] neg_lo:[0,1] neg_hi:[0,1]
	v_mov_b32_e32 v173, v178
	v_sub_f32_e32 v151, v176, v180
	v_pk_add_f32 v[172:173], v[172:173], v[180:181] neg_lo:[0,1] neg_hi:[0,1]
	v_sub_f32_e32 v151, v182, v151
	v_add_f32_e32 v151, v172, v151
	v_add_f32_e32 v151, v151, v173
	v_add_f32_e32 v151, v174, v151
	v_cndmask_b32_e32 v151, v167, v151, vcc
	v_cmp_ngt_f32_e32 vcc, -1.0, v156
	s_nop 1
	v_cndmask_b32_e32 v151, v168, v151, vcc
	v_cmp_neq_f32_e32 vcc, -1.0, v156
	s_nop 1
	v_cndmask_b32_e32 v151, v169, v151, vcc
	v_cmp_lt_f32_e64 vcc, |v156|, s71
	s_nop 1
	v_cndmask_b32_e32 v151, v151, v156, vcc
;     __device__ __forceinline__ void operator()(const f32x4 (&acc)[2][2][4][2], const Unit& u, int wr, int wc, int fr, int fq) const {
;     ...
;                     for (int m = 0; m < 4; ++m) { const int r = row0 + ai * HALF + m * 16;
;                         const f32x4 v0 = acc[ai][0][m][0], v1 = acc[ai][0][m][1]; float* dp = DT + (size_t)r * 32 + c0;
; #pragma unroll
;                         for (int i = 0; i < 4; ++i) { float x0 = v0[i] + dt_bias[c0 + i], x1 = v1[i] + dt_bias[c0 + 4 + i];
;                             dp[i] = x0 > 20.f ? x0 : log1pf(__expf(x0)); dp[4 + i] = x1 > 20.f ? x1 : log1pf(__expf(x1)); }
;                         __builtin_amdgcn_sched_barrier(0); }
.LBB0_893:
	s_or_b64 exec, exec, s[24:25]
	v_add_f32_e32 v136, v27, v136
	v_cmp_nlt_f32_e32 vcc, s67, v136
	flat_store_dword v[154:155], v151 offset:12
	s_and_saveexec_b64 s[24:25], vcc
	s_cbranch_execz .LBB0_895
	v_mul_f32_e32 v136, 0x3fb8aa3b, v136
	v_exp_f32_e32 v136, v136
	s_nop 0
	v_add_f32_e32 v151, 1.0, v136
	v_frexp_mant_f32_e32 v174, v151
	v_cvt_f64_f32_e32 v[172:173], v151
	v_add_f32_e32 v156, -1.0, v151
	v_frexp_exp_i32_f64_e32 v172, v[172:173]
	v_cmp_gt_f32_e32 vcc, s68, v174
	v_sub_f32_e32 v175, v156, v151
	v_sub_f32_e32 v156, v136, v156
	v_subbrev_co_u32_e32 v180, vcc, 0, v172, vcc
	v_add_f32_e32 v175, 1.0, v175
	v_sub_u32_e32 v172, 0, v180
	v_add_f32_e32 v156, v156, v175
	v_ldexp_f32 v151, v151, v172
	v_ldexp_f32 v156, v156, v172
	v_add_f32_e32 v172, -1.0, v151
	v_add_f32_e32 v173, 1.0, v172
	v_sub_f32_e32 v173, v151, v173
	v_add_f32_e32 v174, v156, v173
	v_add_f32_e32 v173, 1.0, v151
	v_add_f32_e32 v175, -1.0, v173
	v_sub_f32_e32 v151, v151, v175
	v_add_f32_e32 v151, v156, v151
	v_add_f32_e32 v156, v173, v151
	v_rcp_f32_e32 v181, v156
	v_sub_f32_e32 v173, v156, v173
	v_sub_f32_e32 v151, v151, v173
	v_add_f32_e32 v173, v172, v174
	v_sub_f32_e32 v172, v173, v172
	v_mul_f32_e32 v183, v173, v181
	v_sub_f32_e32 v182, v174, v172
	v_mul_f32_e32 v174, v156, v183
	v_fma_f32 v176, v183, v156, -v174
	v_fmac_f32_e32 v176, v183, v151
	v_add_f32_e32 v172, v174, v176
	v_sub_f32_e32 v175, v173, v172
	v_pk_add_f32 v[178:179], v[172:173], v[174:175] neg_lo:[0,1] neg_hi:[0,1]
	v_mov_b32_e32 v177, v172
	v_pk_add_f32 v[172:173], v[178:179], v[176:177] neg_lo:[0,1] neg_hi:[0,1]
	v_cmp_neq_f32_e32 vcc, s70, v136
	v_add_f32_e32 v173, v182, v173
	v_add_f32_e32 v172, v172, v173
	v_add_f32_e32 v173, v175, v172
	v_mul_f32_e32 v182, v181, v173
	v_mul_f32_e32 v174, v156, v182
	v_fma_f32 v176, v182, v156, -v174
	v_fmac_f32_e32 v176, v182, v151
	v_sub_f32_e32 v151, v175, v173
	v_add_f32_e32 v151, v172, v151
	v_add_f32_e32 v172, v174, v176
	v_sub_f32_e32 v175, v173, v172
	v_pk_add_f32 v[178:179], v[172:173], v[174:175] neg_lo:[0,1] neg_hi:[0,1]
	v_mov_b32_e32 v177, v172
	v_pk_add_f32 v[172:173], v[178:179], v[176:177] neg_lo:[0,1] neg_hi:[0,1]
	v_add_f32_e32 v156, v183, v182
	v_add_f32_e32 v151, v151, v173
	v_add_f32_e32 v151, v172, v151
	v_add_f32_e32 v151, v175, v151
	v_sub_f32_e32 v172, v156, v183
	v_mul_f32_e32 v151, v181, v151
	v_sub_f32_e32 v172, v182, v172
	v_add_f32_e32 v173, v172, v151
	v_add_f32_e32 v174, v156, v173
	v_cvt_f32_i32_e32 v172, v180
	v_mul_f32_e32 v176, v174, v174
	v_fmamk_f32 v151, v176, 0x3e9b6dac, v166
	v_sub_f32_e32 v156, v174, v156
	v_fmaak_f32 v151, v176, v151, 0x3f2aaada
	v_sub_f32_e32 v156, v173, v156
	v_mul_f32_e32 v173, v174, v176
	v_pk_mul_f32 v[176:177], v[172:173], v[150:151]
	v_ldexp_f32 v175, v174, 1
	v_fma_f32 v174, v172, s69, -v176
	v_fmac_f32_e32 v174, 0xb102e308, v172
	v_pk_add_f32 v[172:173], v[176:177], v[174:175]
	v_ldexp_f32 v156, v156, 1
	v_sub_f32_e32 v151, v173, v175
	v_sub_f32_e32 v151, v177, v151
	v_add_f32_e32 v179, v156, v151
	v_mov_b32_e32 v178, v176
	v_pk_add_f32 v[176:177], v[172:173], v[176:177] neg_lo:[0,1] neg_hi:[0,1]
	v_pk_add_f32 v[180:181], v[172:173], v[178:179]
	v_mov_b32_e32 v175, v172
	v_mov_b32_e32 v177, v181
	v_pk_add_f32 v[182:183], v[174:175], v[176:177] neg_lo:[0,1] neg_hi:[0,1]
	v_pk_add_f32 v[174:175], v[174:175], v[176:177]
	v_mov_b32_e32 v178, v179
	v_pk_add_f32 v[176:177], v[174:175], v[172:173] op_sel:[1,0] op_sel_hi:[0,1] neg_lo:[0,1] neg_hi:[0,1]
	v_pk_add_f32 v[184:185], v[180:181], v[176:177] op_sel_hi:[1,0] neg_lo:[0,1] neg_hi:[0,1]
	v_mov_b32_e32 v180, v181
	v_mov_b32_e32 v181, v175
	v_pk_mov_b32 v[176:177], v[172:173], v[176:177] op_sel:[1,0]
	v_mov_b32_e32 v179, v172
	v_pk_add_f32 v[176:177], v[180:181], v[176:177] neg_lo:[0,1] neg_hi:[0,1]
	v_mov_b32_e32 v184, v182
	v_pk_add_f32 v[172:173], v[178:179], v[176:177] neg_lo:[0,1] neg_hi:[0,1]
	v_mov_b32_e32 v183, v175
	v_pk_add_f32 v[176:177], v[184:185], v[172:173]
	s_nop 0
	v_pk_add_f32 v[178:179], v[176:177], v[176:177] op_sel:[0,1] op_sel_hi:[1,0]
	s_nop 0
	v_pk_add_f32 v[174:175], v[174:175], v[178:179] op_sel:[1,0] op_sel_hi:[0,1]
	v_mov_b32_e32 v177, v174
	v_pk_add_f32 v[180:181], v[176:177], v[182:183] neg_lo:[0,1] neg_hi:[0,1]
	v_mov_b32_e32 v173, v178
	v_sub_f32_e32 v151, v176, v180
	v_pk_add_f32 v[172:173], v[172:173], v[180:181] neg_lo:[0,1] neg_hi:[0,1]
	v_sub_f32_e32 v151, v182, v151
	v_add_f32_e32 v151, v172, v151
	v_add_f32_e32 v151, v151, v173
	v_add_f32_e32 v151, v174, v151
	v_cndmask_b32_e32 v151, v167, v151, vcc
	v_cmp_ngt_f32_e32 vcc, -1.0, v136
	s_nop 1
	v_cndmask_b32_e32 v151, v168, v151, vcc
	v_cmp_neq_f32_e32 vcc, -1.0, v136
	s_nop 1
	v_cndmask_b32_e32 v151, v169, v151, vcc
	v_cmp_lt_f32_e64 vcc, |v136|, s71
	s_nop 1
	v_cndmask_b32_e32 v136, v151, v136, vcc
;     __device__ __forceinline__ void operator()(const f32x4 (&acc)[2][2][4][2], const Unit& u, int wr, int wc, int fr, int fq) const {
;     ...
;                     for (int m = 0; m < 4; ++m) { const int r = row0 + ai * HALF + m * 16;
;                         const f32x4 v0 = acc[ai][0][m][0], v1 = acc[ai][0][m][1]; float* dp = DT + (size_t)r * 32 + c0;
; #pragma unroll
;                         for (int i = 0; i < 4; ++i) { float x0 = v0[i] + dt_bias[c0 + i], x1 = v1[i] + dt_bias[c0 + 4 + i];
;                             dp[i] = x0 > 20.f ? x0 : log1pf(__expf(x0)); dp[4 + i] = x1 > 20.f ? x1 : log1pf(__expf(x1)); }
;                         __builtin_amdgcn_sched_barrier(0); }
.LBB0_895:
	s_or_b64 exec, exec, s[24:25]
	flat_store_dword v[154:155], v136 offset:28
	v_mov_b32_e32 v136, v200
	v_add_f32_e32 v151, v12, v136
	v_mov_b32_e32 v136, v204
	v_cmp_nlt_f32_e32 vcc, s67, v151
	s_and_saveexec_b64 s[24:25], vcc
	s_cbranch_execz .LBB0_897
	v_mul_f32_e32 v151, 0x3fb8aa3b, v151
	v_exp_f32_e32 v156, v151
	s_nop 0
	v_add_f32_e32 v151, 1.0, v156
	v_frexp_mant_f32_e32 v173, v151
	v_cvt_f64_f32_e32 v[154:155], v151
	v_add_f32_e32 v172, -1.0, v151
	v_frexp_exp_i32_f64_e32 v154, v[154:155]
	v_cmp_gt_f32_e32 vcc, s68, v173
	v_sub_f32_e32 v174, v172, v151
	v_sub_f32_e32 v172, v156, v172
	v_subbrev_co_u32_e32 v178, vcc, 0, v154, vcc
	v_add_f32_e32 v174, 1.0, v174
	v_sub_u32_e32 v154, 0, v178
	v_add_f32_e32 v172, v172, v174
	v_ldexp_f32 v151, v151, v154
	v_ldexp_f32 v154, v172, v154
	v_add_f32_e32 v172, -1.0, v151
	v_add_f32_e32 v155, 1.0, v172
	v_sub_f32_e32 v155, v151, v155
	v_add_f32_e32 v173, v154, v155
	v_add_f32_e32 v155, 1.0, v151
	v_add_f32_e32 v174, -1.0, v155
	v_sub_f32_e32 v151, v151, v174
	v_add_f32_e32 v151, v154, v151
	v_add_f32_e32 v179, v155, v151
	v_rcp_f32_e32 v180, v179
	v_sub_f32_e32 v154, v179, v155
	v_add_f32_e32 v155, v172, v173
	v_sub_f32_e32 v151, v151, v154
	v_mul_f32_e32 v182, v155, v180
	v_sub_f32_e32 v154, v155, v172
	v_mul_f32_e32 v172, v179, v182
	v_fma_f32 v174, v182, v179, -v172
	v_fmac_f32_e32 v174, v182, v151
	v_sub_f32_e32 v181, v173, v154
	v_add_f32_e32 v154, v172, v174
	v_sub_f32_e32 v173, v155, v154
	v_pk_add_f32 v[176:177], v[154:155], v[172:173] neg_lo:[0,1] neg_hi:[0,1]
	v_mov_b32_e32 v175, v154
	v_pk_add_f32 v[154:155], v[176:177], v[174:175] neg_lo:[0,1] neg_hi:[0,1]
	v_cmp_neq_f32_e32 vcc, s70, v156
	v_add_f32_e32 v155, v181, v155
	v_add_f32_e32 v154, v154, v155
	v_add_f32_e32 v155, v173, v154
	v_mul_f32_e32 v181, v180, v155
	v_mul_f32_e32 v172, v179, v181
	v_fma_f32 v174, v181, v179, -v172
	v_fmac_f32_e32 v174, v181, v151
	v_sub_f32_e32 v151, v173, v155
	v_add_f32_e32 v151, v154, v151
	v_add_f32_e32 v154, v172, v174
	v_sub_f32_e32 v173, v155, v154
	v_pk_add_f32 v[176:177], v[154:155], v[172:173] neg_lo:[0,1] neg_hi:[0,1]
	v_mov_b32_e32 v175, v154
	v_pk_add_f32 v[154:155], v[176:177], v[174:175] neg_lo:[0,1] neg_hi:[0,1]
	s_nop 0
	v_add_f32_e32 v151, v151, v155
	v_add_f32_e32 v151, v154, v151
	v_add_f32_e32 v155, v182, v181
	v_add_f32_e32 v151, v173, v151
	v_sub_f32_e32 v154, v155, v182
	v_mul_f32_e32 v151, v180, v151
	v_sub_f32_e32 v154, v181, v154
	v_add_f32_e32 v172, v154, v151
	v_add_f32_e32 v174, v155, v172
	v_cvt_f32_i32_e32 v154, v178
	v_mul_f32_e32 v175, v174, v174
	v_sub_f32_e32 v155, v174, v155
	v_fmamk_f32 v151, v175, 0x3e9b6dac, v166
	v_sub_f32_e32 v155, v172, v155
	v_fmaak_f32 v151, v175, v151, 0x3f2aaada
	v_ldexp_f32 v176, v155, 1
	v_mul_f32_e32 v155, v174, v175
	v_ldexp_f32 v173, v174, 1
	v_pk_mul_f32 v[174:175], v[154:155], v[150:151]
	s_nop 0
	v_fma_f32 v172, v154, s69, -v174
	v_fmac_f32_e32 v172, 0xb102e308, v154
	v_pk_add_f32 v[154:155], v[174:175], v[172:173]
	s_nop 0
	v_sub_f32_e32 v151, v155, v173
	v_sub_f32_e32 v151, v175, v151
	v_add_f32_e32 v177, v176, v151
	v_mov_b32_e32 v176, v174
	v_pk_add_f32 v[174:175], v[154:155], v[174:175] neg_lo:[0,1] neg_hi:[0,1]
	v_pk_add_f32 v[178:179], v[154:155], v[176:177]
	v_mov_b32_e32 v173, v154
	v_mov_b32_e32 v175, v179
	v_pk_add_f32 v[180:181], v[172:173], v[174:175] neg_lo:[0,1] neg_hi:[0,1]
	v_pk_add_f32 v[172:173], v[172:173], v[174:175]
	v_mov_b32_e32 v176, v177
	v_pk_add_f32 v[174:175], v[172:173], v[154:155] op_sel:[1,0] op_sel_hi:[0,1] neg_lo:[0,1] neg_hi:[0,1]
	v_pk_add_f32 v[182:183], v[178:179], v[174:175] op_sel_hi:[1,0] neg_lo:[0,1] neg_hi:[0,1]
	v_mov_b32_e32 v178, v179
	v_mov_b32_e32 v179, v173
	v_pk_mov_b32 v[174:175], v[154:155], v[174:175] op_sel:[1,0]
	v_mov_b32_e32 v177, v154
	v_pk_add_f32 v[174:175], v[178:179], v[174:175] neg_lo:[0,1] neg_hi:[0,1]
	v_mov_b32_e32 v182, v180
	v_pk_add_f32 v[154:155], v[176:177], v[174:175] neg_lo:[0,1] neg_hi:[0,1]
	v_mov_b32_e32 v181, v173
	v_pk_add_f32 v[174:175], v[182:183], v[154:155]
	s_nop 0
	v_pk_add_f32 v[176:177], v[174:175], v[174:175] op_sel:[0,1] op_sel_hi:[1,0]
	s_nop 0
	v_pk_add_f32 v[172:173], v[172:173], v[176:177] op_sel:[1,0] op_sel_hi:[0,1]
	v_mov_b32_e32 v175, v172
	v_pk_add_f32 v[178:179], v[174:175], v[180:181] neg_lo:[0,1] neg_hi:[0,1]
	v_mov_b32_e32 v155, v176
	v_sub_f32_e32 v151, v174, v178
	v_pk_add_f32 v[154:155], v[154:155], v[178:179] neg_lo:[0,1] neg_hi:[0,1]
	v_sub_f32_e32 v151, v180, v151
	v_add_f32_e32 v151, v154, v151
	v_add_f32_e32 v151, v151, v155
	v_add_f32_e32 v151, v172, v151
	v_cndmask_b32_e32 v151, v167, v151, vcc
	v_cmp_ngt_f32_e32 vcc, -1.0, v156
	s_nop 1
	v_cndmask_b32_e32 v151, v168, v151, vcc
	v_cmp_neq_f32_e32 vcc, -1.0, v156
	s_nop 1
	v_cndmask_b32_e32 v151, v169, v151, vcc
	v_cmp_lt_f32_e64 vcc, |v156|, s71
	s_nop 1
	v_cndmask_b32_e32 v151, v151, v156, vcc
;     __device__ __forceinline__ void operator()(const f32x4 (&acc)[2][2][4][2], const Unit& u, int wr, int wc, int fr, int fq) const {
;     ...
;                     for (int m = 0; m < 4; ++m) { const int r = row0 + ai * HALF + m * 16;
;                         const f32x4 v0 = acc[ai][0][m][0], v1 = acc[ai][0][m][1]; float* dp = DT + (size_t)r * 32 + c0;
; #pragma unroll
;                         for (int i = 0; i < 4; ++i) { float x0 = v0[i] + dt_bias[c0 + i], x1 = v1[i] + dt_bias[c0 + 4 + i];
;                             dp[i] = x0 > 20.f ? x0 : log1pf(__expf(x0)); dp[4 + i] = x1 > 20.f ? x1 : log1pf(__expf(x1)); }
;                         __builtin_amdgcn_sched_barrier(0); }
.LBB0_897:
	s_or_b64 exec, exec, s[24:25]
	v_lshlrev_b64 v[154:155], 7, v[152:153]
	v_lshl_add_u64 v[154:155], v[138:139], 0, v[154:155]
	v_add_co_u32_e32 v172, vcc, 0x5000, v154
	v_add_f32_e32 v136, v8, v136
	v_addc_co_u32_e32 v173, vcc, 0, v155, vcc
	v_cmp_nlt_f32_e32 vcc, s67, v136
	flat_store_dword v[172:173], v151 offset:2048
	s_and_saveexec_b64 s[24:25], vcc
	s_cbranch_execz .LBB0_899
	v_mul_f32_e32 v136, 0x3fb8aa3b, v136
	v_exp_f32_e32 v136, v136
	s_nop 0
	v_add_f32_e32 v151, 1.0, v136
	v_frexp_mant_f32_e32 v156, v151
	v_cvt_f64_f32_e32 v[172:173], v151
	v_add_f32_e32 v153, -1.0, v151
	v_frexp_exp_i32_f64_e32 v172, v[172:173]
	v_cmp_gt_f32_e32 vcc, s68, v156
	v_sub_f32_e32 v174, v153, v151
	v_sub_f32_e32 v153, v136, v153
	v_subbrev_co_u32_e32 v156, vcc, 0, v172, vcc
	v_add_f32_e32 v174, 1.0, v174
	v_sub_u32_e32 v172, 0, v156
	v_add_f32_e32 v153, v153, v174
	v_ldexp_f32 v151, v151, v172
	v_ldexp_f32 v153, v153, v172
	v_add_f32_e32 v172, -1.0, v151
	v_add_f32_e32 v173, 1.0, v172
	v_sub_f32_e32 v173, v151, v173
	v_add_f32_e32 v174, v153, v173
	v_add_f32_e32 v173, 1.0, v151
	v_add_f32_e32 v175, -1.0, v173
	v_sub_f32_e32 v151, v151, v175
	v_add_f32_e32 v151, v153, v151
	v_add_f32_e32 v153, v173, v151
	v_rcp_f32_e32 v180, v153
	v_sub_f32_e32 v173, v153, v173
	v_sub_f32_e32 v151, v151, v173
	v_add_f32_e32 v173, v172, v174
	v_sub_f32_e32 v172, v173, v172
	v_mul_f32_e32 v182, v173, v180
	v_sub_f32_e32 v181, v174, v172
	v_mul_f32_e32 v174, v153, v182
	v_fma_f32 v176, v182, v153, -v174
	v_fmac_f32_e32 v176, v182, v151
	v_add_f32_e32 v172, v174, v176
	v_sub_f32_e32 v175, v173, v172
	v_pk_add_f32 v[178:179], v[172:173], v[174:175] neg_lo:[0,1] neg_hi:[0,1]
	v_mov_b32_e32 v177, v172
	v_pk_add_f32 v[172:173], v[178:179], v[176:177] neg_lo:[0,1] neg_hi:[0,1]
	v_cmp_neq_f32_e32 vcc, s70, v136
	v_add_f32_e32 v173, v181, v173
	v_add_f32_e32 v172, v172, v173
	v_add_f32_e32 v173, v175, v172
	v_mul_f32_e32 v181, v180, v173
	v_mul_f32_e32 v174, v153, v181
	v_fma_f32 v176, v181, v153, -v174
	v_fmac_f32_e32 v176, v181, v151
	v_sub_f32_e32 v151, v175, v173
	v_add_f32_e32 v151, v172, v151
	v_add_f32_e32 v172, v174, v176
	v_sub_f32_e32 v175, v173, v172
	v_pk_add_f32 v[178:179], v[172:173], v[174:175] neg_lo:[0,1] neg_hi:[0,1]
	v_mov_b32_e32 v177, v172
	v_pk_add_f32 v[172:173], v[178:179], v[176:177] neg_lo:[0,1] neg_hi:[0,1]
	v_add_f32_e32 v153, v182, v181
	v_add_f32_e32 v151, v151, v173
	v_add_f32_e32 v151, v172, v151
	v_add_f32_e32 v151, v175, v151
	v_sub_f32_e32 v172, v153, v182
	v_mul_f32_e32 v151, v180, v151
	v_sub_f32_e32 v172, v181, v172
	v_add_f32_e32 v173, v172, v151
	v_add_f32_e32 v174, v153, v173
	v_cvt_f32_i32_e32 v172, v156
	v_mul_f32_e32 v176, v174, v174
	v_fmamk_f32 v151, v176, 0x3e9b6dac, v166
	v_sub_f32_e32 v153, v174, v153
	v_fmaak_f32 v151, v176, v151, 0x3f2aaada
	v_sub_f32_e32 v153, v173, v153
	v_mul_f32_e32 v173, v174, v176
	v_pk_mul_f32 v[176:177], v[172:173], v[150:151]
	v_ldexp_f32 v175, v174, 1
	v_fma_f32 v174, v172, s69, -v176
	v_fmac_f32_e32 v174, 0xb102e308, v172
	v_pk_add_f32 v[172:173], v[176:177], v[174:175]
	v_ldexp_f32 v153, v153, 1
	v_sub_f32_e32 v151, v173, v175
	v_sub_f32_e32 v151, v177, v151
	v_add_f32_e32 v179, v153, v151
	v_mov_b32_e32 v178, v176
	v_pk_add_f32 v[176:177], v[172:173], v[176:177] neg_lo:[0,1] neg_hi:[0,1]
	v_pk_add_f32 v[180:181], v[172:173], v[178:179]
	v_mov_b32_e32 v175, v172
	v_mov_b32_e32 v177, v181
	v_pk_add_f32 v[182:183], v[174:175], v[176:177] neg_lo:[0,1] neg_hi:[0,1]
	v_pk_add_f32 v[174:175], v[174:175], v[176:177]
	v_mov_b32_e32 v178, v179
	v_pk_add_f32 v[176:177], v[174:175], v[172:173] op_sel:[1,0] op_sel_hi:[0,1] neg_lo:[0,1] neg_hi:[0,1]
	v_pk_add_f32 v[184:185], v[180:181], v[176:177] op_sel_hi:[1,0] neg_lo:[0,1] neg_hi:[0,1]
	v_mov_b32_e32 v180, v181
	v_mov_b32_e32 v181, v175
	v_pk_mov_b32 v[176:177], v[172:173], v[176:177] op_sel:[1,0]
	v_mov_b32_e32 v179, v172
	v_pk_add_f32 v[176:177], v[180:181], v[176:177] neg_lo:[0,1] neg_hi:[0,1]
	v_mov_b32_e32 v184, v182
	v_pk_add_f32 v[172:173], v[178:179], v[176:177] neg_lo:[0,1] neg_hi:[0,1]
	v_mov_b32_e32 v183, v175
	v_pk_add_f32 v[176:177], v[184:185], v[172:173]
	s_nop 0
	v_pk_add_f32 v[178:179], v[176:177], v[176:177] op_sel:[0,1] op_sel_hi:[1,0]
	s_nop 0
	v_pk_add_f32 v[174:175], v[174:175], v[178:179] op_sel:[1,0] op_sel_hi:[0,1]
	v_mov_b32_e32 v177, v174
	v_pk_add_f32 v[180:181], v[176:177], v[182:183] neg_lo:[0,1] neg_hi:[0,1]
	v_mov_b32_e32 v173, v178
	v_sub_f32_e32 v151, v176, v180
	v_pk_add_f32 v[172:173], v[172:173], v[180:181] neg_lo:[0,1] neg_hi:[0,1]
	v_sub_f32_e32 v151, v182, v151
	v_add_f32_e32 v151, v172, v151
	v_add_f32_e32 v151, v151, v173
	v_add_f32_e32 v151, v174, v151
	v_cndmask_b32_e32 v151, v167, v151, vcc
	v_cmp_ngt_f32_e32 vcc, -1.0, v136
	s_nop 1
	v_cndmask_b32_e32 v151, v168, v151, vcc
	v_cmp_neq_f32_e32 vcc, -1.0, v136
	s_nop 1
	v_cndmask_b32_e32 v151, v169, v151, vcc
	v_cmp_lt_f32_e64 vcc, |v136|, s71
	s_nop 1
	v_cndmask_b32_e32 v136, v151, v136, vcc
;     __device__ __forceinline__ void operator()(const f32x4 (&acc)[2][2][4][2], const Unit& u, int wr, int wc, int fr, int fq) const {
;     ...
;                     for (int m = 0; m < 4; ++m) { const int r = row0 + ai * HALF + m * 16;
;                         const f32x4 v0 = acc[ai][0][m][0], v1 = acc[ai][0][m][1]; float* dp = DT + (size_t)r * 32 + c0;
; #pragma unroll
;                         for (int i = 0; i < 4; ++i) { float x0 = v0[i] + dt_bias[c0 + i], x1 = v1[i] + dt_bias[c0 + 4 + i];
;                             dp[i] = x0 > 20.f ? x0 : log1pf(__expf(x0)); dp[4 + i] = x1 > 20.f ? x1 : log1pf(__expf(x1)); }
;                         __builtin_amdgcn_sched_barrier(0); }
.LBB0_899:
	s_or_b64 exec, exec, s[24:25]
	s_mov_b64 s[24:25], 0x5800
	v_lshl_add_u64 v[154:155], v[154:155], 0, s[24:25]
	flat_store_dword v[154:155], v136 offset:16
	v_mov_b32_e32 v151, v201
	s_nop 0
	v_mov_b32_e32 v136, v205
	v_add_f32_e32 v151, v13, v151
	v_cmp_nlt_f32_e32 vcc, s67, v151
	s_and_saveexec_b64 s[24:25], vcc
	s_cbranch_execz .LBB0_901
	v_mul_f32_e32 v151, 0x3fb8aa3b, v151
	v_exp_f32_e32 v153, v151
	s_nop 0
	v_add_f32_e32 v151, 1.0, v153
	v_frexp_mant_f32_e32 v174, v151
	v_cvt_f64_f32_e32 v[172:173], v151
	v_add_f32_e32 v156, -1.0, v151
	v_frexp_exp_i32_f64_e32 v172, v[172:173]
	v_cmp_gt_f32_e32 vcc, s68, v174
	v_sub_f32_e32 v175, v156, v151
	v_sub_f32_e32 v156, v153, v156
	v_subbrev_co_u32_e32 v180, vcc, 0, v172, vcc
	v_add_f32_e32 v175, 1.0, v175
	v_sub_u32_e32 v172, 0, v180
	v_add_f32_e32 v156, v156, v175
	v_ldexp_f32 v151, v151, v172
	v_ldexp_f32 v156, v156, v172
	v_add_f32_e32 v172, -1.0, v151
	v_add_f32_e32 v173, 1.0, v172
	v_sub_f32_e32 v173, v151, v173
	v_add_f32_e32 v174, v156, v173
	v_add_f32_e32 v173, 1.0, v151
	v_add_f32_e32 v175, -1.0, v173
	v_sub_f32_e32 v151, v151, v175
	v_add_f32_e32 v151, v156, v151
	v_add_f32_e32 v156, v173, v151
	v_rcp_f32_e32 v181, v156
	v_sub_f32_e32 v173, v156, v173
	v_sub_f32_e32 v151, v151, v173
	v_add_f32_e32 v173, v172, v174
	v_sub_f32_e32 v172, v173, v172
	v_mul_f32_e32 v183, v173, v181
	v_sub_f32_e32 v182, v174, v172
	v_mul_f32_e32 v174, v156, v183
	v_fma_f32 v176, v183, v156, -v174
	v_fmac_f32_e32 v176, v183, v151
	v_add_f32_e32 v172, v174, v176
	v_sub_f32_e32 v175, v173, v172
	v_pk_add_f32 v[178:179], v[172:173], v[174:175] neg_lo:[0,1] neg_hi:[0,1]
	v_mov_b32_e32 v177, v172
	v_pk_add_f32 v[172:173], v[178:179], v[176:177] neg_lo:[0,1] neg_hi:[0,1]
	v_cmp_neq_f32_e32 vcc, s70, v153
	v_add_f32_e32 v173, v182, v173
	v_add_f32_e32 v172, v172, v173
	v_add_f32_e32 v173, v175, v172
	v_mul_f32_e32 v182, v181, v173
	v_mul_f32_e32 v174, v156, v182
	v_fma_f32 v176, v182, v156, -v174
	v_fmac_f32_e32 v176, v182, v151
	v_sub_f32_e32 v151, v175, v173
	v_add_f32_e32 v151, v172, v151
	v_add_f32_e32 v172, v174, v176
	v_sub_f32_e32 v175, v173, v172
	v_pk_add_f32 v[178:179], v[172:173], v[174:175] neg_lo:[0,1] neg_hi:[0,1]
	v_mov_b32_e32 v177, v172
	v_pk_add_f32 v[172:173], v[178:179], v[176:177] neg_lo:[0,1] neg_hi:[0,1]
	v_add_f32_e32 v156, v183, v182
	v_add_f32_e32 v151, v151, v173
	v_add_f32_e32 v151, v172, v151
	v_add_f32_e32 v151, v175, v151
	v_sub_f32_e32 v172, v156, v183
	v_mul_f32_e32 v151, v181, v151
	v_sub_f32_e32 v172, v182, v172
	v_add_f32_e32 v173, v172, v151
	v_add_f32_e32 v174, v156, v173
	v_cvt_f32_i32_e32 v172, v180
	v_mul_f32_e32 v176, v174, v174
	v_fmamk_f32 v151, v176, 0x3e9b6dac, v166
	v_sub_f32_e32 v156, v174, v156
	v_fmaak_f32 v151, v176, v151, 0x3f2aaada
	v_sub_f32_e32 v156, v173, v156
	v_mul_f32_e32 v173, v174, v176
	v_pk_mul_f32 v[176:177], v[172:173], v[150:151]
	v_ldexp_f32 v175, v174, 1
	v_fma_f32 v174, v172, s69, -v176
	v_fmac_f32_e32 v174, 0xb102e308, v172
	v_pk_add_f32 v[172:173], v[176:177], v[174:175]
	v_ldexp_f32 v156, v156, 1
	v_sub_f32_e32 v151, v173, v175
	v_sub_f32_e32 v151, v177, v151
	v_add_f32_e32 v179, v156, v151
	v_mov_b32_e32 v178, v176
	v_pk_add_f32 v[176:177], v[172:173], v[176:177] neg_lo:[0,1] neg_hi:[0,1]
	v_pk_add_f32 v[180:181], v[172:173], v[178:179]
	v_mov_b32_e32 v175, v172
	v_mov_b32_e32 v177, v181
	v_pk_add_f32 v[182:183], v[174:175], v[176:177] neg_lo:[0,1] neg_hi:[0,1]
	v_pk_add_f32 v[174:175], v[174:175], v[176:177]
	v_mov_b32_e32 v178, v179
	v_pk_add_f32 v[176:177], v[174:175], v[172:173] op_sel:[1,0] op_sel_hi:[0,1] neg_lo:[0,1] neg_hi:[0,1]
	v_pk_add_f32 v[184:185], v[180:181], v[176:177] op_sel_hi:[1,0] neg_lo:[0,1] neg_hi:[0,1]
	v_mov_b32_e32 v180, v181
	v_mov_b32_e32 v181, v175
	v_pk_mov_b32 v[176:177], v[172:173], v[176:177] op_sel:[1,0]
	v_mov_b32_e32 v179, v172
	v_pk_add_f32 v[176:177], v[180:181], v[176:177] neg_lo:[0,1] neg_hi:[0,1]
	v_mov_b32_e32 v184, v182
	v_pk_add_f32 v[172:173], v[178:179], v[176:177] neg_lo:[0,1] neg_hi:[0,1]
	v_mov_b32_e32 v183, v175
	v_pk_add_f32 v[176:177], v[184:185], v[172:173]
	s_nop 0
	v_pk_add_f32 v[178:179], v[176:177], v[176:177] op_sel:[0,1] op_sel_hi:[1,0]
	s_nop 0
	v_pk_add_f32 v[174:175], v[174:175], v[178:179] op_sel:[1,0] op_sel_hi:[0,1]
	v_mov_b32_e32 v177, v174
	v_pk_add_f32 v[180:181], v[176:177], v[182:183] neg_lo:[0,1] neg_hi:[0,1]
	v_mov_b32_e32 v173, v178
	v_sub_f32_e32 v151, v176, v180
	v_pk_add_f32 v[172:173], v[172:173], v[180:181] neg_lo:[0,1] neg_hi:[0,1]
	v_sub_f32_e32 v151, v182, v151
	v_add_f32_e32 v151, v172, v151
	v_add_f32_e32 v151, v151, v173
	v_add_f32_e32 v151, v174, v151
	v_cndmask_b32_e32 v151, v167, v151, vcc
	v_cmp_ngt_f32_e32 vcc, -1.0, v153
	s_nop 1
	v_cndmask_b32_e32 v151, v168, v151, vcc
	v_cmp_neq_f32_e32 vcc, -1.0, v153
	s_nop 1
	v_cndmask_b32_e32 v151, v169, v151, vcc
	v_cmp_lt_f32_e64 vcc, |v153|, s71
	s_nop 1
	v_cndmask_b32_e32 v151, v151, v153, vcc

;     __device__ __forceinline__ void operator()(const f32x4 (&acc)[2][2][4][2], const Unit& u, int wr, int wc, int fr, int fq) const {
;     ...
;                     for (int m = 0; m < 4; ++m) { const int r = row0 + ai * HALF + m * 16;
;                         const f32x4 v0 = acc[ai][0][m][0], v1 = acc[ai][0][m][1]; float* dp = DT + (size_t)r * 32 + c0;
; #pragma unroll
;                         for (int i = 0; i < 4; ++i) { float x0 = v0[i] + dt_bias[c0 + i], x1 = v1[i] + dt_bias[c0 + 4 + i];
;                             dp[i] = x0 > 20.f ? x0 : log1pf(__expf(x0)); dp[4 + i] = x1 > 20.f ? x1 : log1pf(__expf(x1)); }
;                         __builtin_amdgcn_sched_barrier(0); }
.LBB0_903:
	s_or_b64 exec, exec, s[24:25]
	flat_store_dword v[154:155], v136 offset:20
	v_mov_b32_e32 v136, v202
	v_add_f32_e32 v151, v14, v136
	v_mov_b32_e32 v136, v206
	v_cmp_nlt_f32_e32 vcc, s67, v151
	s_and_saveexec_b64 s[24:25], vcc
	s_cbranch_execz .LBB0_905
	v_mul_f32_e32 v151, 0x3fb8aa3b, v151
	v_exp_f32_e32 v153, v151
	s_nop 0
	v_add_f32_e32 v151, 1.0, v153
	v_frexp_mant_f32_e32 v174, v151
	v_cvt_f64_f32_e32 v[172:173], v151
	v_add_f32_e32 v156, -1.0, v151
	v_frexp_exp_i32_f64_e32 v172, v[172:173]
	v_cmp_gt_f32_e32 vcc, s68, v174
	v_sub_f32_e32 v175, v156, v151
	v_sub_f32_e32 v156, v153, v156
	v_subbrev_co_u32_e32 v180, vcc, 0, v172, vcc
	v_add_f32_e32 v175, 1.0, v175
	v_sub_u32_e32 v172, 0, v180
	v_add_f32_e32 v156, v156, v175
	v_ldexp_f32 v151, v151, v172
	v_ldexp_f32 v156, v156, v172
	v_add_f32_e32 v172, -1.0, v151
	v_add_f32_e32 v173, 1.0, v172
	v_sub_f32_e32 v173, v151, v173
	v_add_f32_e32 v174, v156, v173
	v_add_f32_e32 v173, 1.0, v151
	v_add_f32_e32 v175, -1.0, v173
	v_sub_f32_e32 v151, v151, v175
	v_add_f32_e32 v151, v156, v151
	v_add_f32_e32 v156, v173, v151
	v_rcp_f32_e32 v181, v156
	v_sub_f32_e32 v173, v156, v173
	v_sub_f32_e32 v151, v151, v173
	v_add_f32_e32 v173, v172, v174
	v_sub_f32_e32 v172, v173, v172
	v_mul_f32_e32 v183, v173, v181
	v_sub_f32_e32 v182, v174, v172
	v_mul_f32_e32 v174, v156, v183
	v_fma_f32 v176, v183, v156, -v174
	v_fmac_f32_e32 v176, v183, v151
	v_add_f32_e32 v172, v174, v176
	v_sub_f32_e32 v175, v173, v172
	v_pk_add_f32 v[178:179], v[172:173], v[174:175] neg_lo:[0,1] neg_hi:[0,1]
	v_mov_b32_e32 v177, v172
	v_pk_add_f32 v[172:173], v[178:179], v[176:177] neg_lo:[0,1] neg_hi:[0,1]
	v_cmp_neq_f32_e32 vcc, s70, v153
	v_add_f32_e32 v173, v182, v173
	v_add_f32_e32 v172, v172, v173
	v_add_f32_e32 v173, v175, v172
	v_mul_f32_e32 v182, v181, v173
	v_mul_f32_e32 v174, v156, v182
	v_fma_f32 v176, v182, v156, -v174
	v_fmac_f32_e32 v176, v182, v151
	v_sub_f32_e32 v151, v175, v173
	v_add_f32_e32 v151, v172, v151
	v_add_f32_e32 v172, v174, v176
	v_sub_f32_e32 v175, v173, v172
	v_pk_add_f32 v[178:179], v[172:173], v[174:175] neg_lo:[0,1] neg_hi:[0,1]
	v_mov_b32_e32 v177, v172
	v_pk_add_f32 v[172:173], v[178:179], v[176:177] neg_lo:[0,1] neg_hi:[0,1]
	v_add_f32_e32 v156, v183, v182
	v_add_f32_e32 v151, v151, v173
	v_add_f32_e32 v151, v172, v151
	v_add_f32_e32 v151, v175, v151
	v_sub_f32_e32 v172, v156, v183
	v_mul_f32_e32 v151, v181, v151
	v_sub_f32_e32 v172, v182, v172
	v_add_f32_e32 v173, v172, v151
	v_add_f32_e32 v174, v156, v173
	v_cvt_f32_i32_e32 v172, v180
	v_mul_f32_e32 v176, v174, v174
	v_fmamk_f32 v151, v176, 0x3e9b6dac, v166
	v_sub_f32_e32 v156, v174, v156
	v_fmaak_f32 v151, v176, v151, 0x3f2aaada
	v_sub_f32_e32 v156, v173, v156
	v_mul_f32_e32 v173, v174, v176
	v_pk_mul_f32 v[176:177], v[172:173], v[150:151]
	v_ldexp_f32 v175, v174, 1
	v_fma_f32 v174, v172, s69, -v176
	v_fmac_f32_e32 v174, 0xb102e308, v172
	v_pk_add_f32 v[172:173], v[176:177], v[174:175]
	v_ldexp_f32 v156, v156, 1
	v_sub_f32_e32 v151, v173, v175
	v_sub_f32_e32 v151, v177, v151
	v_add_f32_e32 v179, v156, v151
	v_mov_b32_e32 v178, v176
	v_pk_add_f32 v[176:177], v[172:173], v[176:177] neg_lo:[0,1] neg_hi:[0,1]
	v_pk_add_f32 v[180:181], v[172:173], v[178:179]
	v_mov_b32_e32 v175, v172
	v_mov_b32_e32 v177, v181
	v_pk_add_f32 v[182:183], v[174:175], v[176:177] neg_lo:[0,1] neg_hi:[0,1]
	v_pk_add_f32 v[174:175], v[174:175], v[176:177]
	v_mov_b32_e32 v178, v179
	v_pk_add_f32 v[176:177], v[174:175], v[172:173] op_sel:[1,0] op_sel_hi:[0,1] neg_lo:[0,1] neg_hi:[0,1]
	v_pk_add_f32 v[184:185], v[180:181], v[176:177] op_sel_hi:[1,0] neg_lo:[0,1] neg_hi:[0,1]
	v_mov_b32_e32 v180, v181
	v_mov_b32_e32 v181, v175
	v_pk_mov_b32 v[176:177], v[172:173], v[176:177] op_sel:[1,0]
	v_mov_b32_e32 v179, v172
	v_pk_add_f32 v[176:177], v[180:181], v[176:177] neg_lo:[0,1] neg_hi:[0,1]
	v_mov_b32_e32 v184, v182
	v_pk_add_f32 v[172:173], v[178:179], v[176:177] neg_lo:[0,1] neg_hi:[0,1]
	v_mov_b32_e32 v183, v175
	v_pk_add_f32 v[176:177], v[184:185], v[172:173]
	s_nop 0
	v_pk_add_f32 v[178:179], v[176:177], v[176:177] op_sel:[0,1] op_sel_hi:[1,0]
	s_nop 0
	v_pk_add_f32 v[174:175], v[174:175], v[178:179] op_sel:[1,0] op_sel_hi:[0,1]
	v_mov_b32_e32 v177, v174
	v_pk_add_f32 v[180:181], v[176:177], v[182:183] neg_lo:[0,1] neg_hi:[0,1]
	v_mov_b32_e32 v173, v178
	v_sub_f32_e32 v151, v176, v180
	v_pk_add_f32 v[172:173], v[172:173], v[180:181] neg_lo:[0,1] neg_hi:[0,1]
	v_sub_f32_e32 v151, v182, v151
	v_add_f32_e32 v151, v172, v151
	v_add_f32_e32 v151, v151, v173
	v_add_f32_e32 v151, v174, v151
	v_cndmask_b32_e32 v151, v167, v151, vcc
	v_cmp_ngt_f32_e32 vcc, -1.0, v153
	s_nop 1
	v_cndmask_b32_e32 v151, v168, v151, vcc
	v_cmp_neq_f32_e32 vcc, -1.0, v153
	s_nop 1
	v_cndmask_b32_e32 v151, v169, v151, vcc
	v_cmp_lt_f32_e64 vcc, |v153|, s71
	s_nop 1
	v_cndmask_b32_e32 v151, v151, v153, vcc
;     __device__ __forceinline__ void operator()(const f32x4 (&acc)[2][2][4][2], const Unit& u, int wr, int wc, int fr, int fq) const {
;     ...
;                     for (int m = 0; m < 4; ++m) { const int r = row0 + ai * HALF + m * 16;
;                         const f32x4 v0 = acc[ai][0][m][0], v1 = acc[ai][0][m][1]; float* dp = DT + (size_t)r * 32 + c0;
; #pragma unroll
;                         for (int i = 0; i < 4; ++i) { float x0 = v0[i] + dt_bias[c0 + i], x1 = v1[i] + dt_bias[c0 + 4 + i];
;                             dp[i] = x0 > 20.f ? x0 : log1pf(__expf(x0)); dp[4 + i] = x1 > 20.f ? x1 : log1pf(__expf(x1)); }
;                         __builtin_amdgcn_sched_barrier(0); }
.LBB0_905:
	s_or_b64 exec, exec, s[24:25]
	v_add_f32_e32 v136, v10, v136
	v_cmp_nlt_f32_e32 vcc, s67, v136
	flat_store_dword v[154:155], v151 offset:8
	s_and_saveexec_b64 s[24:25], vcc
	s_cbranch_execz .LBB0_907
	v_mul_f32_e32 v136, 0x3fb8aa3b, v136
	v_exp_f32_e32 v136, v136
	s_nop 0
	v_add_f32_e32 v151, 1.0, v136
	v_frexp_mant_f32_e32 v156, v151
	v_cvt_f64_f32_e32 v[172:173], v151
	v_add_f32_e32 v153, -1.0, v151
	v_frexp_exp_i32_f64_e32 v172, v[172:173]
	v_cmp_gt_f32_e32 vcc, s68, v156
	v_sub_f32_e32 v174, v153, v151
	v_sub_f32_e32 v153, v136, v153
	v_subbrev_co_u32_e32 v156, vcc, 0, v172, vcc
	v_add_f32_e32 v174, 1.0, v174
	v_sub_u32_e32 v172, 0, v156
	v_add_f32_e32 v153, v153, v174
	v_ldexp_f32 v151, v151, v172
	v_ldexp_f32 v153, v153, v172
	v_add_f32_e32 v172, -1.0, v151
	v_add_f32_e32 v173, 1.0, v172
	v_sub_f32_e32 v173, v151, v173
	v_add_f32_e32 v174, v153, v173
	v_add_f32_e32 v173, 1.0, v151
	v_add_f32_e32 v175, -1.0, v173
	v_sub_f32_e32 v151, v151, v175
	v_add_f32_e32 v151, v153, v151
	v_add_f32_e32 v153, v173, v151
	v_rcp_f32_e32 v180, v153
	v_sub_f32_e32 v173, v153, v173
	v_sub_f32_e32 v151, v151, v173
	v_add_f32_e32 v173, v172, v174
	v_sub_f32_e32 v172, v173, v172
	v_mul_f32_e32 v182, v173, v180
	v_sub_f32_e32 v181, v174, v172
	v_mul_f32_e32 v174, v153, v182
	v_fma_f32 v176, v182, v153, -v174
	v_fmac_f32_e32 v176, v182, v151
	v_add_f32_e32 v172, v174, v176
	v_sub_f32_e32 v175, v173, v172
	v_pk_add_f32 v[178:179], v[172:173], v[174:175] neg_lo:[0,1] neg_hi:[0,1]
	v_mov_b32_e32 v177, v172
	v_pk_add_f32 v[172:173], v[178:179], v[176:177] neg_lo:[0,1] neg_hi:[0,1]
	v_cmp_neq_f32_e32 vcc, s70, v136
	v_add_f32_e32 v173, v181, v173
	v_add_f32_e32 v172, v172, v173
	v_add_f32_e32 v173, v175, v172
	v_mul_f32_e32 v181, v180, v173
	v_mul_f32_e32 v174, v153, v181
	v_fma_f32 v176, v181, v153, -v174
	v_fmac_f32_e32 v176, v181, v151
	v_sub_f32_e32 v151, v175, v173
	v_add_f32_e32 v151, v172, v151
	v_add_f32_e32 v172, v174, v176
	v_sub_f32_e32 v175, v173, v172
	v_pk_add_f32 v[178:179], v[172:173], v[174:175] neg_lo:[0,1] neg_hi:[0,1]
	v_mov_b32_e32 v177, v172
	v_pk_add_f32 v[172:173], v[178:179], v[176:177] neg_lo:[0,1] neg_hi:[0,1]
	v_add_f32_e32 v153, v182, v181
	v_add_f32_e32 v151, v151, v173
	v_add_f32_e32 v151, v172, v151
	v_add_f32_e32 v151, v175, v151
	v_sub_f32_e32 v172, v153, v182
	v_mul_f32_e32 v151, v180, v151
	v_sub_f32_e32 v172, v181, v172
	v_add_f32_e32 v173, v172, v151
	v_add_f32_e32 v174, v153, v173
	v_cvt_f32_i32_e32 v172, v156
	v_mul_f32_e32 v176, v174, v174
	v_fmamk_f32 v151, v176, 0x3e9b6dac, v166
	v_sub_f32_e32 v153, v174, v153
	v_fmaak_f32 v151, v176, v151, 0x3f2aaada
	v_sub_f32_e32 v153, v173, v153
	v_mul_f32_e32 v173, v174, v176
	v_pk_mul_f32 v[176:177], v[172:173], v[150:151]
	v_ldexp_f32 v175, v174, 1
	v_fma_f32 v174, v172, s69, -v176
	v_fmac_f32_e32 v174, 0xb102e308, v172
	v_pk_add_f32 v[172:173], v[176:177], v[174:175]
	v_ldexp_f32 v153, v153, 1
	v_sub_f32_e32 v151, v173, v175
	v_sub_f32_e32 v151, v177, v151
	v_add_f32_e32 v179, v153, v151
	v_mov_b32_e32 v178, v176
	v_pk_add_f32 v[176:177], v[172:173], v[176:177] neg_lo:[0,1] neg_hi:[0,1]
	v_pk_add_f32 v[180:181], v[172:173], v[178:179]
	v_mov_b32_e32 v175, v172
	v_mov_b32_e32 v177, v181
	v_pk_add_f32 v[182:183], v[174:175], v[176:177] neg_lo:[0,1] neg_hi:[0,1]
	v_pk_add_f32 v[174:175], v[174:175], v[176:177]
	v_mov_b32_e32 v178, v179
	v_pk_add_f32 v[176:177], v[174:175], v[172:173] op_sel:[1,0] op_sel_hi:[0,1] neg_lo:[0,1] neg_hi:[0,1]
	v_pk_add_f32 v[184:185], v[180:181], v[176:177] op_sel_hi:[1,0] neg_lo:[0,1] neg_hi:[0,1]
	v_mov_b32_e32 v180, v181
	v_mov_b32_e32 v181, v175
	v_pk_mov_b32 v[176:177], v[172:173], v[176:177] op_sel:[1,0]
	v_mov_b32_e32 v179, v172
	v_pk_add_f32 v[176:177], v[180:181], v[176:177] neg_lo:[0,1] neg_hi:[0,1]
	v_mov_b32_e32 v184, v182
	v_pk_add_f32 v[172:173], v[178:179], v[176:177] neg_lo:[0,1] neg_hi:[0,1]
	v_mov_b32_e32 v183, v175
	v_pk_add_f32 v[176:177], v[184:185], v[172:173]
	s_nop 0
	v_pk_add_f32 v[178:179], v[176:177], v[176:177] op_sel:[0,1] op_sel_hi:[1,0]
	s_nop 0
	v_pk_add_f32 v[174:175], v[174:175], v[178:179] op_sel:[1,0] op_sel_hi:[0,1]
	v_mov_b32_e32 v177, v174
	v_pk_add_f32 v[180:181], v[176:177], v[182:183] neg_lo:[0,1] neg_hi:[0,1]
	v_mov_b32_e32 v173, v178
	v_sub_f32_e32 v151, v176, v180
	v_pk_add_f32 v[172:173], v[172:173], v[180:181] neg_lo:[0,1] neg_hi:[0,1]
	v_sub_f32_e32 v151, v182, v151
	v_add_f32_e32 v151, v172, v151
	v_add_f32_e32 v151, v151, v173
	v_add_f32_e32 v151, v174, v151
	v_cndmask_b32_e32 v151, v167, v151, vcc
	v_cmp_ngt_f32_e32 vcc, -1.0, v136
	s_nop 1
	v_cndmask_b32_e32 v151, v168, v151, vcc
	v_cmp_neq_f32_e32 vcc, -1.0, v136
	s_nop 1
	v_cndmask_b32_e32 v151, v169, v151, vcc
	v_cmp_lt_f32_e64 vcc, |v136|, s71
	s_nop 1
	v_cndmask_b32_e32 v136, v151, v136, vcc
;     __device__ __forceinline__ void operator()(const f32x4 (&acc)[2][2][4][2], const Unit& u, int wr, int wc, int fr, int fq) const {
;     ...
;                     for (int m = 0; m < 4; ++m) { const int r = row0 + ai * HALF + m * 16;
;                         const f32x4 v0 = acc[ai][0][m][0], v1 = acc[ai][0][m][1]; float* dp = DT + (size_t)r * 32 + c0;
; #pragma unroll
;                         for (int i = 0; i < 4; ++i) { float x0 = v0[i] + dt_bias[c0 + i], x1 = v1[i] + dt_bias[c0 + 4 + i];
;                             dp[i] = x0 > 20.f ? x0 : log1pf(__expf(x0)); dp[4 + i] = x1 > 20.f ? x1 : log1pf(__expf(x1)); }
;                         __builtin_amdgcn_sched_barrier(0); }
.LBB0_907:
	s_or_b64 exec, exec, s[24:25]
	flat_store_dword v[154:155], v136 offset:24
	v_mov_b32_e32 v136, v203
	v_add_f32_e32 v151, v15, v136
	v_mov_b32_e32 v136, v207
	v_cmp_nlt_f32_e32 vcc, s67, v151
	s_and_saveexec_b64 s[24:25], vcc
	s_cbranch_execz .LBB0_909
	v_mul_f32_e32 v151, 0x3fb8aa3b, v151
	v_exp_f32_e32 v153, v151
	s_nop 0
	v_add_f32_e32 v151, 1.0, v153
	v_frexp_mant_f32_e32 v174, v151
	v_cvt_f64_f32_e32 v[172:173], v151
	v_add_f32_e32 v156, -1.0, v151
	v_frexp_exp_i32_f64_e32 v172, v[172:173]
	v_cmp_gt_f32_e32 vcc, s68, v174
	v_sub_f32_e32 v175, v156, v151
	v_sub_f32_e32 v156, v153, v156
	v_subbrev_co_u32_e32 v180, vcc, 0, v172, vcc
	v_add_f32_e32 v175, 1.0, v175
	v_sub_u32_e32 v172, 0, v180
	v_add_f32_e32 v156, v156, v175
	v_ldexp_f32 v151, v151, v172
	v_ldexp_f32 v156, v156, v172
	v_add_f32_e32 v172, -1.0, v151
	v_add_f32_e32 v173, 1.0, v172
	v_sub_f32_e32 v173, v151, v173
	v_add_f32_e32 v174, v156, v173
	v_add_f32_e32 v173, 1.0, v151
	v_add_f32_e32 v175, -1.0, v173
	v_sub_f32_e32 v151, v151, v175
	v_add_f32_e32 v151, v156, v151
	v_add_f32_e32 v156, v173, v151
	v_rcp_f32_e32 v181, v156
	v_sub_f32_e32 v173, v156, v173
	v_sub_f32_e32 v151, v151, v173
	v_add_f32_e32 v173, v172, v174
	v_sub_f32_e32 v172, v173, v172
	v_mul_f32_e32 v183, v173, v181
	v_sub_f32_e32 v182, v174, v172
	v_mul_f32_e32 v174, v156, v183
	v_fma_f32 v176, v183, v156, -v174
	v_fmac_f32_e32 v176, v183, v151
	v_add_f32_e32 v172, v174, v176
	v_sub_f32_e32 v175, v173, v172
	v_pk_add_f32 v[178:179], v[172:173], v[174:175] neg_lo:[0,1] neg_hi:[0,1]
	v_mov_b32_e32 v177, v172
	v_pk_add_f32 v[172:173], v[178:179], v[176:177] neg_lo:[0,1] neg_hi:[0,1]
	v_cmp_neq_f32_e32 vcc, s70, v153
	v_add_f32_e32 v173, v182, v173
	v_add_f32_e32 v172, v172, v173
	v_add_f32_e32 v173, v175, v172
	v_mul_f32_e32 v182, v181, v173
	v_mul_f32_e32 v174, v156, v182
	v_fma_f32 v176, v182, v156, -v174
	v_fmac_f32_e32 v176, v182, v151
	v_sub_f32_e32 v151, v175, v173
	v_add_f32_e32 v151, v172, v151
	v_add_f32_e32 v172, v174, v176
	v_sub_f32_e32 v175, v173, v172
	v_pk_add_f32 v[178:179], v[172:173], v[174:175] neg_lo:[0,1] neg_hi:[0,1]
	v_mov_b32_e32 v177, v172
	v_pk_add_f32 v[172:173], v[178:179], v[176:177] neg_lo:[0,1] neg_hi:[0,1]
	v_add_f32_e32 v156, v183, v182
	v_add_f32_e32 v151, v151, v173
	v_add_f32_e32 v151, v172, v151
	v_add_f32_e32 v151, v175, v151
	v_sub_f32_e32 v172, v156, v183
	v_mul_f32_e32 v151, v181, v151
	v_sub_f32_e32 v172, v182, v172
	v_add_f32_e32 v173, v172, v151
	v_add_f32_e32 v174, v156, v173
	v_cvt_f32_i32_e32 v172, v180
	v_mul_f32_e32 v176, v174, v174
	v_fmamk_f32 v151, v176, 0x3e9b6dac, v166
	v_sub_f32_e32 v156, v174, v156
	v_fmaak_f32 v151, v176, v151, 0x3f2aaada
	v_sub_f32_e32 v156, v173, v156
	v_mul_f32_e32 v173, v174, v176
	v_pk_mul_f32 v[176:177], v[172:173], v[150:151]
	v_ldexp_f32 v175, v174, 1
	v_fma_f32 v174, v172, s69, -v176
	v_fmac_f32_e32 v174, 0xb102e308, v172
	v_pk_add_f32 v[172:173], v[176:177], v[174:175]
	v_ldexp_f32 v156, v156, 1
	v_sub_f32_e32 v151, v173, v175
	v_sub_f32_e32 v151, v177, v151
	v_add_f32_e32 v179, v156, v151
	v_mov_b32_e32 v178, v176
	v_pk_add_f32 v[176:177], v[172:173], v[176:177] neg_lo:[0,1] neg_hi:[0,1]
	v_pk_add_f32 v[180:181], v[172:173], v[178:179]
	v_mov_b32_e32 v175, v172
	v_mov_b32_e32 v177, v181
	v_pk_add_f32 v[182:183], v[174:175], v[176:177] neg_lo:[0,1] neg_hi:[0,1]
	v_pk_add_f32 v[174:175], v[174:175], v[176:177]
	v_mov_b32_e32 v178, v179
	v_pk_add_f32 v[176:177], v[174:175], v[172:173] op_sel:[1,0] op_sel_hi:[0,1] neg_lo:[0,1] neg_hi:[0,1]
	v_pk_add_f32 v[184:185], v[180:181], v[176:177] op_sel_hi:[1,0] neg_lo:[0,1] neg_hi:[0,1]
	v_mov_b32_e32 v180, v181
	v_mov_b32_e32 v181, v175
	v_pk_mov_b32 v[176:177], v[172:173], v[176:177] op_sel:[1,0]
	v_mov_b32_e32 v179, v172
	v_pk_add_f32 v[176:177], v[180:181], v[176:177] neg_lo:[0,1] neg_hi:[0,1]
	v_mov_b32_e32 v184, v182
	v_pk_add_f32 v[172:173], v[178:179], v[176:177] neg_lo:[0,1] neg_hi:[0,1]
	v_mov_b32_e32 v183, v175
	v_pk_add_f32 v[176:177], v[184:185], v[172:173]
	s_nop 0
	v_pk_add_f32 v[178:179], v[176:177], v[176:177] op_sel:[0,1] op_sel_hi:[1,0]
	s_nop 0
	v_pk_add_f32 v[174:175], v[174:175], v[178:179] op_sel:[1,0] op_sel_hi:[0,1]
	v_mov_b32_e32 v177, v174
	v_pk_add_f32 v[180:181], v[176:177], v[182:183] neg_lo:[0,1] neg_hi:[0,1]
	v_mov_b32_e32 v173, v178
	v_sub_f32_e32 v151, v176, v180
	v_pk_add_f32 v[172:173], v[172:173], v[180:181] neg_lo:[0,1] neg_hi:[0,1]
	v_sub_f32_e32 v151, v182, v151
	v_add_f32_e32 v151, v172, v151
	v_add_f32_e32 v151, v151, v173
	v_add_f32_e32 v151, v174, v151
	v_cndmask_b32_e32 v151, v167, v151, vcc
	v_cmp_ngt_f32_e32 vcc, -1.0, v153
	s_nop 1
	v_cndmask_b32_e32 v151, v168, v151, vcc
	v_cmp_neq_f32_e32 vcc, -1.0, v153
	s_nop 1
	v_cndmask_b32_e32 v151, v169, v151, vcc
	v_cmp_lt_f32_e64 vcc, |v153|, s71
	s_nop 1
	v_cndmask_b32_e32 v151, v151, v153, vcc
;     __device__ __forceinline__ void operator()(const f32x4 (&acc)[2][2][4][2], const Unit& u, int wr, int wc, int fr, int fq) const {
;     ...
;                     for (int m = 0; m < 4; ++m) { const int r = row0 + ai * HALF + m * 16;
;                         const f32x4 v0 = acc[ai][0][m][0], v1 = acc[ai][0][m][1]; float* dp = DT + (size_t)r * 32 + c0;
; #pragma unroll
;                         for (int i = 0; i < 4; ++i) { float x0 = v0[i] + dt_bias[c0 + i], x1 = v1[i] + dt_bias[c0 + 4 + i];
;                             dp[i] = x0 > 20.f ? x0 : log1pf(__expf(x0)); dp[4 + i] = x1 > 20.f ? x1 : log1pf(__expf(x1)); }
;                         __builtin_amdgcn_sched_barrier(0); }
.LBB0_909:
	s_or_b64 exec, exec, s[24:25]
	v_add_f32_e32 v136, v11, v136
	v_cmp_nlt_f32_e32 vcc, s67, v136
	flat_store_dword v[154:155], v151 offset:12
	s_and_saveexec_b64 s[24:25], vcc
	s_cbranch_execz .LBB0_911
	v_mul_f32_e32 v136, 0x3fb8aa3b, v136
	v_exp_f32_e32 v136, v136
	s_nop 0
	v_add_f32_e32 v151, 1.0, v136
	v_frexp_mant_f32_e32 v156, v151
	v_cvt_f64_f32_e32 v[172:173], v151
	v_add_f32_e32 v153, -1.0, v151
	v_frexp_exp_i32_f64_e32 v172, v[172:173]
	v_cmp_gt_f32_e32 vcc, s68, v156
	v_sub_f32_e32 v174, v153, v151
	v_sub_f32_e32 v153, v136, v153
	v_subbrev_co_u32_e32 v156, vcc, 0, v172, vcc
	v_add_f32_e32 v174, 1.0, v174
	v_sub_u32_e32 v172, 0, v156
	v_add_f32_e32 v153, v153, v174
	v_ldexp_f32 v151, v151, v172
	v_ldexp_f32 v153, v153, v172
	v_add_f32_e32 v172, -1.0, v151
	v_add_f32_e32 v173, 1.0, v172
	v_sub_f32_e32 v173, v151, v173
	v_add_f32_e32 v174, v153, v173
	v_add_f32_e32 v173, 1.0, v151
	v_add_f32_e32 v175, -1.0, v173
	v_sub_f32_e32 v151, v151, v175
	v_add_f32_e32 v151, v153, v151
	v_add_f32_e32 v153, v173, v151
	v_rcp_f32_e32 v180, v153
	v_sub_f32_e32 v173, v153, v173
	v_sub_f32_e32 v151, v151, v173
	v_add_f32_e32 v173, v172, v174
	v_sub_f32_e32 v172, v173, v172
	v_mul_f32_e32 v182, v173, v180
	v_sub_f32_e32 v181, v174, v172
	v_mul_f32_e32 v174, v153, v182
	v_fma_f32 v176, v182, v153, -v174
	v_fmac_f32_e32 v176, v182, v151
	v_add_f32_e32 v172, v174, v176
	v_sub_f32_e32 v175, v173, v172
	v_pk_add_f32 v[178:179], v[172:173], v[174:175] neg_lo:[0,1] neg_hi:[0,1]
	v_mov_b32_e32 v177, v172
	v_pk_add_f32 v[172:173], v[178:179], v[176:177] neg_lo:[0,1] neg_hi:[0,1]
	v_cmp_neq_f32_e32 vcc, s70, v136
	v_add_f32_e32 v173, v181, v173
	v_add_f32_e32 v172, v172, v173
	v_add_f32_e32 v173, v175, v172
	v_mul_f32_e32 v181, v180, v173
	v_mul_f32_e32 v174, v153, v181
	v_fma_f32 v176, v181, v153, -v174
	v_fmac_f32_e32 v176, v181, v151
	v_sub_f32_e32 v151, v175, v173
	v_add_f32_e32 v151, v172, v151
	v_add_f32_e32 v172, v174, v176
	v_sub_f32_e32 v175, v173, v172
	v_pk_add_f32 v[178:179], v[172:173], v[174:175] neg_lo:[0,1] neg_hi:[0,1]
	v_mov_b32_e32 v177, v172
	v_pk_add_f32 v[172:173], v[178:179], v[176:177] neg_lo:[0,1] neg_hi:[0,1]
	v_add_f32_e32 v153, v182, v181
	v_add_f32_e32 v151, v151, v173
	v_add_f32_e32 v151, v172, v151
	v_add_f32_e32 v151, v175, v151
	v_sub_f32_e32 v172, v153, v182
	v_mul_f32_e32 v151, v180, v151
	v_sub_f32_e32 v172, v181, v172
	v_add_f32_e32 v173, v172, v151
	v_add_f32_e32 v174, v153, v173
	v_cvt_f32_i32_e32 v172, v156
	v_mul_f32_e32 v176, v174, v174
	v_fmamk_f32 v151, v176, 0x3e9b6dac, v166
	v_sub_f32_e32 v153, v174, v153
	v_fmaak_f32 v151, v176, v151, 0x3f2aaada
	v_sub_f32_e32 v153, v173, v153
	v_mul_f32_e32 v173, v174, v176
	v_pk_mul_f32 v[176:177], v[172:173], v[150:151]
	v_ldexp_f32 v175, v174, 1
	v_fma_f32 v174, v172, s69, -v176
	v_fmac_f32_e32 v174, 0xb102e308, v172
	v_pk_add_f32 v[172:173], v[176:177], v[174:175]
	v_ldexp_f32 v153, v153, 1
	v_sub_f32_e32 v151, v173, v175
	v_sub_f32_e32 v151, v177, v151
	v_add_f32_e32 v179, v153, v151
	v_mov_b32_e32 v178, v176
	v_pk_add_f32 v[176:177], v[172:173], v[176:177] neg_lo:[0,1] neg_hi:[0,1]
	v_pk_add_f32 v[180:181], v[172:173], v[178:179]
	v_mov_b32_e32 v175, v172
	v_mov_b32_e32 v177, v181
	v_pk_add_f32 v[182:183], v[174:175], v[176:177] neg_lo:[0,1] neg_hi:[0,1]
	v_pk_add_f32 v[174:175], v[174:175], v[176:177]
	v_mov_b32_e32 v178, v179
	v_pk_add_f32 v[176:177], v[174:175], v[172:173] op_sel:[1,0] op_sel_hi:[0,1] neg_lo:[0,1] neg_hi:[0,1]
	v_pk_add_f32 v[184:185], v[180:181], v[176:177] op_sel_hi:[1,0] neg_lo:[0,1] neg_hi:[0,1]
	v_mov_b32_e32 v180, v181
	v_mov_b32_e32 v181, v175
	v_pk_mov_b32 v[176:177], v[172:173], v[176:177] op_sel:[1,0]
	v_mov_b32_e32 v179, v172
	v_pk_add_f32 v[176:177], v[180:181], v[176:177] neg_lo:[0,1] neg_hi:[0,1]
	v_mov_b32_e32 v184, v182
	v_pk_add_f32 v[172:173], v[178:179], v[176:177] neg_lo:[0,1] neg_hi:[0,1]
	v_mov_b32_e32 v183, v175
	v_pk_add_f32 v[176:177], v[184:185], v[172:173]
	s_nop 0
	v_pk_add_f32 v[178:179], v[176:177], v[176:177] op_sel:[0,1] op_sel_hi:[1,0]
	s_nop 0
	v_pk_add_f32 v[174:175], v[174:175], v[178:179] op_sel:[1,0] op_sel_hi:[0,1]
	v_mov_b32_e32 v177, v174
	v_pk_add_f32 v[180:181], v[176:177], v[182:183] neg_lo:[0,1] neg_hi:[0,1]
	v_mov_b32_e32 v173, v178
	v_sub_f32_e32 v151, v176, v180
	v_pk_add_f32 v[172:173], v[172:173], v[180:181] neg_lo:[0,1] neg_hi:[0,1]
	v_sub_f32_e32 v151, v182, v151
	v_add_f32_e32 v151, v172, v151
	v_add_f32_e32 v151, v151, v173
	v_add_f32_e32 v151, v174, v151
	v_cndmask_b32_e32 v151, v167, v151, vcc
	v_cmp_ngt_f32_e32 vcc, -1.0, v136
	s_nop 1
	v_cndmask_b32_e32 v151, v168, v151, vcc
	v_cmp_neq_f32_e32 vcc, -1.0, v136
	s_nop 1
	v_cndmask_b32_e32 v151, v169, v151, vcc
	v_cmp_lt_f32_e64 vcc, |v136|, s71
	s_nop 1
	v_cndmask_b32_e32 v136, v151, v136, vcc
